# v18
# baseline (speedup 1.0000x reference)
; __device__ __forceinline__ void skinny_proj(const Ctx& C, const bf16* X, const bf16* Wt, const float* SS, bf16* PROJ) {
;     const int fr = C.lane & 15, fq = C.lane >> 4;
;     const int r0 = (C.bid - 128) * 128 + C.wave * 16;
;     const bf16* A = X + (size_t)(r0 + fr) * D + fq * 8;
;     const bf16* W0 = Wt + (size_t)(NMAIN + fr) * D + fq * 8;
.LBB0_321:
	s_cmpk_eq_i32 s46, 0x100
	s_cselect_b64 s[6:7], -1, 0
	s_cmpk_gt_i32 s2, 0x7f
	s_cselect_b64 s[10:11], -1, 0
	s_and_b64 s[48:49], s[10:11], s[6:7]
	s_andn2_b64 vcc, exec, s[48:49]
	s_cbranch_vccnz .LBB0_325
	s_ashr_i32 s6, s36, 2
	v_and_b32_e32 v13, 15, v164
	s_and_b32 s10, s2, 7
	s_lshl_b32 s10, s10, 11
	s_sub_u32 s11, s2, 128
	s_lshr_b32 s11, s11, 3
	s_lshl_b32 s11, s11, 7
	s_add_u32 s10, s10, s11
	s_addk_i32 s10, 0x4000
	s_and_b32 s11, s6, -16
	v_and_b32_e32 v4, 48, v164
	v_lshl_or_b32 v0, v13, 12, v4
	v_mov_b32_e32 v1, 0
	s_add_i32 s6, s10, s11
	v_lshl_add_u64 v[2:3], v[0:1], 0, s[8:9]
	v_or_b32_e32 v0, s6, v13
	v_lshl_add_u64 v[8:9], v[128:129], 0, v[2:3]
	v_add_u32_e32 v2, 0xffffc000, v0
	v_ashrrev_i32_e32 v3, 31, v2
	v_lshlrev_b64 v[2:3], 12, v[2:3]
	v_or_b32_e32 v2, v2, v4
	v_lshl_add_u64 v[2:3], v[2:3], 0, s[8:9]
	v_lshl_add_u64 v[2:3], v[128:129], 0, v[2:3]
	s_mov_b64 s[6:7], 0x26100100
	v_lshrrev_b32_e32 v12, 4, v164
	v_lshl_add_u64 v[10:11], v[2:3], 0, s[6:7]
	s_mov_b64 s[6:7], 0
	v_mov_b32_e32 v0, v1
	v_mov_b32_e32 v2, v1
	v_mov_b32_e32 v3, v1
	v_mov_b32_e32 v4, v1
	v_mov_b32_e32 v5, v1
	v_mov_b32_e32 v6, v1
	v_mov_b32_e32 v7, v1

; __global__ void __launch_bounds__(NTHR, 2) fwd_megakernel(Args args) {
;     ...
; #pragma unroll 1
;         for (int it = blockIdx.x; it < 1536; it += gridDim.x) { MKCTX();
;             if (it < 1024) b1_gla_item(C, li, it >> 7, (it >> 2) & 31, it & 3);
;             else { const int r = it - 1024; b1_ssd_item(C, li, r >> 6, (r >> 1) & 31, r & 1); }
;         }
.LBB0_377:
	s_or_b64 exec, exec, s[6:7]
	s_waitcnt lgkmcnt(0)
	s_barrier
	s_load_dwordx2 s[16:17], s[0:1], 0xc0
	s_cmpk_lt_i32 s2, 0x600
	s_cselect_b64 s[38:39], -1, 0
	s_cmpk_gt_i32 s2, 0x5ff
	s_cbranch_scc1 .LBB0_423
	v_mbcnt_hi_u32_b32 v126, -1, v235
	v_bfrev_b32_e32 v0, 0.5
	s_mov_b32 s19, 0
	s_movk_i32 s33, 0x2e00
	s_movk_i32 s52, 0x2000
	v_mov_b32_e32 v85, 0
	s_mov_b32 s53, 0x41a00000
	s_mov_b32 s54, 0x800000
	s_mov_b32 s55, 0x3f317217
	s_mov_b32 s56, 0x7f800000
	v_mov_b32_e32 v124, 0x25c00000
	s_movk_i32 s57, 0x1700
	s_movk_i32 s58, 0x5000
	s_mov_b64 s[20:21], 0x1800
	s_movk_i32 s59, 0x1000
	s_mov_b64 s[22:23], 0x3000
	s_movk_i32 s60, 0x3000
	s_mov_b64 s[24:25], 0x4800
	s_movk_i32 s61, 0x4000
	s_movk_i32 s62, 0x90
	s_mov_b32 s63, 0xffff0000
	s_mov_b32 s64, 0xbfb8aa3b
	s_movk_i32 s65, 0x7fff
	s_movk_i32 s66, 0x80
	s_mov_b64 s[26:27], 0x1000
	s_mov_b32 s67, 0x12000
	s_add_i32 s68, 0, 0x12000
	s_mov_b64 s[28:29], 0x1dc00000
	s_movk_i32 s71, 0x7f
	s_movk_i32 s72, 0x6000
	s_movk_i32 s73, 0x7000
	s_mov_b32 s74, 0x3d800000
	s_mov_b32 s75, 0xa000
	s_mov_b32 s76, 0xd000
	s_mov_b32 s77, 0xf000
	s_mov_b32 s78, 0x15000
	s_mov_b32 s79, 0x18000
	s_mov_b32 s80, 0x1b000
	s_mov_b32 s81, 0x1e000
	s_mov_b32 s82, 0x21000
	s_mov_b32 s83, 0x24000
	s_mov_b32 s84, 0x26000
	s_mov_b32 s85, 0x29000
	s_mov_b32 s86, 0x2c000
	s_mov_b64 s[30:31], 0x21c00000
	s_mov_b32 s87, 0x21c01000
	v_mov_b32_e32 v125, 0x41b17218
	v_and_b32_e32 v127, 64, v126
	v_add_u32_e32 v128, -1, v126
	v_add_u32_e32 v129, -2, v126
	v_add_u32_e32 v130, -4, v126
	v_add_u32_e32 v131, -8, v126
	v_add_u32_e32 v132, -16, v126
	v_subrev_u32_e32 v133, 32, v126
	v_lshl_or_b32 v134, v126, 2, v0
	s_and_b32 s88, s2, 7
	s_lshl_b32 s88, s88, 7
	s_lshr_b32 s6, s2, 3
	s_add_u32 s88, s88, s6
	s_mov_b32 m0, 0
	s_branch .LBB0_381

; __global__ void __launch_bounds__(NTHR, 2) fwd_megakernel(Args args) {
;     ...
; #pragma unroll 1
;         for (int it = blockIdx.x; it < 1536; it += gridDim.x) { MKCTX();
.LBB0_380:
	s_add_u32 s6, m0, 1
	s_mov_b32 m0, s6
	s_add_i32 s88, s88, 32
	s_cmp_eq_u32 s6, 4
	s_cbranch_scc0 .Lrg_skip_b1l0
	s_and_b32 s6, s2, 7
	s_lshl_b32 s6, s6, 6
	s_sub_i32 s88, s88, s6
	s_addk_i32 s88, 0x380
.Lrg_skip_b1l0:
	s_cmp_gt_u32 m0, 5
	s_cbranch_scc1 .LBB0_422

; __device__ __forceinline__ void b2_scan(const Ctx& C) {
;     const float* SDEC = (const float*)(C.ws + WS_SDEC); const float* GDEC = (const float*)(C.ws + WS_GDEC);
;     const int idx = C.bid * NTHR + C.tid;
;     if (idx >= 131072) return;
;     const bool gla = idx >= 65536; const int r = idx & 65535;
;     bf16* base; size_t cstride, vstride; const float* dec; int dstride;
;     if (!gla) { const int b = r >> 13, h = (r >> 9) & 15, e = r & 511;
;         base = (bf16*)(C.ws + WS_HS) + ((size_t)(b * NC) * 16 + h) * 8192 + (size_t)e * 8; vstride = 512 * 8; cstride = (size_t)16 * 8192; dec = SDEC + (b * NC) * 16 + h; dstride = 16; }
;     else { const int b = r >> 13, h = (r >> 11) & 3, q = r & 2047, doct = q & 15, vp = q >> 4;
;         base = (bf16*)(C.ws + WS_GS) + ((size_t)(b * NC) * 4 + h) * 32768 + (size_t)(2 * vp) * 128 + doct * 8; vstride = 128; cstride = (size_t)4 * 32768; dec = GDEC + ((b * NC) * 4 + h) * 128 + doct * 8; dstride = 512; }
;     float run[2][8];
; #pragma unroll
;     for (int j = 0; j < 2; ++j)
; #pragma unroll
;         for (int q = 0; q < 8; ++q) run[j][q] = 0.f;
;     v4u loc[2][4][2]; f32x4 d0[2][4], d1[2][4];
;     ...
;     B2_LOAD(0, 0);
; #pragma unroll
;     for (int g = 0; g < 8; ++g) {
;         const int cur = g & 1;
;         if (g + 1 < 8) B2_LOAD(g + 1, cur ^ 1);
.LBB0_475:
	s_or_b64 exec, exec, s[6:7]
	v_mov_b32_e32 v8, v234
	s_mov_b32 s10, 0
	s_waitcnt lgkmcnt(0)
	s_barrier
	s_lshl_b32 s6, s2, 9
	v_writelane_b32 v254, s6, 3
	s_load_dwordx2 s[14:15], s[0:1], 0xc0
	s_mov_b64 s[8:9], exec
	s_cmp_ge_u32 s2, 256
	s_cbranch_scc1 .Lb2_end_l0
	v_mov_b32_e32 v16, 0
	v_mov_b32_e32 v17, 0
	v_mov_b32_e32 v18, 0
	v_mov_b32_e32 v19, 0
	v_mov_b32_e32 v20, 0
	v_mov_b32_e32 v21, 0
	v_mov_b32_e32 v22, 0
	v_mov_b32_e32 v23, 0
	v_mov_b32_e32 v24, 0
	v_mov_b32_e32 v25, 0
	v_mov_b32_e32 v26, 0
	v_mov_b32_e32 v27, 0
	v_mov_b32_e32 v28, 0
	v_mov_b32_e32 v29, 0
	v_mov_b32_e32 v30, 0
	v_mov_b32_e32 v31, 0
	v_mov_b32_e32 v4, 0
	s_cmp_ge_u32 s2, 128
	s_cbranch_scc1 .Lb2_gla_l0
	s_and_b32 s6, s2, 7
	s_lshl_b32 s6, s6, 9
	s_lshr_b32 s12, s2, 3
	s_add_u32 s6, s6, s12
	s_lshl_b32 s12, s6, 2
	s_lshl_b32 s6, s6, 14
	v_lshlrev_b32_e32 v2, 4, v234
	v_add_u32_e32 v3, 0x2000, v2
	s_waitcnt lgkmcnt(0)
	s_add_u32 s6, s6, s14
	s_addc_u32 s7, s15, 0
	s_add_u32 s6, s6, 0x1dc00000
	s_addc_u32 s7, s7, 0
	s_add_u32 s12, s12, s14
	s_addc_u32 s13, s15, 0
	s_add_u32 s12, s12, 0x25c00000
	s_addc_u32 s13, s13, 0
	s_mov_b32 s10, s6
	s_mov_b32 s11, s7
	global_load_dwordx4 v[64:67], v2, s[6:7] nt
	global_load_dwordx4 v[68:71], v3, s[6:7] nt
	global_load_dword v72, v4, s[12:13]
	s_add_u32 s6, s6, 0x40000
	s_addc_u32 s7, s7, 0
	s_add_u32 s12, s12, 64
	s_addc_u32 s13, s13, 0
	global_load_dwordx4 v[80:83], v2, s[6:7] nt
	global_load_dwordx4 v[84:87], v3, s[6:7] nt
	global_load_dword v88, v4, s[12:13]
	s_add_u32 s6, s6, 0x40000
	s_addc_u32 s7, s7, 0
	s_add_u32 s12, s12, 64
	s_addc_u32 s13, s13, 0
	global_load_dwordx4 v[96:99], v2, s[6:7] nt
	global_load_dwordx4 v[100:103], v3, s[6:7] nt
	global_load_dword v104, v4, s[12:13]
	s_add_u32 s6, s6, 0x40000
	s_addc_u32 s7, s7, 0
	s_add_u32 s12, s12, 64
	s_addc_u32 s13, s13, 0
	global_load_dwordx4 v[112:115], v2, s[6:7] nt
	global_load_dwordx4 v[116:119], v3, s[6:7] nt
	global_load_dword v120, v4, s[12:13]
	s_add_u32 s6, s6, 0x40000
	s_addc_u32 s7, s7, 0
	s_add_u32 s12, s12, 64
	s_addc_u32 s13, s13, 0
	global_load_dwordx4 v[128:131], v2, s[6:7] nt
	global_load_dwordx4 v[132:135], v3, s[6:7] nt
	global_load_dword v136, v4, s[12:13]
	s_add_u32 s6, s6, 0x40000
	s_addc_u32 s7, s7, 0
	s_add_u32 s12, s12, 64
	s_addc_u32 s13, s13, 0
	global_load_dwordx4 v[144:147], v2, s[6:7] nt
	global_load_dwordx4 v[148:151], v3, s[6:7] nt
	global_load_dword v152, v4, s[12:13]
	s_add_u32 s6, s6, 0x40000
	s_addc_u32 s7, s7, 0
	s_add_u32 s12, s12, 64
	s_addc_u32 s13, s13, 0
	global_load_dwordx4 v[160:163], v2, s[6:7] nt
	global_load_dwordx4 v[164:167], v3, s[6:7] nt
	global_load_dword v168, v4, s[12:13]
	s_add_u32 s6, s6, 0x40000
	s_addc_u32 s7, s7, 0
	s_add_u32 s12, s12, 64
	s_addc_u32 s13, s13, 0
	global_load_dwordx4 v[176:179], v2, s[6:7] nt
	global_load_dwordx4 v[180:183], v3, s[6:7] nt
	global_load_dword v184, v4, s[12:13]
	s_add_u32 s6, s6, 0x40000
	s_addc_u32 s7, s7, 0
	s_add_u32 s12, s12, 64
	s_addc_u32 s13, s13, 0
	s_waitcnt vmcnt(21)
	v_cvt_pk_bf16_f32 v32, v16, v17
	v_cvt_pk_bf16_f32 v33, v18, v19
	v_cvt_pk_bf16_f32 v34, v20, v21
	v_cvt_pk_bf16_f32 v35, v22, v23
	global_store_dwordx4 v2, v[32:35], s[10:11] nt
	v_cvt_pk_bf16_f32 v36, v24, v25
	v_cvt_pk_bf16_f32 v37, v26, v27
	v_cvt_pk_bf16_f32 v38, v28, v29
	v_cvt_pk_bf16_f32 v39, v30, v31
	global_store_dwordx4 v3, v[36:39], s[10:11] nt
	s_add_u32 s10, s10, 0x40000
	s_addc_u32 s11, s11, 0
	v_lshlrev_b32_e32 v48, 16, v64
	v_and_b32_e32 v49, 0xffff0000, v64
	v_fma_f32 v16, v72, v16, v48
	v_fma_f32 v17, v72, v17, v49
	v_lshlrev_b32_e32 v48, 16, v65
	v_and_b32_e32 v49, 0xffff0000, v65
	v_fma_f32 v18, v72, v18, v48
	v_fma_f32 v19, v72, v19, v49
	v_lshlrev_b32_e32 v48, 16, v66
	v_and_b32_e32 v49, 0xffff0000, v66
	v_fma_f32 v20, v72, v20, v48
	v_fma_f32 v21, v72, v21, v49
	v_lshlrev_b32_e32 v48, 16, v67
	v_and_b32_e32 v49, 0xffff0000, v67
	v_fma_f32 v22, v72, v22, v48
	v_fma_f32 v23, v72, v23, v49
	v_lshlrev_b32_e32 v48, 16, v68
	v_and_b32_e32 v49, 0xffff0000, v68
	v_fma_f32 v24, v72, v24, v48
	v_fma_f32 v25, v72, v25, v49
	v_lshlrev_b32_e32 v48, 16, v69
	v_and_b32_e32 v49, 0xffff0000, v69
	v_fma_f32 v26, v72, v26, v48
	v_fma_f32 v27, v72, v27, v49
	v_lshlrev_b32_e32 v48, 16, v70
	v_and_b32_e32 v49, 0xffff0000, v70
	v_fma_f32 v28, v72, v28, v48
	v_fma_f32 v29, v72, v29, v49
	v_lshlrev_b32_e32 v48, 16, v71
	v_and_b32_e32 v49, 0xffff0000, v71
	v_fma_f32 v30, v72, v30, v48
	v_fma_f32 v31, v72, v31, v49
	global_load_dwordx4 v[64:67], v2, s[6:7] nt
	global_load_dwordx4 v[68:71], v3, s[6:7] nt
	global_load_dword v72, v4, s[12:13]
	s_add_u32 s6, s6, 0x40000
	s_addc_u32 s7, s7, 0
	s_add_u32 s12, s12, 64
	s_addc_u32 s13, s13, 0
	s_waitcnt vmcnt(23)
	v_cvt_pk_bf16_f32 v40, v16, v17
	v_cvt_pk_bf16_f32 v41, v18, v19
	v_cvt_pk_bf16_f32 v42, v20, v21
	v_cvt_pk_bf16_f32 v43, v22, v23
	global_store_dwordx4 v2, v[40:43], s[10:11] nt
	v_cvt_pk_bf16_f32 v44, v24, v25
	v_cvt_pk_bf16_f32 v45, v26, v27
	v_cvt_pk_bf16_f32 v46, v28, v29
	v_cvt_pk_bf16_f32 v47, v30, v31
	global_store_dwordx4 v3, v[44:47], s[10:11] nt
	s_add_u32 s10, s10, 0x40000
	s_addc_u32 s11, s11, 0
	v_lshlrev_b32_e32 v48, 16, v80
	v_and_b32_e32 v49, 0xffff0000, v80
	v_fma_f32 v16, v88, v16, v48
	v_fma_f32 v17, v88, v17, v49
	v_lshlrev_b32_e32 v48, 16, v81
	v_and_b32_e32 v49, 0xffff0000, v81
	v_fma_f32 v18, v88, v18, v48
	v_fma_f32 v19, v88, v19, v49
	v_lshlrev_b32_e32 v48, 16, v82
	v_and_b32_e32 v49, 0xffff0000, v82
	v_fma_f32 v20, v88, v20, v48
	v_fma_f32 v21, v88, v21, v49
	v_lshlrev_b32_e32 v48, 16, v83
	v_and_b32_e32 v49, 0xffff0000, v83
	v_fma_f32 v22, v88, v22, v48
	v_fma_f32 v23, v88, v23, v49
	v_lshlrev_b32_e32 v48, 16, v84
	v_and_b32_e32 v49, 0xffff0000, v84
	v_fma_f32 v24, v88, v24, v48
	v_fma_f32 v25, v88, v25, v49
	v_lshlrev_b32_e32 v48, 16, v85
	v_and_b32_e32 v49, 0xffff0000, v85
	v_fma_f32 v26, v88, v26, v48
	v_fma_f32 v27, v88, v27, v49
	v_lshlrev_b32_e32 v48, 16, v86
	v_and_b32_e32 v49, 0xffff0000, v86
	v_fma_f32 v28, v88, v28, v48
	v_fma_f32 v29, v88, v29, v49
	v_lshlrev_b32_e32 v48, 16, v87
	v_and_b32_e32 v49, 0xffff0000, v87
	v_fma_f32 v30, v88, v30, v48
	v_fma_f32 v31, v88, v31, v49
	global_load_dwordx4 v[80:83], v2, s[6:7] nt
	global_load_dwordx4 v[84:87], v3, s[6:7] nt
	global_load_dword v88, v4, s[12:13]
	s_add_u32 s6, s6, 0x40000
	s_addc_u32 s7, s7, 0
	s_add_u32 s12, s12, 64
	s_addc_u32 s13, s13, 0
	s_waitcnt vmcnt(25)
; __device__ __forceinline__ float bf2f(unsigned h) { return __uint_as_float(h << 16); }
; __device__ __forceinline__ unsigned pk2(float lo, float hi) { return pg8::cvt_pk_bf16(lo, hi); }
; __device__ __forceinline__ void b2_scan(const Ctx& C) {
;     ...
;     for (int g = 0; g < 8; ++g) {
;         const int cur = g & 1;
;         if (g + 1 < 8) B2_LOAD(g + 1, cur ^ 1);
; #pragma unroll
;         for (int k = 0; k < 4; ++k) {
;             const int c = 4 * g + k;
;             const float dd[8] = {d0[cur][k][0], d0[cur][k][1], d0[cur][k][2], d0[cur][k][3], d1[cur][k][0], d1[cur][k][1], d1[cur][k][2], d1[cur][k][3]};
; #pragma unroll
;             for (int j = 0; j < 2; ++j) {
;                 v4u o; o.x = pk2(run[j][0], run[j][1]); o.y = pk2(run[j][2], run[j][3]); o.z = pk2(run[j][4], run[j][5]); o.w = pk2(run[j][6], run[j][7]);
;                 __builtin_nontemporal_store(o, (v4u*)(base + (size_t)c * cstride + (size_t)j * vstride));
;                 const unsigned lw[4] = {loc[cur][k][j].x, loc[cur][k][j].y, loc[cur][k][j].z, loc[cur][k][j].w};
; #pragma unroll
;                 for (int q = 0; q < 4; ++q) {
;                     run[j][2 * q] = dd[2 * q] * run[j][2 * q] + bf2f(lw[q] & 0xffffu);
;                     run[j][2 * q + 1] = dd[2 * q + 1] * run[j][2 * q + 1] + __uint_as_float(lw[q] & 0xffff0000u);
;                 }
;             }
;         }
;     }
	v_cvt_pk_bf16_f32 v32, v16, v17
	v_cvt_pk_bf16_f32 v33, v18, v19
	v_cvt_pk_bf16_f32 v34, v20, v21
	v_cvt_pk_bf16_f32 v35, v22, v23
	global_store_dwordx4 v2, v[32:35], s[10:11] nt
	v_cvt_pk_bf16_f32 v36, v24, v25
	v_cvt_pk_bf16_f32 v37, v26, v27
	v_cvt_pk_bf16_f32 v38, v28, v29
	v_cvt_pk_bf16_f32 v39, v30, v31
	global_store_dwordx4 v3, v[36:39], s[10:11] nt
	s_add_u32 s10, s10, 0x40000
	s_addc_u32 s11, s11, 0
	v_lshlrev_b32_e32 v48, 16, v96
	v_and_b32_e32 v49, 0xffff0000, v96
	v_fma_f32 v16, v104, v16, v48
	v_fma_f32 v17, v104, v17, v49
	v_lshlrev_b32_e32 v48, 16, v97
	v_and_b32_e32 v49, 0xffff0000, v97
	v_fma_f32 v18, v104, v18, v48
	v_fma_f32 v19, v104, v19, v49
	v_lshlrev_b32_e32 v48, 16, v98
	v_and_b32_e32 v49, 0xffff0000, v98
	v_fma_f32 v20, v104, v20, v48
	v_fma_f32 v21, v104, v21, v49
	v_lshlrev_b32_e32 v48, 16, v99
	v_and_b32_e32 v49, 0xffff0000, v99
	v_fma_f32 v22, v104, v22, v48
	v_fma_f32 v23, v104, v23, v49
	v_lshlrev_b32_e32 v48, 16, v100
	v_and_b32_e32 v49, 0xffff0000, v100
	v_fma_f32 v24, v104, v24, v48
	v_fma_f32 v25, v104, v25, v49
	v_lshlrev_b32_e32 v48, 16, v101
	v_and_b32_e32 v49, 0xffff0000, v101
	v_fma_f32 v26, v104, v26, v48
	v_fma_f32 v27, v104, v27, v49
	v_lshlrev_b32_e32 v48, 16, v102
	v_and_b32_e32 v49, 0xffff0000, v102
	v_fma_f32 v28, v104, v28, v48
	v_fma_f32 v29, v104, v29, v49
	v_lshlrev_b32_e32 v48, 16, v103
	v_and_b32_e32 v49, 0xffff0000, v103
	v_fma_f32 v30, v104, v30, v48
	v_fma_f32 v31, v104, v31, v49
	global_load_dwordx4 v[96:99], v2, s[6:7] nt
	global_load_dwordx4 v[100:103], v3, s[6:7] nt
	global_load_dword v104, v4, s[12:13]
	s_add_u32 s6, s6, 0x40000
	s_addc_u32 s7, s7, 0
	s_add_u32 s12, s12, 64
	s_addc_u32 s13, s13, 0
	s_waitcnt vmcnt(27)
	v_cvt_pk_bf16_f32 v40, v16, v17
	v_cvt_pk_bf16_f32 v41, v18, v19
	v_cvt_pk_bf16_f32 v42, v20, v21
	v_cvt_pk_bf16_f32 v43, v22, v23
	global_store_dwordx4 v2, v[40:43], s[10:11] nt
	v_cvt_pk_bf16_f32 v44, v24, v25
	v_cvt_pk_bf16_f32 v45, v26, v27
	v_cvt_pk_bf16_f32 v46, v28, v29
	v_cvt_pk_bf16_f32 v47, v30, v31
	global_store_dwordx4 v3, v[44:47], s[10:11] nt
	s_add_u32 s10, s10, 0x40000
	s_addc_u32 s11, s11, 0
	v_lshlrev_b32_e32 v48, 16, v112
	v_and_b32_e32 v49, 0xffff0000, v112
	v_fma_f32 v16, v120, v16, v48
	v_fma_f32 v17, v120, v17, v49
	v_lshlrev_b32_e32 v48, 16, v113
	v_and_b32_e32 v49, 0xffff0000, v113
	v_fma_f32 v18, v120, v18, v48
	v_fma_f32 v19, v120, v19, v49
	v_lshlrev_b32_e32 v48, 16, v114
	v_and_b32_e32 v49, 0xffff0000, v114
	v_fma_f32 v20, v120, v20, v48
	v_fma_f32 v21, v120, v21, v49
	v_lshlrev_b32_e32 v48, 16, v115
	v_and_b32_e32 v49, 0xffff0000, v115
	v_fma_f32 v22, v120, v22, v48
	v_fma_f32 v23, v120, v23, v49
	v_lshlrev_b32_e32 v48, 16, v116
	v_and_b32_e32 v49, 0xffff0000, v116
	v_fma_f32 v24, v120, v24, v48
	v_fma_f32 v25, v120, v25, v49
	v_lshlrev_b32_e32 v48, 16, v117
	v_and_b32_e32 v49, 0xffff0000, v117
	v_fma_f32 v26, v120, v26, v48
	v_fma_f32 v27, v120, v27, v49
	v_lshlrev_b32_e32 v48, 16, v118
	v_and_b32_e32 v49, 0xffff0000, v118
	v_fma_f32 v28, v120, v28, v48
	v_fma_f32 v29, v120, v29, v49
	v_lshlrev_b32_e32 v48, 16, v119
	v_and_b32_e32 v49, 0xffff0000, v119
	v_fma_f32 v30, v120, v30, v48
	v_fma_f32 v31, v120, v31, v49
	global_load_dwordx4 v[112:115], v2, s[6:7] nt
	global_load_dwordx4 v[116:119], v3, s[6:7] nt
	global_load_dword v120, v4, s[12:13]
	s_add_u32 s6, s6, 0x40000
	s_addc_u32 s7, s7, 0
	s_add_u32 s12, s12, 64
	s_addc_u32 s13, s13, 0
	s_waitcnt vmcnt(29)
	v_cvt_pk_bf16_f32 v32, v16, v17
	v_cvt_pk_bf16_f32 v33, v18, v19
	v_cvt_pk_bf16_f32 v34, v20, v21
	v_cvt_pk_bf16_f32 v35, v22, v23
	global_store_dwordx4 v2, v[32:35], s[10:11] nt
	v_cvt_pk_bf16_f32 v36, v24, v25
	v_cvt_pk_bf16_f32 v37, v26, v27
	v_cvt_pk_bf16_f32 v38, v28, v29
	v_cvt_pk_bf16_f32 v39, v30, v31
	global_store_dwordx4 v3, v[36:39], s[10:11] nt
	s_add_u32 s10, s10, 0x40000
	s_addc_u32 s11, s11, 0
	v_lshlrev_b32_e32 v48, 16, v128
	v_and_b32_e32 v49, 0xffff0000, v128
	v_fma_f32 v16, v136, v16, v48
	v_fma_f32 v17, v136, v17, v49
	v_lshlrev_b32_e32 v48, 16, v129
	v_and_b32_e32 v49, 0xffff0000, v129
	v_fma_f32 v18, v136, v18, v48
	v_fma_f32 v19, v136, v19, v49
	v_lshlrev_b32_e32 v48, 16, v130
	v_and_b32_e32 v49, 0xffff0000, v130
	v_fma_f32 v20, v136, v20, v48
	v_fma_f32 v21, v136, v21, v49
	v_lshlrev_b32_e32 v48, 16, v131
	v_and_b32_e32 v49, 0xffff0000, v131
	v_fma_f32 v22, v136, v22, v48
	v_fma_f32 v23, v136, v23, v49
	v_lshlrev_b32_e32 v48, 16, v132
	v_and_b32_e32 v49, 0xffff0000, v132
	v_fma_f32 v24, v136, v24, v48
	v_fma_f32 v25, v136, v25, v49
	v_lshlrev_b32_e32 v48, 16, v133
	v_and_b32_e32 v49, 0xffff0000, v133
	v_fma_f32 v26, v136, v26, v48
	v_fma_f32 v27, v136, v27, v49
	v_lshlrev_b32_e32 v48, 16, v134
	v_and_b32_e32 v49, 0xffff0000, v134
	v_fma_f32 v28, v136, v28, v48
	v_fma_f32 v29, v136, v29, v49
	v_lshlrev_b32_e32 v48, 16, v135
	v_and_b32_e32 v49, 0xffff0000, v135
	v_fma_f32 v30, v136, v30, v48
	v_fma_f32 v31, v136, v31, v49
	global_load_dwordx4 v[128:131], v2, s[6:7] nt
	global_load_dwordx4 v[132:135], v3, s[6:7] nt
	global_load_dword v136, v4, s[12:13]
	s_add_u32 s6, s6, 0x40000
	s_addc_u32 s7, s7, 0
	s_add_u32 s12, s12, 64
	s_addc_u32 s13, s13, 0
	s_waitcnt vmcnt(31)
; __device__ __forceinline__ float bf2f(unsigned h) { return __uint_as_float(h << 16); }
; __device__ __forceinline__ unsigned pk2(float lo, float hi) { return pg8::cvt_pk_bf16(lo, hi); }
; __device__ __forceinline__ void b2_scan(const Ctx& C) {
;     ...
;     for (int g = 0; g < 8; ++g) {
;         const int cur = g & 1;
;         if (g + 1 < 8) B2_LOAD(g + 1, cur ^ 1);
; #pragma unroll
;         for (int k = 0; k < 4; ++k) {
;             const int c = 4 * g + k;
;             const float dd[8] = {d0[cur][k][0], d0[cur][k][1], d0[cur][k][2], d0[cur][k][3], d1[cur][k][0], d1[cur][k][1], d1[cur][k][2], d1[cur][k][3]};
; #pragma unroll
;             for (int j = 0; j < 2; ++j) {
;                 v4u o; o.x = pk2(run[j][0], run[j][1]); o.y = pk2(run[j][2], run[j][3]); o.z = pk2(run[j][4], run[j][5]); o.w = pk2(run[j][6], run[j][7]);
;                 __builtin_nontemporal_store(o, (v4u*)(base + (size_t)c * cstride + (size_t)j * vstride));
;                 const unsigned lw[4] = {loc[cur][k][j].x, loc[cur][k][j].y, loc[cur][k][j].z, loc[cur][k][j].w};
; #pragma unroll
;                 for (int q = 0; q < 4; ++q) {
;                     run[j][2 * q] = dd[2 * q] * run[j][2 * q] + bf2f(lw[q] & 0xffffu);
;                     run[j][2 * q + 1] = dd[2 * q + 1] * run[j][2 * q + 1] + __uint_as_float(lw[q] & 0xffff0000u);
;                 }
;             }
;         }
;     }
	v_cvt_pk_bf16_f32 v40, v16, v17
	v_cvt_pk_bf16_f32 v41, v18, v19
	v_cvt_pk_bf16_f32 v42, v20, v21
	v_cvt_pk_bf16_f32 v43, v22, v23
	global_store_dwordx4 v2, v[40:43], s[10:11] nt
	v_cvt_pk_bf16_f32 v44, v24, v25
	v_cvt_pk_bf16_f32 v45, v26, v27
	v_cvt_pk_bf16_f32 v46, v28, v29
	v_cvt_pk_bf16_f32 v47, v30, v31
	global_store_dwordx4 v3, v[44:47], s[10:11] nt
	s_add_u32 s10, s10, 0x40000
	s_addc_u32 s11, s11, 0
	v_lshlrev_b32_e32 v48, 16, v144
	v_and_b32_e32 v49, 0xffff0000, v144
	v_fma_f32 v16, v152, v16, v48
	v_fma_f32 v17, v152, v17, v49
	v_lshlrev_b32_e32 v48, 16, v145
	v_and_b32_e32 v49, 0xffff0000, v145
	v_fma_f32 v18, v152, v18, v48
	v_fma_f32 v19, v152, v19, v49
	v_lshlrev_b32_e32 v48, 16, v146
	v_and_b32_e32 v49, 0xffff0000, v146
	v_fma_f32 v20, v152, v20, v48
	v_fma_f32 v21, v152, v21, v49
	v_lshlrev_b32_e32 v48, 16, v147
	v_and_b32_e32 v49, 0xffff0000, v147
	v_fma_f32 v22, v152, v22, v48
	v_fma_f32 v23, v152, v23, v49
	v_lshlrev_b32_e32 v48, 16, v148
	v_and_b32_e32 v49, 0xffff0000, v148
	v_fma_f32 v24, v152, v24, v48
	v_fma_f32 v25, v152, v25, v49
	v_lshlrev_b32_e32 v48, 16, v149
	v_and_b32_e32 v49, 0xffff0000, v149
	v_fma_f32 v26, v152, v26, v48
	v_fma_f32 v27, v152, v27, v49
	v_lshlrev_b32_e32 v48, 16, v150
	v_and_b32_e32 v49, 0xffff0000, v150
	v_fma_f32 v28, v152, v28, v48
	v_fma_f32 v29, v152, v29, v49
	v_lshlrev_b32_e32 v48, 16, v151
	v_and_b32_e32 v49, 0xffff0000, v151
	v_fma_f32 v30, v152, v30, v48
	v_fma_f32 v31, v152, v31, v49
	global_load_dwordx4 v[144:147], v2, s[6:7] nt
	global_load_dwordx4 v[148:151], v3, s[6:7] nt
	global_load_dword v152, v4, s[12:13]
	s_add_u32 s6, s6, 0x40000
	s_addc_u32 s7, s7, 0
	s_add_u32 s12, s12, 64
	s_addc_u32 s13, s13, 0
	s_waitcnt vmcnt(33)
	v_cvt_pk_bf16_f32 v32, v16, v17
	v_cvt_pk_bf16_f32 v33, v18, v19
	v_cvt_pk_bf16_f32 v34, v20, v21
	v_cvt_pk_bf16_f32 v35, v22, v23
	global_store_dwordx4 v2, v[32:35], s[10:11] nt
	v_cvt_pk_bf16_f32 v36, v24, v25
	v_cvt_pk_bf16_f32 v37, v26, v27
	v_cvt_pk_bf16_f32 v38, v28, v29
	v_cvt_pk_bf16_f32 v39, v30, v31
	global_store_dwordx4 v3, v[36:39], s[10:11] nt
	s_add_u32 s10, s10, 0x40000
	s_addc_u32 s11, s11, 0
	v_lshlrev_b32_e32 v48, 16, v160
	v_and_b32_e32 v49, 0xffff0000, v160
	v_fma_f32 v16, v168, v16, v48
	v_fma_f32 v17, v168, v17, v49
	v_lshlrev_b32_e32 v48, 16, v161
	v_and_b32_e32 v49, 0xffff0000, v161
	v_fma_f32 v18, v168, v18, v48
	v_fma_f32 v19, v168, v19, v49
	v_lshlrev_b32_e32 v48, 16, v162
	v_and_b32_e32 v49, 0xffff0000, v162
	v_fma_f32 v20, v168, v20, v48
	v_fma_f32 v21, v168, v21, v49
	v_lshlrev_b32_e32 v48, 16, v163
	v_and_b32_e32 v49, 0xffff0000, v163
	v_fma_f32 v22, v168, v22, v48
	v_fma_f32 v23, v168, v23, v49
	v_lshlrev_b32_e32 v48, 16, v164
	v_and_b32_e32 v49, 0xffff0000, v164
	v_fma_f32 v24, v168, v24, v48
	v_fma_f32 v25, v168, v25, v49
	v_lshlrev_b32_e32 v48, 16, v165
	v_and_b32_e32 v49, 0xffff0000, v165
	v_fma_f32 v26, v168, v26, v48
	v_fma_f32 v27, v168, v27, v49
	v_lshlrev_b32_e32 v48, 16, v166
	v_and_b32_e32 v49, 0xffff0000, v166
	v_fma_f32 v28, v168, v28, v48
	v_fma_f32 v29, v168, v29, v49
	v_lshlrev_b32_e32 v48, 16, v167
	v_and_b32_e32 v49, 0xffff0000, v167
	v_fma_f32 v30, v168, v30, v48
	v_fma_f32 v31, v168, v31, v49
	global_load_dwordx4 v[160:163], v2, s[6:7] nt
	global_load_dwordx4 v[164:167], v3, s[6:7] nt
	global_load_dword v168, v4, s[12:13]
	s_add_u32 s6, s6, 0x40000
	s_addc_u32 s7, s7, 0
	s_add_u32 s12, s12, 64
	s_addc_u32 s13, s13, 0
	s_waitcnt vmcnt(35)
	v_cvt_pk_bf16_f32 v40, v16, v17
	v_cvt_pk_bf16_f32 v41, v18, v19
	v_cvt_pk_bf16_f32 v42, v20, v21
	v_cvt_pk_bf16_f32 v43, v22, v23
	global_store_dwordx4 v2, v[40:43], s[10:11] nt
	v_cvt_pk_bf16_f32 v44, v24, v25
	v_cvt_pk_bf16_f32 v45, v26, v27
	v_cvt_pk_bf16_f32 v46, v28, v29
	v_cvt_pk_bf16_f32 v47, v30, v31
	global_store_dwordx4 v3, v[44:47], s[10:11] nt
	s_add_u32 s10, s10, 0x40000
	s_addc_u32 s11, s11, 0
	v_lshlrev_b32_e32 v48, 16, v176
	v_and_b32_e32 v49, 0xffff0000, v176
	v_fma_f32 v16, v184, v16, v48
	v_fma_f32 v17, v184, v17, v49
	v_lshlrev_b32_e32 v48, 16, v177
	v_and_b32_e32 v49, 0xffff0000, v177
	v_fma_f32 v18, v184, v18, v48
	v_fma_f32 v19, v184, v19, v49
	v_lshlrev_b32_e32 v48, 16, v178
	v_and_b32_e32 v49, 0xffff0000, v178
	v_fma_f32 v20, v184, v20, v48
	v_fma_f32 v21, v184, v21, v49
	v_lshlrev_b32_e32 v48, 16, v179
	v_and_b32_e32 v49, 0xffff0000, v179
	v_fma_f32 v22, v184, v22, v48
	v_fma_f32 v23, v184, v23, v49
	v_lshlrev_b32_e32 v48, 16, v180
	v_and_b32_e32 v49, 0xffff0000, v180
	v_fma_f32 v24, v184, v24, v48
	v_fma_f32 v25, v184, v25, v49
	v_lshlrev_b32_e32 v48, 16, v181
	v_and_b32_e32 v49, 0xffff0000, v181
	v_fma_f32 v26, v184, v26, v48
	v_fma_f32 v27, v184, v27, v49
	v_lshlrev_b32_e32 v48, 16, v182
	v_and_b32_e32 v49, 0xffff0000, v182
	v_fma_f32 v28, v184, v28, v48
	v_fma_f32 v29, v184, v29, v49
	v_lshlrev_b32_e32 v48, 16, v183
	v_and_b32_e32 v49, 0xffff0000, v183
	v_fma_f32 v30, v184, v30, v48
	v_fma_f32 v31, v184, v31, v49
	global_load_dwordx4 v[176:179], v2, s[6:7] nt
	global_load_dwordx4 v[180:183], v3, s[6:7] nt
	global_load_dword v184, v4, s[12:13]
	s_add_u32 s6, s6, 0x40000
	s_addc_u32 s7, s7, 0
	s_add_u32 s12, s12, 64
	s_addc_u32 s13, s13, 0
	s_waitcnt vmcnt(35)
; __device__ __forceinline__ float bf2f(unsigned h) { return __uint_as_float(h << 16); }
; __device__ __forceinline__ unsigned pk2(float lo, float hi) { return pg8::cvt_pk_bf16(lo, hi); }
; __device__ __forceinline__ void b2_scan(const Ctx& C) {
;     ...
;     for (int g = 0; g < 8; ++g) {
;         const int cur = g & 1;
;         if (g + 1 < 8) B2_LOAD(g + 1, cur ^ 1);
; #pragma unroll
;         for (int k = 0; k < 4; ++k) {
;             const int c = 4 * g + k;
;             const float dd[8] = {d0[cur][k][0], d0[cur][k][1], d0[cur][k][2], d0[cur][k][3], d1[cur][k][0], d1[cur][k][1], d1[cur][k][2], d1[cur][k][3]};
; #pragma unroll
;             for (int j = 0; j < 2; ++j) {
;                 v4u o; o.x = pk2(run[j][0], run[j][1]); o.y = pk2(run[j][2], run[j][3]); o.z = pk2(run[j][4], run[j][5]); o.w = pk2(run[j][6], run[j][7]);
;                 __builtin_nontemporal_store(o, (v4u*)(base + (size_t)c * cstride + (size_t)j * vstride));
;                 const unsigned lw[4] = {loc[cur][k][j].x, loc[cur][k][j].y, loc[cur][k][j].z, loc[cur][k][j].w};
; #pragma unroll
;                 for (int q = 0; q < 4; ++q) {
;                     run[j][2 * q] = dd[2 * q] * run[j][2 * q] + bf2f(lw[q] & 0xffffu);
;                     run[j][2 * q + 1] = dd[2 * q + 1] * run[j][2 * q + 1] + __uint_as_float(lw[q] & 0xffff0000u);
;                 }
;             }
;         }
;     }
	v_cvt_pk_bf16_f32 v32, v16, v17
	v_cvt_pk_bf16_f32 v33, v18, v19
	v_cvt_pk_bf16_f32 v34, v20, v21
	v_cvt_pk_bf16_f32 v35, v22, v23
	global_store_dwordx4 v2, v[32:35], s[10:11] nt
	v_cvt_pk_bf16_f32 v36, v24, v25
	v_cvt_pk_bf16_f32 v37, v26, v27
	v_cvt_pk_bf16_f32 v38, v28, v29
	v_cvt_pk_bf16_f32 v39, v30, v31
	global_store_dwordx4 v3, v[36:39], s[10:11] nt
	s_add_u32 s10, s10, 0x40000
	s_addc_u32 s11, s11, 0
	v_lshlrev_b32_e32 v48, 16, v64
	v_and_b32_e32 v49, 0xffff0000, v64
	v_fma_f32 v16, v72, v16, v48
	v_fma_f32 v17, v72, v17, v49
	v_lshlrev_b32_e32 v48, 16, v65
	v_and_b32_e32 v49, 0xffff0000, v65
	v_fma_f32 v18, v72, v18, v48
	v_fma_f32 v19, v72, v19, v49
	v_lshlrev_b32_e32 v48, 16, v66
	v_and_b32_e32 v49, 0xffff0000, v66
	v_fma_f32 v20, v72, v20, v48
	v_fma_f32 v21, v72, v21, v49
	v_lshlrev_b32_e32 v48, 16, v67
	v_and_b32_e32 v49, 0xffff0000, v67
	v_fma_f32 v22, v72, v22, v48
	v_fma_f32 v23, v72, v23, v49
	v_lshlrev_b32_e32 v48, 16, v68
	v_and_b32_e32 v49, 0xffff0000, v68
	v_fma_f32 v24, v72, v24, v48
	v_fma_f32 v25, v72, v25, v49
	v_lshlrev_b32_e32 v48, 16, v69
	v_and_b32_e32 v49, 0xffff0000, v69
	v_fma_f32 v26, v72, v26, v48
	v_fma_f32 v27, v72, v27, v49
	v_lshlrev_b32_e32 v48, 16, v70
	v_and_b32_e32 v49, 0xffff0000, v70
	v_fma_f32 v28, v72, v28, v48
	v_fma_f32 v29, v72, v29, v49
	v_lshlrev_b32_e32 v48, 16, v71
	v_and_b32_e32 v49, 0xffff0000, v71
	v_fma_f32 v30, v72, v30, v48
	v_fma_f32 v31, v72, v31, v49
	global_load_dwordx4 v[64:67], v2, s[6:7] nt
	global_load_dwordx4 v[68:71], v3, s[6:7] nt
	global_load_dword v72, v4, s[12:13]
	s_add_u32 s6, s6, 0x40000
	s_addc_u32 s7, s7, 0
	s_add_u32 s12, s12, 64
	s_addc_u32 s13, s13, 0
	s_waitcnt vmcnt(35)
	v_cvt_pk_bf16_f32 v40, v16, v17
	v_cvt_pk_bf16_f32 v41, v18, v19
	v_cvt_pk_bf16_f32 v42, v20, v21
	v_cvt_pk_bf16_f32 v43, v22, v23
	global_store_dwordx4 v2, v[40:43], s[10:11] nt
	v_cvt_pk_bf16_f32 v44, v24, v25
	v_cvt_pk_bf16_f32 v45, v26, v27
	v_cvt_pk_bf16_f32 v46, v28, v29
	v_cvt_pk_bf16_f32 v47, v30, v31
	global_store_dwordx4 v3, v[44:47], s[10:11] nt
	s_add_u32 s10, s10, 0x40000
	s_addc_u32 s11, s11, 0
	v_lshlrev_b32_e32 v48, 16, v80
	v_and_b32_e32 v49, 0xffff0000, v80
	v_fma_f32 v16, v88, v16, v48
	v_fma_f32 v17, v88, v17, v49
	v_lshlrev_b32_e32 v48, 16, v81
	v_and_b32_e32 v49, 0xffff0000, v81
	v_fma_f32 v18, v88, v18, v48
	v_fma_f32 v19, v88, v19, v49
	v_lshlrev_b32_e32 v48, 16, v82
	v_and_b32_e32 v49, 0xffff0000, v82
	v_fma_f32 v20, v88, v20, v48
	v_fma_f32 v21, v88, v21, v49
	v_lshlrev_b32_e32 v48, 16, v83
	v_and_b32_e32 v49, 0xffff0000, v83
	v_fma_f32 v22, v88, v22, v48
	v_fma_f32 v23, v88, v23, v49
	v_lshlrev_b32_e32 v48, 16, v84
	v_and_b32_e32 v49, 0xffff0000, v84
	v_fma_f32 v24, v88, v24, v48
	v_fma_f32 v25, v88, v25, v49
	v_lshlrev_b32_e32 v48, 16, v85
	v_and_b32_e32 v49, 0xffff0000, v85
	v_fma_f32 v26, v88, v26, v48
	v_fma_f32 v27, v88, v27, v49
	v_lshlrev_b32_e32 v48, 16, v86
	v_and_b32_e32 v49, 0xffff0000, v86
	v_fma_f32 v28, v88, v28, v48
	v_fma_f32 v29, v88, v29, v49
	v_lshlrev_b32_e32 v48, 16, v87
	v_and_b32_e32 v49, 0xffff0000, v87
	v_fma_f32 v30, v88, v30, v48
	v_fma_f32 v31, v88, v31, v49
	global_load_dwordx4 v[80:83], v2, s[6:7] nt
	global_load_dwordx4 v[84:87], v3, s[6:7] nt
	global_load_dword v88, v4, s[12:13]
	s_add_u32 s6, s6, 0x40000
	s_addc_u32 s7, s7, 0
	s_add_u32 s12, s12, 64
	s_addc_u32 s13, s13, 0
	s_waitcnt vmcnt(35)
	v_cvt_pk_bf16_f32 v32, v16, v17
	v_cvt_pk_bf16_f32 v33, v18, v19
	v_cvt_pk_bf16_f32 v34, v20, v21
	v_cvt_pk_bf16_f32 v35, v22, v23
	global_store_dwordx4 v2, v[32:35], s[10:11] nt
	v_cvt_pk_bf16_f32 v36, v24, v25
	v_cvt_pk_bf16_f32 v37, v26, v27
	v_cvt_pk_bf16_f32 v38, v28, v29
	v_cvt_pk_bf16_f32 v39, v30, v31
	global_store_dwordx4 v3, v[36:39], s[10:11] nt
	s_add_u32 s10, s10, 0x40000
	s_addc_u32 s11, s11, 0
	v_lshlrev_b32_e32 v48, 16, v96
	v_and_b32_e32 v49, 0xffff0000, v96
	v_fma_f32 v16, v104, v16, v48
	v_fma_f32 v17, v104, v17, v49
	v_lshlrev_b32_e32 v48, 16, v97
	v_and_b32_e32 v49, 0xffff0000, v97
	v_fma_f32 v18, v104, v18, v48
	v_fma_f32 v19, v104, v19, v49
	v_lshlrev_b32_e32 v48, 16, v98
	v_and_b32_e32 v49, 0xffff0000, v98
	v_fma_f32 v20, v104, v20, v48
	v_fma_f32 v21, v104, v21, v49
	v_lshlrev_b32_e32 v48, 16, v99
	v_and_b32_e32 v49, 0xffff0000, v99
	v_fma_f32 v22, v104, v22, v48
	v_fma_f32 v23, v104, v23, v49
	v_lshlrev_b32_e32 v48, 16, v100
	v_and_b32_e32 v49, 0xffff0000, v100
	v_fma_f32 v24, v104, v24, v48
	v_fma_f32 v25, v104, v25, v49
	v_lshlrev_b32_e32 v48, 16, v101
	v_and_b32_e32 v49, 0xffff0000, v101
	v_fma_f32 v26, v104, v26, v48
	v_fma_f32 v27, v104, v27, v49
	v_lshlrev_b32_e32 v48, 16, v102
	v_and_b32_e32 v49, 0xffff0000, v102
	v_fma_f32 v28, v104, v28, v48
	v_fma_f32 v29, v104, v29, v49
	v_lshlrev_b32_e32 v48, 16, v103
	v_and_b32_e32 v49, 0xffff0000, v103
	v_fma_f32 v30, v104, v30, v48
	v_fma_f32 v31, v104, v31, v49
	global_load_dwordx4 v[96:99], v2, s[6:7] nt
	global_load_dwordx4 v[100:103], v3, s[6:7] nt
	global_load_dword v104, v4, s[12:13]
	s_add_u32 s6, s6, 0x40000
	s_addc_u32 s7, s7, 0
	s_add_u32 s12, s12, 64
	s_addc_u32 s13, s13, 0
	s_waitcnt vmcnt(35)
; __device__ __forceinline__ float bf2f(unsigned h) { return __uint_as_float(h << 16); }
; __device__ __forceinline__ unsigned pk2(float lo, float hi) { return pg8::cvt_pk_bf16(lo, hi); }
; __device__ __forceinline__ void b2_scan(const Ctx& C) {
;     ...
;     for (int g = 0; g < 8; ++g) {
;         const int cur = g & 1;
;         if (g + 1 < 8) B2_LOAD(g + 1, cur ^ 1);
; #pragma unroll
;         for (int k = 0; k < 4; ++k) {
;             const int c = 4 * g + k;
;             const float dd[8] = {d0[cur][k][0], d0[cur][k][1], d0[cur][k][2], d0[cur][k][3], d1[cur][k][0], d1[cur][k][1], d1[cur][k][2], d1[cur][k][3]};
; #pragma unroll
;             for (int j = 0; j < 2; ++j) {
;                 v4u o; o.x = pk2(run[j][0], run[j][1]); o.y = pk2(run[j][2], run[j][3]); o.z = pk2(run[j][4], run[j][5]); o.w = pk2(run[j][6], run[j][7]);
;                 __builtin_nontemporal_store(o, (v4u*)(base + (size_t)c * cstride + (size_t)j * vstride));
;                 const unsigned lw[4] = {loc[cur][k][j].x, loc[cur][k][j].y, loc[cur][k][j].z, loc[cur][k][j].w};
; #pragma unroll
;                 for (int q = 0; q < 4; ++q) {
;                     run[j][2 * q] = dd[2 * q] * run[j][2 * q] + bf2f(lw[q] & 0xffffu);
;                     run[j][2 * q + 1] = dd[2 * q + 1] * run[j][2 * q + 1] + __uint_as_float(lw[q] & 0xffff0000u);
;                 }
;             }
;         }
;     }
	v_cvt_pk_bf16_f32 v40, v16, v17
	v_cvt_pk_bf16_f32 v41, v18, v19
	v_cvt_pk_bf16_f32 v42, v20, v21
	v_cvt_pk_bf16_f32 v43, v22, v23
	global_store_dwordx4 v2, v[40:43], s[10:11] nt
	v_cvt_pk_bf16_f32 v44, v24, v25
	v_cvt_pk_bf16_f32 v45, v26, v27
	v_cvt_pk_bf16_f32 v46, v28, v29
	v_cvt_pk_bf16_f32 v47, v30, v31
	global_store_dwordx4 v3, v[44:47], s[10:11] nt
	s_add_u32 s10, s10, 0x40000
	s_addc_u32 s11, s11, 0
	v_lshlrev_b32_e32 v48, 16, v112
	v_and_b32_e32 v49, 0xffff0000, v112
	v_fma_f32 v16, v120, v16, v48
	v_fma_f32 v17, v120, v17, v49
	v_lshlrev_b32_e32 v48, 16, v113
	v_and_b32_e32 v49, 0xffff0000, v113
	v_fma_f32 v18, v120, v18, v48
	v_fma_f32 v19, v120, v19, v49
	v_lshlrev_b32_e32 v48, 16, v114
	v_and_b32_e32 v49, 0xffff0000, v114
	v_fma_f32 v20, v120, v20, v48
	v_fma_f32 v21, v120, v21, v49
	v_lshlrev_b32_e32 v48, 16, v115
	v_and_b32_e32 v49, 0xffff0000, v115
	v_fma_f32 v22, v120, v22, v48
	v_fma_f32 v23, v120, v23, v49
	v_lshlrev_b32_e32 v48, 16, v116
	v_and_b32_e32 v49, 0xffff0000, v116
	v_fma_f32 v24, v120, v24, v48
	v_fma_f32 v25, v120, v25, v49
	v_lshlrev_b32_e32 v48, 16, v117
	v_and_b32_e32 v49, 0xffff0000, v117
	v_fma_f32 v26, v120, v26, v48
	v_fma_f32 v27, v120, v27, v49
	v_lshlrev_b32_e32 v48, 16, v118
	v_and_b32_e32 v49, 0xffff0000, v118
	v_fma_f32 v28, v120, v28, v48
	v_fma_f32 v29, v120, v29, v49
	v_lshlrev_b32_e32 v48, 16, v119
	v_and_b32_e32 v49, 0xffff0000, v119
	v_fma_f32 v30, v120, v30, v48
	v_fma_f32 v31, v120, v31, v49
	global_load_dwordx4 v[112:115], v2, s[6:7] nt
	global_load_dwordx4 v[116:119], v3, s[6:7] nt
	global_load_dword v120, v4, s[12:13]
	s_add_u32 s6, s6, 0x40000
	s_addc_u32 s7, s7, 0
	s_add_u32 s12, s12, 64
	s_addc_u32 s13, s13, 0
	s_waitcnt vmcnt(35)
	v_cvt_pk_bf16_f32 v32, v16, v17
	v_cvt_pk_bf16_f32 v33, v18, v19
	v_cvt_pk_bf16_f32 v34, v20, v21
	v_cvt_pk_bf16_f32 v35, v22, v23
	global_store_dwordx4 v2, v[32:35], s[10:11] nt
	v_cvt_pk_bf16_f32 v36, v24, v25
	v_cvt_pk_bf16_f32 v37, v26, v27
	v_cvt_pk_bf16_f32 v38, v28, v29
	v_cvt_pk_bf16_f32 v39, v30, v31
	global_store_dwordx4 v3, v[36:39], s[10:11] nt
	s_add_u32 s10, s10, 0x40000
	s_addc_u32 s11, s11, 0
	v_lshlrev_b32_e32 v48, 16, v128
	v_and_b32_e32 v49, 0xffff0000, v128
	v_fma_f32 v16, v136, v16, v48
	v_fma_f32 v17, v136, v17, v49
	v_lshlrev_b32_e32 v48, 16, v129
	v_and_b32_e32 v49, 0xffff0000, v129
	v_fma_f32 v18, v136, v18, v48
	v_fma_f32 v19, v136, v19, v49
	v_lshlrev_b32_e32 v48, 16, v130
	v_and_b32_e32 v49, 0xffff0000, v130
	v_fma_f32 v20, v136, v20, v48
	v_fma_f32 v21, v136, v21, v49
	v_lshlrev_b32_e32 v48, 16, v131
	v_and_b32_e32 v49, 0xffff0000, v131
	v_fma_f32 v22, v136, v22, v48
	v_fma_f32 v23, v136, v23, v49
	v_lshlrev_b32_e32 v48, 16, v132
	v_and_b32_e32 v49, 0xffff0000, v132
	v_fma_f32 v24, v136, v24, v48
	v_fma_f32 v25, v136, v25, v49
	v_lshlrev_b32_e32 v48, 16, v133
	v_and_b32_e32 v49, 0xffff0000, v133
	v_fma_f32 v26, v136, v26, v48
	v_fma_f32 v27, v136, v27, v49
	v_lshlrev_b32_e32 v48, 16, v134
	v_and_b32_e32 v49, 0xffff0000, v134
	v_fma_f32 v28, v136, v28, v48
	v_fma_f32 v29, v136, v29, v49
	v_lshlrev_b32_e32 v48, 16, v135
	v_and_b32_e32 v49, 0xffff0000, v135
	v_fma_f32 v30, v136, v30, v48
	v_fma_f32 v31, v136, v31, v49
	global_load_dwordx4 v[128:131], v2, s[6:7] nt
	global_load_dwordx4 v[132:135], v3, s[6:7] nt
	global_load_dword v136, v4, s[12:13]
	s_add_u32 s6, s6, 0x40000
	s_addc_u32 s7, s7, 0
	s_add_u32 s12, s12, 64
	s_addc_u32 s13, s13, 0
	s_waitcnt vmcnt(35)
	v_cvt_pk_bf16_f32 v40, v16, v17
	v_cvt_pk_bf16_f32 v41, v18, v19
	v_cvt_pk_bf16_f32 v42, v20, v21
	v_cvt_pk_bf16_f32 v43, v22, v23
	global_store_dwordx4 v2, v[40:43], s[10:11] nt
	v_cvt_pk_bf16_f32 v44, v24, v25
	v_cvt_pk_bf16_f32 v45, v26, v27
	v_cvt_pk_bf16_f32 v46, v28, v29
	v_cvt_pk_bf16_f32 v47, v30, v31
	global_store_dwordx4 v3, v[44:47], s[10:11] nt
	s_add_u32 s10, s10, 0x40000
	s_addc_u32 s11, s11, 0
	v_lshlrev_b32_e32 v48, 16, v144
	v_and_b32_e32 v49, 0xffff0000, v144
	v_fma_f32 v16, v152, v16, v48
	v_fma_f32 v17, v152, v17, v49
	v_lshlrev_b32_e32 v48, 16, v145
	v_and_b32_e32 v49, 0xffff0000, v145
	v_fma_f32 v18, v152, v18, v48
	v_fma_f32 v19, v152, v19, v49
	v_lshlrev_b32_e32 v48, 16, v146
	v_and_b32_e32 v49, 0xffff0000, v146
	v_fma_f32 v20, v152, v20, v48
	v_fma_f32 v21, v152, v21, v49
	v_lshlrev_b32_e32 v48, 16, v147
	v_and_b32_e32 v49, 0xffff0000, v147
	v_fma_f32 v22, v152, v22, v48
	v_fma_f32 v23, v152, v23, v49
	v_lshlrev_b32_e32 v48, 16, v148
	v_and_b32_e32 v49, 0xffff0000, v148
	v_fma_f32 v24, v152, v24, v48
	v_fma_f32 v25, v152, v25, v49
	v_lshlrev_b32_e32 v48, 16, v149
	v_and_b32_e32 v49, 0xffff0000, v149
	v_fma_f32 v26, v152, v26, v48
	v_fma_f32 v27, v152, v27, v49
	v_lshlrev_b32_e32 v48, 16, v150
	v_and_b32_e32 v49, 0xffff0000, v150
	v_fma_f32 v28, v152, v28, v48
	v_fma_f32 v29, v152, v29, v49
	v_lshlrev_b32_e32 v48, 16, v151
	v_and_b32_e32 v49, 0xffff0000, v151
	v_fma_f32 v30, v152, v30, v48
	v_fma_f32 v31, v152, v31, v49
	global_load_dwordx4 v[144:147], v2, s[6:7] nt
	global_load_dwordx4 v[148:151], v3, s[6:7] nt
	global_load_dword v152, v4, s[12:13]
	s_add_u32 s6, s6, 0x40000
	s_addc_u32 s7, s7, 0
	s_add_u32 s12, s12, 64
	s_addc_u32 s13, s13, 0
	s_waitcnt vmcnt(35)
; __device__ __forceinline__ float bf2f(unsigned h) { return __uint_as_float(h << 16); }
; __device__ __forceinline__ unsigned pk2(float lo, float hi) { return pg8::cvt_pk_bf16(lo, hi); }
; __device__ __forceinline__ void b2_scan(const Ctx& C) {
;     ...
;     for (int g = 0; g < 8; ++g) {
;         const int cur = g & 1;
;         if (g + 1 < 8) B2_LOAD(g + 1, cur ^ 1);
; #pragma unroll
;         for (int k = 0; k < 4; ++k) {
;             const int c = 4 * g + k;
;             const float dd[8] = {d0[cur][k][0], d0[cur][k][1], d0[cur][k][2], d0[cur][k][3], d1[cur][k][0], d1[cur][k][1], d1[cur][k][2], d1[cur][k][3]};
; #pragma unroll
;             for (int j = 0; j < 2; ++j) {
;                 v4u o; o.x = pk2(run[j][0], run[j][1]); o.y = pk2(run[j][2], run[j][3]); o.z = pk2(run[j][4], run[j][5]); o.w = pk2(run[j][6], run[j][7]);
;                 __builtin_nontemporal_store(o, (v4u*)(base + (size_t)c * cstride + (size_t)j * vstride));
;                 const unsigned lw[4] = {loc[cur][k][j].x, loc[cur][k][j].y, loc[cur][k][j].z, loc[cur][k][j].w};
; #pragma unroll
;                 for (int q = 0; q < 4; ++q) {
;                     run[j][2 * q] = dd[2 * q] * run[j][2 * q] + bf2f(lw[q] & 0xffffu);
;                     run[j][2 * q + 1] = dd[2 * q + 1] * run[j][2 * q + 1] + __uint_as_float(lw[q] & 0xffff0000u);
;                 }
;             }
;         }
;     }
	v_cvt_pk_bf16_f32 v32, v16, v17
	v_cvt_pk_bf16_f32 v33, v18, v19
	v_cvt_pk_bf16_f32 v34, v20, v21
	v_cvt_pk_bf16_f32 v35, v22, v23
	global_store_dwordx4 v2, v[32:35], s[10:11] nt
	v_cvt_pk_bf16_f32 v36, v24, v25
	v_cvt_pk_bf16_f32 v37, v26, v27
	v_cvt_pk_bf16_f32 v38, v28, v29
	v_cvt_pk_bf16_f32 v39, v30, v31
	global_store_dwordx4 v3, v[36:39], s[10:11] nt
	s_add_u32 s10, s10, 0x40000
	s_addc_u32 s11, s11, 0
	v_lshlrev_b32_e32 v48, 16, v160
	v_and_b32_e32 v49, 0xffff0000, v160
	v_fma_f32 v16, v168, v16, v48
	v_fma_f32 v17, v168, v17, v49
	v_lshlrev_b32_e32 v48, 16, v161
	v_and_b32_e32 v49, 0xffff0000, v161
	v_fma_f32 v18, v168, v18, v48
	v_fma_f32 v19, v168, v19, v49
	v_lshlrev_b32_e32 v48, 16, v162
	v_and_b32_e32 v49, 0xffff0000, v162
	v_fma_f32 v20, v168, v20, v48
	v_fma_f32 v21, v168, v21, v49
	v_lshlrev_b32_e32 v48, 16, v163
	v_and_b32_e32 v49, 0xffff0000, v163
	v_fma_f32 v22, v168, v22, v48
	v_fma_f32 v23, v168, v23, v49
	v_lshlrev_b32_e32 v48, 16, v164
	v_and_b32_e32 v49, 0xffff0000, v164
	v_fma_f32 v24, v168, v24, v48
	v_fma_f32 v25, v168, v25, v49
	v_lshlrev_b32_e32 v48, 16, v165
	v_and_b32_e32 v49, 0xffff0000, v165
	v_fma_f32 v26, v168, v26, v48
	v_fma_f32 v27, v168, v27, v49
	v_lshlrev_b32_e32 v48, 16, v166
	v_and_b32_e32 v49, 0xffff0000, v166
	v_fma_f32 v28, v168, v28, v48
	v_fma_f32 v29, v168, v29, v49
	v_lshlrev_b32_e32 v48, 16, v167
	v_and_b32_e32 v49, 0xffff0000, v167
	v_fma_f32 v30, v168, v30, v48
	v_fma_f32 v31, v168, v31, v49
	global_load_dwordx4 v[160:163], v2, s[6:7] nt
	global_load_dwordx4 v[164:167], v3, s[6:7] nt
	global_load_dword v168, v4, s[12:13]
	s_add_u32 s6, s6, 0x40000
	s_addc_u32 s7, s7, 0
	s_add_u32 s12, s12, 64
	s_addc_u32 s13, s13, 0
	s_waitcnt vmcnt(35)
	v_cvt_pk_bf16_f32 v40, v16, v17
	v_cvt_pk_bf16_f32 v41, v18, v19
	v_cvt_pk_bf16_f32 v42, v20, v21
	v_cvt_pk_bf16_f32 v43, v22, v23
	global_store_dwordx4 v2, v[40:43], s[10:11] nt
	v_cvt_pk_bf16_f32 v44, v24, v25
	v_cvt_pk_bf16_f32 v45, v26, v27
	v_cvt_pk_bf16_f32 v46, v28, v29
	v_cvt_pk_bf16_f32 v47, v30, v31
	global_store_dwordx4 v3, v[44:47], s[10:11] nt
	s_add_u32 s10, s10, 0x40000
	s_addc_u32 s11, s11, 0
	v_lshlrev_b32_e32 v48, 16, v176
	v_and_b32_e32 v49, 0xffff0000, v176
	v_fma_f32 v16, v184, v16, v48
	v_fma_f32 v17, v184, v17, v49
	v_lshlrev_b32_e32 v48, 16, v177
	v_and_b32_e32 v49, 0xffff0000, v177
	v_fma_f32 v18, v184, v18, v48
	v_fma_f32 v19, v184, v19, v49
	v_lshlrev_b32_e32 v48, 16, v178
	v_and_b32_e32 v49, 0xffff0000, v178
	v_fma_f32 v20, v184, v20, v48
	v_fma_f32 v21, v184, v21, v49
	v_lshlrev_b32_e32 v48, 16, v179
	v_and_b32_e32 v49, 0xffff0000, v179
	v_fma_f32 v22, v184, v22, v48
	v_fma_f32 v23, v184, v23, v49
	v_lshlrev_b32_e32 v48, 16, v180
	v_and_b32_e32 v49, 0xffff0000, v180
	v_fma_f32 v24, v184, v24, v48
	v_fma_f32 v25, v184, v25, v49
	v_lshlrev_b32_e32 v48, 16, v181
	v_and_b32_e32 v49, 0xffff0000, v181
	v_fma_f32 v26, v184, v26, v48
	v_fma_f32 v27, v184, v27, v49
	v_lshlrev_b32_e32 v48, 16, v182
	v_and_b32_e32 v49, 0xffff0000, v182
	v_fma_f32 v28, v184, v28, v48
	v_fma_f32 v29, v184, v29, v49
	v_lshlrev_b32_e32 v48, 16, v183
	v_and_b32_e32 v49, 0xffff0000, v183
	v_fma_f32 v30, v184, v30, v48
	v_fma_f32 v31, v184, v31, v49
	global_load_dwordx4 v[176:179], v2, s[6:7] nt
	global_load_dwordx4 v[180:183], v3, s[6:7] nt
	global_load_dword v184, v4, s[12:13]
	s_add_u32 s6, s6, 0x40000
	s_addc_u32 s7, s7, 0
	s_add_u32 s12, s12, 64
	s_addc_u32 s13, s13, 0
	s_waitcnt vmcnt(35)
	v_cvt_pk_bf16_f32 v32, v16, v17
	v_cvt_pk_bf16_f32 v33, v18, v19
	v_cvt_pk_bf16_f32 v34, v20, v21
	v_cvt_pk_bf16_f32 v35, v22, v23
	global_store_dwordx4 v2, v[32:35], s[10:11] nt
	v_cvt_pk_bf16_f32 v36, v24, v25
	v_cvt_pk_bf16_f32 v37, v26, v27
	v_cvt_pk_bf16_f32 v38, v28, v29
	v_cvt_pk_bf16_f32 v39, v30, v31
	global_store_dwordx4 v3, v[36:39], s[10:11] nt
	s_add_u32 s10, s10, 0x40000
	s_addc_u32 s11, s11, 0
	v_lshlrev_b32_e32 v48, 16, v64
	v_and_b32_e32 v49, 0xffff0000, v64
	v_fma_f32 v16, v72, v16, v48
	v_fma_f32 v17, v72, v17, v49
	v_lshlrev_b32_e32 v48, 16, v65
	v_and_b32_e32 v49, 0xffff0000, v65
	v_fma_f32 v18, v72, v18, v48
	v_fma_f32 v19, v72, v19, v49
	v_lshlrev_b32_e32 v48, 16, v66
	v_and_b32_e32 v49, 0xffff0000, v66
	v_fma_f32 v20, v72, v20, v48
	v_fma_f32 v21, v72, v21, v49
	v_lshlrev_b32_e32 v48, 16, v67
	v_and_b32_e32 v49, 0xffff0000, v67
	v_fma_f32 v22, v72, v22, v48
	v_fma_f32 v23, v72, v23, v49
	v_lshlrev_b32_e32 v48, 16, v68
	v_and_b32_e32 v49, 0xffff0000, v68
	v_fma_f32 v24, v72, v24, v48
	v_fma_f32 v25, v72, v25, v49
	v_lshlrev_b32_e32 v48, 16, v69
	v_and_b32_e32 v49, 0xffff0000, v69
	v_fma_f32 v26, v72, v26, v48
	v_fma_f32 v27, v72, v27, v49
	v_lshlrev_b32_e32 v48, 16, v70
	v_and_b32_e32 v49, 0xffff0000, v70
	v_fma_f32 v28, v72, v28, v48
	v_fma_f32 v29, v72, v29, v49
	v_lshlrev_b32_e32 v48, 16, v71
	v_and_b32_e32 v49, 0xffff0000, v71
	v_fma_f32 v30, v72, v30, v48
	v_fma_f32 v31, v72, v31, v49
	global_load_dwordx4 v[64:67], v2, s[6:7] nt
	global_load_dwordx4 v[68:71], v3, s[6:7] nt
	global_load_dword v72, v4, s[12:13]
	s_add_u32 s6, s6, 0x40000
	s_addc_u32 s7, s7, 0
	s_add_u32 s12, s12, 64
	s_addc_u32 s13, s13, 0
	s_waitcnt vmcnt(35)
; __device__ __forceinline__ float bf2f(unsigned h) { return __uint_as_float(h << 16); }
; __device__ __forceinline__ unsigned pk2(float lo, float hi) { return pg8::cvt_pk_bf16(lo, hi); }
; __device__ __forceinline__ void b2_scan(const Ctx& C) {
;     ...
;     for (int g = 0; g < 8; ++g) {
;         const int cur = g & 1;
;         if (g + 1 < 8) B2_LOAD(g + 1, cur ^ 1);
; #pragma unroll
;         for (int k = 0; k < 4; ++k) {
;             const int c = 4 * g + k;
;             const float dd[8] = {d0[cur][k][0], d0[cur][k][1], d0[cur][k][2], d0[cur][k][3], d1[cur][k][0], d1[cur][k][1], d1[cur][k][2], d1[cur][k][3]};
; #pragma unroll
;             for (int j = 0; j < 2; ++j) {
;                 v4u o; o.x = pk2(run[j][0], run[j][1]); o.y = pk2(run[j][2], run[j][3]); o.z = pk2(run[j][4], run[j][5]); o.w = pk2(run[j][6], run[j][7]);
;                 __builtin_nontemporal_store(o, (v4u*)(base + (size_t)c * cstride + (size_t)j * vstride));
;                 const unsigned lw[4] = {loc[cur][k][j].x, loc[cur][k][j].y, loc[cur][k][j].z, loc[cur][k][j].w};
; #pragma unroll
;                 for (int q = 0; q < 4; ++q) {
;                     run[j][2 * q] = dd[2 * q] * run[j][2 * q] + bf2f(lw[q] & 0xffffu);
;                     run[j][2 * q + 1] = dd[2 * q + 1] * run[j][2 * q + 1] + __uint_as_float(lw[q] & 0xffff0000u);
;                 }
;             }
;         }
;     }
	v_cvt_pk_bf16_f32 v40, v16, v17
	v_cvt_pk_bf16_f32 v41, v18, v19
	v_cvt_pk_bf16_f32 v42, v20, v21
	v_cvt_pk_bf16_f32 v43, v22, v23
	global_store_dwordx4 v2, v[40:43], s[10:11] nt
	v_cvt_pk_bf16_f32 v44, v24, v25
	v_cvt_pk_bf16_f32 v45, v26, v27
	v_cvt_pk_bf16_f32 v46, v28, v29
	v_cvt_pk_bf16_f32 v47, v30, v31
	global_store_dwordx4 v3, v[44:47], s[10:11] nt
	s_add_u32 s10, s10, 0x40000
	s_addc_u32 s11, s11, 0
	v_lshlrev_b32_e32 v48, 16, v80
	v_and_b32_e32 v49, 0xffff0000, v80
	v_fma_f32 v16, v88, v16, v48
	v_fma_f32 v17, v88, v17, v49
	v_lshlrev_b32_e32 v48, 16, v81
	v_and_b32_e32 v49, 0xffff0000, v81
	v_fma_f32 v18, v88, v18, v48
	v_fma_f32 v19, v88, v19, v49
	v_lshlrev_b32_e32 v48, 16, v82
	v_and_b32_e32 v49, 0xffff0000, v82
	v_fma_f32 v20, v88, v20, v48
	v_fma_f32 v21, v88, v21, v49
	v_lshlrev_b32_e32 v48, 16, v83
	v_and_b32_e32 v49, 0xffff0000, v83
	v_fma_f32 v22, v88, v22, v48
	v_fma_f32 v23, v88, v23, v49
	v_lshlrev_b32_e32 v48, 16, v84
	v_and_b32_e32 v49, 0xffff0000, v84
	v_fma_f32 v24, v88, v24, v48
	v_fma_f32 v25, v88, v25, v49
	v_lshlrev_b32_e32 v48, 16, v85
	v_and_b32_e32 v49, 0xffff0000, v85
	v_fma_f32 v26, v88, v26, v48
	v_fma_f32 v27, v88, v27, v49
	v_lshlrev_b32_e32 v48, 16, v86
	v_and_b32_e32 v49, 0xffff0000, v86
	v_fma_f32 v28, v88, v28, v48
	v_fma_f32 v29, v88, v29, v49
	v_lshlrev_b32_e32 v48, 16, v87
	v_and_b32_e32 v49, 0xffff0000, v87
	v_fma_f32 v30, v88, v30, v48
	v_fma_f32 v31, v88, v31, v49
	global_load_dwordx4 v[80:83], v2, s[6:7] nt
	global_load_dwordx4 v[84:87], v3, s[6:7] nt
	global_load_dword v88, v4, s[12:13]
	s_add_u32 s6, s6, 0x40000
	s_addc_u32 s7, s7, 0
	s_add_u32 s12, s12, 64
	s_addc_u32 s13, s13, 0
	s_waitcnt vmcnt(35)
	v_cvt_pk_bf16_f32 v32, v16, v17
	v_cvt_pk_bf16_f32 v33, v18, v19
	v_cvt_pk_bf16_f32 v34, v20, v21
	v_cvt_pk_bf16_f32 v35, v22, v23
	global_store_dwordx4 v2, v[32:35], s[10:11] nt
	v_cvt_pk_bf16_f32 v36, v24, v25
	v_cvt_pk_bf16_f32 v37, v26, v27
	v_cvt_pk_bf16_f32 v38, v28, v29
	v_cvt_pk_bf16_f32 v39, v30, v31
	global_store_dwordx4 v3, v[36:39], s[10:11] nt
	s_add_u32 s10, s10, 0x40000
	s_addc_u32 s11, s11, 0
	v_lshlrev_b32_e32 v48, 16, v96
	v_and_b32_e32 v49, 0xffff0000, v96
	v_fma_f32 v16, v104, v16, v48
	v_fma_f32 v17, v104, v17, v49
	v_lshlrev_b32_e32 v48, 16, v97
	v_and_b32_e32 v49, 0xffff0000, v97
	v_fma_f32 v18, v104, v18, v48
	v_fma_f32 v19, v104, v19, v49
	v_lshlrev_b32_e32 v48, 16, v98
	v_and_b32_e32 v49, 0xffff0000, v98
	v_fma_f32 v20, v104, v20, v48
	v_fma_f32 v21, v104, v21, v49
	v_lshlrev_b32_e32 v48, 16, v99
	v_and_b32_e32 v49, 0xffff0000, v99
	v_fma_f32 v22, v104, v22, v48
	v_fma_f32 v23, v104, v23, v49
	v_lshlrev_b32_e32 v48, 16, v100
	v_and_b32_e32 v49, 0xffff0000, v100
	v_fma_f32 v24, v104, v24, v48
	v_fma_f32 v25, v104, v25, v49
	v_lshlrev_b32_e32 v48, 16, v101
	v_and_b32_e32 v49, 0xffff0000, v101
	v_fma_f32 v26, v104, v26, v48
	v_fma_f32 v27, v104, v27, v49
	v_lshlrev_b32_e32 v48, 16, v102
	v_and_b32_e32 v49, 0xffff0000, v102
	v_fma_f32 v28, v104, v28, v48
	v_fma_f32 v29, v104, v29, v49
	v_lshlrev_b32_e32 v48, 16, v103
	v_and_b32_e32 v49, 0xffff0000, v103
	v_fma_f32 v30, v104, v30, v48
	v_fma_f32 v31, v104, v31, v49
	global_load_dwordx4 v[96:99], v2, s[6:7] nt
	global_load_dwordx4 v[100:103], v3, s[6:7] nt
	global_load_dword v104, v4, s[12:13]
	s_add_u32 s6, s6, 0x40000
	s_addc_u32 s7, s7, 0
	s_add_u32 s12, s12, 64
	s_addc_u32 s13, s13, 0
	s_waitcnt vmcnt(35)
	v_cvt_pk_bf16_f32 v40, v16, v17
	v_cvt_pk_bf16_f32 v41, v18, v19
	v_cvt_pk_bf16_f32 v42, v20, v21
	v_cvt_pk_bf16_f32 v43, v22, v23
	global_store_dwordx4 v2, v[40:43], s[10:11] nt
	v_cvt_pk_bf16_f32 v44, v24, v25
	v_cvt_pk_bf16_f32 v45, v26, v27
	v_cvt_pk_bf16_f32 v46, v28, v29
	v_cvt_pk_bf16_f32 v47, v30, v31
	global_store_dwordx4 v3, v[44:47], s[10:11] nt
	s_add_u32 s10, s10, 0x40000
	s_addc_u32 s11, s11, 0
	v_lshlrev_b32_e32 v48, 16, v112
	v_and_b32_e32 v49, 0xffff0000, v112
	v_fma_f32 v16, v120, v16, v48
	v_fma_f32 v17, v120, v17, v49
	v_lshlrev_b32_e32 v48, 16, v113
	v_and_b32_e32 v49, 0xffff0000, v113
	v_fma_f32 v18, v120, v18, v48
	v_fma_f32 v19, v120, v19, v49
	v_lshlrev_b32_e32 v48, 16, v114
	v_and_b32_e32 v49, 0xffff0000, v114
	v_fma_f32 v20, v120, v20, v48
	v_fma_f32 v21, v120, v21, v49
	v_lshlrev_b32_e32 v48, 16, v115
	v_and_b32_e32 v49, 0xffff0000, v115
	v_fma_f32 v22, v120, v22, v48
	v_fma_f32 v23, v120, v23, v49
	v_lshlrev_b32_e32 v48, 16, v116
	v_and_b32_e32 v49, 0xffff0000, v116
	v_fma_f32 v24, v120, v24, v48
	v_fma_f32 v25, v120, v25, v49
	v_lshlrev_b32_e32 v48, 16, v117
	v_and_b32_e32 v49, 0xffff0000, v117
	v_fma_f32 v26, v120, v26, v48
	v_fma_f32 v27, v120, v27, v49
	v_lshlrev_b32_e32 v48, 16, v118
	v_and_b32_e32 v49, 0xffff0000, v118
	v_fma_f32 v28, v120, v28, v48
	v_fma_f32 v29, v120, v29, v49
	v_lshlrev_b32_e32 v48, 16, v119
	v_and_b32_e32 v49, 0xffff0000, v119
	v_fma_f32 v30, v120, v30, v48
	v_fma_f32 v31, v120, v31, v49
	global_load_dwordx4 v[112:115], v2, s[6:7] nt
	global_load_dwordx4 v[116:119], v3, s[6:7] nt
	global_load_dword v120, v4, s[12:13]
	s_add_u32 s6, s6, 0x40000
	s_addc_u32 s7, s7, 0
	s_add_u32 s12, s12, 64
	s_addc_u32 s13, s13, 0
	s_waitcnt vmcnt(35)
; __device__ __forceinline__ float bf2f(unsigned h) { return __uint_as_float(h << 16); }
; __device__ __forceinline__ unsigned pk2(float lo, float hi) { return pg8::cvt_pk_bf16(lo, hi); }
; __device__ __forceinline__ void b2_scan(const Ctx& C) {
;     ...
;     for (int g = 0; g < 8; ++g) {
;         const int cur = g & 1;
;         if (g + 1 < 8) B2_LOAD(g + 1, cur ^ 1);
; #pragma unroll
;         for (int k = 0; k < 4; ++k) {
;             const int c = 4 * g + k;
;             const float dd[8] = {d0[cur][k][0], d0[cur][k][1], d0[cur][k][2], d0[cur][k][3], d1[cur][k][0], d1[cur][k][1], d1[cur][k][2], d1[cur][k][3]};
; #pragma unroll
;             for (int j = 0; j < 2; ++j) {
;                 v4u o; o.x = pk2(run[j][0], run[j][1]); o.y = pk2(run[j][2], run[j][3]); o.z = pk2(run[j][4], run[j][5]); o.w = pk2(run[j][6], run[j][7]);
;                 __builtin_nontemporal_store(o, (v4u*)(base + (size_t)c * cstride + (size_t)j * vstride));
;                 const unsigned lw[4] = {loc[cur][k][j].x, loc[cur][k][j].y, loc[cur][k][j].z, loc[cur][k][j].w};
; #pragma unroll
;                 for (int q = 0; q < 4; ++q) {
;                     run[j][2 * q] = dd[2 * q] * run[j][2 * q] + bf2f(lw[q] & 0xffffu);
;                     run[j][2 * q + 1] = dd[2 * q + 1] * run[j][2 * q + 1] + __uint_as_float(lw[q] & 0xffff0000u);
;                 }
;             }
;         }
;     }
	v_cvt_pk_bf16_f32 v32, v16, v17
	v_cvt_pk_bf16_f32 v33, v18, v19
	v_cvt_pk_bf16_f32 v34, v20, v21
	v_cvt_pk_bf16_f32 v35, v22, v23
	global_store_dwordx4 v2, v[32:35], s[10:11] nt
	v_cvt_pk_bf16_f32 v36, v24, v25
	v_cvt_pk_bf16_f32 v37, v26, v27
	v_cvt_pk_bf16_f32 v38, v28, v29
	v_cvt_pk_bf16_f32 v39, v30, v31
	global_store_dwordx4 v3, v[36:39], s[10:11] nt
	s_add_u32 s10, s10, 0x40000
	s_addc_u32 s11, s11, 0
	v_lshlrev_b32_e32 v48, 16, v128
	v_and_b32_e32 v49, 0xffff0000, v128
	v_fma_f32 v16, v136, v16, v48
	v_fma_f32 v17, v136, v17, v49
	v_lshlrev_b32_e32 v48, 16, v129
	v_and_b32_e32 v49, 0xffff0000, v129
	v_fma_f32 v18, v136, v18, v48
	v_fma_f32 v19, v136, v19, v49
	v_lshlrev_b32_e32 v48, 16, v130
	v_and_b32_e32 v49, 0xffff0000, v130
	v_fma_f32 v20, v136, v20, v48
	v_fma_f32 v21, v136, v21, v49
	v_lshlrev_b32_e32 v48, 16, v131
	v_and_b32_e32 v49, 0xffff0000, v131
	v_fma_f32 v22, v136, v22, v48
	v_fma_f32 v23, v136, v23, v49
	v_lshlrev_b32_e32 v48, 16, v132
	v_and_b32_e32 v49, 0xffff0000, v132
	v_fma_f32 v24, v136, v24, v48
	v_fma_f32 v25, v136, v25, v49
	v_lshlrev_b32_e32 v48, 16, v133
	v_and_b32_e32 v49, 0xffff0000, v133
	v_fma_f32 v26, v136, v26, v48
	v_fma_f32 v27, v136, v27, v49
	v_lshlrev_b32_e32 v48, 16, v134
	v_and_b32_e32 v49, 0xffff0000, v134
	v_fma_f32 v28, v136, v28, v48
	v_fma_f32 v29, v136, v29, v49
	v_lshlrev_b32_e32 v48, 16, v135
	v_and_b32_e32 v49, 0xffff0000, v135
	v_fma_f32 v30, v136, v30, v48
	v_fma_f32 v31, v136, v31, v49
	global_load_dwordx4 v[128:131], v2, s[6:7] nt
	global_load_dwordx4 v[132:135], v3, s[6:7] nt
	global_load_dword v136, v4, s[12:13]
	s_add_u32 s6, s6, 0x40000
	s_addc_u32 s7, s7, 0
	s_add_u32 s12, s12, 64
	s_addc_u32 s13, s13, 0
	s_waitcnt vmcnt(35)
	v_cvt_pk_bf16_f32 v40, v16, v17
	v_cvt_pk_bf16_f32 v41, v18, v19
	v_cvt_pk_bf16_f32 v42, v20, v21
	v_cvt_pk_bf16_f32 v43, v22, v23
	global_store_dwordx4 v2, v[40:43], s[10:11] nt
	v_cvt_pk_bf16_f32 v44, v24, v25
	v_cvt_pk_bf16_f32 v45, v26, v27
	v_cvt_pk_bf16_f32 v46, v28, v29
	v_cvt_pk_bf16_f32 v47, v30, v31
	global_store_dwordx4 v3, v[44:47], s[10:11] nt
	s_add_u32 s10, s10, 0x40000
	s_addc_u32 s11, s11, 0
	v_lshlrev_b32_e32 v48, 16, v144
	v_and_b32_e32 v49, 0xffff0000, v144
	v_fma_f32 v16, v152, v16, v48
	v_fma_f32 v17, v152, v17, v49
	v_lshlrev_b32_e32 v48, 16, v145
	v_and_b32_e32 v49, 0xffff0000, v145
	v_fma_f32 v18, v152, v18, v48
	v_fma_f32 v19, v152, v19, v49
	v_lshlrev_b32_e32 v48, 16, v146
	v_and_b32_e32 v49, 0xffff0000, v146
	v_fma_f32 v20, v152, v20, v48
	v_fma_f32 v21, v152, v21, v49
	v_lshlrev_b32_e32 v48, 16, v147
	v_and_b32_e32 v49, 0xffff0000, v147
	v_fma_f32 v22, v152, v22, v48
	v_fma_f32 v23, v152, v23, v49
	v_lshlrev_b32_e32 v48, 16, v148
	v_and_b32_e32 v49, 0xffff0000, v148
	v_fma_f32 v24, v152, v24, v48
	v_fma_f32 v25, v152, v25, v49
	v_lshlrev_b32_e32 v48, 16, v149
	v_and_b32_e32 v49, 0xffff0000, v149
	v_fma_f32 v26, v152, v26, v48
	v_fma_f32 v27, v152, v27, v49
	v_lshlrev_b32_e32 v48, 16, v150
	v_and_b32_e32 v49, 0xffff0000, v150
	v_fma_f32 v28, v152, v28, v48
	v_fma_f32 v29, v152, v29, v49
	v_lshlrev_b32_e32 v48, 16, v151
	v_and_b32_e32 v49, 0xffff0000, v151
	v_fma_f32 v30, v152, v30, v48
	v_fma_f32 v31, v152, v31, v49
	global_load_dwordx4 v[144:147], v2, s[6:7] nt
	global_load_dwordx4 v[148:151], v3, s[6:7] nt
	global_load_dword v152, v4, s[12:13]
	s_add_u32 s6, s6, 0x40000
	s_addc_u32 s7, s7, 0
	s_add_u32 s12, s12, 64
	s_addc_u32 s13, s13, 0
	s_waitcnt vmcnt(35)
	v_cvt_pk_bf16_f32 v32, v16, v17
	v_cvt_pk_bf16_f32 v33, v18, v19
	v_cvt_pk_bf16_f32 v34, v20, v21
	v_cvt_pk_bf16_f32 v35, v22, v23
	global_store_dwordx4 v2, v[32:35], s[10:11] nt
	v_cvt_pk_bf16_f32 v36, v24, v25
	v_cvt_pk_bf16_f32 v37, v26, v27
	v_cvt_pk_bf16_f32 v38, v28, v29
	v_cvt_pk_bf16_f32 v39, v30, v31
	global_store_dwordx4 v3, v[36:39], s[10:11] nt
	s_add_u32 s10, s10, 0x40000
	s_addc_u32 s11, s11, 0
	v_lshlrev_b32_e32 v48, 16, v160
	v_and_b32_e32 v49, 0xffff0000, v160
	v_fma_f32 v16, v168, v16, v48
	v_fma_f32 v17, v168, v17, v49
	v_lshlrev_b32_e32 v48, 16, v161
	v_and_b32_e32 v49, 0xffff0000, v161
	v_fma_f32 v18, v168, v18, v48
	v_fma_f32 v19, v168, v19, v49
	v_lshlrev_b32_e32 v48, 16, v162
	v_and_b32_e32 v49, 0xffff0000, v162
	v_fma_f32 v20, v168, v20, v48
	v_fma_f32 v21, v168, v21, v49
	v_lshlrev_b32_e32 v48, 16, v163
	v_and_b32_e32 v49, 0xffff0000, v163
	v_fma_f32 v22, v168, v22, v48
	v_fma_f32 v23, v168, v23, v49
	v_lshlrev_b32_e32 v48, 16, v164
	v_and_b32_e32 v49, 0xffff0000, v164
	v_fma_f32 v24, v168, v24, v48
	v_fma_f32 v25, v168, v25, v49
	v_lshlrev_b32_e32 v48, 16, v165
	v_and_b32_e32 v49, 0xffff0000, v165
	v_fma_f32 v26, v168, v26, v48
	v_fma_f32 v27, v168, v27, v49
	v_lshlrev_b32_e32 v48, 16, v166
	v_and_b32_e32 v49, 0xffff0000, v166
	v_fma_f32 v28, v168, v28, v48
	v_fma_f32 v29, v168, v29, v49
	v_lshlrev_b32_e32 v48, 16, v167
	v_and_b32_e32 v49, 0xffff0000, v167
	v_fma_f32 v30, v168, v30, v48
	v_fma_f32 v31, v168, v31, v49
	global_load_dwordx4 v[160:163], v2, s[6:7] nt
	global_load_dwordx4 v[164:167], v3, s[6:7] nt
	global_load_dword v168, v4, s[12:13]
	s_add_u32 s6, s6, 0x40000
	s_addc_u32 s7, s7, 0
	s_add_u32 s12, s12, 64
	s_addc_u32 s13, s13, 0
	s_waitcnt vmcnt(35)
; __device__ __forceinline__ float bf2f(unsigned h) { return __uint_as_float(h << 16); }
; __device__ __forceinline__ unsigned pk2(float lo, float hi) { return pg8::cvt_pk_bf16(lo, hi); }
; __device__ __forceinline__ void b2_scan(const Ctx& C) {
;     ...
;     for (int g = 0; g < 8; ++g) {
;         const int cur = g & 1;
;         if (g + 1 < 8) B2_LOAD(g + 1, cur ^ 1);
; #pragma unroll
;         for (int k = 0; k < 4; ++k) {
;             const int c = 4 * g + k;
;             const float dd[8] = {d0[cur][k][0], d0[cur][k][1], d0[cur][k][2], d0[cur][k][3], d1[cur][k][0], d1[cur][k][1], d1[cur][k][2], d1[cur][k][3]};
; #pragma unroll
;             for (int j = 0; j < 2; ++j) {
;                 v4u o; o.x = pk2(run[j][0], run[j][1]); o.y = pk2(run[j][2], run[j][3]); o.z = pk2(run[j][4], run[j][5]); o.w = pk2(run[j][6], run[j][7]);
;                 __builtin_nontemporal_store(o, (v4u*)(base + (size_t)c * cstride + (size_t)j * vstride));
;                 const unsigned lw[4] = {loc[cur][k][j].x, loc[cur][k][j].y, loc[cur][k][j].z, loc[cur][k][j].w};
; #pragma unroll
;                 for (int q = 0; q < 4; ++q) {
;                     run[j][2 * q] = dd[2 * q] * run[j][2 * q] + bf2f(lw[q] & 0xffffu);
;                     run[j][2 * q + 1] = dd[2 * q + 1] * run[j][2 * q + 1] + __uint_as_float(lw[q] & 0xffff0000u);
;                 }
;             }
;         }
;     }
	v_cvt_pk_bf16_f32 v40, v16, v17
	v_cvt_pk_bf16_f32 v41, v18, v19
	v_cvt_pk_bf16_f32 v42, v20, v21
	v_cvt_pk_bf16_f32 v43, v22, v23
	global_store_dwordx4 v2, v[40:43], s[10:11] nt
	v_cvt_pk_bf16_f32 v44, v24, v25
	v_cvt_pk_bf16_f32 v45, v26, v27
	v_cvt_pk_bf16_f32 v46, v28, v29
	v_cvt_pk_bf16_f32 v47, v30, v31
	global_store_dwordx4 v3, v[44:47], s[10:11] nt
	s_add_u32 s10, s10, 0x40000
	s_addc_u32 s11, s11, 0
	v_lshlrev_b32_e32 v48, 16, v176
	v_and_b32_e32 v49, 0xffff0000, v176
	v_fma_f32 v16, v184, v16, v48
	v_fma_f32 v17, v184, v17, v49
	v_lshlrev_b32_e32 v48, 16, v177
	v_and_b32_e32 v49, 0xffff0000, v177
	v_fma_f32 v18, v184, v18, v48
	v_fma_f32 v19, v184, v19, v49
	v_lshlrev_b32_e32 v48, 16, v178
	v_and_b32_e32 v49, 0xffff0000, v178
	v_fma_f32 v20, v184, v20, v48
	v_fma_f32 v21, v184, v21, v49
	v_lshlrev_b32_e32 v48, 16, v179
	v_and_b32_e32 v49, 0xffff0000, v179
	v_fma_f32 v22, v184, v22, v48
	v_fma_f32 v23, v184, v23, v49
	v_lshlrev_b32_e32 v48, 16, v180
	v_and_b32_e32 v49, 0xffff0000, v180
	v_fma_f32 v24, v184, v24, v48
	v_fma_f32 v25, v184, v25, v49
	v_lshlrev_b32_e32 v48, 16, v181
	v_and_b32_e32 v49, 0xffff0000, v181
	v_fma_f32 v26, v184, v26, v48
	v_fma_f32 v27, v184, v27, v49
	v_lshlrev_b32_e32 v48, 16, v182
	v_and_b32_e32 v49, 0xffff0000, v182
	v_fma_f32 v28, v184, v28, v48
	v_fma_f32 v29, v184, v29, v49
	v_lshlrev_b32_e32 v48, 16, v183
	v_and_b32_e32 v49, 0xffff0000, v183
	v_fma_f32 v30, v184, v30, v48
	v_fma_f32 v31, v184, v31, v49
	global_load_dwordx4 v[176:179], v2, s[6:7] nt
	global_load_dwordx4 v[180:183], v3, s[6:7] nt
	global_load_dword v184, v4, s[12:13]
	s_add_u32 s6, s6, 0x40000
	s_addc_u32 s7, s7, 0
	s_add_u32 s12, s12, 64
	s_addc_u32 s13, s13, 0
	s_waitcnt vmcnt(35)
	v_cvt_pk_bf16_f32 v32, v16, v17
	v_cvt_pk_bf16_f32 v33, v18, v19
	v_cvt_pk_bf16_f32 v34, v20, v21
	v_cvt_pk_bf16_f32 v35, v22, v23
	global_store_dwordx4 v2, v[32:35], s[10:11] nt
	v_cvt_pk_bf16_f32 v36, v24, v25
	v_cvt_pk_bf16_f32 v37, v26, v27
	v_cvt_pk_bf16_f32 v38, v28, v29
	v_cvt_pk_bf16_f32 v39, v30, v31
	global_store_dwordx4 v3, v[36:39], s[10:11] nt
	s_add_u32 s10, s10, 0x40000
	s_addc_u32 s11, s11, 0
	v_lshlrev_b32_e32 v48, 16, v64
	v_and_b32_e32 v49, 0xffff0000, v64
	v_fma_f32 v16, v72, v16, v48
	v_fma_f32 v17, v72, v17, v49
	v_lshlrev_b32_e32 v48, 16, v65
	v_and_b32_e32 v49, 0xffff0000, v65
	v_fma_f32 v18, v72, v18, v48
	v_fma_f32 v19, v72, v19, v49
	v_lshlrev_b32_e32 v48, 16, v66
	v_and_b32_e32 v49, 0xffff0000, v66
	v_fma_f32 v20, v72, v20, v48
	v_fma_f32 v21, v72, v21, v49
	v_lshlrev_b32_e32 v48, 16, v67
	v_and_b32_e32 v49, 0xffff0000, v67
	v_fma_f32 v22, v72, v22, v48
	v_fma_f32 v23, v72, v23, v49
	v_lshlrev_b32_e32 v48, 16, v68
	v_and_b32_e32 v49, 0xffff0000, v68
	v_fma_f32 v24, v72, v24, v48
	v_fma_f32 v25, v72, v25, v49
	v_lshlrev_b32_e32 v48, 16, v69
	v_and_b32_e32 v49, 0xffff0000, v69
	v_fma_f32 v26, v72, v26, v48
	v_fma_f32 v27, v72, v27, v49
	v_lshlrev_b32_e32 v48, 16, v70
	v_and_b32_e32 v49, 0xffff0000, v70
	v_fma_f32 v28, v72, v28, v48
	v_fma_f32 v29, v72, v29, v49
	v_lshlrev_b32_e32 v48, 16, v71
	v_and_b32_e32 v49, 0xffff0000, v71
	v_fma_f32 v30, v72, v30, v48
	v_fma_f32 v31, v72, v31, v49
	s_waitcnt vmcnt(32)
	v_cvt_pk_bf16_f32 v40, v16, v17
	v_cvt_pk_bf16_f32 v41, v18, v19
	v_cvt_pk_bf16_f32 v42, v20, v21
	v_cvt_pk_bf16_f32 v43, v22, v23
	global_store_dwordx4 v2, v[40:43], s[10:11] nt
	v_cvt_pk_bf16_f32 v44, v24, v25
	v_cvt_pk_bf16_f32 v45, v26, v27
	v_cvt_pk_bf16_f32 v46, v28, v29
	v_cvt_pk_bf16_f32 v47, v30, v31
	global_store_dwordx4 v3, v[44:47], s[10:11] nt
	s_add_u32 s10, s10, 0x40000
	s_addc_u32 s11, s11, 0
	v_lshlrev_b32_e32 v48, 16, v80
	v_and_b32_e32 v49, 0xffff0000, v80
	v_fma_f32 v16, v88, v16, v48
	v_fma_f32 v17, v88, v17, v49
	v_lshlrev_b32_e32 v48, 16, v81
	v_and_b32_e32 v49, 0xffff0000, v81
	v_fma_f32 v18, v88, v18, v48
	v_fma_f32 v19, v88, v19, v49
	v_lshlrev_b32_e32 v48, 16, v82
	v_and_b32_e32 v49, 0xffff0000, v82
	v_fma_f32 v20, v88, v20, v48
	v_fma_f32 v21, v88, v21, v49
	v_lshlrev_b32_e32 v48, 16, v83
	v_and_b32_e32 v49, 0xffff0000, v83
	v_fma_f32 v22, v88, v22, v48
	v_fma_f32 v23, v88, v23, v49
	v_lshlrev_b32_e32 v48, 16, v84
	v_and_b32_e32 v49, 0xffff0000, v84
	v_fma_f32 v24, v88, v24, v48
	v_fma_f32 v25, v88, v25, v49
	v_lshlrev_b32_e32 v48, 16, v85
	v_and_b32_e32 v49, 0xffff0000, v85
	v_fma_f32 v26, v88, v26, v48
	v_fma_f32 v27, v88, v27, v49
	v_lshlrev_b32_e32 v48, 16, v86
	v_and_b32_e32 v49, 0xffff0000, v86
	v_fma_f32 v28, v88, v28, v48
	v_fma_f32 v29, v88, v29, v49
	v_lshlrev_b32_e32 v48, 16, v87
	v_and_b32_e32 v49, 0xffff0000, v87
	v_fma_f32 v30, v88, v30, v48
	v_fma_f32 v31, v88, v31, v49
	s_waitcnt vmcnt(29)
	v_cvt_pk_bf16_f32 v32, v16, v17
	v_cvt_pk_bf16_f32 v33, v18, v19
	v_cvt_pk_bf16_f32 v34, v20, v21
	v_cvt_pk_bf16_f32 v35, v22, v23
	global_store_dwordx4 v2, v[32:35], s[10:11] nt
	v_cvt_pk_bf16_f32 v36, v24, v25
	v_cvt_pk_bf16_f32 v37, v26, v27
	v_cvt_pk_bf16_f32 v38, v28, v29
	v_cvt_pk_bf16_f32 v39, v30, v31
	global_store_dwordx4 v3, v[36:39], s[10:11] nt
	s_add_u32 s10, s10, 0x40000
	s_addc_u32 s11, s11, 0
	v_lshlrev_b32_e32 v48, 16, v96
	v_and_b32_e32 v49, 0xffff0000, v96
	v_fma_f32 v16, v104, v16, v48
	v_fma_f32 v17, v104, v17, v49
	v_lshlrev_b32_e32 v48, 16, v97
	v_and_b32_e32 v49, 0xffff0000, v97
	v_fma_f32 v18, v104, v18, v48
	v_fma_f32 v19, v104, v19, v49
	v_lshlrev_b32_e32 v48, 16, v98
	v_and_b32_e32 v49, 0xffff0000, v98
	v_fma_f32 v20, v104, v20, v48
	v_fma_f32 v21, v104, v21, v49
	v_lshlrev_b32_e32 v48, 16, v99
	v_and_b32_e32 v49, 0xffff0000, v99
	v_fma_f32 v22, v104, v22, v48
	v_fma_f32 v23, v104, v23, v49
	v_lshlrev_b32_e32 v48, 16, v100
	v_and_b32_e32 v49, 0xffff0000, v100
	v_fma_f32 v24, v104, v24, v48
	v_fma_f32 v25, v104, v25, v49
	v_lshlrev_b32_e32 v48, 16, v101
	v_and_b32_e32 v49, 0xffff0000, v101
	v_fma_f32 v26, v104, v26, v48
	v_fma_f32 v27, v104, v27, v49
	v_lshlrev_b32_e32 v48, 16, v102
	v_and_b32_e32 v49, 0xffff0000, v102
	v_fma_f32 v28, v104, v28, v48
	v_fma_f32 v29, v104, v29, v49
	v_lshlrev_b32_e32 v48, 16, v103
	v_and_b32_e32 v49, 0xffff0000, v103
	v_fma_f32 v30, v104, v30, v48
	v_fma_f32 v31, v104, v31, v49
	s_waitcnt vmcnt(26)
; __device__ __forceinline__ float bf2f(unsigned h) { return __uint_as_float(h << 16); }
; __device__ __forceinline__ unsigned pk2(float lo, float hi) { return pg8::cvt_pk_bf16(lo, hi); }
; __device__ __forceinline__ void b2_scan(const Ctx& C) {
;     ...
;     for (int g = 0; g < 8; ++g) {
;         const int cur = g & 1;
;         if (g + 1 < 8) B2_LOAD(g + 1, cur ^ 1);
; #pragma unroll
;         for (int k = 0; k < 4; ++k) {
;             const int c = 4 * g + k;
;             const float dd[8] = {d0[cur][k][0], d0[cur][k][1], d0[cur][k][2], d0[cur][k][3], d1[cur][k][0], d1[cur][k][1], d1[cur][k][2], d1[cur][k][3]};
; #pragma unroll
;             for (int j = 0; j < 2; ++j) {
;                 v4u o; o.x = pk2(run[j][0], run[j][1]); o.y = pk2(run[j][2], run[j][3]); o.z = pk2(run[j][4], run[j][5]); o.w = pk2(run[j][6], run[j][7]);
;                 __builtin_nontemporal_store(o, (v4u*)(base + (size_t)c * cstride + (size_t)j * vstride));
;                 const unsigned lw[4] = {loc[cur][k][j].x, loc[cur][k][j].y, loc[cur][k][j].z, loc[cur][k][j].w};
; #pragma unroll
;                 for (int q = 0; q < 4; ++q) {
;                     run[j][2 * q] = dd[2 * q] * run[j][2 * q] + bf2f(lw[q] & 0xffffu);
;                     run[j][2 * q + 1] = dd[2 * q + 1] * run[j][2 * q + 1] + __uint_as_float(lw[q] & 0xffff0000u);
;                 }
;             }
;         }
;     }
	v_cvt_pk_bf16_f32 v40, v16, v17
	v_cvt_pk_bf16_f32 v41, v18, v19
	v_cvt_pk_bf16_f32 v42, v20, v21
	v_cvt_pk_bf16_f32 v43, v22, v23
	global_store_dwordx4 v2, v[40:43], s[10:11] nt
	v_cvt_pk_bf16_f32 v44, v24, v25
	v_cvt_pk_bf16_f32 v45, v26, v27
	v_cvt_pk_bf16_f32 v46, v28, v29
	v_cvt_pk_bf16_f32 v47, v30, v31
	global_store_dwordx4 v3, v[44:47], s[10:11] nt
	s_add_u32 s10, s10, 0x40000
	s_addc_u32 s11, s11, 0
	v_lshlrev_b32_e32 v48, 16, v112
	v_and_b32_e32 v49, 0xffff0000, v112
	v_fma_f32 v16, v120, v16, v48
	v_fma_f32 v17, v120, v17, v49
	v_lshlrev_b32_e32 v48, 16, v113
	v_and_b32_e32 v49, 0xffff0000, v113
	v_fma_f32 v18, v120, v18, v48
	v_fma_f32 v19, v120, v19, v49
	v_lshlrev_b32_e32 v48, 16, v114
	v_and_b32_e32 v49, 0xffff0000, v114
	v_fma_f32 v20, v120, v20, v48
	v_fma_f32 v21, v120, v21, v49
	v_lshlrev_b32_e32 v48, 16, v115
	v_and_b32_e32 v49, 0xffff0000, v115
	v_fma_f32 v22, v120, v22, v48
	v_fma_f32 v23, v120, v23, v49
	v_lshlrev_b32_e32 v48, 16, v116
	v_and_b32_e32 v49, 0xffff0000, v116
	v_fma_f32 v24, v120, v24, v48
	v_fma_f32 v25, v120, v25, v49
	v_lshlrev_b32_e32 v48, 16, v117
	v_and_b32_e32 v49, 0xffff0000, v117
	v_fma_f32 v26, v120, v26, v48
	v_fma_f32 v27, v120, v27, v49
	v_lshlrev_b32_e32 v48, 16, v118
	v_and_b32_e32 v49, 0xffff0000, v118
	v_fma_f32 v28, v120, v28, v48
	v_fma_f32 v29, v120, v29, v49
	v_lshlrev_b32_e32 v48, 16, v119
	v_and_b32_e32 v49, 0xffff0000, v119
	v_fma_f32 v30, v120, v30, v48
	v_fma_f32 v31, v120, v31, v49
	s_waitcnt vmcnt(23)
	v_cvt_pk_bf16_f32 v32, v16, v17
	v_cvt_pk_bf16_f32 v33, v18, v19
	v_cvt_pk_bf16_f32 v34, v20, v21
	v_cvt_pk_bf16_f32 v35, v22, v23
	global_store_dwordx4 v2, v[32:35], s[10:11] nt
	v_cvt_pk_bf16_f32 v36, v24, v25
	v_cvt_pk_bf16_f32 v37, v26, v27
	v_cvt_pk_bf16_f32 v38, v28, v29
	v_cvt_pk_bf16_f32 v39, v30, v31
	global_store_dwordx4 v3, v[36:39], s[10:11] nt
	s_add_u32 s10, s10, 0x40000
	s_addc_u32 s11, s11, 0
	v_lshlrev_b32_e32 v48, 16, v128
	v_and_b32_e32 v49, 0xffff0000, v128
	v_fma_f32 v16, v136, v16, v48
	v_fma_f32 v17, v136, v17, v49
	v_lshlrev_b32_e32 v48, 16, v129
	v_and_b32_e32 v49, 0xffff0000, v129
	v_fma_f32 v18, v136, v18, v48
	v_fma_f32 v19, v136, v19, v49
	v_lshlrev_b32_e32 v48, 16, v130
	v_and_b32_e32 v49, 0xffff0000, v130
	v_fma_f32 v20, v136, v20, v48
	v_fma_f32 v21, v136, v21, v49
	v_lshlrev_b32_e32 v48, 16, v131
	v_and_b32_e32 v49, 0xffff0000, v131
	v_fma_f32 v22, v136, v22, v48
	v_fma_f32 v23, v136, v23, v49
	v_lshlrev_b32_e32 v48, 16, v132
	v_and_b32_e32 v49, 0xffff0000, v132
	v_fma_f32 v24, v136, v24, v48
	v_fma_f32 v25, v136, v25, v49
	v_lshlrev_b32_e32 v48, 16, v133
	v_and_b32_e32 v49, 0xffff0000, v133
	v_fma_f32 v26, v136, v26, v48
	v_fma_f32 v27, v136, v27, v49
	v_lshlrev_b32_e32 v48, 16, v134
	v_and_b32_e32 v49, 0xffff0000, v134
	v_fma_f32 v28, v136, v28, v48
	v_fma_f32 v29, v136, v29, v49
	v_lshlrev_b32_e32 v48, 16, v135
	v_and_b32_e32 v49, 0xffff0000, v135
	v_fma_f32 v30, v136, v30, v48
	v_fma_f32 v31, v136, v31, v49
	s_waitcnt vmcnt(20)
	v_cvt_pk_bf16_f32 v40, v16, v17
	v_cvt_pk_bf16_f32 v41, v18, v19
	v_cvt_pk_bf16_f32 v42, v20, v21
	v_cvt_pk_bf16_f32 v43, v22, v23
	global_store_dwordx4 v2, v[40:43], s[10:11] nt
	v_cvt_pk_bf16_f32 v44, v24, v25
	v_cvt_pk_bf16_f32 v45, v26, v27
	v_cvt_pk_bf16_f32 v46, v28, v29
	v_cvt_pk_bf16_f32 v47, v30, v31
	global_store_dwordx4 v3, v[44:47], s[10:11] nt
	s_add_u32 s10, s10, 0x40000
	s_addc_u32 s11, s11, 0
	v_lshlrev_b32_e32 v48, 16, v144
	v_and_b32_e32 v49, 0xffff0000, v144
	v_fma_f32 v16, v152, v16, v48
	v_fma_f32 v17, v152, v17, v49
	v_lshlrev_b32_e32 v48, 16, v145
	v_and_b32_e32 v49, 0xffff0000, v145
	v_fma_f32 v18, v152, v18, v48
	v_fma_f32 v19, v152, v19, v49
	v_lshlrev_b32_e32 v48, 16, v146
	v_and_b32_e32 v49, 0xffff0000, v146
	v_fma_f32 v20, v152, v20, v48
	v_fma_f32 v21, v152, v21, v49
	v_lshlrev_b32_e32 v48, 16, v147
	v_and_b32_e32 v49, 0xffff0000, v147
	v_fma_f32 v22, v152, v22, v48
	v_fma_f32 v23, v152, v23, v49
	v_lshlrev_b32_e32 v48, 16, v148
	v_and_b32_e32 v49, 0xffff0000, v148
	v_fma_f32 v24, v152, v24, v48
	v_fma_f32 v25, v152, v25, v49
	v_lshlrev_b32_e32 v48, 16, v149
	v_and_b32_e32 v49, 0xffff0000, v149
	v_fma_f32 v26, v152, v26, v48
	v_fma_f32 v27, v152, v27, v49
	v_lshlrev_b32_e32 v48, 16, v150
	v_and_b32_e32 v49, 0xffff0000, v150
	v_fma_f32 v28, v152, v28, v48
	v_fma_f32 v29, v152, v29, v49
	v_lshlrev_b32_e32 v48, 16, v151
	v_and_b32_e32 v49, 0xffff0000, v151
	v_fma_f32 v30, v152, v30, v48
	v_fma_f32 v31, v152, v31, v49
	s_waitcnt vmcnt(17)
	v_cvt_pk_bf16_f32 v32, v16, v17
	v_cvt_pk_bf16_f32 v33, v18, v19
	v_cvt_pk_bf16_f32 v34, v20, v21
	v_cvt_pk_bf16_f32 v35, v22, v23
	global_store_dwordx4 v2, v[32:35], s[10:11] nt
	v_cvt_pk_bf16_f32 v36, v24, v25
	v_cvt_pk_bf16_f32 v37, v26, v27
	v_cvt_pk_bf16_f32 v38, v28, v29
	v_cvt_pk_bf16_f32 v39, v30, v31
	global_store_dwordx4 v3, v[36:39], s[10:11] nt
	s_add_u32 s10, s10, 0x40000
	s_addc_u32 s11, s11, 0
	v_lshlrev_b32_e32 v48, 16, v160
	v_and_b32_e32 v49, 0xffff0000, v160
	v_fma_f32 v16, v168, v16, v48
	v_fma_f32 v17, v168, v17, v49
	v_lshlrev_b32_e32 v48, 16, v161
	v_and_b32_e32 v49, 0xffff0000, v161
	v_fma_f32 v18, v168, v18, v48
	v_fma_f32 v19, v168, v19, v49
	v_lshlrev_b32_e32 v48, 16, v162
	v_and_b32_e32 v49, 0xffff0000, v162
	v_fma_f32 v20, v168, v20, v48
	v_fma_f32 v21, v168, v21, v49
	v_lshlrev_b32_e32 v48, 16, v163
	v_and_b32_e32 v49, 0xffff0000, v163
	v_fma_f32 v22, v168, v22, v48
	v_fma_f32 v23, v168, v23, v49
	v_lshlrev_b32_e32 v48, 16, v164
	v_and_b32_e32 v49, 0xffff0000, v164
	v_fma_f32 v24, v168, v24, v48
	v_fma_f32 v25, v168, v25, v49
	v_lshlrev_b32_e32 v48, 16, v165
	v_and_b32_e32 v49, 0xffff0000, v165
	v_fma_f32 v26, v168, v26, v48
	v_fma_f32 v27, v168, v27, v49
	v_lshlrev_b32_e32 v48, 16, v166
	v_and_b32_e32 v49, 0xffff0000, v166
	v_fma_f32 v28, v168, v28, v48
	v_fma_f32 v29, v168, v29, v49
	v_lshlrev_b32_e32 v48, 16, v167
	v_and_b32_e32 v49, 0xffff0000, v167
	v_fma_f32 v30, v168, v30, v48
	v_fma_f32 v31, v168, v31, v49
	s_waitcnt vmcnt(14)
; __device__ __forceinline__ float bf2f(unsigned h) { return __uint_as_float(h << 16); }
; __device__ __forceinline__ unsigned pk2(float lo, float hi) { return pg8::cvt_pk_bf16(lo, hi); }
; __device__ __forceinline__ void b2_scan(const Ctx& C) {
;     ...
;     if (!gla) { const int b = r >> 13, h = (r >> 9) & 15, e = r & 511;
;         base = (bf16*)(C.ws + WS_HS) + ((size_t)(b * NC) * 16 + h) * 8192 + (size_t)e * 8; vstride = 512 * 8; cstride = (size_t)16 * 8192; dec = SDEC + (b * NC) * 16 + h; dstride = 16; }
;     else { const int b = r >> 13, h = (r >> 11) & 3, q = r & 2047, doct = q & 15, vp = q >> 4;
;         base = (bf16*)(C.ws + WS_GS) + ((size_t)(b * NC) * 4 + h) * 32768 + (size_t)(2 * vp) * 128 + doct * 8; vstride = 128; cstride = (size_t)4 * 32768; dec = GDEC + ((b * NC) * 4 + h) * 128 + doct * 8; dstride = 512; }
;     float run[2][8];
; #pragma unroll
;     for (int j = 0; j < 2; ++j)
; #pragma unroll
;         for (int q = 0; q < 8; ++q) run[j][q] = 0.f;
;     v4u loc[2][4][2]; f32x4 d0[2][4], d1[2][4];
;     ...
;     B2_LOAD(0, 0);
; #pragma unroll
;     for (int g = 0; g < 8; ++g) {
;         const int cur = g & 1;
;         if (g + 1 < 8) B2_LOAD(g + 1, cur ^ 1);
; #pragma unroll
;         for (int k = 0; k < 4; ++k) {
;             const int c = 4 * g + k;
;             const float dd[8] = {d0[cur][k][0], d0[cur][k][1], d0[cur][k][2], d0[cur][k][3], d1[cur][k][0], d1[cur][k][1], d1[cur][k][2], d1[cur][k][3]};
; #pragma unroll
;             for (int j = 0; j < 2; ++j) {
;                 v4u o; o.x = pk2(run[j][0], run[j][1]); o.y = pk2(run[j][2], run[j][3]); o.z = pk2(run[j][4], run[j][5]); o.w = pk2(run[j][6], run[j][7]);
;                 __builtin_nontemporal_store(o, (v4u*)(base + (size_t)c * cstride + (size_t)j * vstride));
;                 const unsigned lw[4] = {loc[cur][k][j].x, loc[cur][k][j].y, loc[cur][k][j].z, loc[cur][k][j].w};
; #pragma unroll
;                 for (int q = 0; q < 4; ++q) {
;                     run[j][2 * q] = dd[2 * q] * run[j][2 * q] + bf2f(lw[q] & 0xffffu);
;                     run[j][2 * q + 1] = dd[2 * q + 1] * run[j][2 * q + 1] + __uint_as_float(lw[q] & 0xffff0000u);
;                 }
;             }
;         }
;     }
	v_cvt_pk_bf16_f32 v40, v16, v17
	v_cvt_pk_bf16_f32 v41, v18, v19
	v_cvt_pk_bf16_f32 v42, v20, v21
	v_cvt_pk_bf16_f32 v43, v22, v23
	global_store_dwordx4 v2, v[40:43], s[10:11] nt
	v_cvt_pk_bf16_f32 v44, v24, v25
	v_cvt_pk_bf16_f32 v45, v26, v27
	v_cvt_pk_bf16_f32 v46, v28, v29
	v_cvt_pk_bf16_f32 v47, v30, v31
	global_store_dwordx4 v3, v[44:47], s[10:11] nt
	s_add_u32 s10, s10, 0x40000
	s_addc_u32 s11, s11, 0
	v_lshlrev_b32_e32 v48, 16, v176
	v_and_b32_e32 v49, 0xffff0000, v176
	v_fma_f32 v16, v184, v16, v48
	v_fma_f32 v17, v184, v17, v49
	v_lshlrev_b32_e32 v48, 16, v177
	v_and_b32_e32 v49, 0xffff0000, v177
	v_fma_f32 v18, v184, v18, v48
	v_fma_f32 v19, v184, v19, v49
	v_lshlrev_b32_e32 v48, 16, v178
	v_and_b32_e32 v49, 0xffff0000, v178
	v_fma_f32 v20, v184, v20, v48
	v_fma_f32 v21, v184, v21, v49
	v_lshlrev_b32_e32 v48, 16, v179
	v_and_b32_e32 v49, 0xffff0000, v179
	v_fma_f32 v22, v184, v22, v48
	v_fma_f32 v23, v184, v23, v49
	v_lshlrev_b32_e32 v48, 16, v180
	v_and_b32_e32 v49, 0xffff0000, v180
	v_fma_f32 v24, v184, v24, v48
	v_fma_f32 v25, v184, v25, v49
	v_lshlrev_b32_e32 v48, 16, v181
	v_and_b32_e32 v49, 0xffff0000, v181
	v_fma_f32 v26, v184, v26, v48
	v_fma_f32 v27, v184, v27, v49
	v_lshlrev_b32_e32 v48, 16, v182
	v_and_b32_e32 v49, 0xffff0000, v182
	v_fma_f32 v28, v184, v28, v48
	v_fma_f32 v29, v184, v29, v49
	v_lshlrev_b32_e32 v48, 16, v183
	v_and_b32_e32 v49, 0xffff0000, v183
	v_fma_f32 v30, v184, v30, v48
	v_fma_f32 v31, v184, v31, v49
	s_branch .Lb2_end_l0
.Lb2_gla_l0:
	s_sub_u32 s6, s2, 128
	s_and_b32 s12, s6, 7
	s_lshl_b32 s12, s12, 7
	s_lshr_b32 s10, s6, 5
	s_add_u32 s12, s12, s10
	s_lshr_b32 s10, s6, 3
	s_and_b32 s10, s10, 3
	s_lshl_b32 s10, s10, 14
	s_lshl_b32 s6, s12, 16
	s_add_u32 s6, s6, s10
	s_lshl_b32 s12, s12, 9
	v_lshrrev_b32_e32 v2, 4, v234
	v_lshlrev_b32_e32 v2, 9, v2
	v_and_b32_e32 v5, 15, v234
	v_lshl_add_u32 v2, v5, 4, v2
	v_add_u32_e32 v3, 0x100, v2
	v_lshlrev_b32_e32 v5, 5, v5
	s_waitcnt lgkmcnt(0)
	s_add_u32 s6, s6, s14
	s_addc_u32 s7, s15, 0
	s_add_u32 s6, s6, 0x21c00000
	s_addc_u32 s7, s7, 0
	s_add_u32 s12, s12, s14
	s_addc_u32 s13, s15, 0
	s_add_u32 s12, s12, 0x25c10000
	s_addc_u32 s13, s13, 0
	s_mov_b32 s10, s6
	s_mov_b32 s11, s7
	global_load_dwordx4 v[64:67], v2, s[6:7] nt
	global_load_dwordx4 v[68:71], v3, s[6:7] nt
	global_load_dwordx4 v[72:75], v5, s[12:13]
	global_load_dwordx4 v[76:79], v5, s[12:13] offset:16
	s_add_u32 s6, s6, 0x40000
	s_addc_u32 s7, s7, 0
	s_add_u32 s12, s12, 2048
	s_addc_u32 s13, s13, 0
	global_load_dwordx4 v[80:83], v2, s[6:7] nt
	global_load_dwordx4 v[84:87], v3, s[6:7] nt
	global_load_dwordx4 v[88:91], v5, s[12:13]
	global_load_dwordx4 v[92:95], v5, s[12:13] offset:16
	s_add_u32 s6, s6, 0x40000
	s_addc_u32 s7, s7, 0
	s_add_u32 s12, s12, 2048
	s_addc_u32 s13, s13, 0
	global_load_dwordx4 v[96:99], v2, s[6:7] nt
	global_load_dwordx4 v[100:103], v3, s[6:7] nt
	global_load_dwordx4 v[104:107], v5, s[12:13]
	global_load_dwordx4 v[108:111], v5, s[12:13] offset:16
	s_add_u32 s6, s6, 0x40000
	s_addc_u32 s7, s7, 0
	s_add_u32 s12, s12, 2048
	s_addc_u32 s13, s13, 0
	global_load_dwordx4 v[112:115], v2, s[6:7] nt
	global_load_dwordx4 v[116:119], v3, s[6:7] nt
	global_load_dwordx4 v[120:123], v5, s[12:13]
	global_load_dwordx4 v[124:127], v5, s[12:13] offset:16
	s_add_u32 s6, s6, 0x40000
	s_addc_u32 s7, s7, 0
	s_add_u32 s12, s12, 2048
	s_addc_u32 s13, s13, 0
	global_load_dwordx4 v[128:131], v2, s[6:7] nt
	global_load_dwordx4 v[132:135], v3, s[6:7] nt
	global_load_dwordx4 v[136:139], v5, s[12:13]
	global_load_dwordx4 v[140:143], v5, s[12:13] offset:16
	s_add_u32 s6, s6, 0x40000
	s_addc_u32 s7, s7, 0
	s_add_u32 s12, s12, 2048
	s_addc_u32 s13, s13, 0
	global_load_dwordx4 v[144:147], v2, s[6:7] nt
	global_load_dwordx4 v[148:151], v3, s[6:7] nt
	global_load_dwordx4 v[152:155], v5, s[12:13]
	global_load_dwordx4 v[156:159], v5, s[12:13] offset:16
	s_add_u32 s6, s6, 0x40000
	s_addc_u32 s7, s7, 0
	s_add_u32 s12, s12, 2048
	s_addc_u32 s13, s13, 0
	global_load_dwordx4 v[160:163], v2, s[6:7] nt
	global_load_dwordx4 v[164:167], v3, s[6:7] nt
	global_load_dwordx4 v[168:171], v5, s[12:13]
	global_load_dwordx4 v[172:175], v5, s[12:13] offset:16
	s_add_u32 s6, s6, 0x40000
	s_addc_u32 s7, s7, 0
	s_add_u32 s12, s12, 2048
	s_addc_u32 s13, s13, 0
	global_load_dwordx4 v[176:179], v2, s[6:7] nt
	global_load_dwordx4 v[180:183], v3, s[6:7] nt
	global_load_dwordx4 v[184:187], v5, s[12:13]
	global_load_dwordx4 v[188:191], v5, s[12:13] offset:16
	s_add_u32 s6, s6, 0x40000
	s_addc_u32 s7, s7, 0
	s_add_u32 s12, s12, 2048
	s_addc_u32 s13, s13, 0
	s_waitcnt vmcnt(28)
	v_cvt_pk_bf16_f32 v32, v16, v17
	v_cvt_pk_bf16_f32 v33, v18, v19
	v_cvt_pk_bf16_f32 v34, v20, v21
	v_cvt_pk_bf16_f32 v35, v22, v23
	global_store_dwordx4 v2, v[32:35], s[10:11] nt
	v_cvt_pk_bf16_f32 v36, v24, v25
	v_cvt_pk_bf16_f32 v37, v26, v27
	v_cvt_pk_bf16_f32 v38, v28, v29
	v_cvt_pk_bf16_f32 v39, v30, v31
	global_store_dwordx4 v3, v[36:39], s[10:11] nt
	s_add_u32 s10, s10, 0x40000
	s_addc_u32 s11, s11, 0
	v_lshlrev_b32_e32 v48, 16, v64
	v_and_b32_e32 v49, 0xffff0000, v64
	v_fma_f32 v16, v72, v16, v48
	v_fma_f32 v17, v73, v17, v49
	v_lshlrev_b32_e32 v48, 16, v65
	v_and_b32_e32 v49, 0xffff0000, v65
	v_fma_f32 v18, v74, v18, v48
	v_fma_f32 v19, v75, v19, v49
	v_lshlrev_b32_e32 v48, 16, v66
	v_and_b32_e32 v49, 0xffff0000, v66
	v_fma_f32 v20, v76, v20, v48
	v_fma_f32 v21, v77, v21, v49
	v_lshlrev_b32_e32 v48, 16, v67
	v_and_b32_e32 v49, 0xffff0000, v67
	v_fma_f32 v22, v78, v22, v48
	v_fma_f32 v23, v79, v23, v49
	v_lshlrev_b32_e32 v48, 16, v68
	v_and_b32_e32 v49, 0xffff0000, v68
	v_fma_f32 v24, v72, v24, v48
	v_fma_f32 v25, v73, v25, v49
	v_lshlrev_b32_e32 v48, 16, v69
	v_and_b32_e32 v49, 0xffff0000, v69
	v_fma_f32 v26, v74, v26, v48
	v_fma_f32 v27, v75, v27, v49
	v_lshlrev_b32_e32 v48, 16, v70
	v_and_b32_e32 v49, 0xffff0000, v70
	v_fma_f32 v28, v76, v28, v48
	v_fma_f32 v29, v77, v29, v49
	v_lshlrev_b32_e32 v48, 16, v71
	v_and_b32_e32 v49, 0xffff0000, v71
	v_fma_f32 v30, v78, v30, v48
	v_fma_f32 v31, v79, v31, v49
	global_load_dwordx4 v[64:67], v2, s[6:7] nt
	global_load_dwordx4 v[68:71], v3, s[6:7] nt
	global_load_dwordx4 v[72:75], v5, s[12:13]
	global_load_dwordx4 v[76:79], v5, s[12:13] offset:16
	s_add_u32 s6, s6, 0x40000
	s_addc_u32 s7, s7, 0
	s_add_u32 s12, s12, 2048
	s_addc_u32 s13, s13, 0
	s_waitcnt vmcnt(30)
; __device__ __forceinline__ float bf2f(unsigned h) { return __uint_as_float(h << 16); }
; __device__ __forceinline__ unsigned pk2(float lo, float hi) { return pg8::cvt_pk_bf16(lo, hi); }
; __device__ __forceinline__ void b2_scan(const Ctx& C) {
;     ...
;     B2_LOAD(0, 0);
; #pragma unroll
;     for (int g = 0; g < 8; ++g) {
;         const int cur = g & 1;
;         if (g + 1 < 8) B2_LOAD(g + 1, cur ^ 1);
; #pragma unroll
;         for (int k = 0; k < 4; ++k) {
;             const int c = 4 * g + k;
;             const float dd[8] = {d0[cur][k][0], d0[cur][k][1], d0[cur][k][2], d0[cur][k][3], d1[cur][k][0], d1[cur][k][1], d1[cur][k][2], d1[cur][k][3]};
; #pragma unroll
;             for (int j = 0; j < 2; ++j) {
;                 v4u o; o.x = pk2(run[j][0], run[j][1]); o.y = pk2(run[j][2], run[j][3]); o.z = pk2(run[j][4], run[j][5]); o.w = pk2(run[j][6], run[j][7]);
;                 __builtin_nontemporal_store(o, (v4u*)(base + (size_t)c * cstride + (size_t)j * vstride));
;                 const unsigned lw[4] = {loc[cur][k][j].x, loc[cur][k][j].y, loc[cur][k][j].z, loc[cur][k][j].w};
; #pragma unroll
;                 for (int q = 0; q < 4; ++q) {
;                     run[j][2 * q] = dd[2 * q] * run[j][2 * q] + bf2f(lw[q] & 0xffffu);
;                     run[j][2 * q + 1] = dd[2 * q + 1] * run[j][2 * q + 1] + __uint_as_float(lw[q] & 0xffff0000u);
;                 }
;             }
;         }
;     }
	v_cvt_pk_bf16_f32 v40, v16, v17
	v_cvt_pk_bf16_f32 v41, v18, v19
	v_cvt_pk_bf16_f32 v42, v20, v21
	v_cvt_pk_bf16_f32 v43, v22, v23
	global_store_dwordx4 v2, v[40:43], s[10:11] nt
	v_cvt_pk_bf16_f32 v44, v24, v25
	v_cvt_pk_bf16_f32 v45, v26, v27
	v_cvt_pk_bf16_f32 v46, v28, v29
	v_cvt_pk_bf16_f32 v47, v30, v31
	global_store_dwordx4 v3, v[44:47], s[10:11] nt
	s_add_u32 s10, s10, 0x40000
	s_addc_u32 s11, s11, 0
	v_lshlrev_b32_e32 v48, 16, v80
	v_and_b32_e32 v49, 0xffff0000, v80
	v_fma_f32 v16, v88, v16, v48
	v_fma_f32 v17, v89, v17, v49
	v_lshlrev_b32_e32 v48, 16, v81
	v_and_b32_e32 v49, 0xffff0000, v81
	v_fma_f32 v18, v90, v18, v48
	v_fma_f32 v19, v91, v19, v49
	v_lshlrev_b32_e32 v48, 16, v82
	v_and_b32_e32 v49, 0xffff0000, v82
	v_fma_f32 v20, v92, v20, v48
	v_fma_f32 v21, v93, v21, v49
	v_lshlrev_b32_e32 v48, 16, v83
	v_and_b32_e32 v49, 0xffff0000, v83
	v_fma_f32 v22, v94, v22, v48
	v_fma_f32 v23, v95, v23, v49
	v_lshlrev_b32_e32 v48, 16, v84
	v_and_b32_e32 v49, 0xffff0000, v84
	v_fma_f32 v24, v88, v24, v48
	v_fma_f32 v25, v89, v25, v49
	v_lshlrev_b32_e32 v48, 16, v85
	v_and_b32_e32 v49, 0xffff0000, v85
	v_fma_f32 v26, v90, v26, v48
	v_fma_f32 v27, v91, v27, v49
	v_lshlrev_b32_e32 v48, 16, v86
	v_and_b32_e32 v49, 0xffff0000, v86
	v_fma_f32 v28, v92, v28, v48
	v_fma_f32 v29, v93, v29, v49
	v_lshlrev_b32_e32 v48, 16, v87
	v_and_b32_e32 v49, 0xffff0000, v87
	v_fma_f32 v30, v94, v30, v48
	v_fma_f32 v31, v95, v31, v49
	global_load_dwordx4 v[80:83], v2, s[6:7] nt
	global_load_dwordx4 v[84:87], v3, s[6:7] nt
	global_load_dwordx4 v[88:91], v5, s[12:13]
	global_load_dwordx4 v[92:95], v5, s[12:13] offset:16
	s_add_u32 s6, s6, 0x40000
	s_addc_u32 s7, s7, 0
	s_add_u32 s12, s12, 2048
	s_addc_u32 s13, s13, 0
	s_waitcnt vmcnt(32)
	v_cvt_pk_bf16_f32 v32, v16, v17
	v_cvt_pk_bf16_f32 v33, v18, v19
	v_cvt_pk_bf16_f32 v34, v20, v21
	v_cvt_pk_bf16_f32 v35, v22, v23
	global_store_dwordx4 v2, v[32:35], s[10:11] nt
	v_cvt_pk_bf16_f32 v36, v24, v25
	v_cvt_pk_bf16_f32 v37, v26, v27
	v_cvt_pk_bf16_f32 v38, v28, v29
	v_cvt_pk_bf16_f32 v39, v30, v31
	global_store_dwordx4 v3, v[36:39], s[10:11] nt
	s_add_u32 s10, s10, 0x40000
	s_addc_u32 s11, s11, 0
	v_lshlrev_b32_e32 v48, 16, v96
	v_and_b32_e32 v49, 0xffff0000, v96
	v_fma_f32 v16, v104, v16, v48
	v_fma_f32 v17, v105, v17, v49
	v_lshlrev_b32_e32 v48, 16, v97
	v_and_b32_e32 v49, 0xffff0000, v97
	v_fma_f32 v18, v106, v18, v48
	v_fma_f32 v19, v107, v19, v49
	v_lshlrev_b32_e32 v48, 16, v98
	v_and_b32_e32 v49, 0xffff0000, v98
	v_fma_f32 v20, v108, v20, v48
	v_fma_f32 v21, v109, v21, v49
	v_lshlrev_b32_e32 v48, 16, v99
	v_and_b32_e32 v49, 0xffff0000, v99
	v_fma_f32 v22, v110, v22, v48
	v_fma_f32 v23, v111, v23, v49
	v_lshlrev_b32_e32 v48, 16, v100
	v_and_b32_e32 v49, 0xffff0000, v100
	v_fma_f32 v24, v104, v24, v48
	v_fma_f32 v25, v105, v25, v49
	v_lshlrev_b32_e32 v48, 16, v101
	v_and_b32_e32 v49, 0xffff0000, v101
	v_fma_f32 v26, v106, v26, v48
	v_fma_f32 v27, v107, v27, v49
	v_lshlrev_b32_e32 v48, 16, v102
	v_and_b32_e32 v49, 0xffff0000, v102
	v_fma_f32 v28, v108, v28, v48
	v_fma_f32 v29, v109, v29, v49
	v_lshlrev_b32_e32 v48, 16, v103
	v_and_b32_e32 v49, 0xffff0000, v103
	v_fma_f32 v30, v110, v30, v48
	v_fma_f32 v31, v111, v31, v49
	global_load_dwordx4 v[96:99], v2, s[6:7] nt
	global_load_dwordx4 v[100:103], v3, s[6:7] nt
	global_load_dwordx4 v[104:107], v5, s[12:13]
	global_load_dwordx4 v[108:111], v5, s[12:13] offset:16
	s_add_u32 s6, s6, 0x40000
	s_addc_u32 s7, s7, 0
	s_add_u32 s12, s12, 2048
	s_addc_u32 s13, s13, 0
	s_waitcnt vmcnt(34)
	v_cvt_pk_bf16_f32 v40, v16, v17
	v_cvt_pk_bf16_f32 v41, v18, v19
	v_cvt_pk_bf16_f32 v42, v20, v21
	v_cvt_pk_bf16_f32 v43, v22, v23
	global_store_dwordx4 v2, v[40:43], s[10:11] nt
	v_cvt_pk_bf16_f32 v44, v24, v25
	v_cvt_pk_bf16_f32 v45, v26, v27
	v_cvt_pk_bf16_f32 v46, v28, v29
	v_cvt_pk_bf16_f32 v47, v30, v31
	global_store_dwordx4 v3, v[44:47], s[10:11] nt
	s_add_u32 s10, s10, 0x40000
	s_addc_u32 s11, s11, 0
	v_lshlrev_b32_e32 v48, 16, v112
	v_and_b32_e32 v49, 0xffff0000, v112
	v_fma_f32 v16, v120, v16, v48
	v_fma_f32 v17, v121, v17, v49
	v_lshlrev_b32_e32 v48, 16, v113
	v_and_b32_e32 v49, 0xffff0000, v113
	v_fma_f32 v18, v122, v18, v48
	v_fma_f32 v19, v123, v19, v49
	v_lshlrev_b32_e32 v48, 16, v114
	v_and_b32_e32 v49, 0xffff0000, v114
	v_fma_f32 v20, v124, v20, v48
	v_fma_f32 v21, v125, v21, v49
	v_lshlrev_b32_e32 v48, 16, v115
	v_and_b32_e32 v49, 0xffff0000, v115
	v_fma_f32 v22, v126, v22, v48
	v_fma_f32 v23, v127, v23, v49
	v_lshlrev_b32_e32 v48, 16, v116
	v_and_b32_e32 v49, 0xffff0000, v116
	v_fma_f32 v24, v120, v24, v48
	v_fma_f32 v25, v121, v25, v49
	v_lshlrev_b32_e32 v48, 16, v117
	v_and_b32_e32 v49, 0xffff0000, v117
	v_fma_f32 v26, v122, v26, v48
	v_fma_f32 v27, v123, v27, v49
	v_lshlrev_b32_e32 v48, 16, v118
	v_and_b32_e32 v49, 0xffff0000, v118
	v_fma_f32 v28, v124, v28, v48
	v_fma_f32 v29, v125, v29, v49
	v_lshlrev_b32_e32 v48, 16, v119
	v_and_b32_e32 v49, 0xffff0000, v119
	v_fma_f32 v30, v126, v30, v48
	v_fma_f32 v31, v127, v31, v49
	global_load_dwordx4 v[112:115], v2, s[6:7] nt
	global_load_dwordx4 v[116:119], v3, s[6:7] nt
	global_load_dwordx4 v[120:123], v5, s[12:13]
	global_load_dwordx4 v[124:127], v5, s[12:13] offset:16
	s_add_u32 s6, s6, 0x40000
	s_addc_u32 s7, s7, 0
	s_add_u32 s12, s12, 2048
	s_addc_u32 s13, s13, 0
	s_waitcnt vmcnt(36)
; __device__ __forceinline__ float bf2f(unsigned h) { return __uint_as_float(h << 16); }
; __device__ __forceinline__ unsigned pk2(float lo, float hi) { return pg8::cvt_pk_bf16(lo, hi); }
; __device__ __forceinline__ void b2_scan(const Ctx& C) {
;     ...
;     B2_LOAD(0, 0);
; #pragma unroll
;     for (int g = 0; g < 8; ++g) {
;         const int cur = g & 1;
;         if (g + 1 < 8) B2_LOAD(g + 1, cur ^ 1);
; #pragma unroll
;         for (int k = 0; k < 4; ++k) {
;             const int c = 4 * g + k;
;             const float dd[8] = {d0[cur][k][0], d0[cur][k][1], d0[cur][k][2], d0[cur][k][3], d1[cur][k][0], d1[cur][k][1], d1[cur][k][2], d1[cur][k][3]};
; #pragma unroll
;             for (int j = 0; j < 2; ++j) {
;                 v4u o; o.x = pk2(run[j][0], run[j][1]); o.y = pk2(run[j][2], run[j][3]); o.z = pk2(run[j][4], run[j][5]); o.w = pk2(run[j][6], run[j][7]);
;                 __builtin_nontemporal_store(o, (v4u*)(base + (size_t)c * cstride + (size_t)j * vstride));
;                 const unsigned lw[4] = {loc[cur][k][j].x, loc[cur][k][j].y, loc[cur][k][j].z, loc[cur][k][j].w};
; #pragma unroll
;                 for (int q = 0; q < 4; ++q) {
;                     run[j][2 * q] = dd[2 * q] * run[j][2 * q] + bf2f(lw[q] & 0xffffu);
;                     run[j][2 * q + 1] = dd[2 * q + 1] * run[j][2 * q + 1] + __uint_as_float(lw[q] & 0xffff0000u);
;                 }
;             }
;         }
;     }
	v_cvt_pk_bf16_f32 v32, v16, v17
	v_cvt_pk_bf16_f32 v33, v18, v19
	v_cvt_pk_bf16_f32 v34, v20, v21
	v_cvt_pk_bf16_f32 v35, v22, v23
	global_store_dwordx4 v2, v[32:35], s[10:11] nt
	v_cvt_pk_bf16_f32 v36, v24, v25
	v_cvt_pk_bf16_f32 v37, v26, v27
	v_cvt_pk_bf16_f32 v38, v28, v29
	v_cvt_pk_bf16_f32 v39, v30, v31
	global_store_dwordx4 v3, v[36:39], s[10:11] nt
	s_add_u32 s10, s10, 0x40000
	s_addc_u32 s11, s11, 0
	v_lshlrev_b32_e32 v48, 16, v128
	v_and_b32_e32 v49, 0xffff0000, v128
	v_fma_f32 v16, v136, v16, v48
	v_fma_f32 v17, v137, v17, v49
	v_lshlrev_b32_e32 v48, 16, v129
	v_and_b32_e32 v49, 0xffff0000, v129
	v_fma_f32 v18, v138, v18, v48
	v_fma_f32 v19, v139, v19, v49
	v_lshlrev_b32_e32 v48, 16, v130
	v_and_b32_e32 v49, 0xffff0000, v130
	v_fma_f32 v20, v140, v20, v48
	v_fma_f32 v21, v141, v21, v49
	v_lshlrev_b32_e32 v48, 16, v131
	v_and_b32_e32 v49, 0xffff0000, v131
	v_fma_f32 v22, v142, v22, v48
	v_fma_f32 v23, v143, v23, v49
	v_lshlrev_b32_e32 v48, 16, v132
	v_and_b32_e32 v49, 0xffff0000, v132
	v_fma_f32 v24, v136, v24, v48
	v_fma_f32 v25, v137, v25, v49
	v_lshlrev_b32_e32 v48, 16, v133
	v_and_b32_e32 v49, 0xffff0000, v133
	v_fma_f32 v26, v138, v26, v48
	v_fma_f32 v27, v139, v27, v49
	v_lshlrev_b32_e32 v48, 16, v134
	v_and_b32_e32 v49, 0xffff0000, v134
	v_fma_f32 v28, v140, v28, v48
	v_fma_f32 v29, v141, v29, v49
	v_lshlrev_b32_e32 v48, 16, v135
	v_and_b32_e32 v49, 0xffff0000, v135
	v_fma_f32 v30, v142, v30, v48
	v_fma_f32 v31, v143, v31, v49
	global_load_dwordx4 v[128:131], v2, s[6:7] nt
	global_load_dwordx4 v[132:135], v3, s[6:7] nt
	global_load_dwordx4 v[136:139], v5, s[12:13]
	global_load_dwordx4 v[140:143], v5, s[12:13] offset:16
	s_add_u32 s6, s6, 0x40000
	s_addc_u32 s7, s7, 0
	s_add_u32 s12, s12, 2048
	s_addc_u32 s13, s13, 0
	s_waitcnt vmcnt(38)
	v_cvt_pk_bf16_f32 v40, v16, v17
	v_cvt_pk_bf16_f32 v41, v18, v19
	v_cvt_pk_bf16_f32 v42, v20, v21
	v_cvt_pk_bf16_f32 v43, v22, v23
	global_store_dwordx4 v2, v[40:43], s[10:11] nt
	v_cvt_pk_bf16_f32 v44, v24, v25
	v_cvt_pk_bf16_f32 v45, v26, v27
	v_cvt_pk_bf16_f32 v46, v28, v29
	v_cvt_pk_bf16_f32 v47, v30, v31
	global_store_dwordx4 v3, v[44:47], s[10:11] nt
	s_add_u32 s10, s10, 0x40000
	s_addc_u32 s11, s11, 0
	v_lshlrev_b32_e32 v48, 16, v144
	v_and_b32_e32 v49, 0xffff0000, v144
	v_fma_f32 v16, v152, v16, v48
	v_fma_f32 v17, v153, v17, v49
	v_lshlrev_b32_e32 v48, 16, v145
	v_and_b32_e32 v49, 0xffff0000, v145
	v_fma_f32 v18, v154, v18, v48
	v_fma_f32 v19, v155, v19, v49
	v_lshlrev_b32_e32 v48, 16, v146
	v_and_b32_e32 v49, 0xffff0000, v146
	v_fma_f32 v20, v156, v20, v48
	v_fma_f32 v21, v157, v21, v49
	v_lshlrev_b32_e32 v48, 16, v147
	v_and_b32_e32 v49, 0xffff0000, v147
	v_fma_f32 v22, v158, v22, v48
	v_fma_f32 v23, v159, v23, v49
	v_lshlrev_b32_e32 v48, 16, v148
	v_and_b32_e32 v49, 0xffff0000, v148
	v_fma_f32 v24, v152, v24, v48
	v_fma_f32 v25, v153, v25, v49
	v_lshlrev_b32_e32 v48, 16, v149
	v_and_b32_e32 v49, 0xffff0000, v149
	v_fma_f32 v26, v154, v26, v48
	v_fma_f32 v27, v155, v27, v49
	v_lshlrev_b32_e32 v48, 16, v150
	v_and_b32_e32 v49, 0xffff0000, v150
	v_fma_f32 v28, v156, v28, v48
	v_fma_f32 v29, v157, v29, v49
	v_lshlrev_b32_e32 v48, 16, v151
	v_and_b32_e32 v49, 0xffff0000, v151
	v_fma_f32 v30, v158, v30, v48
	v_fma_f32 v31, v159, v31, v49
	global_load_dwordx4 v[144:147], v2, s[6:7] nt
	global_load_dwordx4 v[148:151], v3, s[6:7] nt
	global_load_dwordx4 v[152:155], v5, s[12:13]
	global_load_dwordx4 v[156:159], v5, s[12:13] offset:16
	s_add_u32 s6, s6, 0x40000
	s_addc_u32 s7, s7, 0
	s_add_u32 s12, s12, 2048
	s_addc_u32 s13, s13, 0
	s_waitcnt vmcnt(40)
	v_cvt_pk_bf16_f32 v32, v16, v17
	v_cvt_pk_bf16_f32 v33, v18, v19
	v_cvt_pk_bf16_f32 v34, v20, v21
	v_cvt_pk_bf16_f32 v35, v22, v23
	global_store_dwordx4 v2, v[32:35], s[10:11] nt
	v_cvt_pk_bf16_f32 v36, v24, v25
	v_cvt_pk_bf16_f32 v37, v26, v27
	v_cvt_pk_bf16_f32 v38, v28, v29
	v_cvt_pk_bf16_f32 v39, v30, v31
	global_store_dwordx4 v3, v[36:39], s[10:11] nt
	s_add_u32 s10, s10, 0x40000
	s_addc_u32 s11, s11, 0
	v_lshlrev_b32_e32 v48, 16, v160
	v_and_b32_e32 v49, 0xffff0000, v160
	v_fma_f32 v16, v168, v16, v48
	v_fma_f32 v17, v169, v17, v49
	v_lshlrev_b32_e32 v48, 16, v161
	v_and_b32_e32 v49, 0xffff0000, v161
	v_fma_f32 v18, v170, v18, v48
	v_fma_f32 v19, v171, v19, v49
	v_lshlrev_b32_e32 v48, 16, v162
	v_and_b32_e32 v49, 0xffff0000, v162
	v_fma_f32 v20, v172, v20, v48
	v_fma_f32 v21, v173, v21, v49
	v_lshlrev_b32_e32 v48, 16, v163
	v_and_b32_e32 v49, 0xffff0000, v163
	v_fma_f32 v22, v174, v22, v48
	v_fma_f32 v23, v175, v23, v49
	v_lshlrev_b32_e32 v48, 16, v164
	v_and_b32_e32 v49, 0xffff0000, v164
	v_fma_f32 v24, v168, v24, v48
	v_fma_f32 v25, v169, v25, v49
	v_lshlrev_b32_e32 v48, 16, v165
	v_and_b32_e32 v49, 0xffff0000, v165
	v_fma_f32 v26, v170, v26, v48
	v_fma_f32 v27, v171, v27, v49
	v_lshlrev_b32_e32 v48, 16, v166
	v_and_b32_e32 v49, 0xffff0000, v166
	v_fma_f32 v28, v172, v28, v48
	v_fma_f32 v29, v173, v29, v49
	v_lshlrev_b32_e32 v48, 16, v167
	v_and_b32_e32 v49, 0xffff0000, v167
	v_fma_f32 v30, v174, v30, v48
	v_fma_f32 v31, v175, v31, v49
	global_load_dwordx4 v[160:163], v2, s[6:7] nt
	global_load_dwordx4 v[164:167], v3, s[6:7] nt
	global_load_dwordx4 v[168:171], v5, s[12:13]
	global_load_dwordx4 v[172:175], v5, s[12:13] offset:16
	s_add_u32 s6, s6, 0x40000
	s_addc_u32 s7, s7, 0
	s_add_u32 s12, s12, 2048
	s_addc_u32 s13, s13, 0
	s_waitcnt vmcnt(42)
; __device__ __forceinline__ float bf2f(unsigned h) { return __uint_as_float(h << 16); }
; __device__ __forceinline__ unsigned pk2(float lo, float hi) { return pg8::cvt_pk_bf16(lo, hi); }
; __device__ __forceinline__ void b2_scan(const Ctx& C) {
;     ...
;     B2_LOAD(0, 0);
; #pragma unroll
;     for (int g = 0; g < 8; ++g) {
;         const int cur = g & 1;
;         if (g + 1 < 8) B2_LOAD(g + 1, cur ^ 1);
; #pragma unroll
;         for (int k = 0; k < 4; ++k) {
;             const int c = 4 * g + k;
;             const float dd[8] = {d0[cur][k][0], d0[cur][k][1], d0[cur][k][2], d0[cur][k][3], d1[cur][k][0], d1[cur][k][1], d1[cur][k][2], d1[cur][k][3]};
; #pragma unroll
;             for (int j = 0; j < 2; ++j) {
;                 v4u o; o.x = pk2(run[j][0], run[j][1]); o.y = pk2(run[j][2], run[j][3]); o.z = pk2(run[j][4], run[j][5]); o.w = pk2(run[j][6], run[j][7]);
;                 __builtin_nontemporal_store(o, (v4u*)(base + (size_t)c * cstride + (size_t)j * vstride));
;                 const unsigned lw[4] = {loc[cur][k][j].x, loc[cur][k][j].y, loc[cur][k][j].z, loc[cur][k][j].w};
; #pragma unroll
;                 for (int q = 0; q < 4; ++q) {
;                     run[j][2 * q] = dd[2 * q] * run[j][2 * q] + bf2f(lw[q] & 0xffffu);
;                     run[j][2 * q + 1] = dd[2 * q + 1] * run[j][2 * q + 1] + __uint_as_float(lw[q] & 0xffff0000u);
;                 }
;             }
;         }
;     }
	v_cvt_pk_bf16_f32 v40, v16, v17
	v_cvt_pk_bf16_f32 v41, v18, v19
	v_cvt_pk_bf16_f32 v42, v20, v21
	v_cvt_pk_bf16_f32 v43, v22, v23
	global_store_dwordx4 v2, v[40:43], s[10:11] nt
	v_cvt_pk_bf16_f32 v44, v24, v25
	v_cvt_pk_bf16_f32 v45, v26, v27
	v_cvt_pk_bf16_f32 v46, v28, v29
	v_cvt_pk_bf16_f32 v47, v30, v31
	global_store_dwordx4 v3, v[44:47], s[10:11] nt
	s_add_u32 s10, s10, 0x40000
	s_addc_u32 s11, s11, 0
	v_lshlrev_b32_e32 v48, 16, v176
	v_and_b32_e32 v49, 0xffff0000, v176
	v_fma_f32 v16, v184, v16, v48
	v_fma_f32 v17, v185, v17, v49
	v_lshlrev_b32_e32 v48, 16, v177
	v_and_b32_e32 v49, 0xffff0000, v177
	v_fma_f32 v18, v186, v18, v48
	v_fma_f32 v19, v187, v19, v49
	v_lshlrev_b32_e32 v48, 16, v178
	v_and_b32_e32 v49, 0xffff0000, v178
	v_fma_f32 v20, v188, v20, v48
	v_fma_f32 v21, v189, v21, v49
	v_lshlrev_b32_e32 v48, 16, v179
	v_and_b32_e32 v49, 0xffff0000, v179
	v_fma_f32 v22, v190, v22, v48
	v_fma_f32 v23, v191, v23, v49
	v_lshlrev_b32_e32 v48, 16, v180
	v_and_b32_e32 v49, 0xffff0000, v180
	v_fma_f32 v24, v184, v24, v48
	v_fma_f32 v25, v185, v25, v49
	v_lshlrev_b32_e32 v48, 16, v181
	v_and_b32_e32 v49, 0xffff0000, v181
	v_fma_f32 v26, v186, v26, v48
	v_fma_f32 v27, v187, v27, v49
	v_lshlrev_b32_e32 v48, 16, v182
	v_and_b32_e32 v49, 0xffff0000, v182
	v_fma_f32 v28, v188, v28, v48
	v_fma_f32 v29, v189, v29, v49
	v_lshlrev_b32_e32 v48, 16, v183
	v_and_b32_e32 v49, 0xffff0000, v183
	v_fma_f32 v30, v190, v30, v48
	v_fma_f32 v31, v191, v31, v49
	global_load_dwordx4 v[176:179], v2, s[6:7] nt
	global_load_dwordx4 v[180:183], v3, s[6:7] nt
	global_load_dwordx4 v[184:187], v5, s[12:13]
	global_load_dwordx4 v[188:191], v5, s[12:13] offset:16
	s_add_u32 s6, s6, 0x40000
	s_addc_u32 s7, s7, 0
	s_add_u32 s12, s12, 2048
	s_addc_u32 s13, s13, 0
	s_waitcnt vmcnt(42)
	v_cvt_pk_bf16_f32 v32, v16, v17
	v_cvt_pk_bf16_f32 v33, v18, v19
	v_cvt_pk_bf16_f32 v34, v20, v21
	v_cvt_pk_bf16_f32 v35, v22, v23
	global_store_dwordx4 v2, v[32:35], s[10:11] nt
	v_cvt_pk_bf16_f32 v36, v24, v25
	v_cvt_pk_bf16_f32 v37, v26, v27
	v_cvt_pk_bf16_f32 v38, v28, v29
	v_cvt_pk_bf16_f32 v39, v30, v31
	global_store_dwordx4 v3, v[36:39], s[10:11] nt
	s_add_u32 s10, s10, 0x40000
	s_addc_u32 s11, s11, 0
	v_lshlrev_b32_e32 v48, 16, v64
	v_and_b32_e32 v49, 0xffff0000, v64
	v_fma_f32 v16, v72, v16, v48
	v_fma_f32 v17, v73, v17, v49
	v_lshlrev_b32_e32 v48, 16, v65
	v_and_b32_e32 v49, 0xffff0000, v65
	v_fma_f32 v18, v74, v18, v48
	v_fma_f32 v19, v75, v19, v49
	v_lshlrev_b32_e32 v48, 16, v66
	v_and_b32_e32 v49, 0xffff0000, v66
	v_fma_f32 v20, v76, v20, v48
	v_fma_f32 v21, v77, v21, v49
	v_lshlrev_b32_e32 v48, 16, v67
	v_and_b32_e32 v49, 0xffff0000, v67
	v_fma_f32 v22, v78, v22, v48
	v_fma_f32 v23, v79, v23, v49
	v_lshlrev_b32_e32 v48, 16, v68
	v_and_b32_e32 v49, 0xffff0000, v68
	v_fma_f32 v24, v72, v24, v48
	v_fma_f32 v25, v73, v25, v49
	v_lshlrev_b32_e32 v48, 16, v69
	v_and_b32_e32 v49, 0xffff0000, v69
	v_fma_f32 v26, v74, v26, v48
	v_fma_f32 v27, v75, v27, v49
	v_lshlrev_b32_e32 v48, 16, v70
	v_and_b32_e32 v49, 0xffff0000, v70
	v_fma_f32 v28, v76, v28, v48
	v_fma_f32 v29, v77, v29, v49
	v_lshlrev_b32_e32 v48, 16, v71
	v_and_b32_e32 v49, 0xffff0000, v71
	v_fma_f32 v30, v78, v30, v48
	v_fma_f32 v31, v79, v31, v49
	global_load_dwordx4 v[64:67], v2, s[6:7] nt
	global_load_dwordx4 v[68:71], v3, s[6:7] nt
	global_load_dwordx4 v[72:75], v5, s[12:13]
	global_load_dwordx4 v[76:79], v5, s[12:13] offset:16
	s_add_u32 s6, s6, 0x40000
	s_addc_u32 s7, s7, 0
	s_add_u32 s12, s12, 2048
	s_addc_u32 s13, s13, 0
	s_waitcnt vmcnt(42)
	v_cvt_pk_bf16_f32 v40, v16, v17
	v_cvt_pk_bf16_f32 v41, v18, v19
	v_cvt_pk_bf16_f32 v42, v20, v21
	v_cvt_pk_bf16_f32 v43, v22, v23
	global_store_dwordx4 v2, v[40:43], s[10:11] nt
	v_cvt_pk_bf16_f32 v44, v24, v25
	v_cvt_pk_bf16_f32 v45, v26, v27
	v_cvt_pk_bf16_f32 v46, v28, v29
	v_cvt_pk_bf16_f32 v47, v30, v31
	global_store_dwordx4 v3, v[44:47], s[10:11] nt
	s_add_u32 s10, s10, 0x40000
	s_addc_u32 s11, s11, 0
	v_lshlrev_b32_e32 v48, 16, v80
	v_and_b32_e32 v49, 0xffff0000, v80
	v_fma_f32 v16, v88, v16, v48
	v_fma_f32 v17, v89, v17, v49
	v_lshlrev_b32_e32 v48, 16, v81
	v_and_b32_e32 v49, 0xffff0000, v81
	v_fma_f32 v18, v90, v18, v48
	v_fma_f32 v19, v91, v19, v49
	v_lshlrev_b32_e32 v48, 16, v82
	v_and_b32_e32 v49, 0xffff0000, v82
	v_fma_f32 v20, v92, v20, v48
	v_fma_f32 v21, v93, v21, v49
	v_lshlrev_b32_e32 v48, 16, v83
	v_and_b32_e32 v49, 0xffff0000, v83
	v_fma_f32 v22, v94, v22, v48
	v_fma_f32 v23, v95, v23, v49
	v_lshlrev_b32_e32 v48, 16, v84
	v_and_b32_e32 v49, 0xffff0000, v84
	v_fma_f32 v24, v88, v24, v48
	v_fma_f32 v25, v89, v25, v49
	v_lshlrev_b32_e32 v48, 16, v85
	v_and_b32_e32 v49, 0xffff0000, v85
	v_fma_f32 v26, v90, v26, v48
	v_fma_f32 v27, v91, v27, v49
	v_lshlrev_b32_e32 v48, 16, v86
	v_and_b32_e32 v49, 0xffff0000, v86
	v_fma_f32 v28, v92, v28, v48
	v_fma_f32 v29, v93, v29, v49
	v_lshlrev_b32_e32 v48, 16, v87
	v_and_b32_e32 v49, 0xffff0000, v87
	v_fma_f32 v30, v94, v30, v48
	v_fma_f32 v31, v95, v31, v49
	global_load_dwordx4 v[80:83], v2, s[6:7] nt
	global_load_dwordx4 v[84:87], v3, s[6:7] nt
	global_load_dwordx4 v[88:91], v5, s[12:13]
	global_load_dwordx4 v[92:95], v5, s[12:13] offset:16
	s_add_u32 s6, s6, 0x40000
	s_addc_u32 s7, s7, 0
	s_add_u32 s12, s12, 2048
	s_addc_u32 s13, s13, 0
	s_waitcnt vmcnt(42)
; __device__ __forceinline__ float bf2f(unsigned h) { return __uint_as_float(h << 16); }
; __device__ __forceinline__ unsigned pk2(float lo, float hi) { return pg8::cvt_pk_bf16(lo, hi); }
; __device__ __forceinline__ void b2_scan(const Ctx& C) {
;     ...
;     B2_LOAD(0, 0);
; #pragma unroll
;     for (int g = 0; g < 8; ++g) {
;         const int cur = g & 1;
;         if (g + 1 < 8) B2_LOAD(g + 1, cur ^ 1);
; #pragma unroll
;         for (int k = 0; k < 4; ++k) {
;             const int c = 4 * g + k;
;             const float dd[8] = {d0[cur][k][0], d0[cur][k][1], d0[cur][k][2], d0[cur][k][3], d1[cur][k][0], d1[cur][k][1], d1[cur][k][2], d1[cur][k][3]};
; #pragma unroll
;             for (int j = 0; j < 2; ++j) {
;                 v4u o; o.x = pk2(run[j][0], run[j][1]); o.y = pk2(run[j][2], run[j][3]); o.z = pk2(run[j][4], run[j][5]); o.w = pk2(run[j][6], run[j][7]);
;                 __builtin_nontemporal_store(o, (v4u*)(base + (size_t)c * cstride + (size_t)j * vstride));
;                 const unsigned lw[4] = {loc[cur][k][j].x, loc[cur][k][j].y, loc[cur][k][j].z, loc[cur][k][j].w};
; #pragma unroll
;                 for (int q = 0; q < 4; ++q) {
;                     run[j][2 * q] = dd[2 * q] * run[j][2 * q] + bf2f(lw[q] & 0xffffu);
;                     run[j][2 * q + 1] = dd[2 * q + 1] * run[j][2 * q + 1] + __uint_as_float(lw[q] & 0xffff0000u);
;                 }
;             }
;         }
;     }
	v_cvt_pk_bf16_f32 v32, v16, v17
	v_cvt_pk_bf16_f32 v33, v18, v19
	v_cvt_pk_bf16_f32 v34, v20, v21
	v_cvt_pk_bf16_f32 v35, v22, v23
	global_store_dwordx4 v2, v[32:35], s[10:11] nt
	v_cvt_pk_bf16_f32 v36, v24, v25
	v_cvt_pk_bf16_f32 v37, v26, v27
	v_cvt_pk_bf16_f32 v38, v28, v29
	v_cvt_pk_bf16_f32 v39, v30, v31
	global_store_dwordx4 v3, v[36:39], s[10:11] nt
	s_add_u32 s10, s10, 0x40000
	s_addc_u32 s11, s11, 0
	v_lshlrev_b32_e32 v48, 16, v96
	v_and_b32_e32 v49, 0xffff0000, v96
	v_fma_f32 v16, v104, v16, v48
	v_fma_f32 v17, v105, v17, v49
	v_lshlrev_b32_e32 v48, 16, v97
	v_and_b32_e32 v49, 0xffff0000, v97
	v_fma_f32 v18, v106, v18, v48
	v_fma_f32 v19, v107, v19, v49
	v_lshlrev_b32_e32 v48, 16, v98
	v_and_b32_e32 v49, 0xffff0000, v98
	v_fma_f32 v20, v108, v20, v48
	v_fma_f32 v21, v109, v21, v49
	v_lshlrev_b32_e32 v48, 16, v99
	v_and_b32_e32 v49, 0xffff0000, v99
	v_fma_f32 v22, v110, v22, v48
	v_fma_f32 v23, v111, v23, v49
	v_lshlrev_b32_e32 v48, 16, v100
	v_and_b32_e32 v49, 0xffff0000, v100
	v_fma_f32 v24, v104, v24, v48
	v_fma_f32 v25, v105, v25, v49
	v_lshlrev_b32_e32 v48, 16, v101
	v_and_b32_e32 v49, 0xffff0000, v101
	v_fma_f32 v26, v106, v26, v48
	v_fma_f32 v27, v107, v27, v49
	v_lshlrev_b32_e32 v48, 16, v102
	v_and_b32_e32 v49, 0xffff0000, v102
	v_fma_f32 v28, v108, v28, v48
	v_fma_f32 v29, v109, v29, v49
	v_lshlrev_b32_e32 v48, 16, v103
	v_and_b32_e32 v49, 0xffff0000, v103
	v_fma_f32 v30, v110, v30, v48
	v_fma_f32 v31, v111, v31, v49
	global_load_dwordx4 v[96:99], v2, s[6:7] nt
	global_load_dwordx4 v[100:103], v3, s[6:7] nt
	global_load_dwordx4 v[104:107], v5, s[12:13]
	global_load_dwordx4 v[108:111], v5, s[12:13] offset:16
	s_add_u32 s6, s6, 0x40000
	s_addc_u32 s7, s7, 0
	s_add_u32 s12, s12, 2048
	s_addc_u32 s13, s13, 0
	s_waitcnt vmcnt(42)
	v_cvt_pk_bf16_f32 v40, v16, v17
	v_cvt_pk_bf16_f32 v41, v18, v19
	v_cvt_pk_bf16_f32 v42, v20, v21
	v_cvt_pk_bf16_f32 v43, v22, v23
	global_store_dwordx4 v2, v[40:43], s[10:11] nt
	v_cvt_pk_bf16_f32 v44, v24, v25
	v_cvt_pk_bf16_f32 v45, v26, v27
	v_cvt_pk_bf16_f32 v46, v28, v29
	v_cvt_pk_bf16_f32 v47, v30, v31
	global_store_dwordx4 v3, v[44:47], s[10:11] nt
	s_add_u32 s10, s10, 0x40000
	s_addc_u32 s11, s11, 0
	v_lshlrev_b32_e32 v48, 16, v112
	v_and_b32_e32 v49, 0xffff0000, v112
	v_fma_f32 v16, v120, v16, v48
	v_fma_f32 v17, v121, v17, v49
	v_lshlrev_b32_e32 v48, 16, v113
	v_and_b32_e32 v49, 0xffff0000, v113
	v_fma_f32 v18, v122, v18, v48
	v_fma_f32 v19, v123, v19, v49
	v_lshlrev_b32_e32 v48, 16, v114
	v_and_b32_e32 v49, 0xffff0000, v114
	v_fma_f32 v20, v124, v20, v48
	v_fma_f32 v21, v125, v21, v49
	v_lshlrev_b32_e32 v48, 16, v115
	v_and_b32_e32 v49, 0xffff0000, v115
	v_fma_f32 v22, v126, v22, v48
	v_fma_f32 v23, v127, v23, v49
	v_lshlrev_b32_e32 v48, 16, v116
	v_and_b32_e32 v49, 0xffff0000, v116
	v_fma_f32 v24, v120, v24, v48
	v_fma_f32 v25, v121, v25, v49
	v_lshlrev_b32_e32 v48, 16, v117
	v_and_b32_e32 v49, 0xffff0000, v117
	v_fma_f32 v26, v122, v26, v48
	v_fma_f32 v27, v123, v27, v49
	v_lshlrev_b32_e32 v48, 16, v118
	v_and_b32_e32 v49, 0xffff0000, v118
	v_fma_f32 v28, v124, v28, v48
	v_fma_f32 v29, v125, v29, v49
	v_lshlrev_b32_e32 v48, 16, v119
	v_and_b32_e32 v49, 0xffff0000, v119
	v_fma_f32 v30, v126, v30, v48
	v_fma_f32 v31, v127, v31, v49
	global_load_dwordx4 v[112:115], v2, s[6:7] nt
	global_load_dwordx4 v[116:119], v3, s[6:7] nt
	global_load_dwordx4 v[120:123], v5, s[12:13]
	global_load_dwordx4 v[124:127], v5, s[12:13] offset:16
	s_add_u32 s6, s6, 0x40000
	s_addc_u32 s7, s7, 0
	s_add_u32 s12, s12, 2048
	s_addc_u32 s13, s13, 0
	s_waitcnt vmcnt(42)
	v_cvt_pk_bf16_f32 v32, v16, v17
	v_cvt_pk_bf16_f32 v33, v18, v19
	v_cvt_pk_bf16_f32 v34, v20, v21
	v_cvt_pk_bf16_f32 v35, v22, v23
	global_store_dwordx4 v2, v[32:35], s[10:11] nt
	v_cvt_pk_bf16_f32 v36, v24, v25
	v_cvt_pk_bf16_f32 v37, v26, v27
	v_cvt_pk_bf16_f32 v38, v28, v29
	v_cvt_pk_bf16_f32 v39, v30, v31
	global_store_dwordx4 v3, v[36:39], s[10:11] nt
	s_add_u32 s10, s10, 0x40000
	s_addc_u32 s11, s11, 0
	v_lshlrev_b32_e32 v48, 16, v128
	v_and_b32_e32 v49, 0xffff0000, v128
	v_fma_f32 v16, v136, v16, v48
	v_fma_f32 v17, v137, v17, v49
	v_lshlrev_b32_e32 v48, 16, v129
	v_and_b32_e32 v49, 0xffff0000, v129
	v_fma_f32 v18, v138, v18, v48
	v_fma_f32 v19, v139, v19, v49
	v_lshlrev_b32_e32 v48, 16, v130
	v_and_b32_e32 v49, 0xffff0000, v130
	v_fma_f32 v20, v140, v20, v48
	v_fma_f32 v21, v141, v21, v49
	v_lshlrev_b32_e32 v48, 16, v131
	v_and_b32_e32 v49, 0xffff0000, v131
	v_fma_f32 v22, v142, v22, v48
	v_fma_f32 v23, v143, v23, v49
	v_lshlrev_b32_e32 v48, 16, v132
	v_and_b32_e32 v49, 0xffff0000, v132
	v_fma_f32 v24, v136, v24, v48
	v_fma_f32 v25, v137, v25, v49
	v_lshlrev_b32_e32 v48, 16, v133
	v_and_b32_e32 v49, 0xffff0000, v133
	v_fma_f32 v26, v138, v26, v48
	v_fma_f32 v27, v139, v27, v49
	v_lshlrev_b32_e32 v48, 16, v134
	v_and_b32_e32 v49, 0xffff0000, v134
	v_fma_f32 v28, v140, v28, v48
	v_fma_f32 v29, v141, v29, v49
	v_lshlrev_b32_e32 v48, 16, v135
	v_and_b32_e32 v49, 0xffff0000, v135
	v_fma_f32 v30, v142, v30, v48
	v_fma_f32 v31, v143, v31, v49
	global_load_dwordx4 v[128:131], v2, s[6:7] nt
	global_load_dwordx4 v[132:135], v3, s[6:7] nt
	global_load_dwordx4 v[136:139], v5, s[12:13]
	global_load_dwordx4 v[140:143], v5, s[12:13] offset:16
	s_add_u32 s6, s6, 0x40000
	s_addc_u32 s7, s7, 0
	s_add_u32 s12, s12, 2048
	s_addc_u32 s13, s13, 0
	s_waitcnt vmcnt(42)
; __device__ __forceinline__ float bf2f(unsigned h) { return __uint_as_float(h << 16); }
; __device__ __forceinline__ unsigned pk2(float lo, float hi) { return pg8::cvt_pk_bf16(lo, hi); }
; __device__ __forceinline__ void b2_scan(const Ctx& C) {
;     ...
;     B2_LOAD(0, 0);
; #pragma unroll
;     for (int g = 0; g < 8; ++g) {
;         const int cur = g & 1;
;         if (g + 1 < 8) B2_LOAD(g + 1, cur ^ 1);
; #pragma unroll
;         for (int k = 0; k < 4; ++k) {
;             const int c = 4 * g + k;
;             const float dd[8] = {d0[cur][k][0], d0[cur][k][1], d0[cur][k][2], d0[cur][k][3], d1[cur][k][0], d1[cur][k][1], d1[cur][k][2], d1[cur][k][3]};
; #pragma unroll
;             for (int j = 0; j < 2; ++j) {
;                 v4u o; o.x = pk2(run[j][0], run[j][1]); o.y = pk2(run[j][2], run[j][3]); o.z = pk2(run[j][4], run[j][5]); o.w = pk2(run[j][6], run[j][7]);
;                 __builtin_nontemporal_store(o, (v4u*)(base + (size_t)c * cstride + (size_t)j * vstride));
;                 const unsigned lw[4] = {loc[cur][k][j].x, loc[cur][k][j].y, loc[cur][k][j].z, loc[cur][k][j].w};
; #pragma unroll
;                 for (int q = 0; q < 4; ++q) {
;                     run[j][2 * q] = dd[2 * q] * run[j][2 * q] + bf2f(lw[q] & 0xffffu);
;                     run[j][2 * q + 1] = dd[2 * q + 1] * run[j][2 * q + 1] + __uint_as_float(lw[q] & 0xffff0000u);
;                 }
;             }
;         }
;     }
	v_cvt_pk_bf16_f32 v40, v16, v17
	v_cvt_pk_bf16_f32 v41, v18, v19
	v_cvt_pk_bf16_f32 v42, v20, v21
	v_cvt_pk_bf16_f32 v43, v22, v23
	global_store_dwordx4 v2, v[40:43], s[10:11] nt
	v_cvt_pk_bf16_f32 v44, v24, v25
	v_cvt_pk_bf16_f32 v45, v26, v27
	v_cvt_pk_bf16_f32 v46, v28, v29
	v_cvt_pk_bf16_f32 v47, v30, v31
	global_store_dwordx4 v3, v[44:47], s[10:11] nt
	s_add_u32 s10, s10, 0x40000
	s_addc_u32 s11, s11, 0
	v_lshlrev_b32_e32 v48, 16, v144
	v_and_b32_e32 v49, 0xffff0000, v144
	v_fma_f32 v16, v152, v16, v48
	v_fma_f32 v17, v153, v17, v49
	v_lshlrev_b32_e32 v48, 16, v145
	v_and_b32_e32 v49, 0xffff0000, v145
	v_fma_f32 v18, v154, v18, v48
	v_fma_f32 v19, v155, v19, v49
	v_lshlrev_b32_e32 v48, 16, v146
	v_and_b32_e32 v49, 0xffff0000, v146
	v_fma_f32 v20, v156, v20, v48
	v_fma_f32 v21, v157, v21, v49
	v_lshlrev_b32_e32 v48, 16, v147
	v_and_b32_e32 v49, 0xffff0000, v147
	v_fma_f32 v22, v158, v22, v48
	v_fma_f32 v23, v159, v23, v49
	v_lshlrev_b32_e32 v48, 16, v148
	v_and_b32_e32 v49, 0xffff0000, v148
	v_fma_f32 v24, v152, v24, v48
	v_fma_f32 v25, v153, v25, v49
	v_lshlrev_b32_e32 v48, 16, v149
	v_and_b32_e32 v49, 0xffff0000, v149
	v_fma_f32 v26, v154, v26, v48
	v_fma_f32 v27, v155, v27, v49
	v_lshlrev_b32_e32 v48, 16, v150
	v_and_b32_e32 v49, 0xffff0000, v150
	v_fma_f32 v28, v156, v28, v48
	v_fma_f32 v29, v157, v29, v49
	v_lshlrev_b32_e32 v48, 16, v151
	v_and_b32_e32 v49, 0xffff0000, v151
	v_fma_f32 v30, v158, v30, v48
	v_fma_f32 v31, v159, v31, v49
	global_load_dwordx4 v[144:147], v2, s[6:7] nt
	global_load_dwordx4 v[148:151], v3, s[6:7] nt
	global_load_dwordx4 v[152:155], v5, s[12:13]
	global_load_dwordx4 v[156:159], v5, s[12:13] offset:16
	s_add_u32 s6, s6, 0x40000
	s_addc_u32 s7, s7, 0
	s_add_u32 s12, s12, 2048
	s_addc_u32 s13, s13, 0
	s_waitcnt vmcnt(42)
	v_cvt_pk_bf16_f32 v32, v16, v17
	v_cvt_pk_bf16_f32 v33, v18, v19
	v_cvt_pk_bf16_f32 v34, v20, v21
	v_cvt_pk_bf16_f32 v35, v22, v23
	global_store_dwordx4 v2, v[32:35], s[10:11] nt
	v_cvt_pk_bf16_f32 v36, v24, v25
	v_cvt_pk_bf16_f32 v37, v26, v27
	v_cvt_pk_bf16_f32 v38, v28, v29
	v_cvt_pk_bf16_f32 v39, v30, v31
	global_store_dwordx4 v3, v[36:39], s[10:11] nt
	s_add_u32 s10, s10, 0x40000
	s_addc_u32 s11, s11, 0
	v_lshlrev_b32_e32 v48, 16, v160
	v_and_b32_e32 v49, 0xffff0000, v160
	v_fma_f32 v16, v168, v16, v48
	v_fma_f32 v17, v169, v17, v49
	v_lshlrev_b32_e32 v48, 16, v161
	v_and_b32_e32 v49, 0xffff0000, v161
	v_fma_f32 v18, v170, v18, v48
	v_fma_f32 v19, v171, v19, v49
	v_lshlrev_b32_e32 v48, 16, v162
	v_and_b32_e32 v49, 0xffff0000, v162
	v_fma_f32 v20, v172, v20, v48
	v_fma_f32 v21, v173, v21, v49
	v_lshlrev_b32_e32 v48, 16, v163
	v_and_b32_e32 v49, 0xffff0000, v163
	v_fma_f32 v22, v174, v22, v48
	v_fma_f32 v23, v175, v23, v49
	v_lshlrev_b32_e32 v48, 16, v164
	v_and_b32_e32 v49, 0xffff0000, v164
	v_fma_f32 v24, v168, v24, v48
	v_fma_f32 v25, v169, v25, v49
	v_lshlrev_b32_e32 v48, 16, v165
	v_and_b32_e32 v49, 0xffff0000, v165
	v_fma_f32 v26, v170, v26, v48
	v_fma_f32 v27, v171, v27, v49
	v_lshlrev_b32_e32 v48, 16, v166
	v_and_b32_e32 v49, 0xffff0000, v166
	v_fma_f32 v28, v172, v28, v48
	v_fma_f32 v29, v173, v29, v49
	v_lshlrev_b32_e32 v48, 16, v167
	v_and_b32_e32 v49, 0xffff0000, v167
	v_fma_f32 v30, v174, v30, v48
	v_fma_f32 v31, v175, v31, v49
	global_load_dwordx4 v[160:163], v2, s[6:7] nt
	global_load_dwordx4 v[164:167], v3, s[6:7] nt
	global_load_dwordx4 v[168:171], v5, s[12:13]
	global_load_dwordx4 v[172:175], v5, s[12:13] offset:16
	s_add_u32 s6, s6, 0x40000
	s_addc_u32 s7, s7, 0
	s_add_u32 s12, s12, 2048
	s_addc_u32 s13, s13, 0
	s_waitcnt vmcnt(42)
	v_cvt_pk_bf16_f32 v40, v16, v17
	v_cvt_pk_bf16_f32 v41, v18, v19
	v_cvt_pk_bf16_f32 v42, v20, v21
	v_cvt_pk_bf16_f32 v43, v22, v23
	global_store_dwordx4 v2, v[40:43], s[10:11] nt
	v_cvt_pk_bf16_f32 v44, v24, v25
	v_cvt_pk_bf16_f32 v45, v26, v27
	v_cvt_pk_bf16_f32 v46, v28, v29
	v_cvt_pk_bf16_f32 v47, v30, v31
	global_store_dwordx4 v3, v[44:47], s[10:11] nt
	s_add_u32 s10, s10, 0x40000
	s_addc_u32 s11, s11, 0
	v_lshlrev_b32_e32 v48, 16, v176
	v_and_b32_e32 v49, 0xffff0000, v176
	v_fma_f32 v16, v184, v16, v48
	v_fma_f32 v17, v185, v17, v49
	v_lshlrev_b32_e32 v48, 16, v177
	v_and_b32_e32 v49, 0xffff0000, v177
	v_fma_f32 v18, v186, v18, v48
	v_fma_f32 v19, v187, v19, v49
	v_lshlrev_b32_e32 v48, 16, v178
	v_and_b32_e32 v49, 0xffff0000, v178
	v_fma_f32 v20, v188, v20, v48
	v_fma_f32 v21, v189, v21, v49
	v_lshlrev_b32_e32 v48, 16, v179
	v_and_b32_e32 v49, 0xffff0000, v179
	v_fma_f32 v22, v190, v22, v48
	v_fma_f32 v23, v191, v23, v49
	v_lshlrev_b32_e32 v48, 16, v180
	v_and_b32_e32 v49, 0xffff0000, v180
	v_fma_f32 v24, v184, v24, v48
	v_fma_f32 v25, v185, v25, v49
	v_lshlrev_b32_e32 v48, 16, v181
	v_and_b32_e32 v49, 0xffff0000, v181
	v_fma_f32 v26, v186, v26, v48
	v_fma_f32 v27, v187, v27, v49
	v_lshlrev_b32_e32 v48, 16, v182
	v_and_b32_e32 v49, 0xffff0000, v182
	v_fma_f32 v28, v188, v28, v48
	v_fma_f32 v29, v189, v29, v49
	v_lshlrev_b32_e32 v48, 16, v183
	v_and_b32_e32 v49, 0xffff0000, v183
	v_fma_f32 v30, v190, v30, v48
	v_fma_f32 v31, v191, v31, v49
	global_load_dwordx4 v[176:179], v2, s[6:7] nt
	global_load_dwordx4 v[180:183], v3, s[6:7] nt
	global_load_dwordx4 v[184:187], v5, s[12:13]
	global_load_dwordx4 v[188:191], v5, s[12:13] offset:16
	s_add_u32 s6, s6, 0x40000
	s_addc_u32 s7, s7, 0
	s_add_u32 s12, s12, 2048
	s_addc_u32 s13, s13, 0
	s_waitcnt vmcnt(42)
; __device__ __forceinline__ float bf2f(unsigned h) { return __uint_as_float(h << 16); }
; __device__ __forceinline__ unsigned pk2(float lo, float hi) { return pg8::cvt_pk_bf16(lo, hi); }
; __device__ __forceinline__ void b2_scan(const Ctx& C) {
;     ...
;     B2_LOAD(0, 0);
; #pragma unroll
;     for (int g = 0; g < 8; ++g) {
;         const int cur = g & 1;
;         if (g + 1 < 8) B2_LOAD(g + 1, cur ^ 1);
; #pragma unroll
;         for (int k = 0; k < 4; ++k) {
;             const int c = 4 * g + k;
;             const float dd[8] = {d0[cur][k][0], d0[cur][k][1], d0[cur][k][2], d0[cur][k][3], d1[cur][k][0], d1[cur][k][1], d1[cur][k][2], d1[cur][k][3]};
; #pragma unroll
;             for (int j = 0; j < 2; ++j) {
;                 v4u o; o.x = pk2(run[j][0], run[j][1]); o.y = pk2(run[j][2], run[j][3]); o.z = pk2(run[j][4], run[j][5]); o.w = pk2(run[j][6], run[j][7]);
;                 __builtin_nontemporal_store(o, (v4u*)(base + (size_t)c * cstride + (size_t)j * vstride));
;                 const unsigned lw[4] = {loc[cur][k][j].x, loc[cur][k][j].y, loc[cur][k][j].z, loc[cur][k][j].w};
; #pragma unroll
;                 for (int q = 0; q < 4; ++q) {
;                     run[j][2 * q] = dd[2 * q] * run[j][2 * q] + bf2f(lw[q] & 0xffffu);
;                     run[j][2 * q + 1] = dd[2 * q + 1] * run[j][2 * q + 1] + __uint_as_float(lw[q] & 0xffff0000u);
;                 }
;             }
;         }
;     }
	v_cvt_pk_bf16_f32 v32, v16, v17
	v_cvt_pk_bf16_f32 v33, v18, v19
	v_cvt_pk_bf16_f32 v34, v20, v21
	v_cvt_pk_bf16_f32 v35, v22, v23
	global_store_dwordx4 v2, v[32:35], s[10:11] nt
	v_cvt_pk_bf16_f32 v36, v24, v25
	v_cvt_pk_bf16_f32 v37, v26, v27
	v_cvt_pk_bf16_f32 v38, v28, v29
	v_cvt_pk_bf16_f32 v39, v30, v31
	global_store_dwordx4 v3, v[36:39], s[10:11] nt
	s_add_u32 s10, s10, 0x40000
	s_addc_u32 s11, s11, 0
	v_lshlrev_b32_e32 v48, 16, v64
	v_and_b32_e32 v49, 0xffff0000, v64
	v_fma_f32 v16, v72, v16, v48
	v_fma_f32 v17, v73, v17, v49
	v_lshlrev_b32_e32 v48, 16, v65
	v_and_b32_e32 v49, 0xffff0000, v65
	v_fma_f32 v18, v74, v18, v48
	v_fma_f32 v19, v75, v19, v49
	v_lshlrev_b32_e32 v48, 16, v66
	v_and_b32_e32 v49, 0xffff0000, v66
	v_fma_f32 v20, v76, v20, v48
	v_fma_f32 v21, v77, v21, v49
	v_lshlrev_b32_e32 v48, 16, v67
	v_and_b32_e32 v49, 0xffff0000, v67
	v_fma_f32 v22, v78, v22, v48
	v_fma_f32 v23, v79, v23, v49
	v_lshlrev_b32_e32 v48, 16, v68
	v_and_b32_e32 v49, 0xffff0000, v68
	v_fma_f32 v24, v72, v24, v48
	v_fma_f32 v25, v73, v25, v49
	v_lshlrev_b32_e32 v48, 16, v69
	v_and_b32_e32 v49, 0xffff0000, v69
	v_fma_f32 v26, v74, v26, v48
	v_fma_f32 v27, v75, v27, v49
	v_lshlrev_b32_e32 v48, 16, v70
	v_and_b32_e32 v49, 0xffff0000, v70
	v_fma_f32 v28, v76, v28, v48
	v_fma_f32 v29, v77, v29, v49
	v_lshlrev_b32_e32 v48, 16, v71
	v_and_b32_e32 v49, 0xffff0000, v71
	v_fma_f32 v30, v78, v30, v48
	v_fma_f32 v31, v79, v31, v49
	global_load_dwordx4 v[64:67], v2, s[6:7] nt
	global_load_dwordx4 v[68:71], v3, s[6:7] nt
	global_load_dwordx4 v[72:75], v5, s[12:13]
	global_load_dwordx4 v[76:79], v5, s[12:13] offset:16
	s_add_u32 s6, s6, 0x40000
	s_addc_u32 s7, s7, 0
	s_add_u32 s12, s12, 2048
	s_addc_u32 s13, s13, 0
	s_waitcnt vmcnt(42)
	v_cvt_pk_bf16_f32 v40, v16, v17
	v_cvt_pk_bf16_f32 v41, v18, v19
	v_cvt_pk_bf16_f32 v42, v20, v21
	v_cvt_pk_bf16_f32 v43, v22, v23
	global_store_dwordx4 v2, v[40:43], s[10:11] nt
	v_cvt_pk_bf16_f32 v44, v24, v25
	v_cvt_pk_bf16_f32 v45, v26, v27
	v_cvt_pk_bf16_f32 v46, v28, v29
	v_cvt_pk_bf16_f32 v47, v30, v31
	global_store_dwordx4 v3, v[44:47], s[10:11] nt
	s_add_u32 s10, s10, 0x40000
	s_addc_u32 s11, s11, 0
	v_lshlrev_b32_e32 v48, 16, v80
	v_and_b32_e32 v49, 0xffff0000, v80
	v_fma_f32 v16, v88, v16, v48
	v_fma_f32 v17, v89, v17, v49
	v_lshlrev_b32_e32 v48, 16, v81
	v_and_b32_e32 v49, 0xffff0000, v81
	v_fma_f32 v18, v90, v18, v48
	v_fma_f32 v19, v91, v19, v49
	v_lshlrev_b32_e32 v48, 16, v82
	v_and_b32_e32 v49, 0xffff0000, v82
	v_fma_f32 v20, v92, v20, v48
	v_fma_f32 v21, v93, v21, v49
	v_lshlrev_b32_e32 v48, 16, v83
	v_and_b32_e32 v49, 0xffff0000, v83
	v_fma_f32 v22, v94, v22, v48
	v_fma_f32 v23, v95, v23, v49
	v_lshlrev_b32_e32 v48, 16, v84
	v_and_b32_e32 v49, 0xffff0000, v84
	v_fma_f32 v24, v88, v24, v48
	v_fma_f32 v25, v89, v25, v49
	v_lshlrev_b32_e32 v48, 16, v85
	v_and_b32_e32 v49, 0xffff0000, v85
	v_fma_f32 v26, v90, v26, v48
	v_fma_f32 v27, v91, v27, v49
	v_lshlrev_b32_e32 v48, 16, v86
	v_and_b32_e32 v49, 0xffff0000, v86
	v_fma_f32 v28, v92, v28, v48
	v_fma_f32 v29, v93, v29, v49
	v_lshlrev_b32_e32 v48, 16, v87
	v_and_b32_e32 v49, 0xffff0000, v87
	v_fma_f32 v30, v94, v30, v48
	v_fma_f32 v31, v95, v31, v49
	global_load_dwordx4 v[80:83], v2, s[6:7] nt
	global_load_dwordx4 v[84:87], v3, s[6:7] nt
	global_load_dwordx4 v[88:91], v5, s[12:13]
	global_load_dwordx4 v[92:95], v5, s[12:13] offset:16
	s_add_u32 s6, s6, 0x40000
	s_addc_u32 s7, s7, 0
	s_add_u32 s12, s12, 2048
	s_addc_u32 s13, s13, 0
	s_waitcnt vmcnt(42)
	v_cvt_pk_bf16_f32 v32, v16, v17
	v_cvt_pk_bf16_f32 v33, v18, v19
	v_cvt_pk_bf16_f32 v34, v20, v21
	v_cvt_pk_bf16_f32 v35, v22, v23
	global_store_dwordx4 v2, v[32:35], s[10:11] nt
	v_cvt_pk_bf16_f32 v36, v24, v25
	v_cvt_pk_bf16_f32 v37, v26, v27
	v_cvt_pk_bf16_f32 v38, v28, v29
	v_cvt_pk_bf16_f32 v39, v30, v31
	global_store_dwordx4 v3, v[36:39], s[10:11] nt
	s_add_u32 s10, s10, 0x40000
	s_addc_u32 s11, s11, 0
	v_lshlrev_b32_e32 v48, 16, v96
	v_and_b32_e32 v49, 0xffff0000, v96
	v_fma_f32 v16, v104, v16, v48
	v_fma_f32 v17, v105, v17, v49
	v_lshlrev_b32_e32 v48, 16, v97
	v_and_b32_e32 v49, 0xffff0000, v97
	v_fma_f32 v18, v106, v18, v48
	v_fma_f32 v19, v107, v19, v49
	v_lshlrev_b32_e32 v48, 16, v98
	v_and_b32_e32 v49, 0xffff0000, v98
	v_fma_f32 v20, v108, v20, v48
	v_fma_f32 v21, v109, v21, v49
	v_lshlrev_b32_e32 v48, 16, v99
	v_and_b32_e32 v49, 0xffff0000, v99
	v_fma_f32 v22, v110, v22, v48
	v_fma_f32 v23, v111, v23, v49
	v_lshlrev_b32_e32 v48, 16, v100
	v_and_b32_e32 v49, 0xffff0000, v100
	v_fma_f32 v24, v104, v24, v48
	v_fma_f32 v25, v105, v25, v49
	v_lshlrev_b32_e32 v48, 16, v101
	v_and_b32_e32 v49, 0xffff0000, v101
	v_fma_f32 v26, v106, v26, v48
	v_fma_f32 v27, v107, v27, v49
	v_lshlrev_b32_e32 v48, 16, v102
	v_and_b32_e32 v49, 0xffff0000, v102
	v_fma_f32 v28, v108, v28, v48
	v_fma_f32 v29, v109, v29, v49
	v_lshlrev_b32_e32 v48, 16, v103
	v_and_b32_e32 v49, 0xffff0000, v103
	v_fma_f32 v30, v110, v30, v48
	v_fma_f32 v31, v111, v31, v49
	global_load_dwordx4 v[96:99], v2, s[6:7] nt
	global_load_dwordx4 v[100:103], v3, s[6:7] nt
	global_load_dwordx4 v[104:107], v5, s[12:13]
	global_load_dwordx4 v[108:111], v5, s[12:13] offset:16
	s_add_u32 s6, s6, 0x40000
	s_addc_u32 s7, s7, 0
	s_add_u32 s12, s12, 2048
	s_addc_u32 s13, s13, 0
	s_waitcnt vmcnt(42)
; __device__ __forceinline__ float bf2f(unsigned h) { return __uint_as_float(h << 16); }
; __device__ __forceinline__ unsigned pk2(float lo, float hi) { return pg8::cvt_pk_bf16(lo, hi); }
; __device__ __forceinline__ void b2_scan(const Ctx& C) {
;     ...
;     B2_LOAD(0, 0);
; #pragma unroll
;     for (int g = 0; g < 8; ++g) {
;         const int cur = g & 1;
;         if (g + 1 < 8) B2_LOAD(g + 1, cur ^ 1);
; #pragma unroll
;         for (int k = 0; k < 4; ++k) {
;             const int c = 4 * g + k;
;             const float dd[8] = {d0[cur][k][0], d0[cur][k][1], d0[cur][k][2], d0[cur][k][3], d1[cur][k][0], d1[cur][k][1], d1[cur][k][2], d1[cur][k][3]};
; #pragma unroll
;             for (int j = 0; j < 2; ++j) {
;                 v4u o; o.x = pk2(run[j][0], run[j][1]); o.y = pk2(run[j][2], run[j][3]); o.z = pk2(run[j][4], run[j][5]); o.w = pk2(run[j][6], run[j][7]);
;                 __builtin_nontemporal_store(o, (v4u*)(base + (size_t)c * cstride + (size_t)j * vstride));
;                 const unsigned lw[4] = {loc[cur][k][j].x, loc[cur][k][j].y, loc[cur][k][j].z, loc[cur][k][j].w};
; #pragma unroll
;                 for (int q = 0; q < 4; ++q) {
;                     run[j][2 * q] = dd[2 * q] * run[j][2 * q] + bf2f(lw[q] & 0xffffu);
;                     run[j][2 * q + 1] = dd[2 * q + 1] * run[j][2 * q + 1] + __uint_as_float(lw[q] & 0xffff0000u);
;                 }
;             }
;         }
;     }
	v_cvt_pk_bf16_f32 v40, v16, v17
	v_cvt_pk_bf16_f32 v41, v18, v19
	v_cvt_pk_bf16_f32 v42, v20, v21
	v_cvt_pk_bf16_f32 v43, v22, v23
	global_store_dwordx4 v2, v[40:43], s[10:11] nt
	v_cvt_pk_bf16_f32 v44, v24, v25
	v_cvt_pk_bf16_f32 v45, v26, v27
	v_cvt_pk_bf16_f32 v46, v28, v29
	v_cvt_pk_bf16_f32 v47, v30, v31
	global_store_dwordx4 v3, v[44:47], s[10:11] nt
	s_add_u32 s10, s10, 0x40000
	s_addc_u32 s11, s11, 0
	v_lshlrev_b32_e32 v48, 16, v112
	v_and_b32_e32 v49, 0xffff0000, v112
	v_fma_f32 v16, v120, v16, v48
	v_fma_f32 v17, v121, v17, v49
	v_lshlrev_b32_e32 v48, 16, v113
	v_and_b32_e32 v49, 0xffff0000, v113
	v_fma_f32 v18, v122, v18, v48
	v_fma_f32 v19, v123, v19, v49
	v_lshlrev_b32_e32 v48, 16, v114
	v_and_b32_e32 v49, 0xffff0000, v114
	v_fma_f32 v20, v124, v20, v48
	v_fma_f32 v21, v125, v21, v49
	v_lshlrev_b32_e32 v48, 16, v115
	v_and_b32_e32 v49, 0xffff0000, v115
	v_fma_f32 v22, v126, v22, v48
	v_fma_f32 v23, v127, v23, v49
	v_lshlrev_b32_e32 v48, 16, v116
	v_and_b32_e32 v49, 0xffff0000, v116
	v_fma_f32 v24, v120, v24, v48
	v_fma_f32 v25, v121, v25, v49
	v_lshlrev_b32_e32 v48, 16, v117
	v_and_b32_e32 v49, 0xffff0000, v117
	v_fma_f32 v26, v122, v26, v48
	v_fma_f32 v27, v123, v27, v49
	v_lshlrev_b32_e32 v48, 16, v118
	v_and_b32_e32 v49, 0xffff0000, v118
	v_fma_f32 v28, v124, v28, v48
	v_fma_f32 v29, v125, v29, v49
	v_lshlrev_b32_e32 v48, 16, v119
	v_and_b32_e32 v49, 0xffff0000, v119
	v_fma_f32 v30, v126, v30, v48
	v_fma_f32 v31, v127, v31, v49
	global_load_dwordx4 v[112:115], v2, s[6:7] nt
	global_load_dwordx4 v[116:119], v3, s[6:7] nt
	global_load_dwordx4 v[120:123], v5, s[12:13]
	global_load_dwordx4 v[124:127], v5, s[12:13] offset:16
	s_add_u32 s6, s6, 0x40000
	s_addc_u32 s7, s7, 0
	s_add_u32 s12, s12, 2048
	s_addc_u32 s13, s13, 0
	s_waitcnt vmcnt(42)
	v_cvt_pk_bf16_f32 v32, v16, v17
	v_cvt_pk_bf16_f32 v33, v18, v19
	v_cvt_pk_bf16_f32 v34, v20, v21
	v_cvt_pk_bf16_f32 v35, v22, v23
	global_store_dwordx4 v2, v[32:35], s[10:11] nt
	v_cvt_pk_bf16_f32 v36, v24, v25
	v_cvt_pk_bf16_f32 v37, v26, v27
	v_cvt_pk_bf16_f32 v38, v28, v29
	v_cvt_pk_bf16_f32 v39, v30, v31
	global_store_dwordx4 v3, v[36:39], s[10:11] nt
	s_add_u32 s10, s10, 0x40000
	s_addc_u32 s11, s11, 0
	v_lshlrev_b32_e32 v48, 16, v128
	v_and_b32_e32 v49, 0xffff0000, v128
	v_fma_f32 v16, v136, v16, v48
	v_fma_f32 v17, v137, v17, v49
	v_lshlrev_b32_e32 v48, 16, v129
	v_and_b32_e32 v49, 0xffff0000, v129
	v_fma_f32 v18, v138, v18, v48
	v_fma_f32 v19, v139, v19, v49
	v_lshlrev_b32_e32 v48, 16, v130
	v_and_b32_e32 v49, 0xffff0000, v130
	v_fma_f32 v20, v140, v20, v48
	v_fma_f32 v21, v141, v21, v49
	v_lshlrev_b32_e32 v48, 16, v131
	v_and_b32_e32 v49, 0xffff0000, v131
	v_fma_f32 v22, v142, v22, v48
	v_fma_f32 v23, v143, v23, v49
	v_lshlrev_b32_e32 v48, 16, v132
	v_and_b32_e32 v49, 0xffff0000, v132
	v_fma_f32 v24, v136, v24, v48
	v_fma_f32 v25, v137, v25, v49
	v_lshlrev_b32_e32 v48, 16, v133
	v_and_b32_e32 v49, 0xffff0000, v133
	v_fma_f32 v26, v138, v26, v48
	v_fma_f32 v27, v139, v27, v49
	v_lshlrev_b32_e32 v48, 16, v134
	v_and_b32_e32 v49, 0xffff0000, v134
	v_fma_f32 v28, v140, v28, v48
	v_fma_f32 v29, v141, v29, v49
	v_lshlrev_b32_e32 v48, 16, v135
	v_and_b32_e32 v49, 0xffff0000, v135
	v_fma_f32 v30, v142, v30, v48
	v_fma_f32 v31, v143, v31, v49
	global_load_dwordx4 v[128:131], v2, s[6:7] nt
	global_load_dwordx4 v[132:135], v3, s[6:7] nt
	global_load_dwordx4 v[136:139], v5, s[12:13]
	global_load_dwordx4 v[140:143], v5, s[12:13] offset:16
	s_add_u32 s6, s6, 0x40000
	s_addc_u32 s7, s7, 0
	s_add_u32 s12, s12, 2048
	s_addc_u32 s13, s13, 0
	s_waitcnt vmcnt(42)
	v_cvt_pk_bf16_f32 v40, v16, v17
	v_cvt_pk_bf16_f32 v41, v18, v19
	v_cvt_pk_bf16_f32 v42, v20, v21
	v_cvt_pk_bf16_f32 v43, v22, v23
	global_store_dwordx4 v2, v[40:43], s[10:11] nt
	v_cvt_pk_bf16_f32 v44, v24, v25
	v_cvt_pk_bf16_f32 v45, v26, v27
	v_cvt_pk_bf16_f32 v46, v28, v29
	v_cvt_pk_bf16_f32 v47, v30, v31
	global_store_dwordx4 v3, v[44:47], s[10:11] nt
	s_add_u32 s10, s10, 0x40000
	s_addc_u32 s11, s11, 0
	v_lshlrev_b32_e32 v48, 16, v144
	v_and_b32_e32 v49, 0xffff0000, v144
	v_fma_f32 v16, v152, v16, v48
	v_fma_f32 v17, v153, v17, v49
	v_lshlrev_b32_e32 v48, 16, v145
	v_and_b32_e32 v49, 0xffff0000, v145
	v_fma_f32 v18, v154, v18, v48
	v_fma_f32 v19, v155, v19, v49
	v_lshlrev_b32_e32 v48, 16, v146
	v_and_b32_e32 v49, 0xffff0000, v146
	v_fma_f32 v20, v156, v20, v48
	v_fma_f32 v21, v157, v21, v49
	v_lshlrev_b32_e32 v48, 16, v147
	v_and_b32_e32 v49, 0xffff0000, v147
	v_fma_f32 v22, v158, v22, v48
	v_fma_f32 v23, v159, v23, v49
	v_lshlrev_b32_e32 v48, 16, v148
	v_and_b32_e32 v49, 0xffff0000, v148
	v_fma_f32 v24, v152, v24, v48
	v_fma_f32 v25, v153, v25, v49
	v_lshlrev_b32_e32 v48, 16, v149
	v_and_b32_e32 v49, 0xffff0000, v149
	v_fma_f32 v26, v154, v26, v48
	v_fma_f32 v27, v155, v27, v49
	v_lshlrev_b32_e32 v48, 16, v150
	v_and_b32_e32 v49, 0xffff0000, v150
	v_fma_f32 v28, v156, v28, v48
	v_fma_f32 v29, v157, v29, v49
	v_lshlrev_b32_e32 v48, 16, v151
	v_and_b32_e32 v49, 0xffff0000, v151
	v_fma_f32 v30, v158, v30, v48
	v_fma_f32 v31, v159, v31, v49
	global_load_dwordx4 v[144:147], v2, s[6:7] nt
	global_load_dwordx4 v[148:151], v3, s[6:7] nt
	global_load_dwordx4 v[152:155], v5, s[12:13]
	global_load_dwordx4 v[156:159], v5, s[12:13] offset:16
	s_add_u32 s6, s6, 0x40000
	s_addc_u32 s7, s7, 0
	s_add_u32 s12, s12, 2048
	s_addc_u32 s13, s13, 0
	s_waitcnt vmcnt(42)
; __device__ __forceinline__ float bf2f(unsigned h) { return __uint_as_float(h << 16); }
; __device__ __forceinline__ unsigned pk2(float lo, float hi) { return pg8::cvt_pk_bf16(lo, hi); }
; __device__ __forceinline__ void b2_scan(const Ctx& C) {
;     ...
;     B2_LOAD(0, 0);
; #pragma unroll
;     for (int g = 0; g < 8; ++g) {
;         const int cur = g & 1;
;         if (g + 1 < 8) B2_LOAD(g + 1, cur ^ 1);
; #pragma unroll
;         for (int k = 0; k < 4; ++k) {
;             const int c = 4 * g + k;
;             const float dd[8] = {d0[cur][k][0], d0[cur][k][1], d0[cur][k][2], d0[cur][k][3], d1[cur][k][0], d1[cur][k][1], d1[cur][k][2], d1[cur][k][3]};
; #pragma unroll
;             for (int j = 0; j < 2; ++j) {
;                 v4u o; o.x = pk2(run[j][0], run[j][1]); o.y = pk2(run[j][2], run[j][3]); o.z = pk2(run[j][4], run[j][5]); o.w = pk2(run[j][6], run[j][7]);
;                 __builtin_nontemporal_store(o, (v4u*)(base + (size_t)c * cstride + (size_t)j * vstride));
;                 const unsigned lw[4] = {loc[cur][k][j].x, loc[cur][k][j].y, loc[cur][k][j].z, loc[cur][k][j].w};
; #pragma unroll
;                 for (int q = 0; q < 4; ++q) {
;                     run[j][2 * q] = dd[2 * q] * run[j][2 * q] + bf2f(lw[q] & 0xffffu);
;                     run[j][2 * q + 1] = dd[2 * q + 1] * run[j][2 * q + 1] + __uint_as_float(lw[q] & 0xffff0000u);
;                 }
;             }
;         }
;     }
	v_cvt_pk_bf16_f32 v32, v16, v17
	v_cvt_pk_bf16_f32 v33, v18, v19
	v_cvt_pk_bf16_f32 v34, v20, v21
	v_cvt_pk_bf16_f32 v35, v22, v23
	global_store_dwordx4 v2, v[32:35], s[10:11] nt
	v_cvt_pk_bf16_f32 v36, v24, v25
	v_cvt_pk_bf16_f32 v37, v26, v27
	v_cvt_pk_bf16_f32 v38, v28, v29
	v_cvt_pk_bf16_f32 v39, v30, v31
	global_store_dwordx4 v3, v[36:39], s[10:11] nt
	s_add_u32 s10, s10, 0x40000
	s_addc_u32 s11, s11, 0
	v_lshlrev_b32_e32 v48, 16, v160
	v_and_b32_e32 v49, 0xffff0000, v160
	v_fma_f32 v16, v168, v16, v48
	v_fma_f32 v17, v169, v17, v49
	v_lshlrev_b32_e32 v48, 16, v161
	v_and_b32_e32 v49, 0xffff0000, v161
	v_fma_f32 v18, v170, v18, v48
	v_fma_f32 v19, v171, v19, v49
	v_lshlrev_b32_e32 v48, 16, v162
	v_and_b32_e32 v49, 0xffff0000, v162
	v_fma_f32 v20, v172, v20, v48
	v_fma_f32 v21, v173, v21, v49
	v_lshlrev_b32_e32 v48, 16, v163
	v_and_b32_e32 v49, 0xffff0000, v163
	v_fma_f32 v22, v174, v22, v48
	v_fma_f32 v23, v175, v23, v49
	v_lshlrev_b32_e32 v48, 16, v164
	v_and_b32_e32 v49, 0xffff0000, v164
	v_fma_f32 v24, v168, v24, v48
	v_fma_f32 v25, v169, v25, v49
	v_lshlrev_b32_e32 v48, 16, v165
	v_and_b32_e32 v49, 0xffff0000, v165
	v_fma_f32 v26, v170, v26, v48
	v_fma_f32 v27, v171, v27, v49
	v_lshlrev_b32_e32 v48, 16, v166
	v_and_b32_e32 v49, 0xffff0000, v166
	v_fma_f32 v28, v172, v28, v48
	v_fma_f32 v29, v173, v29, v49
	v_lshlrev_b32_e32 v48, 16, v167
	v_and_b32_e32 v49, 0xffff0000, v167
	v_fma_f32 v30, v174, v30, v48
	v_fma_f32 v31, v175, v31, v49
	global_load_dwordx4 v[160:163], v2, s[6:7] nt
	global_load_dwordx4 v[164:167], v3, s[6:7] nt
	global_load_dwordx4 v[168:171], v5, s[12:13]
	global_load_dwordx4 v[172:175], v5, s[12:13] offset:16
	s_add_u32 s6, s6, 0x40000
	s_addc_u32 s7, s7, 0
	s_add_u32 s12, s12, 2048
	s_addc_u32 s13, s13, 0
	s_waitcnt vmcnt(42)
	v_cvt_pk_bf16_f32 v40, v16, v17
	v_cvt_pk_bf16_f32 v41, v18, v19
	v_cvt_pk_bf16_f32 v42, v20, v21
	v_cvt_pk_bf16_f32 v43, v22, v23
	global_store_dwordx4 v2, v[40:43], s[10:11] nt
	v_cvt_pk_bf16_f32 v44, v24, v25
	v_cvt_pk_bf16_f32 v45, v26, v27
	v_cvt_pk_bf16_f32 v46, v28, v29
	v_cvt_pk_bf16_f32 v47, v30, v31
	global_store_dwordx4 v3, v[44:47], s[10:11] nt
	s_add_u32 s10, s10, 0x40000
	s_addc_u32 s11, s11, 0
	v_lshlrev_b32_e32 v48, 16, v176
	v_and_b32_e32 v49, 0xffff0000, v176
	v_fma_f32 v16, v184, v16, v48
	v_fma_f32 v17, v185, v17, v49
	v_lshlrev_b32_e32 v48, 16, v177
	v_and_b32_e32 v49, 0xffff0000, v177
	v_fma_f32 v18, v186, v18, v48
	v_fma_f32 v19, v187, v19, v49
	v_lshlrev_b32_e32 v48, 16, v178
	v_and_b32_e32 v49, 0xffff0000, v178
	v_fma_f32 v20, v188, v20, v48
	v_fma_f32 v21, v189, v21, v49
	v_lshlrev_b32_e32 v48, 16, v179
	v_and_b32_e32 v49, 0xffff0000, v179
	v_fma_f32 v22, v190, v22, v48
	v_fma_f32 v23, v191, v23, v49
	v_lshlrev_b32_e32 v48, 16, v180
	v_and_b32_e32 v49, 0xffff0000, v180
	v_fma_f32 v24, v184, v24, v48
	v_fma_f32 v25, v185, v25, v49
	v_lshlrev_b32_e32 v48, 16, v181
	v_and_b32_e32 v49, 0xffff0000, v181
	v_fma_f32 v26, v186, v26, v48
	v_fma_f32 v27, v187, v27, v49
	v_lshlrev_b32_e32 v48, 16, v182
	v_and_b32_e32 v49, 0xffff0000, v182
	v_fma_f32 v28, v188, v28, v48
	v_fma_f32 v29, v189, v29, v49
	v_lshlrev_b32_e32 v48, 16, v183
	v_and_b32_e32 v49, 0xffff0000, v183
	v_fma_f32 v30, v190, v30, v48
	v_fma_f32 v31, v191, v31, v49
	global_load_dwordx4 v[176:179], v2, s[6:7] nt
	global_load_dwordx4 v[180:183], v3, s[6:7] nt
	global_load_dwordx4 v[184:187], v5, s[12:13]
	global_load_dwordx4 v[188:191], v5, s[12:13] offset:16
	s_add_u32 s6, s6, 0x40000
	s_addc_u32 s7, s7, 0
	s_add_u32 s12, s12, 2048
	s_addc_u32 s13, s13, 0
	s_waitcnt vmcnt(42)
	v_cvt_pk_bf16_f32 v32, v16, v17
	v_cvt_pk_bf16_f32 v33, v18, v19
	v_cvt_pk_bf16_f32 v34, v20, v21
	v_cvt_pk_bf16_f32 v35, v22, v23
	global_store_dwordx4 v2, v[32:35], s[10:11] nt
	v_cvt_pk_bf16_f32 v36, v24, v25
	v_cvt_pk_bf16_f32 v37, v26, v27
	v_cvt_pk_bf16_f32 v38, v28, v29
	v_cvt_pk_bf16_f32 v39, v30, v31
	global_store_dwordx4 v3, v[36:39], s[10:11] nt
	s_add_u32 s10, s10, 0x40000
	s_addc_u32 s11, s11, 0
	v_lshlrev_b32_e32 v48, 16, v64
	v_and_b32_e32 v49, 0xffff0000, v64
	v_fma_f32 v16, v72, v16, v48
	v_fma_f32 v17, v73, v17, v49
	v_lshlrev_b32_e32 v48, 16, v65
	v_and_b32_e32 v49, 0xffff0000, v65
	v_fma_f32 v18, v74, v18, v48
	v_fma_f32 v19, v75, v19, v49
	v_lshlrev_b32_e32 v48, 16, v66
	v_and_b32_e32 v49, 0xffff0000, v66
	v_fma_f32 v20, v76, v20, v48
	v_fma_f32 v21, v77, v21, v49
	v_lshlrev_b32_e32 v48, 16, v67
	v_and_b32_e32 v49, 0xffff0000, v67
	v_fma_f32 v22, v78, v22, v48
	v_fma_f32 v23, v79, v23, v49
	v_lshlrev_b32_e32 v48, 16, v68
	v_and_b32_e32 v49, 0xffff0000, v68
	v_fma_f32 v24, v72, v24, v48
	v_fma_f32 v25, v73, v25, v49
	v_lshlrev_b32_e32 v48, 16, v69
	v_and_b32_e32 v49, 0xffff0000, v69
	v_fma_f32 v26, v74, v26, v48
	v_fma_f32 v27, v75, v27, v49
	v_lshlrev_b32_e32 v48, 16, v70
	v_and_b32_e32 v49, 0xffff0000, v70
	v_fma_f32 v28, v76, v28, v48
	v_fma_f32 v29, v77, v29, v49
	v_lshlrev_b32_e32 v48, 16, v71
	v_and_b32_e32 v49, 0xffff0000, v71
	v_fma_f32 v30, v78, v30, v48
	v_fma_f32 v31, v79, v31, v49
	s_waitcnt vmcnt(38)
; __device__ __forceinline__ float bf2f(unsigned h) { return __uint_as_float(h << 16); }
; __device__ __forceinline__ unsigned pk2(float lo, float hi) { return pg8::cvt_pk_bf16(lo, hi); }
; __device__ __forceinline__ void b2_scan(const Ctx& C) {
;     ...
;     B2_LOAD(0, 0);
; #pragma unroll
;     for (int g = 0; g < 8; ++g) {
;         const int cur = g & 1;
;         if (g + 1 < 8) B2_LOAD(g + 1, cur ^ 1);
; #pragma unroll
;         for (int k = 0; k < 4; ++k) {
;             const int c = 4 * g + k;
;             const float dd[8] = {d0[cur][k][0], d0[cur][k][1], d0[cur][k][2], d0[cur][k][3], d1[cur][k][0], d1[cur][k][1], d1[cur][k][2], d1[cur][k][3]};
; #pragma unroll
;             for (int j = 0; j < 2; ++j) {
;                 v4u o; o.x = pk2(run[j][0], run[j][1]); o.y = pk2(run[j][2], run[j][3]); o.z = pk2(run[j][4], run[j][5]); o.w = pk2(run[j][6], run[j][7]);
;                 __builtin_nontemporal_store(o, (v4u*)(base + (size_t)c * cstride + (size_t)j * vstride));
;                 const unsigned lw[4] = {loc[cur][k][j].x, loc[cur][k][j].y, loc[cur][k][j].z, loc[cur][k][j].w};
; #pragma unroll
;                 for (int q = 0; q < 4; ++q) {
;                     run[j][2 * q] = dd[2 * q] * run[j][2 * q] + bf2f(lw[q] & 0xffffu);
;                     run[j][2 * q + 1] = dd[2 * q + 1] * run[j][2 * q + 1] + __uint_as_float(lw[q] & 0xffff0000u);
;                 }
;             }
;         }
;     }
	v_cvt_pk_bf16_f32 v40, v16, v17
	v_cvt_pk_bf16_f32 v41, v18, v19
	v_cvt_pk_bf16_f32 v42, v20, v21
	v_cvt_pk_bf16_f32 v43, v22, v23
	global_store_dwordx4 v2, v[40:43], s[10:11] nt
	v_cvt_pk_bf16_f32 v44, v24, v25
	v_cvt_pk_bf16_f32 v45, v26, v27
	v_cvt_pk_bf16_f32 v46, v28, v29
	v_cvt_pk_bf16_f32 v47, v30, v31
	global_store_dwordx4 v3, v[44:47], s[10:11] nt
	s_add_u32 s10, s10, 0x40000
	s_addc_u32 s11, s11, 0
	v_lshlrev_b32_e32 v48, 16, v80
	v_and_b32_e32 v49, 0xffff0000, v80
	v_fma_f32 v16, v88, v16, v48
	v_fma_f32 v17, v89, v17, v49
	v_lshlrev_b32_e32 v48, 16, v81
	v_and_b32_e32 v49, 0xffff0000, v81
	v_fma_f32 v18, v90, v18, v48
	v_fma_f32 v19, v91, v19, v49
	v_lshlrev_b32_e32 v48, 16, v82
	v_and_b32_e32 v49, 0xffff0000, v82
	v_fma_f32 v20, v92, v20, v48
	v_fma_f32 v21, v93, v21, v49
	v_lshlrev_b32_e32 v48, 16, v83
	v_and_b32_e32 v49, 0xffff0000, v83
	v_fma_f32 v22, v94, v22, v48
	v_fma_f32 v23, v95, v23, v49
	v_lshlrev_b32_e32 v48, 16, v84
	v_and_b32_e32 v49, 0xffff0000, v84
	v_fma_f32 v24, v88, v24, v48
	v_fma_f32 v25, v89, v25, v49
	v_lshlrev_b32_e32 v48, 16, v85
	v_and_b32_e32 v49, 0xffff0000, v85
	v_fma_f32 v26, v90, v26, v48
	v_fma_f32 v27, v91, v27, v49
	v_lshlrev_b32_e32 v48, 16, v86
	v_and_b32_e32 v49, 0xffff0000, v86
	v_fma_f32 v28, v92, v28, v48
	v_fma_f32 v29, v93, v29, v49
	v_lshlrev_b32_e32 v48, 16, v87
	v_and_b32_e32 v49, 0xffff0000, v87
	v_fma_f32 v30, v94, v30, v48
	v_fma_f32 v31, v95, v31, v49
	s_waitcnt vmcnt(34)
	v_cvt_pk_bf16_f32 v32, v16, v17
	v_cvt_pk_bf16_f32 v33, v18, v19
	v_cvt_pk_bf16_f32 v34, v20, v21
	v_cvt_pk_bf16_f32 v35, v22, v23
	global_store_dwordx4 v2, v[32:35], s[10:11] nt
	v_cvt_pk_bf16_f32 v36, v24, v25
	v_cvt_pk_bf16_f32 v37, v26, v27
	v_cvt_pk_bf16_f32 v38, v28, v29
	v_cvt_pk_bf16_f32 v39, v30, v31
	global_store_dwordx4 v3, v[36:39], s[10:11] nt
	s_add_u32 s10, s10, 0x40000
	s_addc_u32 s11, s11, 0
	v_lshlrev_b32_e32 v48, 16, v96
	v_and_b32_e32 v49, 0xffff0000, v96
	v_fma_f32 v16, v104, v16, v48
	v_fma_f32 v17, v105, v17, v49
	v_lshlrev_b32_e32 v48, 16, v97
	v_and_b32_e32 v49, 0xffff0000, v97
	v_fma_f32 v18, v106, v18, v48
	v_fma_f32 v19, v107, v19, v49
	v_lshlrev_b32_e32 v48, 16, v98
	v_and_b32_e32 v49, 0xffff0000, v98
	v_fma_f32 v20, v108, v20, v48
	v_fma_f32 v21, v109, v21, v49
	v_lshlrev_b32_e32 v48, 16, v99
	v_and_b32_e32 v49, 0xffff0000, v99
	v_fma_f32 v22, v110, v22, v48
	v_fma_f32 v23, v111, v23, v49
	v_lshlrev_b32_e32 v48, 16, v100
	v_and_b32_e32 v49, 0xffff0000, v100
	v_fma_f32 v24, v104, v24, v48
	v_fma_f32 v25, v105, v25, v49
	v_lshlrev_b32_e32 v48, 16, v101
	v_and_b32_e32 v49, 0xffff0000, v101
	v_fma_f32 v26, v106, v26, v48
	v_fma_f32 v27, v107, v27, v49
	v_lshlrev_b32_e32 v48, 16, v102
	v_and_b32_e32 v49, 0xffff0000, v102
	v_fma_f32 v28, v108, v28, v48
	v_fma_f32 v29, v109, v29, v49
	v_lshlrev_b32_e32 v48, 16, v103
	v_and_b32_e32 v49, 0xffff0000, v103
	v_fma_f32 v30, v110, v30, v48
	v_fma_f32 v31, v111, v31, v49
	s_waitcnt vmcnt(30)
	v_cvt_pk_bf16_f32 v40, v16, v17
	v_cvt_pk_bf16_f32 v41, v18, v19
	v_cvt_pk_bf16_f32 v42, v20, v21
	v_cvt_pk_bf16_f32 v43, v22, v23
	global_store_dwordx4 v2, v[40:43], s[10:11] nt
	v_cvt_pk_bf16_f32 v44, v24, v25
	v_cvt_pk_bf16_f32 v45, v26, v27
	v_cvt_pk_bf16_f32 v46, v28, v29
	v_cvt_pk_bf16_f32 v47, v30, v31
	global_store_dwordx4 v3, v[44:47], s[10:11] nt
	s_add_u32 s10, s10, 0x40000
	s_addc_u32 s11, s11, 0
	v_lshlrev_b32_e32 v48, 16, v112
	v_and_b32_e32 v49, 0xffff0000, v112
	v_fma_f32 v16, v120, v16, v48
	v_fma_f32 v17, v121, v17, v49
	v_lshlrev_b32_e32 v48, 16, v113
	v_and_b32_e32 v49, 0xffff0000, v113
	v_fma_f32 v18, v122, v18, v48
	v_fma_f32 v19, v123, v19, v49
	v_lshlrev_b32_e32 v48, 16, v114
	v_and_b32_e32 v49, 0xffff0000, v114
	v_fma_f32 v20, v124, v20, v48
	v_fma_f32 v21, v125, v21, v49
	v_lshlrev_b32_e32 v48, 16, v115
	v_and_b32_e32 v49, 0xffff0000, v115
	v_fma_f32 v22, v126, v22, v48
	v_fma_f32 v23, v127, v23, v49
	v_lshlrev_b32_e32 v48, 16, v116
	v_and_b32_e32 v49, 0xffff0000, v116
	v_fma_f32 v24, v120, v24, v48
	v_fma_f32 v25, v121, v25, v49
	v_lshlrev_b32_e32 v48, 16, v117
	v_and_b32_e32 v49, 0xffff0000, v117
	v_fma_f32 v26, v122, v26, v48
	v_fma_f32 v27, v123, v27, v49
	v_lshlrev_b32_e32 v48, 16, v118
	v_and_b32_e32 v49, 0xffff0000, v118
	v_fma_f32 v28, v124, v28, v48
	v_fma_f32 v29, v125, v29, v49
	v_lshlrev_b32_e32 v48, 16, v119
	v_and_b32_e32 v49, 0xffff0000, v119
	v_fma_f32 v30, v126, v30, v48
	v_fma_f32 v31, v127, v31, v49
	s_waitcnt vmcnt(26)
	v_cvt_pk_bf16_f32 v32, v16, v17
	v_cvt_pk_bf16_f32 v33, v18, v19
	v_cvt_pk_bf16_f32 v34, v20, v21
	v_cvt_pk_bf16_f32 v35, v22, v23
	global_store_dwordx4 v2, v[32:35], s[10:11] nt
	v_cvt_pk_bf16_f32 v36, v24, v25
	v_cvt_pk_bf16_f32 v37, v26, v27
	v_cvt_pk_bf16_f32 v38, v28, v29
	v_cvt_pk_bf16_f32 v39, v30, v31
	global_store_dwordx4 v3, v[36:39], s[10:11] nt
	s_add_u32 s10, s10, 0x40000
	s_addc_u32 s11, s11, 0
	v_lshlrev_b32_e32 v48, 16, v128
	v_and_b32_e32 v49, 0xffff0000, v128
	v_fma_f32 v16, v136, v16, v48
	v_fma_f32 v17, v137, v17, v49
	v_lshlrev_b32_e32 v48, 16, v129
	v_and_b32_e32 v49, 0xffff0000, v129
	v_fma_f32 v18, v138, v18, v48
	v_fma_f32 v19, v139, v19, v49
	v_lshlrev_b32_e32 v48, 16, v130
	v_and_b32_e32 v49, 0xffff0000, v130
	v_fma_f32 v20, v140, v20, v48
	v_fma_f32 v21, v141, v21, v49
	v_lshlrev_b32_e32 v48, 16, v131
	v_and_b32_e32 v49, 0xffff0000, v131
	v_fma_f32 v22, v142, v22, v48
	v_fma_f32 v23, v143, v23, v49
	v_lshlrev_b32_e32 v48, 16, v132
	v_and_b32_e32 v49, 0xffff0000, v132
	v_fma_f32 v24, v136, v24, v48
	v_fma_f32 v25, v137, v25, v49
	v_lshlrev_b32_e32 v48, 16, v133
	v_and_b32_e32 v49, 0xffff0000, v133
	v_fma_f32 v26, v138, v26, v48
	v_fma_f32 v27, v139, v27, v49
	v_lshlrev_b32_e32 v48, 16, v134
	v_and_b32_e32 v49, 0xffff0000, v134
	v_fma_f32 v28, v140, v28, v48
	v_fma_f32 v29, v141, v29, v49
	v_lshlrev_b32_e32 v48, 16, v135
	v_and_b32_e32 v49, 0xffff0000, v135
	v_fma_f32 v30, v142, v30, v48
	v_fma_f32 v31, v143, v31, v49
	s_waitcnt vmcnt(22)
; __device__ __forceinline__ float bf2f(unsigned h) { return __uint_as_float(h << 16); }
; __device__ __forceinline__ unsigned pk2(float lo, float hi) { return pg8::cvt_pk_bf16(lo, hi); }
; __device__ __forceinline__ void b2_scan(const Ctx& C) {
;     ...
;     B2_LOAD(0, 0);
; #pragma unroll
;     for (int g = 0; g < 8; ++g) {
;         const int cur = g & 1;
;         if (g + 1 < 8) B2_LOAD(g + 1, cur ^ 1);
; #pragma unroll
;         for (int k = 0; k < 4; ++k) {
;             const int c = 4 * g + k;
;             const float dd[8] = {d0[cur][k][0], d0[cur][k][1], d0[cur][k][2], d0[cur][k][3], d1[cur][k][0], d1[cur][k][1], d1[cur][k][2], d1[cur][k][3]};
; #pragma unroll
;             for (int j = 0; j < 2; ++j) {
;                 v4u o; o.x = pk2(run[j][0], run[j][1]); o.y = pk2(run[j][2], run[j][3]); o.z = pk2(run[j][4], run[j][5]); o.w = pk2(run[j][6], run[j][7]);
;                 __builtin_nontemporal_store(o, (v4u*)(base + (size_t)c * cstride + (size_t)j * vstride));
;                 const unsigned lw[4] = {loc[cur][k][j].x, loc[cur][k][j].y, loc[cur][k][j].z, loc[cur][k][j].w};
; #pragma unroll
;                 for (int q = 0; q < 4; ++q) {
;                     run[j][2 * q] = dd[2 * q] * run[j][2 * q] + bf2f(lw[q] & 0xffffu);
;                     run[j][2 * q + 1] = dd[2 * q + 1] * run[j][2 * q + 1] + __uint_as_float(lw[q] & 0xffff0000u);
;                 }
;             }
;         }
;     }
	v_cvt_pk_bf16_f32 v40, v16, v17
	v_cvt_pk_bf16_f32 v41, v18, v19
	v_cvt_pk_bf16_f32 v42, v20, v21
	v_cvt_pk_bf16_f32 v43, v22, v23
	global_store_dwordx4 v2, v[40:43], s[10:11] nt
	v_cvt_pk_bf16_f32 v44, v24, v25
	v_cvt_pk_bf16_f32 v45, v26, v27
	v_cvt_pk_bf16_f32 v46, v28, v29
	v_cvt_pk_bf16_f32 v47, v30, v31
	global_store_dwordx4 v3, v[44:47], s[10:11] nt
	s_add_u32 s10, s10, 0x40000
	s_addc_u32 s11, s11, 0
	v_lshlrev_b32_e32 v48, 16, v144
	v_and_b32_e32 v49, 0xffff0000, v144
	v_fma_f32 v16, v152, v16, v48
	v_fma_f32 v17, v153, v17, v49
	v_lshlrev_b32_e32 v48, 16, v145
	v_and_b32_e32 v49, 0xffff0000, v145
	v_fma_f32 v18, v154, v18, v48
	v_fma_f32 v19, v155, v19, v49
	v_lshlrev_b32_e32 v48, 16, v146
	v_and_b32_e32 v49, 0xffff0000, v146
	v_fma_f32 v20, v156, v20, v48
	v_fma_f32 v21, v157, v21, v49
	v_lshlrev_b32_e32 v48, 16, v147
	v_and_b32_e32 v49, 0xffff0000, v147
	v_fma_f32 v22, v158, v22, v48
	v_fma_f32 v23, v159, v23, v49
	v_lshlrev_b32_e32 v48, 16, v148
	v_and_b32_e32 v49, 0xffff0000, v148
	v_fma_f32 v24, v152, v24, v48
	v_fma_f32 v25, v153, v25, v49
	v_lshlrev_b32_e32 v48, 16, v149
	v_and_b32_e32 v49, 0xffff0000, v149
	v_fma_f32 v26, v154, v26, v48
	v_fma_f32 v27, v155, v27, v49
	v_lshlrev_b32_e32 v48, 16, v150
	v_and_b32_e32 v49, 0xffff0000, v150
	v_fma_f32 v28, v156, v28, v48
	v_fma_f32 v29, v157, v29, v49
	v_lshlrev_b32_e32 v48, 16, v151
	v_and_b32_e32 v49, 0xffff0000, v151
	v_fma_f32 v30, v158, v30, v48
	v_fma_f32 v31, v159, v31, v49
	s_waitcnt vmcnt(18)
	v_cvt_pk_bf16_f32 v32, v16, v17
	v_cvt_pk_bf16_f32 v33, v18, v19
	v_cvt_pk_bf16_f32 v34, v20, v21
	v_cvt_pk_bf16_f32 v35, v22, v23
	global_store_dwordx4 v2, v[32:35], s[10:11] nt
	v_cvt_pk_bf16_f32 v36, v24, v25
	v_cvt_pk_bf16_f32 v37, v26, v27
	v_cvt_pk_bf16_f32 v38, v28, v29
	v_cvt_pk_bf16_f32 v39, v30, v31
	global_store_dwordx4 v3, v[36:39], s[10:11] nt
	s_add_u32 s10, s10, 0x40000
	s_addc_u32 s11, s11, 0
	v_lshlrev_b32_e32 v48, 16, v160
	v_and_b32_e32 v49, 0xffff0000, v160
	v_fma_f32 v16, v168, v16, v48
	v_fma_f32 v17, v169, v17, v49
	v_lshlrev_b32_e32 v48, 16, v161
	v_and_b32_e32 v49, 0xffff0000, v161
	v_fma_f32 v18, v170, v18, v48
	v_fma_f32 v19, v171, v19, v49
	v_lshlrev_b32_e32 v48, 16, v162
	v_and_b32_e32 v49, 0xffff0000, v162
	v_fma_f32 v20, v172, v20, v48
	v_fma_f32 v21, v173, v21, v49
	v_lshlrev_b32_e32 v48, 16, v163
	v_and_b32_e32 v49, 0xffff0000, v163
	v_fma_f32 v22, v174, v22, v48
	v_fma_f32 v23, v175, v23, v49
	v_lshlrev_b32_e32 v48, 16, v164
	v_and_b32_e32 v49, 0xffff0000, v164
	v_fma_f32 v24, v168, v24, v48
	v_fma_f32 v25, v169, v25, v49
	v_lshlrev_b32_e32 v48, 16, v165
	v_and_b32_e32 v49, 0xffff0000, v165
	v_fma_f32 v26, v170, v26, v48
	v_fma_f32 v27, v171, v27, v49
	v_lshlrev_b32_e32 v48, 16, v166
	v_and_b32_e32 v49, 0xffff0000, v166
	v_fma_f32 v28, v172, v28, v48
	v_fma_f32 v29, v173, v29, v49
	v_lshlrev_b32_e32 v48, 16, v167
	v_and_b32_e32 v49, 0xffff0000, v167
	v_fma_f32 v30, v174, v30, v48
	v_fma_f32 v31, v175, v31, v49
	s_waitcnt vmcnt(14)
	v_cvt_pk_bf16_f32 v40, v16, v17
	v_cvt_pk_bf16_f32 v41, v18, v19
	v_cvt_pk_bf16_f32 v42, v20, v21
	v_cvt_pk_bf16_f32 v43, v22, v23
	global_store_dwordx4 v2, v[40:43], s[10:11] nt
	v_cvt_pk_bf16_f32 v44, v24, v25
	v_cvt_pk_bf16_f32 v45, v26, v27
	v_cvt_pk_bf16_f32 v46, v28, v29
	v_cvt_pk_bf16_f32 v47, v30, v31
	global_store_dwordx4 v3, v[44:47], s[10:11] nt
	s_add_u32 s10, s10, 0x40000
	s_addc_u32 s11, s11, 0
	v_lshlrev_b32_e32 v48, 16, v176
	v_and_b32_e32 v49, 0xffff0000, v176
	v_fma_f32 v16, v184, v16, v48
	v_fma_f32 v17, v185, v17, v49
	v_lshlrev_b32_e32 v48, 16, v177
	v_and_b32_e32 v49, 0xffff0000, v177
	v_fma_f32 v18, v186, v18, v48
	v_fma_f32 v19, v187, v19, v49
	v_lshlrev_b32_e32 v48, 16, v178
	v_and_b32_e32 v49, 0xffff0000, v178
	v_fma_f32 v20, v188, v20, v48
	v_fma_f32 v21, v189, v21, v49
	v_lshlrev_b32_e32 v48, 16, v179
	v_and_b32_e32 v49, 0xffff0000, v179
	v_fma_f32 v22, v190, v22, v48
	v_fma_f32 v23, v191, v23, v49
	v_lshlrev_b32_e32 v48, 16, v180
	v_and_b32_e32 v49, 0xffff0000, v180
	v_fma_f32 v24, v184, v24, v48
	v_fma_f32 v25, v185, v25, v49
	v_lshlrev_b32_e32 v48, 16, v181
	v_and_b32_e32 v49, 0xffff0000, v181
	v_fma_f32 v26, v186, v26, v48
	v_fma_f32 v27, v187, v27, v49
	v_lshlrev_b32_e32 v48, 16, v182
	v_and_b32_e32 v49, 0xffff0000, v182
	v_fma_f32 v28, v188, v28, v48
	v_fma_f32 v29, v189, v29, v49
	v_lshlrev_b32_e32 v48, 16, v183
	v_and_b32_e32 v49, 0xffff0000, v183
	v_fma_f32 v30, v190, v30, v48
	v_fma_f32 v31, v191, v31, v49

; __global__ void __launch_bounds__(NTHR, 2) fwd_megakernel(Args args) {
;     ...
; #pragma unroll 1
;         for (int it = blockIdx.x; it < 1536; it += gridDim.x) { MKCTX();
;             if (it < 1024) b3_gla_item(C, li, it >> 7, (it >> 2) & 31, it & 3);
;             else { const int r = it - 1024; b3_ssd_item(C, li, r >> 6, (r >> 1) & 31, r & 1); }
;         }
.LBB0_649:
	s_or_b64 exec, exec, s[40:41]
	s_waitcnt lgkmcnt(0)
	s_barrier
	s_load_dwordx2 s[24:25], s[0:1], 0xc0
	v_cndmask_b32_e64 v0, 0, 1, s[38:39]
	v_cmp_ne_u32_e64 s[8:9], 1, v0
	s_andn2_b64 vcc, exec, s[38:39]
	s_cbranch_vccnz .LBB0_813
	v_mbcnt_hi_u32_b32 v113, -1, v235
	s_lshl_b32 s37, s2, 4
	s_lshl_b32 s39, s46, 4
	s_mov_b32 s27, 0
	s_movk_i32 s55, 0x2e00
	s_movk_i32 s66, 0x2000
	s_mov_b32 s67, 0x800000
	s_mov_b32 s72, 0x3f317217
	s_mov_b32 s73, 0x7f800000
	s_movk_i32 s74, 0x1700
	v_mov_b32_e32 v105, 0
	s_movk_i32 s75, 0x90
	s_movk_i32 s76, 0x5000
	s_mov_b64 s[28:29], 0x1800
	s_movk_i32 s77, 0x1000
	s_mov_b64 s[30:31], 0x3000
	s_movk_i32 s78, 0x3000
	s_mov_b64 s[34:35], 0x4800
	s_movk_i32 s79, 0x4000
	s_mov_b32 s80, 0xffff0000
	s_mov_b32 s81, 0xbfb8aa3b
	s_movk_i32 s82, 0x7fff
	s_add_i32 s83, 0, 0x12000
	s_add_i32 s84, 0, 0x16400
	s_movk_i32 s85, 0x110
	s_add_i32 s86, 0, 0x1a800
	s_mov_b32 s36, 0x3b000000
	s_mov_b32 s38, 0x358637bd
	s_mov_b32 s87, 0xe400000
	s_movk_i32 s88, 0x7000
	s_movk_i32 s89, 0x88
	s_mov_b32 s90, 0xa000
	s_mov_b32 s91, 0x29000
	s_mov_b32 s92, 0x2c000
	s_add_i32 s93, 0, 0x13000
	s_mov_b64 s[40:41], 0x21c00000
	s_mov_b64 s[42:43], 0x2400
	s_mov_b64 s[52:53], 0xe400800
	s_mov_b32 s54, 0x3b800000
	v_mov_b32_e32 v112, 0x41b17218
	v_and_b32_e32 v114, 64, v113
	v_add_u32_e32 v115, -1, v113
	v_add_u32_e32 v116, -2, v113
	v_add_u32_e32 v117, -4, v113
	v_add_u32_e32 v118, -8, v113
	v_add_u32_e32 v119, -16, v113
	v_subrev_u32_e32 v120, 32, v113
	v_mov_b32_e32 v121, 0x1200
	v_mov_b32_e32 v122, 0x1000
	v_mov_b32_e32 v123, 0x500
	v_mov_b32_e32 v124, 0x400
	s_and_b32 s94, s2, 7
	s_lshl_b32 s94, s94, 7
	s_lshr_b32 s6, s2, 3
	s_add_u32 s94, s94, s6
	s_lshl_b32 s37, s94, 4
	s_mov_b32 m0, 0
	s_branch .LBB0_653

; __global__ void __launch_bounds__(NTHR, 2) fwd_megakernel(Args args) {
;     ...
;         for (int it = blockIdx.x; it < 1536; it += gridDim.x) { MKCTX();
.LBB0_652:
	s_add_u32 s6, m0, 1
	s_mov_b32 m0, s6
	s_add_i32 s94, s94, 32
	s_cmp_eq_u32 s6, 4
	s_cbranch_scc0 .Lrg_skip_b3l0
	s_and_b32 s6, s2, 7
	s_lshl_b32 s6, s6, 6
	s_sub_i32 s94, s94, s6
	s_addk_i32 s94, 0x380
.Lrg_skip_b3l0:
	s_lshl_b32 s37, s94, 4
	s_cmp_gt_u32 m0, 5
	s_cbranch_scc1 .LBB0_812

; __device__ __forceinline__ void skinny_proj(const Ctx& C, const bf16* X, const bf16* Wt, const float* SS, bf16* PROJ) {
;     const int fr = C.lane & 15, fq = C.lane >> 4;
;     const int r0 = (C.bid - 128) * 128 + C.wave * 16;
;     const bf16* A = X + (size_t)(r0 + fr) * D + fq * 8;
;     const bf16* W0 = Wt + (size_t)(NMAIN + fr) * D + fq * 8;
;     f32x4 acc0 = (f32x4){0.f, 0.f, 0.f, 0.f}, acc1 = acc0;
; #pragma unroll 8
;     for (int ks = 0; ks < D / 32; ++ks) {
;         const bf16x8 a = *(const bf16x8*)(A + ks * 32), b0 = *(const bf16x8*)(W0 + ks * 32), b1 = *(const bf16x8*)(W0 + (size_t)16 * D + ks * 32);
.LBB0_1409:
	s_and_b64 vcc, exec, s[48:49]
	s_cbranch_vccz .LBB0_1413
	s_and_b32 s10, s2, 7
	s_lshl_b32 s10, s10, 11
	s_sub_u32 s11, s2, 128
	s_lshr_b32 s11, s11, 3
	s_lshl_b32 s11, s11, 7
	s_add_u32 s10, s10, s11
	s_addk_i32 s10, 0x4000
	v_and_b32_e32 v4, 15, v148
	s_ashr_i32 s11, s54, 2
	s_addk_i32 s10, 0xc000
	s_and_b32 s11, s11, -16
	v_or_b32_e32 v0, s10, v4
	v_add_u32_e32 v8, s11, v0
	v_ashrrev_i32_e32 v9, 31, v8
	v_bfe_u32 v14, v148, 4, 2
	v_lshlrev_b64 v[0:1], 12, v[8:9]
	v_lshl_add_u64 v[2:3], s[22:23], 0, v[0:1]
	v_lshlrev_b32_e32 v0, 4, v14
	v_mov_b32_e32 v1, 0
	s_add_u32 s10, s18, s14
	v_lshl_add_u64 v[10:11], v[2:3], 0, v[0:1]
	v_lshl_or_b32 v0, v4, 12, v0
	s_addc_u32 s11, s19, s15
	v_lshl_add_u64 v[12:13], s[10:11], 0, v[0:1]
	s_mov_b64 s[12:13], 0
	v_mov_b32_e32 v0, v1
	v_mov_b32_e32 v2, v1
	v_mov_b32_e32 v3, v1
	v_mov_b32_e32 v4, v1
	v_mov_b32_e32 v5, v1
	v_mov_b32_e32 v6, v1
	v_mov_b32_e32 v7, v1

; __global__ void __launch_bounds__(NTHR, 2) fwd_megakernel(Args args) {
;     ...
; #pragma unroll 1
;         for (int it = blockIdx.x; it < 1536; it += gridDim.x) { MKCTX();
;             if (it < 1024) b1_gla_item(C, li, it >> 7, (it >> 2) & 31, it & 3);
;             else { const int r = it - 1024; b1_ssd_item(C, li, r >> 6, (r >> 1) & 31, r & 1); }
;         }
.LBB0_1465:
	s_or_b64 exec, exec, s[12:13]
	s_waitcnt lgkmcnt(0)
	s_barrier
	s_load_dwordx2 s[24:25], s[0:1], 0xc0
	s_and_b64 vcc, exec, s[8:9]
	s_cbranch_vccnz .LBB0_1511
	v_mbcnt_hi_u32_b32 v126, -1, v235
	v_bfrev_b32_e32 v0, 0.5
	s_mov_b32 s27, 0
	s_movk_i32 s33, 0x2e00
	s_movk_i32 s54, 0x2000
	v_mov_b32_e32 v85, 0
	s_mov_b32 s55, 0x800000
	s_mov_b32 s56, 0x3f317217
	s_mov_b32 s57, 0x7f800000
	v_mov_b32_e32 v124, 0x25c00000
	s_mov_b64 s[28:29], 0x1800
	s_mov_b32 s58, 0xb000
	s_mov_b32 s59, 0xe000
	s_mov_b32 s60, 0x11000
	s_mov_b32 s61, 0x14000
	s_movk_i32 s62, 0x1000
	s_mov_b64 s[30:31], 0x3000
	s_movk_i32 s63, 0x3000
	s_mov_b64 s[34:35], 0x4800
	s_movk_i32 s64, 0x4000
	s_movk_i32 s65, 0x90
	s_mov_b32 s66, 0xffff0000
	s_mov_b32 s67, 0xbfb8aa3b
	s_movk_i32 s68, 0x7fff
	s_movk_i32 s72, 0x80
	s_mov_b64 s[36:37], 0x1000
	s_mov_b32 s73, 0x12000
	s_add_i32 s74, 0, 0x12000
	s_mov_b64 s[38:39], 0x1dc00000
	s_movk_i32 s75, 0x7f
	s_mov_b64 s[40:41], 0x8000
	s_mov_b32 s76, 0x9000
	s_mov_b32 s77, 0xa000
	s_mov_b32 s78, 0xc000
	s_mov_b32 s79, 0xd000
	s_mov_b32 s80, 0xf000
	s_mov_b32 s81, 0x3d800000
	s_movk_i32 s82, 0x7000
	s_mov_b32 s83, 0x15000
	s_mov_b32 s84, 0x18000
	s_mov_b32 s85, 0x1b000
	s_mov_b32 s86, 0x1e000
	s_mov_b32 s87, 0x21000
	s_mov_b32 s88, 0x24000
	s_mov_b32 s89, 0x26000
	s_mov_b32 s90, 0x29000
	s_mov_b32 s91, 0x2c000
	s_mov_b64 s[42:43], 0x21c00000
	s_mov_b32 s92, 0x21c01000
	v_mov_b32_e32 v125, 0x41b17218
	v_and_b32_e32 v127, 64, v126
	v_add_u32_e32 v128, -1, v126
	v_add_u32_e32 v129, -2, v126
	v_add_u32_e32 v130, -4, v126
	v_add_u32_e32 v131, -8, v126
	v_add_u32_e32 v132, -16, v126
	v_subrev_u32_e32 v133, 32, v126
	v_lshl_or_b32 v134, v126, 2, v0
	s_and_b32 s93, s2, 7
	s_lshl_b32 s93, s93, 7
	s_lshr_b32 s10, s2, 3
	s_add_u32 s93, s93, s10
	s_mov_b32 m0, 0
	s_branch .LBB0_1469

; __global__ void __launch_bounds__(NTHR, 2) fwd_megakernel(Args args) {
;     ...
;         for (int it = blockIdx.x; it < 1536; it += gridDim.x) { MKCTX();
.LBB0_1468:
	s_add_u32 s10, m0, 1
	s_mov_b32 m0, s10
	s_add_i32 s93, s93, 32
	s_cmp_eq_u32 s10, 4
	s_cbranch_scc0 .Lrg_skip_b1l1
	s_and_b32 s10, s2, 7
	s_lshl_b32 s10, s10, 6
	s_sub_i32 s93, s93, s10
	s_addk_i32 s93, 0x380

; __device__ __forceinline__ float bf2f(unsigned h) { return __uint_as_float(h << 16); }
; __device__ __forceinline__ unsigned pk2(float lo, float hi) { return pg8::cvt_pk_bf16(lo, hi); }
; __device__ __forceinline__ void b2_scan(const Ctx& C) {
;     ...
;     if (!gla) { const int b = r >> 13, h = (r >> 9) & 15, e = r & 511;
;         base = (bf16*)(C.ws + WS_HS) + ((size_t)(b * NC) * 16 + h) * 8192 + (size_t)e * 8; vstride = 512 * 8; cstride = (size_t)16 * 8192; dec = SDEC + (b * NC) * 16 + h; dstride = 16; }
;     else { const int b = r >> 13, h = (r >> 11) & 3, q = r & 2047, doct = q & 15, vp = q >> 4;
;         base = (bf16*)(C.ws + WS_GS) + ((size_t)(b * NC) * 4 + h) * 32768 + (size_t)(2 * vp) * 128 + doct * 8; vstride = 128; cstride = (size_t)4 * 32768; dec = GDEC + ((b * NC) * 4 + h) * 128 + doct * 8; dstride = 512; }
;     float run[2][8];
; #pragma unroll
;     for (int j = 0; j < 2; ++j)
; #pragma unroll
;         for (int q = 0; q < 8; ++q) run[j][q] = 0.f;
;     v4u loc[2][4][2]; f32x4 d0[2][4], d1[2][4];
;     ...
;     B2_LOAD(0, 0);
; #pragma unroll
;     for (int g = 0; g < 8; ++g) {
;         const int cur = g & 1;
;         if (g + 1 < 8) B2_LOAD(g + 1, cur ^ 1);
; #pragma unroll
;         for (int k = 0; k < 4; ++k) {
;             const int c = 4 * g + k;
;             const float dd[8] = {d0[cur][k][0], d0[cur][k][1], d0[cur][k][2], d0[cur][k][3], d1[cur][k][0], d1[cur][k][1], d1[cur][k][2], d1[cur][k][3]};
; #pragma unroll
;             for (int j = 0; j < 2; ++j) {
;                 v4u o; o.x = pk2(run[j][0], run[j][1]); o.y = pk2(run[j][2], run[j][3]); o.z = pk2(run[j][4], run[j][5]); o.w = pk2(run[j][6], run[j][7]);
;                 __builtin_nontemporal_store(o, (v4u*)(base + (size_t)c * cstride + (size_t)j * vstride));
;                 const unsigned lw[4] = {loc[cur][k][j].x, loc[cur][k][j].y, loc[cur][k][j].z, loc[cur][k][j].w};
; #pragma unroll
;                 for (int q = 0; q < 4; ++q) {
;                     run[j][2 * q] = dd[2 * q] * run[j][2 * q] + bf2f(lw[q] & 0xffffu);
;                     run[j][2 * q + 1] = dd[2 * q + 1] * run[j][2 * q + 1] + __uint_as_float(lw[q] & 0xffff0000u);
;                 }
;             }
;         }
;     }
.LBB0_1563:
	s_or_b64 exec, exec, s[12:13]
	v_mov_b32_e32 v8, v234
	s_mov_b32 s10, 0
	s_waitcnt lgkmcnt(0)
	s_barrier
	s_load_dwordx2 s[18:19], s[0:1], 0xc0
	s_mov_b64 s[14:15], exec
	s_cmp_ge_u32 s2, 256
	s_cbranch_scc1 .Lb2_end_l1
	v_mov_b32_e32 v16, 0
	v_mov_b32_e32 v17, 0
	v_mov_b32_e32 v18, 0
	v_mov_b32_e32 v19, 0
	v_mov_b32_e32 v20, 0
	v_mov_b32_e32 v21, 0
	v_mov_b32_e32 v22, 0
	v_mov_b32_e32 v23, 0
	v_mov_b32_e32 v24, 0
	v_mov_b32_e32 v25, 0
	v_mov_b32_e32 v26, 0
	v_mov_b32_e32 v27, 0
	v_mov_b32_e32 v28, 0
	v_mov_b32_e32 v29, 0
	v_mov_b32_e32 v30, 0
	v_mov_b32_e32 v31, 0
	v_mov_b32_e32 v4, 0
	s_cmp_ge_u32 s2, 128
	s_cbranch_scc1 .Lb2_gla_l1
	s_and_b32 s10, s2, 7
	s_lshl_b32 s10, s10, 9
	s_lshr_b32 s16, s2, 3
	s_add_u32 s10, s10, s16
	s_lshl_b32 s16, s10, 2
	s_lshl_b32 s10, s10, 14
	v_lshlrev_b32_e32 v2, 4, v234
	v_add_u32_e32 v3, 0x2000, v2
	s_waitcnt lgkmcnt(0)
	s_add_u32 s10, s10, s18
	s_addc_u32 s11, s19, 0
	s_add_u32 s10, s10, 0x1dc00000
	s_addc_u32 s11, s11, 0
	s_add_u32 s16, s16, s18
	s_addc_u32 s17, s19, 0
	s_add_u32 s16, s16, 0x25c00000
	s_addc_u32 s17, s17, 0
	s_mov_b32 s12, s10
	s_mov_b32 s13, s11
	global_load_dwordx4 v[64:67], v2, s[10:11] nt
	global_load_dwordx4 v[68:71], v3, s[10:11] nt
	global_load_dword v72, v4, s[16:17]
	s_add_u32 s10, s10, 0x40000
	s_addc_u32 s11, s11, 0
	s_add_u32 s16, s16, 64
	s_addc_u32 s17, s17, 0
	global_load_dwordx4 v[80:83], v2, s[10:11] nt
	global_load_dwordx4 v[84:87], v3, s[10:11] nt
	global_load_dword v88, v4, s[16:17]
	s_add_u32 s10, s10, 0x40000
	s_addc_u32 s11, s11, 0
	s_add_u32 s16, s16, 64
	s_addc_u32 s17, s17, 0
	global_load_dwordx4 v[96:99], v2, s[10:11] nt
	global_load_dwordx4 v[100:103], v3, s[10:11] nt
	global_load_dword v104, v4, s[16:17]
	s_add_u32 s10, s10, 0x40000
	s_addc_u32 s11, s11, 0
	s_add_u32 s16, s16, 64
	s_addc_u32 s17, s17, 0
	global_load_dwordx4 v[112:115], v2, s[10:11] nt
	global_load_dwordx4 v[116:119], v3, s[10:11] nt
	global_load_dword v120, v4, s[16:17]
	s_add_u32 s10, s10, 0x40000
	s_addc_u32 s11, s11, 0
	s_add_u32 s16, s16, 64
	s_addc_u32 s17, s17, 0
	global_load_dwordx4 v[128:131], v2, s[10:11] nt
	global_load_dwordx4 v[132:135], v3, s[10:11] nt
	global_load_dword v136, v4, s[16:17]
	s_add_u32 s10, s10, 0x40000
	s_addc_u32 s11, s11, 0
	s_add_u32 s16, s16, 64
	s_addc_u32 s17, s17, 0
	global_load_dwordx4 v[144:147], v2, s[10:11] nt
	global_load_dwordx4 v[148:151], v3, s[10:11] nt
	global_load_dword v152, v4, s[16:17]
	s_add_u32 s10, s10, 0x40000
	s_addc_u32 s11, s11, 0
	s_add_u32 s16, s16, 64
	s_addc_u32 s17, s17, 0
	global_load_dwordx4 v[160:163], v2, s[10:11] nt
	global_load_dwordx4 v[164:167], v3, s[10:11] nt
	global_load_dword v168, v4, s[16:17]
	s_add_u32 s10, s10, 0x40000
	s_addc_u32 s11, s11, 0
	s_add_u32 s16, s16, 64
	s_addc_u32 s17, s17, 0
	global_load_dwordx4 v[176:179], v2, s[10:11] nt
	global_load_dwordx4 v[180:183], v3, s[10:11] nt
	global_load_dword v184, v4, s[16:17]
	s_add_u32 s10, s10, 0x40000
	s_addc_u32 s11, s11, 0
	s_add_u32 s16, s16, 64
	s_addc_u32 s17, s17, 0
	s_waitcnt vmcnt(21)
	v_cvt_pk_bf16_f32 v32, v16, v17
	v_cvt_pk_bf16_f32 v33, v18, v19
	v_cvt_pk_bf16_f32 v34, v20, v21
	v_cvt_pk_bf16_f32 v35, v22, v23
	global_store_dwordx4 v2, v[32:35], s[12:13] nt
	v_cvt_pk_bf16_f32 v36, v24, v25
	v_cvt_pk_bf16_f32 v37, v26, v27
	v_cvt_pk_bf16_f32 v38, v28, v29
	v_cvt_pk_bf16_f32 v39, v30, v31
	global_store_dwordx4 v3, v[36:39], s[12:13] nt
	s_add_u32 s12, s12, 0x40000
	s_addc_u32 s13, s13, 0
	v_lshlrev_b32_e32 v48, 16, v64
	v_and_b32_e32 v49, 0xffff0000, v64
	v_fma_f32 v16, v72, v16, v48
	v_fma_f32 v17, v72, v17, v49
	v_lshlrev_b32_e32 v48, 16, v65
	v_and_b32_e32 v49, 0xffff0000, v65
	v_fma_f32 v18, v72, v18, v48
	v_fma_f32 v19, v72, v19, v49
	v_lshlrev_b32_e32 v48, 16, v66
	v_and_b32_e32 v49, 0xffff0000, v66
	v_fma_f32 v20, v72, v20, v48
	v_fma_f32 v21, v72, v21, v49
	v_lshlrev_b32_e32 v48, 16, v67
	v_and_b32_e32 v49, 0xffff0000, v67
	v_fma_f32 v22, v72, v22, v48
	v_fma_f32 v23, v72, v23, v49
	v_lshlrev_b32_e32 v48, 16, v68
	v_and_b32_e32 v49, 0xffff0000, v68
	v_fma_f32 v24, v72, v24, v48
	v_fma_f32 v25, v72, v25, v49
	v_lshlrev_b32_e32 v48, 16, v69
	v_and_b32_e32 v49, 0xffff0000, v69
	v_fma_f32 v26, v72, v26, v48
	v_fma_f32 v27, v72, v27, v49
	v_lshlrev_b32_e32 v48, 16, v70
	v_and_b32_e32 v49, 0xffff0000, v70
	v_fma_f32 v28, v72, v28, v48
	v_fma_f32 v29, v72, v29, v49
	v_lshlrev_b32_e32 v48, 16, v71
	v_and_b32_e32 v49, 0xffff0000, v71
	v_fma_f32 v30, v72, v30, v48
	v_fma_f32 v31, v72, v31, v49
	global_load_dwordx4 v[64:67], v2, s[10:11] nt
	global_load_dwordx4 v[68:71], v3, s[10:11] nt
	global_load_dword v72, v4, s[16:17]
	s_add_u32 s10, s10, 0x40000
	s_addc_u32 s11, s11, 0
	s_add_u32 s16, s16, 64
	s_addc_u32 s17, s17, 0
	s_waitcnt vmcnt(23)
	v_cvt_pk_bf16_f32 v40, v16, v17
	v_cvt_pk_bf16_f32 v41, v18, v19
	v_cvt_pk_bf16_f32 v42, v20, v21
	v_cvt_pk_bf16_f32 v43, v22, v23
	global_store_dwordx4 v2, v[40:43], s[12:13] nt
	v_cvt_pk_bf16_f32 v44, v24, v25
	v_cvt_pk_bf16_f32 v45, v26, v27
	v_cvt_pk_bf16_f32 v46, v28, v29
	v_cvt_pk_bf16_f32 v47, v30, v31
	global_store_dwordx4 v3, v[44:47], s[12:13] nt
	s_add_u32 s12, s12, 0x40000
	s_addc_u32 s13, s13, 0
	v_lshlrev_b32_e32 v48, 16, v80
	v_and_b32_e32 v49, 0xffff0000, v80
	v_fma_f32 v16, v88, v16, v48
	v_fma_f32 v17, v88, v17, v49
	v_lshlrev_b32_e32 v48, 16, v81
	v_and_b32_e32 v49, 0xffff0000, v81
	v_fma_f32 v18, v88, v18, v48
	v_fma_f32 v19, v88, v19, v49
	v_lshlrev_b32_e32 v48, 16, v82
	v_and_b32_e32 v49, 0xffff0000, v82
	v_fma_f32 v20, v88, v20, v48
	v_fma_f32 v21, v88, v21, v49
	v_lshlrev_b32_e32 v48, 16, v83
	v_and_b32_e32 v49, 0xffff0000, v83
	v_fma_f32 v22, v88, v22, v48
	v_fma_f32 v23, v88, v23, v49
	v_lshlrev_b32_e32 v48, 16, v84
	v_and_b32_e32 v49, 0xffff0000, v84
	v_fma_f32 v24, v88, v24, v48
	v_fma_f32 v25, v88, v25, v49
	v_lshlrev_b32_e32 v48, 16, v85
	v_and_b32_e32 v49, 0xffff0000, v85
	v_fma_f32 v26, v88, v26, v48
	v_fma_f32 v27, v88, v27, v49
	v_lshlrev_b32_e32 v48, 16, v86
	v_and_b32_e32 v49, 0xffff0000, v86
	v_fma_f32 v28, v88, v28, v48
	v_fma_f32 v29, v88, v29, v49
	v_lshlrev_b32_e32 v48, 16, v87
	v_and_b32_e32 v49, 0xffff0000, v87
	v_fma_f32 v30, v88, v30, v48
	v_fma_f32 v31, v88, v31, v49
	global_load_dwordx4 v[80:83], v2, s[10:11] nt
	global_load_dwordx4 v[84:87], v3, s[10:11] nt
	global_load_dword v88, v4, s[16:17]
	s_add_u32 s10, s10, 0x40000
	s_addc_u32 s11, s11, 0
	s_add_u32 s16, s16, 64
	s_addc_u32 s17, s17, 0
	s_waitcnt vmcnt(25)
; __device__ __forceinline__ float bf2f(unsigned h) { return __uint_as_float(h << 16); }
; __device__ __forceinline__ unsigned pk2(float lo, float hi) { return pg8::cvt_pk_bf16(lo, hi); }
; __device__ __forceinline__ void b2_scan(const Ctx& C) {
;     ...
;     B2_LOAD(0, 0);
; #pragma unroll
;     for (int g = 0; g < 8; ++g) {
;         const int cur = g & 1;
;         if (g + 1 < 8) B2_LOAD(g + 1, cur ^ 1);
; #pragma unroll
;         for (int k = 0; k < 4; ++k) {
;             const int c = 4 * g + k;
;             const float dd[8] = {d0[cur][k][0], d0[cur][k][1], d0[cur][k][2], d0[cur][k][3], d1[cur][k][0], d1[cur][k][1], d1[cur][k][2], d1[cur][k][3]};
; #pragma unroll
;             for (int j = 0; j < 2; ++j) {
;                 v4u o; o.x = pk2(run[j][0], run[j][1]); o.y = pk2(run[j][2], run[j][3]); o.z = pk2(run[j][4], run[j][5]); o.w = pk2(run[j][6], run[j][7]);
;                 __builtin_nontemporal_store(o, (v4u*)(base + (size_t)c * cstride + (size_t)j * vstride));
;                 const unsigned lw[4] = {loc[cur][k][j].x, loc[cur][k][j].y, loc[cur][k][j].z, loc[cur][k][j].w};
; #pragma unroll
;                 for (int q = 0; q < 4; ++q) {
;                     run[j][2 * q] = dd[2 * q] * run[j][2 * q] + bf2f(lw[q] & 0xffffu);
;                     run[j][2 * q + 1] = dd[2 * q + 1] * run[j][2 * q + 1] + __uint_as_float(lw[q] & 0xffff0000u);
;                 }
;             }
;         }
;     }
	v_cvt_pk_bf16_f32 v32, v16, v17
	v_cvt_pk_bf16_f32 v33, v18, v19
	v_cvt_pk_bf16_f32 v34, v20, v21
	v_cvt_pk_bf16_f32 v35, v22, v23
	global_store_dwordx4 v2, v[32:35], s[12:13] nt
	v_cvt_pk_bf16_f32 v36, v24, v25
	v_cvt_pk_bf16_f32 v37, v26, v27
	v_cvt_pk_bf16_f32 v38, v28, v29
	v_cvt_pk_bf16_f32 v39, v30, v31
	global_store_dwordx4 v3, v[36:39], s[12:13] nt
	s_add_u32 s12, s12, 0x40000
	s_addc_u32 s13, s13, 0
	v_lshlrev_b32_e32 v48, 16, v96
	v_and_b32_e32 v49, 0xffff0000, v96
	v_fma_f32 v16, v104, v16, v48
	v_fma_f32 v17, v104, v17, v49
	v_lshlrev_b32_e32 v48, 16, v97
	v_and_b32_e32 v49, 0xffff0000, v97
	v_fma_f32 v18, v104, v18, v48
	v_fma_f32 v19, v104, v19, v49
	v_lshlrev_b32_e32 v48, 16, v98
	v_and_b32_e32 v49, 0xffff0000, v98
	v_fma_f32 v20, v104, v20, v48
	v_fma_f32 v21, v104, v21, v49
	v_lshlrev_b32_e32 v48, 16, v99
	v_and_b32_e32 v49, 0xffff0000, v99
	v_fma_f32 v22, v104, v22, v48
	v_fma_f32 v23, v104, v23, v49
	v_lshlrev_b32_e32 v48, 16, v100
	v_and_b32_e32 v49, 0xffff0000, v100
	v_fma_f32 v24, v104, v24, v48
	v_fma_f32 v25, v104, v25, v49
	v_lshlrev_b32_e32 v48, 16, v101
	v_and_b32_e32 v49, 0xffff0000, v101
	v_fma_f32 v26, v104, v26, v48
	v_fma_f32 v27, v104, v27, v49
	v_lshlrev_b32_e32 v48, 16, v102
	v_and_b32_e32 v49, 0xffff0000, v102
	v_fma_f32 v28, v104, v28, v48
	v_fma_f32 v29, v104, v29, v49
	v_lshlrev_b32_e32 v48, 16, v103
	v_and_b32_e32 v49, 0xffff0000, v103
	v_fma_f32 v30, v104, v30, v48
	v_fma_f32 v31, v104, v31, v49
	global_load_dwordx4 v[96:99], v2, s[10:11] nt
	global_load_dwordx4 v[100:103], v3, s[10:11] nt
	global_load_dword v104, v4, s[16:17]
	s_add_u32 s10, s10, 0x40000
	s_addc_u32 s11, s11, 0
	s_add_u32 s16, s16, 64
	s_addc_u32 s17, s17, 0
	s_waitcnt vmcnt(27)
	v_cvt_pk_bf16_f32 v40, v16, v17
	v_cvt_pk_bf16_f32 v41, v18, v19
	v_cvt_pk_bf16_f32 v42, v20, v21
	v_cvt_pk_bf16_f32 v43, v22, v23
	global_store_dwordx4 v2, v[40:43], s[12:13] nt
	v_cvt_pk_bf16_f32 v44, v24, v25
	v_cvt_pk_bf16_f32 v45, v26, v27
	v_cvt_pk_bf16_f32 v46, v28, v29
	v_cvt_pk_bf16_f32 v47, v30, v31
	global_store_dwordx4 v3, v[44:47], s[12:13] nt
	s_add_u32 s12, s12, 0x40000
	s_addc_u32 s13, s13, 0
	v_lshlrev_b32_e32 v48, 16, v112
	v_and_b32_e32 v49, 0xffff0000, v112
	v_fma_f32 v16, v120, v16, v48
	v_fma_f32 v17, v120, v17, v49
	v_lshlrev_b32_e32 v48, 16, v113
	v_and_b32_e32 v49, 0xffff0000, v113
	v_fma_f32 v18, v120, v18, v48
	v_fma_f32 v19, v120, v19, v49
	v_lshlrev_b32_e32 v48, 16, v114
	v_and_b32_e32 v49, 0xffff0000, v114
	v_fma_f32 v20, v120, v20, v48
	v_fma_f32 v21, v120, v21, v49
	v_lshlrev_b32_e32 v48, 16, v115
	v_and_b32_e32 v49, 0xffff0000, v115
	v_fma_f32 v22, v120, v22, v48
	v_fma_f32 v23, v120, v23, v49
	v_lshlrev_b32_e32 v48, 16, v116
	v_and_b32_e32 v49, 0xffff0000, v116
	v_fma_f32 v24, v120, v24, v48
	v_fma_f32 v25, v120, v25, v49
	v_lshlrev_b32_e32 v48, 16, v117
	v_and_b32_e32 v49, 0xffff0000, v117
	v_fma_f32 v26, v120, v26, v48
	v_fma_f32 v27, v120, v27, v49
	v_lshlrev_b32_e32 v48, 16, v118
	v_and_b32_e32 v49, 0xffff0000, v118
	v_fma_f32 v28, v120, v28, v48
	v_fma_f32 v29, v120, v29, v49
	v_lshlrev_b32_e32 v48, 16, v119
	v_and_b32_e32 v49, 0xffff0000, v119
	v_fma_f32 v30, v120, v30, v48
	v_fma_f32 v31, v120, v31, v49
	global_load_dwordx4 v[112:115], v2, s[10:11] nt
	global_load_dwordx4 v[116:119], v3, s[10:11] nt
	global_load_dword v120, v4, s[16:17]
	s_add_u32 s10, s10, 0x40000
	s_addc_u32 s11, s11, 0
	s_add_u32 s16, s16, 64
	s_addc_u32 s17, s17, 0
	s_waitcnt vmcnt(29)
	v_cvt_pk_bf16_f32 v32, v16, v17
	v_cvt_pk_bf16_f32 v33, v18, v19
	v_cvt_pk_bf16_f32 v34, v20, v21
	v_cvt_pk_bf16_f32 v35, v22, v23
	global_store_dwordx4 v2, v[32:35], s[12:13] nt
	v_cvt_pk_bf16_f32 v36, v24, v25
	v_cvt_pk_bf16_f32 v37, v26, v27
	v_cvt_pk_bf16_f32 v38, v28, v29
	v_cvt_pk_bf16_f32 v39, v30, v31
	global_store_dwordx4 v3, v[36:39], s[12:13] nt
	s_add_u32 s12, s12, 0x40000
	s_addc_u32 s13, s13, 0
	v_lshlrev_b32_e32 v48, 16, v128
	v_and_b32_e32 v49, 0xffff0000, v128
	v_fma_f32 v16, v136, v16, v48
	v_fma_f32 v17, v136, v17, v49
	v_lshlrev_b32_e32 v48, 16, v129
	v_and_b32_e32 v49, 0xffff0000, v129
	v_fma_f32 v18, v136, v18, v48
	v_fma_f32 v19, v136, v19, v49
	v_lshlrev_b32_e32 v48, 16, v130
	v_and_b32_e32 v49, 0xffff0000, v130
	v_fma_f32 v20, v136, v20, v48
	v_fma_f32 v21, v136, v21, v49
	v_lshlrev_b32_e32 v48, 16, v131
	v_and_b32_e32 v49, 0xffff0000, v131
	v_fma_f32 v22, v136, v22, v48
	v_fma_f32 v23, v136, v23, v49
	v_lshlrev_b32_e32 v48, 16, v132
	v_and_b32_e32 v49, 0xffff0000, v132
	v_fma_f32 v24, v136, v24, v48
	v_fma_f32 v25, v136, v25, v49
	v_lshlrev_b32_e32 v48, 16, v133
	v_and_b32_e32 v49, 0xffff0000, v133
	v_fma_f32 v26, v136, v26, v48
	v_fma_f32 v27, v136, v27, v49
	v_lshlrev_b32_e32 v48, 16, v134
	v_and_b32_e32 v49, 0xffff0000, v134
	v_fma_f32 v28, v136, v28, v48
	v_fma_f32 v29, v136, v29, v49
	v_lshlrev_b32_e32 v48, 16, v135
	v_and_b32_e32 v49, 0xffff0000, v135
	v_fma_f32 v30, v136, v30, v48
	v_fma_f32 v31, v136, v31, v49
	global_load_dwordx4 v[128:131], v2, s[10:11] nt
	global_load_dwordx4 v[132:135], v3, s[10:11] nt
	global_load_dword v136, v4, s[16:17]
	s_add_u32 s10, s10, 0x40000
	s_addc_u32 s11, s11, 0
	s_add_u32 s16, s16, 64
	s_addc_u32 s17, s17, 0
	s_waitcnt vmcnt(31)
; __device__ __forceinline__ float bf2f(unsigned h) { return __uint_as_float(h << 16); }
; __device__ __forceinline__ unsigned pk2(float lo, float hi) { return pg8::cvt_pk_bf16(lo, hi); }
; __device__ __forceinline__ void b2_scan(const Ctx& C) {
;     ...
;     B2_LOAD(0, 0);
; #pragma unroll
;     for (int g = 0; g < 8; ++g) {
;         const int cur = g & 1;
;         if (g + 1 < 8) B2_LOAD(g + 1, cur ^ 1);
; #pragma unroll
;         for (int k = 0; k < 4; ++k) {
;             const int c = 4 * g + k;
;             const float dd[8] = {d0[cur][k][0], d0[cur][k][1], d0[cur][k][2], d0[cur][k][3], d1[cur][k][0], d1[cur][k][1], d1[cur][k][2], d1[cur][k][3]};
; #pragma unroll
;             for (int j = 0; j < 2; ++j) {
;                 v4u o; o.x = pk2(run[j][0], run[j][1]); o.y = pk2(run[j][2], run[j][3]); o.z = pk2(run[j][4], run[j][5]); o.w = pk2(run[j][6], run[j][7]);
;                 __builtin_nontemporal_store(o, (v4u*)(base + (size_t)c * cstride + (size_t)j * vstride));
;                 const unsigned lw[4] = {loc[cur][k][j].x, loc[cur][k][j].y, loc[cur][k][j].z, loc[cur][k][j].w};
; #pragma unroll
;                 for (int q = 0; q < 4; ++q) {
;                     run[j][2 * q] = dd[2 * q] * run[j][2 * q] + bf2f(lw[q] & 0xffffu);
;                     run[j][2 * q + 1] = dd[2 * q + 1] * run[j][2 * q + 1] + __uint_as_float(lw[q] & 0xffff0000u);
;                 }
;             }
;         }
;     }
	v_cvt_pk_bf16_f32 v40, v16, v17
	v_cvt_pk_bf16_f32 v41, v18, v19
	v_cvt_pk_bf16_f32 v42, v20, v21
	v_cvt_pk_bf16_f32 v43, v22, v23
	global_store_dwordx4 v2, v[40:43], s[12:13] nt
	v_cvt_pk_bf16_f32 v44, v24, v25
	v_cvt_pk_bf16_f32 v45, v26, v27
	v_cvt_pk_bf16_f32 v46, v28, v29
	v_cvt_pk_bf16_f32 v47, v30, v31
	global_store_dwordx4 v3, v[44:47], s[12:13] nt
	s_add_u32 s12, s12, 0x40000
	s_addc_u32 s13, s13, 0
	v_lshlrev_b32_e32 v48, 16, v144
	v_and_b32_e32 v49, 0xffff0000, v144
	v_fma_f32 v16, v152, v16, v48
	v_fma_f32 v17, v152, v17, v49
	v_lshlrev_b32_e32 v48, 16, v145
	v_and_b32_e32 v49, 0xffff0000, v145
	v_fma_f32 v18, v152, v18, v48
	v_fma_f32 v19, v152, v19, v49
	v_lshlrev_b32_e32 v48, 16, v146
	v_and_b32_e32 v49, 0xffff0000, v146
	v_fma_f32 v20, v152, v20, v48
	v_fma_f32 v21, v152, v21, v49
	v_lshlrev_b32_e32 v48, 16, v147
	v_and_b32_e32 v49, 0xffff0000, v147
	v_fma_f32 v22, v152, v22, v48
	v_fma_f32 v23, v152, v23, v49
	v_lshlrev_b32_e32 v48, 16, v148
	v_and_b32_e32 v49, 0xffff0000, v148
	v_fma_f32 v24, v152, v24, v48
	v_fma_f32 v25, v152, v25, v49
	v_lshlrev_b32_e32 v48, 16, v149
	v_and_b32_e32 v49, 0xffff0000, v149
	v_fma_f32 v26, v152, v26, v48
	v_fma_f32 v27, v152, v27, v49
	v_lshlrev_b32_e32 v48, 16, v150
	v_and_b32_e32 v49, 0xffff0000, v150
	v_fma_f32 v28, v152, v28, v48
	v_fma_f32 v29, v152, v29, v49
	v_lshlrev_b32_e32 v48, 16, v151
	v_and_b32_e32 v49, 0xffff0000, v151
	v_fma_f32 v30, v152, v30, v48
	v_fma_f32 v31, v152, v31, v49
	global_load_dwordx4 v[144:147], v2, s[10:11] nt
	global_load_dwordx4 v[148:151], v3, s[10:11] nt
	global_load_dword v152, v4, s[16:17]
	s_add_u32 s10, s10, 0x40000
	s_addc_u32 s11, s11, 0
	s_add_u32 s16, s16, 64
	s_addc_u32 s17, s17, 0
	s_waitcnt vmcnt(33)
	v_cvt_pk_bf16_f32 v32, v16, v17
	v_cvt_pk_bf16_f32 v33, v18, v19
	v_cvt_pk_bf16_f32 v34, v20, v21
	v_cvt_pk_bf16_f32 v35, v22, v23
	global_store_dwordx4 v2, v[32:35], s[12:13] nt
	v_cvt_pk_bf16_f32 v36, v24, v25
	v_cvt_pk_bf16_f32 v37, v26, v27
	v_cvt_pk_bf16_f32 v38, v28, v29
	v_cvt_pk_bf16_f32 v39, v30, v31
	global_store_dwordx4 v3, v[36:39], s[12:13] nt
	s_add_u32 s12, s12, 0x40000
	s_addc_u32 s13, s13, 0
	v_lshlrev_b32_e32 v48, 16, v160
	v_and_b32_e32 v49, 0xffff0000, v160
	v_fma_f32 v16, v168, v16, v48
	v_fma_f32 v17, v168, v17, v49
	v_lshlrev_b32_e32 v48, 16, v161
	v_and_b32_e32 v49, 0xffff0000, v161
	v_fma_f32 v18, v168, v18, v48
	v_fma_f32 v19, v168, v19, v49
	v_lshlrev_b32_e32 v48, 16, v162
	v_and_b32_e32 v49, 0xffff0000, v162
	v_fma_f32 v20, v168, v20, v48
	v_fma_f32 v21, v168, v21, v49
	v_lshlrev_b32_e32 v48, 16, v163
	v_and_b32_e32 v49, 0xffff0000, v163
	v_fma_f32 v22, v168, v22, v48
	v_fma_f32 v23, v168, v23, v49
	v_lshlrev_b32_e32 v48, 16, v164
	v_and_b32_e32 v49, 0xffff0000, v164
	v_fma_f32 v24, v168, v24, v48
	v_fma_f32 v25, v168, v25, v49
	v_lshlrev_b32_e32 v48, 16, v165
	v_and_b32_e32 v49, 0xffff0000, v165
	v_fma_f32 v26, v168, v26, v48
	v_fma_f32 v27, v168, v27, v49
	v_lshlrev_b32_e32 v48, 16, v166
	v_and_b32_e32 v49, 0xffff0000, v166
	v_fma_f32 v28, v168, v28, v48
	v_fma_f32 v29, v168, v29, v49
	v_lshlrev_b32_e32 v48, 16, v167
	v_and_b32_e32 v49, 0xffff0000, v167
	v_fma_f32 v30, v168, v30, v48
	v_fma_f32 v31, v168, v31, v49
	global_load_dwordx4 v[160:163], v2, s[10:11] nt
	global_load_dwordx4 v[164:167], v3, s[10:11] nt
	global_load_dword v168, v4, s[16:17]
	s_add_u32 s10, s10, 0x40000
	s_addc_u32 s11, s11, 0
	s_add_u32 s16, s16, 64
	s_addc_u32 s17, s17, 0
	s_waitcnt vmcnt(35)
	v_cvt_pk_bf16_f32 v40, v16, v17
	v_cvt_pk_bf16_f32 v41, v18, v19
	v_cvt_pk_bf16_f32 v42, v20, v21
	v_cvt_pk_bf16_f32 v43, v22, v23
	global_store_dwordx4 v2, v[40:43], s[12:13] nt
	v_cvt_pk_bf16_f32 v44, v24, v25
	v_cvt_pk_bf16_f32 v45, v26, v27
	v_cvt_pk_bf16_f32 v46, v28, v29
	v_cvt_pk_bf16_f32 v47, v30, v31
	global_store_dwordx4 v3, v[44:47], s[12:13] nt
	s_add_u32 s12, s12, 0x40000
	s_addc_u32 s13, s13, 0
	v_lshlrev_b32_e32 v48, 16, v176
	v_and_b32_e32 v49, 0xffff0000, v176
	v_fma_f32 v16, v184, v16, v48
	v_fma_f32 v17, v184, v17, v49
	v_lshlrev_b32_e32 v48, 16, v177
	v_and_b32_e32 v49, 0xffff0000, v177
	v_fma_f32 v18, v184, v18, v48
	v_fma_f32 v19, v184, v19, v49
	v_lshlrev_b32_e32 v48, 16, v178
	v_and_b32_e32 v49, 0xffff0000, v178
	v_fma_f32 v20, v184, v20, v48
	v_fma_f32 v21, v184, v21, v49
	v_lshlrev_b32_e32 v48, 16, v179
	v_and_b32_e32 v49, 0xffff0000, v179
	v_fma_f32 v22, v184, v22, v48
	v_fma_f32 v23, v184, v23, v49
	v_lshlrev_b32_e32 v48, 16, v180
	v_and_b32_e32 v49, 0xffff0000, v180
	v_fma_f32 v24, v184, v24, v48
	v_fma_f32 v25, v184, v25, v49
	v_lshlrev_b32_e32 v48, 16, v181
	v_and_b32_e32 v49, 0xffff0000, v181
	v_fma_f32 v26, v184, v26, v48
	v_fma_f32 v27, v184, v27, v49
	v_lshlrev_b32_e32 v48, 16, v182
	v_and_b32_e32 v49, 0xffff0000, v182
	v_fma_f32 v28, v184, v28, v48
	v_fma_f32 v29, v184, v29, v49
	v_lshlrev_b32_e32 v48, 16, v183
	v_and_b32_e32 v49, 0xffff0000, v183
	v_fma_f32 v30, v184, v30, v48
	v_fma_f32 v31, v184, v31, v49
	global_load_dwordx4 v[176:179], v2, s[10:11] nt
	global_load_dwordx4 v[180:183], v3, s[10:11] nt
	global_load_dword v184, v4, s[16:17]
	s_add_u32 s10, s10, 0x40000
	s_addc_u32 s11, s11, 0
	s_add_u32 s16, s16, 64
	s_addc_u32 s17, s17, 0
	s_waitcnt vmcnt(35)
; __device__ __forceinline__ float bf2f(unsigned h) { return __uint_as_float(h << 16); }
; __device__ __forceinline__ unsigned pk2(float lo, float hi) { return pg8::cvt_pk_bf16(lo, hi); }
; __device__ __forceinline__ void b2_scan(const Ctx& C) {
;     ...
;     B2_LOAD(0, 0);
; #pragma unroll
;     for (int g = 0; g < 8; ++g) {
;         const int cur = g & 1;
;         if (g + 1 < 8) B2_LOAD(g + 1, cur ^ 1);
; #pragma unroll
;         for (int k = 0; k < 4; ++k) {
;             const int c = 4 * g + k;
;             const float dd[8] = {d0[cur][k][0], d0[cur][k][1], d0[cur][k][2], d0[cur][k][3], d1[cur][k][0], d1[cur][k][1], d1[cur][k][2], d1[cur][k][3]};
; #pragma unroll
;             for (int j = 0; j < 2; ++j) {
;                 v4u o; o.x = pk2(run[j][0], run[j][1]); o.y = pk2(run[j][2], run[j][3]); o.z = pk2(run[j][4], run[j][5]); o.w = pk2(run[j][6], run[j][7]);
;                 __builtin_nontemporal_store(o, (v4u*)(base + (size_t)c * cstride + (size_t)j * vstride));
;                 const unsigned lw[4] = {loc[cur][k][j].x, loc[cur][k][j].y, loc[cur][k][j].z, loc[cur][k][j].w};
; #pragma unroll
;                 for (int q = 0; q < 4; ++q) {
;                     run[j][2 * q] = dd[2 * q] * run[j][2 * q] + bf2f(lw[q] & 0xffffu);
;                     run[j][2 * q + 1] = dd[2 * q + 1] * run[j][2 * q + 1] + __uint_as_float(lw[q] & 0xffff0000u);
;                 }
;             }
;         }
;     }
	v_cvt_pk_bf16_f32 v32, v16, v17
	v_cvt_pk_bf16_f32 v33, v18, v19
	v_cvt_pk_bf16_f32 v34, v20, v21
	v_cvt_pk_bf16_f32 v35, v22, v23
	global_store_dwordx4 v2, v[32:35], s[12:13] nt
	v_cvt_pk_bf16_f32 v36, v24, v25
	v_cvt_pk_bf16_f32 v37, v26, v27
	v_cvt_pk_bf16_f32 v38, v28, v29
	v_cvt_pk_bf16_f32 v39, v30, v31
	global_store_dwordx4 v3, v[36:39], s[12:13] nt
	s_add_u32 s12, s12, 0x40000
	s_addc_u32 s13, s13, 0
	v_lshlrev_b32_e32 v48, 16, v64
	v_and_b32_e32 v49, 0xffff0000, v64
	v_fma_f32 v16, v72, v16, v48
	v_fma_f32 v17, v72, v17, v49
	v_lshlrev_b32_e32 v48, 16, v65
	v_and_b32_e32 v49, 0xffff0000, v65
	v_fma_f32 v18, v72, v18, v48
	v_fma_f32 v19, v72, v19, v49
	v_lshlrev_b32_e32 v48, 16, v66
	v_and_b32_e32 v49, 0xffff0000, v66
	v_fma_f32 v20, v72, v20, v48
	v_fma_f32 v21, v72, v21, v49
	v_lshlrev_b32_e32 v48, 16, v67
	v_and_b32_e32 v49, 0xffff0000, v67
	v_fma_f32 v22, v72, v22, v48
	v_fma_f32 v23, v72, v23, v49
	v_lshlrev_b32_e32 v48, 16, v68
	v_and_b32_e32 v49, 0xffff0000, v68
	v_fma_f32 v24, v72, v24, v48
	v_fma_f32 v25, v72, v25, v49
	v_lshlrev_b32_e32 v48, 16, v69
	v_and_b32_e32 v49, 0xffff0000, v69
	v_fma_f32 v26, v72, v26, v48
	v_fma_f32 v27, v72, v27, v49
	v_lshlrev_b32_e32 v48, 16, v70
	v_and_b32_e32 v49, 0xffff0000, v70
	v_fma_f32 v28, v72, v28, v48
	v_fma_f32 v29, v72, v29, v49
	v_lshlrev_b32_e32 v48, 16, v71
	v_and_b32_e32 v49, 0xffff0000, v71
	v_fma_f32 v30, v72, v30, v48
	v_fma_f32 v31, v72, v31, v49
	global_load_dwordx4 v[64:67], v2, s[10:11] nt
	global_load_dwordx4 v[68:71], v3, s[10:11] nt
	global_load_dword v72, v4, s[16:17]
	s_add_u32 s10, s10, 0x40000
	s_addc_u32 s11, s11, 0
	s_add_u32 s16, s16, 64
	s_addc_u32 s17, s17, 0
	s_waitcnt vmcnt(35)
	v_cvt_pk_bf16_f32 v40, v16, v17
	v_cvt_pk_bf16_f32 v41, v18, v19
	v_cvt_pk_bf16_f32 v42, v20, v21
	v_cvt_pk_bf16_f32 v43, v22, v23
	global_store_dwordx4 v2, v[40:43], s[12:13] nt
	v_cvt_pk_bf16_f32 v44, v24, v25
	v_cvt_pk_bf16_f32 v45, v26, v27
	v_cvt_pk_bf16_f32 v46, v28, v29
	v_cvt_pk_bf16_f32 v47, v30, v31
	global_store_dwordx4 v3, v[44:47], s[12:13] nt
	s_add_u32 s12, s12, 0x40000
	s_addc_u32 s13, s13, 0
	v_lshlrev_b32_e32 v48, 16, v80
	v_and_b32_e32 v49, 0xffff0000, v80
	v_fma_f32 v16, v88, v16, v48
	v_fma_f32 v17, v88, v17, v49
	v_lshlrev_b32_e32 v48, 16, v81
	v_and_b32_e32 v49, 0xffff0000, v81
	v_fma_f32 v18, v88, v18, v48
	v_fma_f32 v19, v88, v19, v49
	v_lshlrev_b32_e32 v48, 16, v82
	v_and_b32_e32 v49, 0xffff0000, v82
	v_fma_f32 v20, v88, v20, v48
	v_fma_f32 v21, v88, v21, v49
	v_lshlrev_b32_e32 v48, 16, v83
	v_and_b32_e32 v49, 0xffff0000, v83
	v_fma_f32 v22, v88, v22, v48
	v_fma_f32 v23, v88, v23, v49
	v_lshlrev_b32_e32 v48, 16, v84
	v_and_b32_e32 v49, 0xffff0000, v84
	v_fma_f32 v24, v88, v24, v48
	v_fma_f32 v25, v88, v25, v49
	v_lshlrev_b32_e32 v48, 16, v85
	v_and_b32_e32 v49, 0xffff0000, v85
	v_fma_f32 v26, v88, v26, v48
	v_fma_f32 v27, v88, v27, v49
	v_lshlrev_b32_e32 v48, 16, v86
	v_and_b32_e32 v49, 0xffff0000, v86
	v_fma_f32 v28, v88, v28, v48
	v_fma_f32 v29, v88, v29, v49
	v_lshlrev_b32_e32 v48, 16, v87
	v_and_b32_e32 v49, 0xffff0000, v87
	v_fma_f32 v30, v88, v30, v48
	v_fma_f32 v31, v88, v31, v49
	global_load_dwordx4 v[80:83], v2, s[10:11] nt
	global_load_dwordx4 v[84:87], v3, s[10:11] nt
	global_load_dword v88, v4, s[16:17]
	s_add_u32 s10, s10, 0x40000
	s_addc_u32 s11, s11, 0
	s_add_u32 s16, s16, 64
	s_addc_u32 s17, s17, 0
	s_waitcnt vmcnt(35)
	v_cvt_pk_bf16_f32 v32, v16, v17
	v_cvt_pk_bf16_f32 v33, v18, v19
	v_cvt_pk_bf16_f32 v34, v20, v21
	v_cvt_pk_bf16_f32 v35, v22, v23
	global_store_dwordx4 v2, v[32:35], s[12:13] nt
	v_cvt_pk_bf16_f32 v36, v24, v25
	v_cvt_pk_bf16_f32 v37, v26, v27
	v_cvt_pk_bf16_f32 v38, v28, v29
	v_cvt_pk_bf16_f32 v39, v30, v31
	global_store_dwordx4 v3, v[36:39], s[12:13] nt
	s_add_u32 s12, s12, 0x40000
	s_addc_u32 s13, s13, 0
	v_lshlrev_b32_e32 v48, 16, v96
	v_and_b32_e32 v49, 0xffff0000, v96
	v_fma_f32 v16, v104, v16, v48
	v_fma_f32 v17, v104, v17, v49
	v_lshlrev_b32_e32 v48, 16, v97
	v_and_b32_e32 v49, 0xffff0000, v97
	v_fma_f32 v18, v104, v18, v48
	v_fma_f32 v19, v104, v19, v49
	v_lshlrev_b32_e32 v48, 16, v98
	v_and_b32_e32 v49, 0xffff0000, v98
	v_fma_f32 v20, v104, v20, v48
	v_fma_f32 v21, v104, v21, v49
	v_lshlrev_b32_e32 v48, 16, v99
	v_and_b32_e32 v49, 0xffff0000, v99
	v_fma_f32 v22, v104, v22, v48
	v_fma_f32 v23, v104, v23, v49
	v_lshlrev_b32_e32 v48, 16, v100
	v_and_b32_e32 v49, 0xffff0000, v100
	v_fma_f32 v24, v104, v24, v48
	v_fma_f32 v25, v104, v25, v49
	v_lshlrev_b32_e32 v48, 16, v101
	v_and_b32_e32 v49, 0xffff0000, v101
	v_fma_f32 v26, v104, v26, v48
	v_fma_f32 v27, v104, v27, v49
	v_lshlrev_b32_e32 v48, 16, v102
	v_and_b32_e32 v49, 0xffff0000, v102
	v_fma_f32 v28, v104, v28, v48
	v_fma_f32 v29, v104, v29, v49
	v_lshlrev_b32_e32 v48, 16, v103
	v_and_b32_e32 v49, 0xffff0000, v103
	v_fma_f32 v30, v104, v30, v48
	v_fma_f32 v31, v104, v31, v49
	global_load_dwordx4 v[96:99], v2, s[10:11] nt
	global_load_dwordx4 v[100:103], v3, s[10:11] nt
	global_load_dword v104, v4, s[16:17]
	s_add_u32 s10, s10, 0x40000
	s_addc_u32 s11, s11, 0
	s_add_u32 s16, s16, 64
	s_addc_u32 s17, s17, 0
	s_waitcnt vmcnt(35)
; __device__ __forceinline__ float bf2f(unsigned h) { return __uint_as_float(h << 16); }
; __device__ __forceinline__ unsigned pk2(float lo, float hi) { return pg8::cvt_pk_bf16(lo, hi); }
; __device__ __forceinline__ void b2_scan(const Ctx& C) {
;     ...
;     B2_LOAD(0, 0);
; #pragma unroll
;     for (int g = 0; g < 8; ++g) {
;         const int cur = g & 1;
;         if (g + 1 < 8) B2_LOAD(g + 1, cur ^ 1);
; #pragma unroll
;         for (int k = 0; k < 4; ++k) {
;             const int c = 4 * g + k;
;             const float dd[8] = {d0[cur][k][0], d0[cur][k][1], d0[cur][k][2], d0[cur][k][3], d1[cur][k][0], d1[cur][k][1], d1[cur][k][2], d1[cur][k][3]};
; #pragma unroll
;             for (int j = 0; j < 2; ++j) {
;                 v4u o; o.x = pk2(run[j][0], run[j][1]); o.y = pk2(run[j][2], run[j][3]); o.z = pk2(run[j][4], run[j][5]); o.w = pk2(run[j][6], run[j][7]);
;                 __builtin_nontemporal_store(o, (v4u*)(base + (size_t)c * cstride + (size_t)j * vstride));
;                 const unsigned lw[4] = {loc[cur][k][j].x, loc[cur][k][j].y, loc[cur][k][j].z, loc[cur][k][j].w};
; #pragma unroll
;                 for (int q = 0; q < 4; ++q) {
;                     run[j][2 * q] = dd[2 * q] * run[j][2 * q] + bf2f(lw[q] & 0xffffu);
;                     run[j][2 * q + 1] = dd[2 * q + 1] * run[j][2 * q + 1] + __uint_as_float(lw[q] & 0xffff0000u);
;                 }
;             }
;         }
;     }
	v_cvt_pk_bf16_f32 v40, v16, v17
	v_cvt_pk_bf16_f32 v41, v18, v19
	v_cvt_pk_bf16_f32 v42, v20, v21
	v_cvt_pk_bf16_f32 v43, v22, v23
	global_store_dwordx4 v2, v[40:43], s[12:13] nt
	v_cvt_pk_bf16_f32 v44, v24, v25
	v_cvt_pk_bf16_f32 v45, v26, v27
	v_cvt_pk_bf16_f32 v46, v28, v29
	v_cvt_pk_bf16_f32 v47, v30, v31
	global_store_dwordx4 v3, v[44:47], s[12:13] nt
	s_add_u32 s12, s12, 0x40000
	s_addc_u32 s13, s13, 0
	v_lshlrev_b32_e32 v48, 16, v112
	v_and_b32_e32 v49, 0xffff0000, v112
	v_fma_f32 v16, v120, v16, v48
	v_fma_f32 v17, v120, v17, v49
	v_lshlrev_b32_e32 v48, 16, v113
	v_and_b32_e32 v49, 0xffff0000, v113
	v_fma_f32 v18, v120, v18, v48
	v_fma_f32 v19, v120, v19, v49
	v_lshlrev_b32_e32 v48, 16, v114
	v_and_b32_e32 v49, 0xffff0000, v114
	v_fma_f32 v20, v120, v20, v48
	v_fma_f32 v21, v120, v21, v49
	v_lshlrev_b32_e32 v48, 16, v115
	v_and_b32_e32 v49, 0xffff0000, v115
	v_fma_f32 v22, v120, v22, v48
	v_fma_f32 v23, v120, v23, v49
	v_lshlrev_b32_e32 v48, 16, v116
	v_and_b32_e32 v49, 0xffff0000, v116
	v_fma_f32 v24, v120, v24, v48
	v_fma_f32 v25, v120, v25, v49
	v_lshlrev_b32_e32 v48, 16, v117
	v_and_b32_e32 v49, 0xffff0000, v117
	v_fma_f32 v26, v120, v26, v48
	v_fma_f32 v27, v120, v27, v49
	v_lshlrev_b32_e32 v48, 16, v118
	v_and_b32_e32 v49, 0xffff0000, v118
	v_fma_f32 v28, v120, v28, v48
	v_fma_f32 v29, v120, v29, v49
	v_lshlrev_b32_e32 v48, 16, v119
	v_and_b32_e32 v49, 0xffff0000, v119
	v_fma_f32 v30, v120, v30, v48
	v_fma_f32 v31, v120, v31, v49
	global_load_dwordx4 v[112:115], v2, s[10:11] nt
	global_load_dwordx4 v[116:119], v3, s[10:11] nt
	global_load_dword v120, v4, s[16:17]
	s_add_u32 s10, s10, 0x40000
	s_addc_u32 s11, s11, 0
	s_add_u32 s16, s16, 64
	s_addc_u32 s17, s17, 0
	s_waitcnt vmcnt(35)
	v_cvt_pk_bf16_f32 v32, v16, v17
	v_cvt_pk_bf16_f32 v33, v18, v19
	v_cvt_pk_bf16_f32 v34, v20, v21
	v_cvt_pk_bf16_f32 v35, v22, v23
	global_store_dwordx4 v2, v[32:35], s[12:13] nt
	v_cvt_pk_bf16_f32 v36, v24, v25
	v_cvt_pk_bf16_f32 v37, v26, v27
	v_cvt_pk_bf16_f32 v38, v28, v29
	v_cvt_pk_bf16_f32 v39, v30, v31
	global_store_dwordx4 v3, v[36:39], s[12:13] nt
	s_add_u32 s12, s12, 0x40000
	s_addc_u32 s13, s13, 0
	v_lshlrev_b32_e32 v48, 16, v128
	v_and_b32_e32 v49, 0xffff0000, v128
	v_fma_f32 v16, v136, v16, v48
	v_fma_f32 v17, v136, v17, v49
	v_lshlrev_b32_e32 v48, 16, v129
	v_and_b32_e32 v49, 0xffff0000, v129
	v_fma_f32 v18, v136, v18, v48
	v_fma_f32 v19, v136, v19, v49
	v_lshlrev_b32_e32 v48, 16, v130
	v_and_b32_e32 v49, 0xffff0000, v130
	v_fma_f32 v20, v136, v20, v48
	v_fma_f32 v21, v136, v21, v49
	v_lshlrev_b32_e32 v48, 16, v131
	v_and_b32_e32 v49, 0xffff0000, v131
	v_fma_f32 v22, v136, v22, v48
	v_fma_f32 v23, v136, v23, v49
	v_lshlrev_b32_e32 v48, 16, v132
	v_and_b32_e32 v49, 0xffff0000, v132
	v_fma_f32 v24, v136, v24, v48
	v_fma_f32 v25, v136, v25, v49
	v_lshlrev_b32_e32 v48, 16, v133
	v_and_b32_e32 v49, 0xffff0000, v133
	v_fma_f32 v26, v136, v26, v48
	v_fma_f32 v27, v136, v27, v49
	v_lshlrev_b32_e32 v48, 16, v134
	v_and_b32_e32 v49, 0xffff0000, v134
	v_fma_f32 v28, v136, v28, v48
	v_fma_f32 v29, v136, v29, v49
	v_lshlrev_b32_e32 v48, 16, v135
	v_and_b32_e32 v49, 0xffff0000, v135
	v_fma_f32 v30, v136, v30, v48
	v_fma_f32 v31, v136, v31, v49
	global_load_dwordx4 v[128:131], v2, s[10:11] nt
	global_load_dwordx4 v[132:135], v3, s[10:11] nt
	global_load_dword v136, v4, s[16:17]
	s_add_u32 s10, s10, 0x40000
	s_addc_u32 s11, s11, 0
	s_add_u32 s16, s16, 64
	s_addc_u32 s17, s17, 0
	s_waitcnt vmcnt(35)
	v_cvt_pk_bf16_f32 v40, v16, v17
	v_cvt_pk_bf16_f32 v41, v18, v19
	v_cvt_pk_bf16_f32 v42, v20, v21
	v_cvt_pk_bf16_f32 v43, v22, v23
	global_store_dwordx4 v2, v[40:43], s[12:13] nt
	v_cvt_pk_bf16_f32 v44, v24, v25
	v_cvt_pk_bf16_f32 v45, v26, v27
	v_cvt_pk_bf16_f32 v46, v28, v29
	v_cvt_pk_bf16_f32 v47, v30, v31
	global_store_dwordx4 v3, v[44:47], s[12:13] nt
	s_add_u32 s12, s12, 0x40000
	s_addc_u32 s13, s13, 0
	v_lshlrev_b32_e32 v48, 16, v144
	v_and_b32_e32 v49, 0xffff0000, v144
	v_fma_f32 v16, v152, v16, v48
	v_fma_f32 v17, v152, v17, v49
	v_lshlrev_b32_e32 v48, 16, v145
	v_and_b32_e32 v49, 0xffff0000, v145
	v_fma_f32 v18, v152, v18, v48
	v_fma_f32 v19, v152, v19, v49
	v_lshlrev_b32_e32 v48, 16, v146
	v_and_b32_e32 v49, 0xffff0000, v146
	v_fma_f32 v20, v152, v20, v48
	v_fma_f32 v21, v152, v21, v49
	v_lshlrev_b32_e32 v48, 16, v147
	v_and_b32_e32 v49, 0xffff0000, v147
	v_fma_f32 v22, v152, v22, v48
	v_fma_f32 v23, v152, v23, v49
	v_lshlrev_b32_e32 v48, 16, v148
	v_and_b32_e32 v49, 0xffff0000, v148
	v_fma_f32 v24, v152, v24, v48
	v_fma_f32 v25, v152, v25, v49
	v_lshlrev_b32_e32 v48, 16, v149
	v_and_b32_e32 v49, 0xffff0000, v149
	v_fma_f32 v26, v152, v26, v48
	v_fma_f32 v27, v152, v27, v49
	v_lshlrev_b32_e32 v48, 16, v150
	v_and_b32_e32 v49, 0xffff0000, v150
	v_fma_f32 v28, v152, v28, v48
	v_fma_f32 v29, v152, v29, v49
	v_lshlrev_b32_e32 v48, 16, v151
	v_and_b32_e32 v49, 0xffff0000, v151
	v_fma_f32 v30, v152, v30, v48
	v_fma_f32 v31, v152, v31, v49
	global_load_dwordx4 v[144:147], v2, s[10:11] nt
	global_load_dwordx4 v[148:151], v3, s[10:11] nt
	global_load_dword v152, v4, s[16:17]
	s_add_u32 s10, s10, 0x40000
	s_addc_u32 s11, s11, 0
	s_add_u32 s16, s16, 64
	s_addc_u32 s17, s17, 0
	s_waitcnt vmcnt(35)
; __device__ __forceinline__ float bf2f(unsigned h) { return __uint_as_float(h << 16); }
; __device__ __forceinline__ unsigned pk2(float lo, float hi) { return pg8::cvt_pk_bf16(lo, hi); }
; __device__ __forceinline__ void b2_scan(const Ctx& C) {
;     ...
;     B2_LOAD(0, 0);
; #pragma unroll
;     for (int g = 0; g < 8; ++g) {
;         const int cur = g & 1;
;         if (g + 1 < 8) B2_LOAD(g + 1, cur ^ 1);
; #pragma unroll
;         for (int k = 0; k < 4; ++k) {
;             const int c = 4 * g + k;
;             const float dd[8] = {d0[cur][k][0], d0[cur][k][1], d0[cur][k][2], d0[cur][k][3], d1[cur][k][0], d1[cur][k][1], d1[cur][k][2], d1[cur][k][3]};
; #pragma unroll
;             for (int j = 0; j < 2; ++j) {
;                 v4u o; o.x = pk2(run[j][0], run[j][1]); o.y = pk2(run[j][2], run[j][3]); o.z = pk2(run[j][4], run[j][5]); o.w = pk2(run[j][6], run[j][7]);
;                 __builtin_nontemporal_store(o, (v4u*)(base + (size_t)c * cstride + (size_t)j * vstride));
;                 const unsigned lw[4] = {loc[cur][k][j].x, loc[cur][k][j].y, loc[cur][k][j].z, loc[cur][k][j].w};
; #pragma unroll
;                 for (int q = 0; q < 4; ++q) {
;                     run[j][2 * q] = dd[2 * q] * run[j][2 * q] + bf2f(lw[q] & 0xffffu);
;                     run[j][2 * q + 1] = dd[2 * q + 1] * run[j][2 * q + 1] + __uint_as_float(lw[q] & 0xffff0000u);
;                 }
;             }
;         }
;     }
	v_cvt_pk_bf16_f32 v32, v16, v17
	v_cvt_pk_bf16_f32 v33, v18, v19
	v_cvt_pk_bf16_f32 v34, v20, v21
	v_cvt_pk_bf16_f32 v35, v22, v23
	global_store_dwordx4 v2, v[32:35], s[12:13] nt
	v_cvt_pk_bf16_f32 v36, v24, v25
	v_cvt_pk_bf16_f32 v37, v26, v27
	v_cvt_pk_bf16_f32 v38, v28, v29
	v_cvt_pk_bf16_f32 v39, v30, v31
	global_store_dwordx4 v3, v[36:39], s[12:13] nt
	s_add_u32 s12, s12, 0x40000
	s_addc_u32 s13, s13, 0
	v_lshlrev_b32_e32 v48, 16, v160
	v_and_b32_e32 v49, 0xffff0000, v160
	v_fma_f32 v16, v168, v16, v48
	v_fma_f32 v17, v168, v17, v49
	v_lshlrev_b32_e32 v48, 16, v161
	v_and_b32_e32 v49, 0xffff0000, v161
	v_fma_f32 v18, v168, v18, v48
	v_fma_f32 v19, v168, v19, v49
	v_lshlrev_b32_e32 v48, 16, v162
	v_and_b32_e32 v49, 0xffff0000, v162
	v_fma_f32 v20, v168, v20, v48
	v_fma_f32 v21, v168, v21, v49
	v_lshlrev_b32_e32 v48, 16, v163
	v_and_b32_e32 v49, 0xffff0000, v163
	v_fma_f32 v22, v168, v22, v48
	v_fma_f32 v23, v168, v23, v49
	v_lshlrev_b32_e32 v48, 16, v164
	v_and_b32_e32 v49, 0xffff0000, v164
	v_fma_f32 v24, v168, v24, v48
	v_fma_f32 v25, v168, v25, v49
	v_lshlrev_b32_e32 v48, 16, v165
	v_and_b32_e32 v49, 0xffff0000, v165
	v_fma_f32 v26, v168, v26, v48
	v_fma_f32 v27, v168, v27, v49
	v_lshlrev_b32_e32 v48, 16, v166
	v_and_b32_e32 v49, 0xffff0000, v166
	v_fma_f32 v28, v168, v28, v48
	v_fma_f32 v29, v168, v29, v49
	v_lshlrev_b32_e32 v48, 16, v167
	v_and_b32_e32 v49, 0xffff0000, v167
	v_fma_f32 v30, v168, v30, v48
	v_fma_f32 v31, v168, v31, v49
	global_load_dwordx4 v[160:163], v2, s[10:11] nt
	global_load_dwordx4 v[164:167], v3, s[10:11] nt
	global_load_dword v168, v4, s[16:17]
	s_add_u32 s10, s10, 0x40000
	s_addc_u32 s11, s11, 0
	s_add_u32 s16, s16, 64
	s_addc_u32 s17, s17, 0
	s_waitcnt vmcnt(35)
	v_cvt_pk_bf16_f32 v40, v16, v17
	v_cvt_pk_bf16_f32 v41, v18, v19
	v_cvt_pk_bf16_f32 v42, v20, v21
	v_cvt_pk_bf16_f32 v43, v22, v23
	global_store_dwordx4 v2, v[40:43], s[12:13] nt
	v_cvt_pk_bf16_f32 v44, v24, v25
	v_cvt_pk_bf16_f32 v45, v26, v27
	v_cvt_pk_bf16_f32 v46, v28, v29
	v_cvt_pk_bf16_f32 v47, v30, v31
	global_store_dwordx4 v3, v[44:47], s[12:13] nt
	s_add_u32 s12, s12, 0x40000
	s_addc_u32 s13, s13, 0
	v_lshlrev_b32_e32 v48, 16, v176
	v_and_b32_e32 v49, 0xffff0000, v176
	v_fma_f32 v16, v184, v16, v48
	v_fma_f32 v17, v184, v17, v49
	v_lshlrev_b32_e32 v48, 16, v177
	v_and_b32_e32 v49, 0xffff0000, v177
	v_fma_f32 v18, v184, v18, v48
	v_fma_f32 v19, v184, v19, v49
	v_lshlrev_b32_e32 v48, 16, v178
	v_and_b32_e32 v49, 0xffff0000, v178
	v_fma_f32 v20, v184, v20, v48
	v_fma_f32 v21, v184, v21, v49
	v_lshlrev_b32_e32 v48, 16, v179
	v_and_b32_e32 v49, 0xffff0000, v179
	v_fma_f32 v22, v184, v22, v48
	v_fma_f32 v23, v184, v23, v49
	v_lshlrev_b32_e32 v48, 16, v180
	v_and_b32_e32 v49, 0xffff0000, v180
	v_fma_f32 v24, v184, v24, v48
	v_fma_f32 v25, v184, v25, v49
	v_lshlrev_b32_e32 v48, 16, v181
	v_and_b32_e32 v49, 0xffff0000, v181
	v_fma_f32 v26, v184, v26, v48
	v_fma_f32 v27, v184, v27, v49
	v_lshlrev_b32_e32 v48, 16, v182
	v_and_b32_e32 v49, 0xffff0000, v182
	v_fma_f32 v28, v184, v28, v48
	v_fma_f32 v29, v184, v29, v49
	v_lshlrev_b32_e32 v48, 16, v183
	v_and_b32_e32 v49, 0xffff0000, v183
	v_fma_f32 v30, v184, v30, v48
	v_fma_f32 v31, v184, v31, v49
	global_load_dwordx4 v[176:179], v2, s[10:11] nt
	global_load_dwordx4 v[180:183], v3, s[10:11] nt
	global_load_dword v184, v4, s[16:17]
	s_add_u32 s10, s10, 0x40000
	s_addc_u32 s11, s11, 0
	s_add_u32 s16, s16, 64
	s_addc_u32 s17, s17, 0
	s_waitcnt vmcnt(35)
	v_cvt_pk_bf16_f32 v32, v16, v17
	v_cvt_pk_bf16_f32 v33, v18, v19
	v_cvt_pk_bf16_f32 v34, v20, v21
	v_cvt_pk_bf16_f32 v35, v22, v23
	global_store_dwordx4 v2, v[32:35], s[12:13] nt
	v_cvt_pk_bf16_f32 v36, v24, v25
	v_cvt_pk_bf16_f32 v37, v26, v27
	v_cvt_pk_bf16_f32 v38, v28, v29
	v_cvt_pk_bf16_f32 v39, v30, v31
	global_store_dwordx4 v3, v[36:39], s[12:13] nt
	s_add_u32 s12, s12, 0x40000
	s_addc_u32 s13, s13, 0
	v_lshlrev_b32_e32 v48, 16, v64
	v_and_b32_e32 v49, 0xffff0000, v64
	v_fma_f32 v16, v72, v16, v48
	v_fma_f32 v17, v72, v17, v49
	v_lshlrev_b32_e32 v48, 16, v65
	v_and_b32_e32 v49, 0xffff0000, v65
	v_fma_f32 v18, v72, v18, v48
	v_fma_f32 v19, v72, v19, v49
	v_lshlrev_b32_e32 v48, 16, v66
	v_and_b32_e32 v49, 0xffff0000, v66
	v_fma_f32 v20, v72, v20, v48
	v_fma_f32 v21, v72, v21, v49
	v_lshlrev_b32_e32 v48, 16, v67
	v_and_b32_e32 v49, 0xffff0000, v67
	v_fma_f32 v22, v72, v22, v48
	v_fma_f32 v23, v72, v23, v49
	v_lshlrev_b32_e32 v48, 16, v68
	v_and_b32_e32 v49, 0xffff0000, v68
	v_fma_f32 v24, v72, v24, v48
	v_fma_f32 v25, v72, v25, v49
	v_lshlrev_b32_e32 v48, 16, v69
	v_and_b32_e32 v49, 0xffff0000, v69
	v_fma_f32 v26, v72, v26, v48
	v_fma_f32 v27, v72, v27, v49
	v_lshlrev_b32_e32 v48, 16, v70
	v_and_b32_e32 v49, 0xffff0000, v70
	v_fma_f32 v28, v72, v28, v48
	v_fma_f32 v29, v72, v29, v49
	v_lshlrev_b32_e32 v48, 16, v71
	v_and_b32_e32 v49, 0xffff0000, v71
	v_fma_f32 v30, v72, v30, v48
	v_fma_f32 v31, v72, v31, v49
	global_load_dwordx4 v[64:67], v2, s[10:11] nt
	global_load_dwordx4 v[68:71], v3, s[10:11] nt
	global_load_dword v72, v4, s[16:17]
	s_add_u32 s10, s10, 0x40000
	s_addc_u32 s11, s11, 0
	s_add_u32 s16, s16, 64
	s_addc_u32 s17, s17, 0
	s_waitcnt vmcnt(35)
; __device__ __forceinline__ float bf2f(unsigned h) { return __uint_as_float(h << 16); }
; __device__ __forceinline__ unsigned pk2(float lo, float hi) { return pg8::cvt_pk_bf16(lo, hi); }
; __device__ __forceinline__ void b2_scan(const Ctx& C) {
;     ...
;     B2_LOAD(0, 0);
; #pragma unroll
;     for (int g = 0; g < 8; ++g) {
;         const int cur = g & 1;
;         if (g + 1 < 8) B2_LOAD(g + 1, cur ^ 1);
; #pragma unroll
;         for (int k = 0; k < 4; ++k) {
;             const int c = 4 * g + k;
;             const float dd[8] = {d0[cur][k][0], d0[cur][k][1], d0[cur][k][2], d0[cur][k][3], d1[cur][k][0], d1[cur][k][1], d1[cur][k][2], d1[cur][k][3]};
; #pragma unroll
;             for (int j = 0; j < 2; ++j) {
;                 v4u o; o.x = pk2(run[j][0], run[j][1]); o.y = pk2(run[j][2], run[j][3]); o.z = pk2(run[j][4], run[j][5]); o.w = pk2(run[j][6], run[j][7]);
;                 __builtin_nontemporal_store(o, (v4u*)(base + (size_t)c * cstride + (size_t)j * vstride));
;                 const unsigned lw[4] = {loc[cur][k][j].x, loc[cur][k][j].y, loc[cur][k][j].z, loc[cur][k][j].w};
; #pragma unroll
;                 for (int q = 0; q < 4; ++q) {
;                     run[j][2 * q] = dd[2 * q] * run[j][2 * q] + bf2f(lw[q] & 0xffffu);
;                     run[j][2 * q + 1] = dd[2 * q + 1] * run[j][2 * q + 1] + __uint_as_float(lw[q] & 0xffff0000u);
;                 }
;             }
;         }
;     }
	v_cvt_pk_bf16_f32 v40, v16, v17
	v_cvt_pk_bf16_f32 v41, v18, v19
	v_cvt_pk_bf16_f32 v42, v20, v21
	v_cvt_pk_bf16_f32 v43, v22, v23
	global_store_dwordx4 v2, v[40:43], s[12:13] nt
	v_cvt_pk_bf16_f32 v44, v24, v25
	v_cvt_pk_bf16_f32 v45, v26, v27
	v_cvt_pk_bf16_f32 v46, v28, v29
	v_cvt_pk_bf16_f32 v47, v30, v31
	global_store_dwordx4 v3, v[44:47], s[12:13] nt
	s_add_u32 s12, s12, 0x40000
	s_addc_u32 s13, s13, 0
	v_lshlrev_b32_e32 v48, 16, v80
	v_and_b32_e32 v49, 0xffff0000, v80
	v_fma_f32 v16, v88, v16, v48
	v_fma_f32 v17, v88, v17, v49
	v_lshlrev_b32_e32 v48, 16, v81
	v_and_b32_e32 v49, 0xffff0000, v81
	v_fma_f32 v18, v88, v18, v48
	v_fma_f32 v19, v88, v19, v49
	v_lshlrev_b32_e32 v48, 16, v82
	v_and_b32_e32 v49, 0xffff0000, v82
	v_fma_f32 v20, v88, v20, v48
	v_fma_f32 v21, v88, v21, v49
	v_lshlrev_b32_e32 v48, 16, v83
	v_and_b32_e32 v49, 0xffff0000, v83
	v_fma_f32 v22, v88, v22, v48
	v_fma_f32 v23, v88, v23, v49
	v_lshlrev_b32_e32 v48, 16, v84
	v_and_b32_e32 v49, 0xffff0000, v84
	v_fma_f32 v24, v88, v24, v48
	v_fma_f32 v25, v88, v25, v49
	v_lshlrev_b32_e32 v48, 16, v85
	v_and_b32_e32 v49, 0xffff0000, v85
	v_fma_f32 v26, v88, v26, v48
	v_fma_f32 v27, v88, v27, v49
	v_lshlrev_b32_e32 v48, 16, v86
	v_and_b32_e32 v49, 0xffff0000, v86
	v_fma_f32 v28, v88, v28, v48
	v_fma_f32 v29, v88, v29, v49
	v_lshlrev_b32_e32 v48, 16, v87
	v_and_b32_e32 v49, 0xffff0000, v87
	v_fma_f32 v30, v88, v30, v48
	v_fma_f32 v31, v88, v31, v49
	global_load_dwordx4 v[80:83], v2, s[10:11] nt
	global_load_dwordx4 v[84:87], v3, s[10:11] nt
	global_load_dword v88, v4, s[16:17]
	s_add_u32 s10, s10, 0x40000
	s_addc_u32 s11, s11, 0
	s_add_u32 s16, s16, 64
	s_addc_u32 s17, s17, 0
	s_waitcnt vmcnt(35)
	v_cvt_pk_bf16_f32 v32, v16, v17
	v_cvt_pk_bf16_f32 v33, v18, v19
	v_cvt_pk_bf16_f32 v34, v20, v21
	v_cvt_pk_bf16_f32 v35, v22, v23
	global_store_dwordx4 v2, v[32:35], s[12:13] nt
	v_cvt_pk_bf16_f32 v36, v24, v25
	v_cvt_pk_bf16_f32 v37, v26, v27
	v_cvt_pk_bf16_f32 v38, v28, v29
	v_cvt_pk_bf16_f32 v39, v30, v31
	global_store_dwordx4 v3, v[36:39], s[12:13] nt
	s_add_u32 s12, s12, 0x40000
	s_addc_u32 s13, s13, 0
	v_lshlrev_b32_e32 v48, 16, v96
	v_and_b32_e32 v49, 0xffff0000, v96
	v_fma_f32 v16, v104, v16, v48
	v_fma_f32 v17, v104, v17, v49
	v_lshlrev_b32_e32 v48, 16, v97
	v_and_b32_e32 v49, 0xffff0000, v97
	v_fma_f32 v18, v104, v18, v48
	v_fma_f32 v19, v104, v19, v49
	v_lshlrev_b32_e32 v48, 16, v98
	v_and_b32_e32 v49, 0xffff0000, v98
	v_fma_f32 v20, v104, v20, v48
	v_fma_f32 v21, v104, v21, v49
	v_lshlrev_b32_e32 v48, 16, v99
	v_and_b32_e32 v49, 0xffff0000, v99
	v_fma_f32 v22, v104, v22, v48
	v_fma_f32 v23, v104, v23, v49
	v_lshlrev_b32_e32 v48, 16, v100
	v_and_b32_e32 v49, 0xffff0000, v100
	v_fma_f32 v24, v104, v24, v48
	v_fma_f32 v25, v104, v25, v49
	v_lshlrev_b32_e32 v48, 16, v101
	v_and_b32_e32 v49, 0xffff0000, v101
	v_fma_f32 v26, v104, v26, v48
	v_fma_f32 v27, v104, v27, v49
	v_lshlrev_b32_e32 v48, 16, v102
	v_and_b32_e32 v49, 0xffff0000, v102
	v_fma_f32 v28, v104, v28, v48
	v_fma_f32 v29, v104, v29, v49
	v_lshlrev_b32_e32 v48, 16, v103
	v_and_b32_e32 v49, 0xffff0000, v103
	v_fma_f32 v30, v104, v30, v48
	v_fma_f32 v31, v104, v31, v49
	global_load_dwordx4 v[96:99], v2, s[10:11] nt
	global_load_dwordx4 v[100:103], v3, s[10:11] nt
	global_load_dword v104, v4, s[16:17]
	s_add_u32 s10, s10, 0x40000
	s_addc_u32 s11, s11, 0
	s_add_u32 s16, s16, 64
	s_addc_u32 s17, s17, 0
	s_waitcnt vmcnt(35)
	v_cvt_pk_bf16_f32 v40, v16, v17
	v_cvt_pk_bf16_f32 v41, v18, v19
	v_cvt_pk_bf16_f32 v42, v20, v21
	v_cvt_pk_bf16_f32 v43, v22, v23
	global_store_dwordx4 v2, v[40:43], s[12:13] nt
	v_cvt_pk_bf16_f32 v44, v24, v25
	v_cvt_pk_bf16_f32 v45, v26, v27
	v_cvt_pk_bf16_f32 v46, v28, v29
	v_cvt_pk_bf16_f32 v47, v30, v31
	global_store_dwordx4 v3, v[44:47], s[12:13] nt
	s_add_u32 s12, s12, 0x40000
	s_addc_u32 s13, s13, 0
	v_lshlrev_b32_e32 v48, 16, v112
	v_and_b32_e32 v49, 0xffff0000, v112
	v_fma_f32 v16, v120, v16, v48
	v_fma_f32 v17, v120, v17, v49
	v_lshlrev_b32_e32 v48, 16, v113
	v_and_b32_e32 v49, 0xffff0000, v113
	v_fma_f32 v18, v120, v18, v48
	v_fma_f32 v19, v120, v19, v49
	v_lshlrev_b32_e32 v48, 16, v114
	v_and_b32_e32 v49, 0xffff0000, v114
	v_fma_f32 v20, v120, v20, v48
	v_fma_f32 v21, v120, v21, v49
	v_lshlrev_b32_e32 v48, 16, v115
	v_and_b32_e32 v49, 0xffff0000, v115
	v_fma_f32 v22, v120, v22, v48
	v_fma_f32 v23, v120, v23, v49
	v_lshlrev_b32_e32 v48, 16, v116
	v_and_b32_e32 v49, 0xffff0000, v116
	v_fma_f32 v24, v120, v24, v48
	v_fma_f32 v25, v120, v25, v49
	v_lshlrev_b32_e32 v48, 16, v117
	v_and_b32_e32 v49, 0xffff0000, v117
	v_fma_f32 v26, v120, v26, v48
	v_fma_f32 v27, v120, v27, v49
	v_lshlrev_b32_e32 v48, 16, v118
	v_and_b32_e32 v49, 0xffff0000, v118
	v_fma_f32 v28, v120, v28, v48
	v_fma_f32 v29, v120, v29, v49
	v_lshlrev_b32_e32 v48, 16, v119
	v_and_b32_e32 v49, 0xffff0000, v119
	v_fma_f32 v30, v120, v30, v48
	v_fma_f32 v31, v120, v31, v49
	global_load_dwordx4 v[112:115], v2, s[10:11] nt
	global_load_dwordx4 v[116:119], v3, s[10:11] nt
	global_load_dword v120, v4, s[16:17]
	s_add_u32 s10, s10, 0x40000
	s_addc_u32 s11, s11, 0
	s_add_u32 s16, s16, 64
	s_addc_u32 s17, s17, 0
	s_waitcnt vmcnt(35)
; __device__ __forceinline__ float bf2f(unsigned h) { return __uint_as_float(h << 16); }
; __device__ __forceinline__ unsigned pk2(float lo, float hi) { return pg8::cvt_pk_bf16(lo, hi); }
; __device__ __forceinline__ void b2_scan(const Ctx& C) {
;     ...
;     B2_LOAD(0, 0);
; #pragma unroll
;     for (int g = 0; g < 8; ++g) {
;         const int cur = g & 1;
;         if (g + 1 < 8) B2_LOAD(g + 1, cur ^ 1);
; #pragma unroll
;         for (int k = 0; k < 4; ++k) {
;             const int c = 4 * g + k;
;             const float dd[8] = {d0[cur][k][0], d0[cur][k][1], d0[cur][k][2], d0[cur][k][3], d1[cur][k][0], d1[cur][k][1], d1[cur][k][2], d1[cur][k][3]};
; #pragma unroll
;             for (int j = 0; j < 2; ++j) {
;                 v4u o; o.x = pk2(run[j][0], run[j][1]); o.y = pk2(run[j][2], run[j][3]); o.z = pk2(run[j][4], run[j][5]); o.w = pk2(run[j][6], run[j][7]);
;                 __builtin_nontemporal_store(o, (v4u*)(base + (size_t)c * cstride + (size_t)j * vstride));
;                 const unsigned lw[4] = {loc[cur][k][j].x, loc[cur][k][j].y, loc[cur][k][j].z, loc[cur][k][j].w};
; #pragma unroll
;                 for (int q = 0; q < 4; ++q) {
;                     run[j][2 * q] = dd[2 * q] * run[j][2 * q] + bf2f(lw[q] & 0xffffu);
;                     run[j][2 * q + 1] = dd[2 * q + 1] * run[j][2 * q + 1] + __uint_as_float(lw[q] & 0xffff0000u);
;                 }
;             }
;         }
;     }
	v_cvt_pk_bf16_f32 v32, v16, v17
	v_cvt_pk_bf16_f32 v33, v18, v19
	v_cvt_pk_bf16_f32 v34, v20, v21
	v_cvt_pk_bf16_f32 v35, v22, v23
	global_store_dwordx4 v2, v[32:35], s[12:13] nt
	v_cvt_pk_bf16_f32 v36, v24, v25
	v_cvt_pk_bf16_f32 v37, v26, v27
	v_cvt_pk_bf16_f32 v38, v28, v29
	v_cvt_pk_bf16_f32 v39, v30, v31
	global_store_dwordx4 v3, v[36:39], s[12:13] nt
	s_add_u32 s12, s12, 0x40000
	s_addc_u32 s13, s13, 0
	v_lshlrev_b32_e32 v48, 16, v128
	v_and_b32_e32 v49, 0xffff0000, v128
	v_fma_f32 v16, v136, v16, v48
	v_fma_f32 v17, v136, v17, v49
	v_lshlrev_b32_e32 v48, 16, v129
	v_and_b32_e32 v49, 0xffff0000, v129
	v_fma_f32 v18, v136, v18, v48
	v_fma_f32 v19, v136, v19, v49
	v_lshlrev_b32_e32 v48, 16, v130
	v_and_b32_e32 v49, 0xffff0000, v130
	v_fma_f32 v20, v136, v20, v48
	v_fma_f32 v21, v136, v21, v49
	v_lshlrev_b32_e32 v48, 16, v131
	v_and_b32_e32 v49, 0xffff0000, v131
	v_fma_f32 v22, v136, v22, v48
	v_fma_f32 v23, v136, v23, v49
	v_lshlrev_b32_e32 v48, 16, v132
	v_and_b32_e32 v49, 0xffff0000, v132
	v_fma_f32 v24, v136, v24, v48
	v_fma_f32 v25, v136, v25, v49
	v_lshlrev_b32_e32 v48, 16, v133
	v_and_b32_e32 v49, 0xffff0000, v133
	v_fma_f32 v26, v136, v26, v48
	v_fma_f32 v27, v136, v27, v49
	v_lshlrev_b32_e32 v48, 16, v134
	v_and_b32_e32 v49, 0xffff0000, v134
	v_fma_f32 v28, v136, v28, v48
	v_fma_f32 v29, v136, v29, v49
	v_lshlrev_b32_e32 v48, 16, v135
	v_and_b32_e32 v49, 0xffff0000, v135
	v_fma_f32 v30, v136, v30, v48
	v_fma_f32 v31, v136, v31, v49
	global_load_dwordx4 v[128:131], v2, s[10:11] nt
	global_load_dwordx4 v[132:135], v3, s[10:11] nt
	global_load_dword v136, v4, s[16:17]
	s_add_u32 s10, s10, 0x40000
	s_addc_u32 s11, s11, 0
	s_add_u32 s16, s16, 64
	s_addc_u32 s17, s17, 0
	s_waitcnt vmcnt(35)
	v_cvt_pk_bf16_f32 v40, v16, v17
	v_cvt_pk_bf16_f32 v41, v18, v19
	v_cvt_pk_bf16_f32 v42, v20, v21
	v_cvt_pk_bf16_f32 v43, v22, v23
	global_store_dwordx4 v2, v[40:43], s[12:13] nt
	v_cvt_pk_bf16_f32 v44, v24, v25
	v_cvt_pk_bf16_f32 v45, v26, v27
	v_cvt_pk_bf16_f32 v46, v28, v29
	v_cvt_pk_bf16_f32 v47, v30, v31
	global_store_dwordx4 v3, v[44:47], s[12:13] nt
	s_add_u32 s12, s12, 0x40000
	s_addc_u32 s13, s13, 0
	v_lshlrev_b32_e32 v48, 16, v144
	v_and_b32_e32 v49, 0xffff0000, v144
	v_fma_f32 v16, v152, v16, v48
	v_fma_f32 v17, v152, v17, v49
	v_lshlrev_b32_e32 v48, 16, v145
	v_and_b32_e32 v49, 0xffff0000, v145
	v_fma_f32 v18, v152, v18, v48
	v_fma_f32 v19, v152, v19, v49
	v_lshlrev_b32_e32 v48, 16, v146
	v_and_b32_e32 v49, 0xffff0000, v146
	v_fma_f32 v20, v152, v20, v48
	v_fma_f32 v21, v152, v21, v49
	v_lshlrev_b32_e32 v48, 16, v147
	v_and_b32_e32 v49, 0xffff0000, v147
	v_fma_f32 v22, v152, v22, v48
	v_fma_f32 v23, v152, v23, v49
	v_lshlrev_b32_e32 v48, 16, v148
	v_and_b32_e32 v49, 0xffff0000, v148
	v_fma_f32 v24, v152, v24, v48
	v_fma_f32 v25, v152, v25, v49
	v_lshlrev_b32_e32 v48, 16, v149
	v_and_b32_e32 v49, 0xffff0000, v149
	v_fma_f32 v26, v152, v26, v48
	v_fma_f32 v27, v152, v27, v49
	v_lshlrev_b32_e32 v48, 16, v150
	v_and_b32_e32 v49, 0xffff0000, v150
	v_fma_f32 v28, v152, v28, v48
	v_fma_f32 v29, v152, v29, v49
	v_lshlrev_b32_e32 v48, 16, v151
	v_and_b32_e32 v49, 0xffff0000, v151
	v_fma_f32 v30, v152, v30, v48
	v_fma_f32 v31, v152, v31, v49
	global_load_dwordx4 v[144:147], v2, s[10:11] nt
	global_load_dwordx4 v[148:151], v3, s[10:11] nt
	global_load_dword v152, v4, s[16:17]
	s_add_u32 s10, s10, 0x40000
	s_addc_u32 s11, s11, 0
	s_add_u32 s16, s16, 64
	s_addc_u32 s17, s17, 0
	s_waitcnt vmcnt(35)
	v_cvt_pk_bf16_f32 v32, v16, v17
	v_cvt_pk_bf16_f32 v33, v18, v19
	v_cvt_pk_bf16_f32 v34, v20, v21
	v_cvt_pk_bf16_f32 v35, v22, v23
	global_store_dwordx4 v2, v[32:35], s[12:13] nt
	v_cvt_pk_bf16_f32 v36, v24, v25
	v_cvt_pk_bf16_f32 v37, v26, v27
	v_cvt_pk_bf16_f32 v38, v28, v29
	v_cvt_pk_bf16_f32 v39, v30, v31
	global_store_dwordx4 v3, v[36:39], s[12:13] nt
	s_add_u32 s12, s12, 0x40000
	s_addc_u32 s13, s13, 0
	v_lshlrev_b32_e32 v48, 16, v160
	v_and_b32_e32 v49, 0xffff0000, v160
	v_fma_f32 v16, v168, v16, v48
	v_fma_f32 v17, v168, v17, v49
	v_lshlrev_b32_e32 v48, 16, v161
	v_and_b32_e32 v49, 0xffff0000, v161
	v_fma_f32 v18, v168, v18, v48
	v_fma_f32 v19, v168, v19, v49
	v_lshlrev_b32_e32 v48, 16, v162
	v_and_b32_e32 v49, 0xffff0000, v162
	v_fma_f32 v20, v168, v20, v48
	v_fma_f32 v21, v168, v21, v49
	v_lshlrev_b32_e32 v48, 16, v163
	v_and_b32_e32 v49, 0xffff0000, v163
	v_fma_f32 v22, v168, v22, v48
	v_fma_f32 v23, v168, v23, v49
	v_lshlrev_b32_e32 v48, 16, v164
	v_and_b32_e32 v49, 0xffff0000, v164
	v_fma_f32 v24, v168, v24, v48
	v_fma_f32 v25, v168, v25, v49
	v_lshlrev_b32_e32 v48, 16, v165
	v_and_b32_e32 v49, 0xffff0000, v165
	v_fma_f32 v26, v168, v26, v48
	v_fma_f32 v27, v168, v27, v49
	v_lshlrev_b32_e32 v48, 16, v166
	v_and_b32_e32 v49, 0xffff0000, v166
	v_fma_f32 v28, v168, v28, v48
	v_fma_f32 v29, v168, v29, v49
	v_lshlrev_b32_e32 v48, 16, v167
	v_and_b32_e32 v49, 0xffff0000, v167
	v_fma_f32 v30, v168, v30, v48
	v_fma_f32 v31, v168, v31, v49
	global_load_dwordx4 v[160:163], v2, s[10:11] nt
	global_load_dwordx4 v[164:167], v3, s[10:11] nt
	global_load_dword v168, v4, s[16:17]
	s_add_u32 s10, s10, 0x40000
	s_addc_u32 s11, s11, 0
	s_add_u32 s16, s16, 64
	s_addc_u32 s17, s17, 0
	s_waitcnt vmcnt(35)
; __device__ __forceinline__ float bf2f(unsigned h) { return __uint_as_float(h << 16); }
; __device__ __forceinline__ unsigned pk2(float lo, float hi) { return pg8::cvt_pk_bf16(lo, hi); }
; __device__ __forceinline__ void b2_scan(const Ctx& C) {
;     ...
;     B2_LOAD(0, 0);
; #pragma unroll
;     for (int g = 0; g < 8; ++g) {
;         const int cur = g & 1;
;         if (g + 1 < 8) B2_LOAD(g + 1, cur ^ 1);
; #pragma unroll
;         for (int k = 0; k < 4; ++k) {
;             const int c = 4 * g + k;
;             const float dd[8] = {d0[cur][k][0], d0[cur][k][1], d0[cur][k][2], d0[cur][k][3], d1[cur][k][0], d1[cur][k][1], d1[cur][k][2], d1[cur][k][3]};
; #pragma unroll
;             for (int j = 0; j < 2; ++j) {
;                 v4u o; o.x = pk2(run[j][0], run[j][1]); o.y = pk2(run[j][2], run[j][3]); o.z = pk2(run[j][4], run[j][5]); o.w = pk2(run[j][6], run[j][7]);
;                 __builtin_nontemporal_store(o, (v4u*)(base + (size_t)c * cstride + (size_t)j * vstride));
;                 const unsigned lw[4] = {loc[cur][k][j].x, loc[cur][k][j].y, loc[cur][k][j].z, loc[cur][k][j].w};
; #pragma unroll
;                 for (int q = 0; q < 4; ++q) {
;                     run[j][2 * q] = dd[2 * q] * run[j][2 * q] + bf2f(lw[q] & 0xffffu);
;                     run[j][2 * q + 1] = dd[2 * q + 1] * run[j][2 * q + 1] + __uint_as_float(lw[q] & 0xffff0000u);
;                 }
;             }
;         }
;     }
	v_cvt_pk_bf16_f32 v40, v16, v17
	v_cvt_pk_bf16_f32 v41, v18, v19
	v_cvt_pk_bf16_f32 v42, v20, v21
	v_cvt_pk_bf16_f32 v43, v22, v23
	global_store_dwordx4 v2, v[40:43], s[12:13] nt
	v_cvt_pk_bf16_f32 v44, v24, v25
	v_cvt_pk_bf16_f32 v45, v26, v27
	v_cvt_pk_bf16_f32 v46, v28, v29
	v_cvt_pk_bf16_f32 v47, v30, v31
	global_store_dwordx4 v3, v[44:47], s[12:13] nt
	s_add_u32 s12, s12, 0x40000
	s_addc_u32 s13, s13, 0
	v_lshlrev_b32_e32 v48, 16, v176
	v_and_b32_e32 v49, 0xffff0000, v176
	v_fma_f32 v16, v184, v16, v48
	v_fma_f32 v17, v184, v17, v49
	v_lshlrev_b32_e32 v48, 16, v177
	v_and_b32_e32 v49, 0xffff0000, v177
	v_fma_f32 v18, v184, v18, v48
	v_fma_f32 v19, v184, v19, v49
	v_lshlrev_b32_e32 v48, 16, v178
	v_and_b32_e32 v49, 0xffff0000, v178
	v_fma_f32 v20, v184, v20, v48
	v_fma_f32 v21, v184, v21, v49
	v_lshlrev_b32_e32 v48, 16, v179
	v_and_b32_e32 v49, 0xffff0000, v179
	v_fma_f32 v22, v184, v22, v48
	v_fma_f32 v23, v184, v23, v49
	v_lshlrev_b32_e32 v48, 16, v180
	v_and_b32_e32 v49, 0xffff0000, v180
	v_fma_f32 v24, v184, v24, v48
	v_fma_f32 v25, v184, v25, v49
	v_lshlrev_b32_e32 v48, 16, v181
	v_and_b32_e32 v49, 0xffff0000, v181
	v_fma_f32 v26, v184, v26, v48
	v_fma_f32 v27, v184, v27, v49
	v_lshlrev_b32_e32 v48, 16, v182
	v_and_b32_e32 v49, 0xffff0000, v182
	v_fma_f32 v28, v184, v28, v48
	v_fma_f32 v29, v184, v29, v49
	v_lshlrev_b32_e32 v48, 16, v183
	v_and_b32_e32 v49, 0xffff0000, v183
	v_fma_f32 v30, v184, v30, v48
	v_fma_f32 v31, v184, v31, v49
	global_load_dwordx4 v[176:179], v2, s[10:11] nt
	global_load_dwordx4 v[180:183], v3, s[10:11] nt
	global_load_dword v184, v4, s[16:17]
	s_add_u32 s10, s10, 0x40000
	s_addc_u32 s11, s11, 0
	s_add_u32 s16, s16, 64
	s_addc_u32 s17, s17, 0
	s_waitcnt vmcnt(35)
	v_cvt_pk_bf16_f32 v32, v16, v17
	v_cvt_pk_bf16_f32 v33, v18, v19
	v_cvt_pk_bf16_f32 v34, v20, v21
	v_cvt_pk_bf16_f32 v35, v22, v23
	global_store_dwordx4 v2, v[32:35], s[12:13] nt
	v_cvt_pk_bf16_f32 v36, v24, v25
	v_cvt_pk_bf16_f32 v37, v26, v27
	v_cvt_pk_bf16_f32 v38, v28, v29
	v_cvt_pk_bf16_f32 v39, v30, v31
	global_store_dwordx4 v3, v[36:39], s[12:13] nt
	s_add_u32 s12, s12, 0x40000
	s_addc_u32 s13, s13, 0
	v_lshlrev_b32_e32 v48, 16, v64
	v_and_b32_e32 v49, 0xffff0000, v64
	v_fma_f32 v16, v72, v16, v48
	v_fma_f32 v17, v72, v17, v49
	v_lshlrev_b32_e32 v48, 16, v65
	v_and_b32_e32 v49, 0xffff0000, v65
	v_fma_f32 v18, v72, v18, v48
	v_fma_f32 v19, v72, v19, v49
	v_lshlrev_b32_e32 v48, 16, v66
	v_and_b32_e32 v49, 0xffff0000, v66
	v_fma_f32 v20, v72, v20, v48
	v_fma_f32 v21, v72, v21, v49
	v_lshlrev_b32_e32 v48, 16, v67
	v_and_b32_e32 v49, 0xffff0000, v67
	v_fma_f32 v22, v72, v22, v48
	v_fma_f32 v23, v72, v23, v49
	v_lshlrev_b32_e32 v48, 16, v68
	v_and_b32_e32 v49, 0xffff0000, v68
	v_fma_f32 v24, v72, v24, v48
	v_fma_f32 v25, v72, v25, v49
	v_lshlrev_b32_e32 v48, 16, v69
	v_and_b32_e32 v49, 0xffff0000, v69
	v_fma_f32 v26, v72, v26, v48
	v_fma_f32 v27, v72, v27, v49
	v_lshlrev_b32_e32 v48, 16, v70
	v_and_b32_e32 v49, 0xffff0000, v70
	v_fma_f32 v28, v72, v28, v48
	v_fma_f32 v29, v72, v29, v49
	v_lshlrev_b32_e32 v48, 16, v71
	v_and_b32_e32 v49, 0xffff0000, v71
	v_fma_f32 v30, v72, v30, v48
	v_fma_f32 v31, v72, v31, v49
	s_waitcnt vmcnt(32)
	v_cvt_pk_bf16_f32 v40, v16, v17
	v_cvt_pk_bf16_f32 v41, v18, v19
	v_cvt_pk_bf16_f32 v42, v20, v21
	v_cvt_pk_bf16_f32 v43, v22, v23
	global_store_dwordx4 v2, v[40:43], s[12:13] nt
	v_cvt_pk_bf16_f32 v44, v24, v25
	v_cvt_pk_bf16_f32 v45, v26, v27
	v_cvt_pk_bf16_f32 v46, v28, v29
	v_cvt_pk_bf16_f32 v47, v30, v31
	global_store_dwordx4 v3, v[44:47], s[12:13] nt
	s_add_u32 s12, s12, 0x40000
	s_addc_u32 s13, s13, 0
	v_lshlrev_b32_e32 v48, 16, v80
	v_and_b32_e32 v49, 0xffff0000, v80
	v_fma_f32 v16, v88, v16, v48
	v_fma_f32 v17, v88, v17, v49
	v_lshlrev_b32_e32 v48, 16, v81
	v_and_b32_e32 v49, 0xffff0000, v81
	v_fma_f32 v18, v88, v18, v48
	v_fma_f32 v19, v88, v19, v49
	v_lshlrev_b32_e32 v48, 16, v82
	v_and_b32_e32 v49, 0xffff0000, v82
	v_fma_f32 v20, v88, v20, v48
	v_fma_f32 v21, v88, v21, v49
	v_lshlrev_b32_e32 v48, 16, v83
	v_and_b32_e32 v49, 0xffff0000, v83
	v_fma_f32 v22, v88, v22, v48
	v_fma_f32 v23, v88, v23, v49
	v_lshlrev_b32_e32 v48, 16, v84
	v_and_b32_e32 v49, 0xffff0000, v84
	v_fma_f32 v24, v88, v24, v48
	v_fma_f32 v25, v88, v25, v49
	v_lshlrev_b32_e32 v48, 16, v85
	v_and_b32_e32 v49, 0xffff0000, v85
	v_fma_f32 v26, v88, v26, v48
	v_fma_f32 v27, v88, v27, v49
	v_lshlrev_b32_e32 v48, 16, v86
	v_and_b32_e32 v49, 0xffff0000, v86
	v_fma_f32 v28, v88, v28, v48
	v_fma_f32 v29, v88, v29, v49
	v_lshlrev_b32_e32 v48, 16, v87
	v_and_b32_e32 v49, 0xffff0000, v87
	v_fma_f32 v30, v88, v30, v48
	v_fma_f32 v31, v88, v31, v49
	s_waitcnt vmcnt(29)
	v_cvt_pk_bf16_f32 v32, v16, v17
	v_cvt_pk_bf16_f32 v33, v18, v19
	v_cvt_pk_bf16_f32 v34, v20, v21
	v_cvt_pk_bf16_f32 v35, v22, v23
	global_store_dwordx4 v2, v[32:35], s[12:13] nt
	v_cvt_pk_bf16_f32 v36, v24, v25
	v_cvt_pk_bf16_f32 v37, v26, v27
	v_cvt_pk_bf16_f32 v38, v28, v29
	v_cvt_pk_bf16_f32 v39, v30, v31
	global_store_dwordx4 v3, v[36:39], s[12:13] nt
	s_add_u32 s12, s12, 0x40000
	s_addc_u32 s13, s13, 0
	v_lshlrev_b32_e32 v48, 16, v96
	v_and_b32_e32 v49, 0xffff0000, v96
	v_fma_f32 v16, v104, v16, v48
	v_fma_f32 v17, v104, v17, v49
	v_lshlrev_b32_e32 v48, 16, v97
	v_and_b32_e32 v49, 0xffff0000, v97
	v_fma_f32 v18, v104, v18, v48
	v_fma_f32 v19, v104, v19, v49
	v_lshlrev_b32_e32 v48, 16, v98
	v_and_b32_e32 v49, 0xffff0000, v98
	v_fma_f32 v20, v104, v20, v48
	v_fma_f32 v21, v104, v21, v49
	v_lshlrev_b32_e32 v48, 16, v99
	v_and_b32_e32 v49, 0xffff0000, v99
	v_fma_f32 v22, v104, v22, v48
	v_fma_f32 v23, v104, v23, v49
	v_lshlrev_b32_e32 v48, 16, v100
	v_and_b32_e32 v49, 0xffff0000, v100
	v_fma_f32 v24, v104, v24, v48
	v_fma_f32 v25, v104, v25, v49
	v_lshlrev_b32_e32 v48, 16, v101
	v_and_b32_e32 v49, 0xffff0000, v101
	v_fma_f32 v26, v104, v26, v48
	v_fma_f32 v27, v104, v27, v49
	v_lshlrev_b32_e32 v48, 16, v102
	v_and_b32_e32 v49, 0xffff0000, v102
	v_fma_f32 v28, v104, v28, v48
	v_fma_f32 v29, v104, v29, v49
	v_lshlrev_b32_e32 v48, 16, v103
	v_and_b32_e32 v49, 0xffff0000, v103
	v_fma_f32 v30, v104, v30, v48
	v_fma_f32 v31, v104, v31, v49
	s_waitcnt vmcnt(26)
; __device__ __forceinline__ float bf2f(unsigned h) { return __uint_as_float(h << 16); }
; __device__ __forceinline__ unsigned pk2(float lo, float hi) { return pg8::cvt_pk_bf16(lo, hi); }
; __device__ __forceinline__ void b2_scan(const Ctx& C) {
;     ...
;     B2_LOAD(0, 0);
; #pragma unroll
;     for (int g = 0; g < 8; ++g) {
;         const int cur = g & 1;
;         if (g + 1 < 8) B2_LOAD(g + 1, cur ^ 1);
; #pragma unroll
;         for (int k = 0; k < 4; ++k) {
;             const int c = 4 * g + k;
;             const float dd[8] = {d0[cur][k][0], d0[cur][k][1], d0[cur][k][2], d0[cur][k][3], d1[cur][k][0], d1[cur][k][1], d1[cur][k][2], d1[cur][k][3]};
; #pragma unroll
;             for (int j = 0; j < 2; ++j) {
;                 v4u o; o.x = pk2(run[j][0], run[j][1]); o.y = pk2(run[j][2], run[j][3]); o.z = pk2(run[j][4], run[j][5]); o.w = pk2(run[j][6], run[j][7]);
;                 __builtin_nontemporal_store(o, (v4u*)(base + (size_t)c * cstride + (size_t)j * vstride));
;                 const unsigned lw[4] = {loc[cur][k][j].x, loc[cur][k][j].y, loc[cur][k][j].z, loc[cur][k][j].w};
; #pragma unroll
;                 for (int q = 0; q < 4; ++q) {
;                     run[j][2 * q] = dd[2 * q] * run[j][2 * q] + bf2f(lw[q] & 0xffffu);
;                     run[j][2 * q + 1] = dd[2 * q + 1] * run[j][2 * q + 1] + __uint_as_float(lw[q] & 0xffff0000u);
;                 }
;             }
;         }
;     }
	v_cvt_pk_bf16_f32 v40, v16, v17
	v_cvt_pk_bf16_f32 v41, v18, v19
	v_cvt_pk_bf16_f32 v42, v20, v21
	v_cvt_pk_bf16_f32 v43, v22, v23
	global_store_dwordx4 v2, v[40:43], s[12:13] nt
	v_cvt_pk_bf16_f32 v44, v24, v25
	v_cvt_pk_bf16_f32 v45, v26, v27
	v_cvt_pk_bf16_f32 v46, v28, v29
	v_cvt_pk_bf16_f32 v47, v30, v31
	global_store_dwordx4 v3, v[44:47], s[12:13] nt
	s_add_u32 s12, s12, 0x40000
	s_addc_u32 s13, s13, 0
	v_lshlrev_b32_e32 v48, 16, v112
	v_and_b32_e32 v49, 0xffff0000, v112
	v_fma_f32 v16, v120, v16, v48
	v_fma_f32 v17, v120, v17, v49
	v_lshlrev_b32_e32 v48, 16, v113
	v_and_b32_e32 v49, 0xffff0000, v113
	v_fma_f32 v18, v120, v18, v48
	v_fma_f32 v19, v120, v19, v49
	v_lshlrev_b32_e32 v48, 16, v114
	v_and_b32_e32 v49, 0xffff0000, v114
	v_fma_f32 v20, v120, v20, v48
	v_fma_f32 v21, v120, v21, v49
	v_lshlrev_b32_e32 v48, 16, v115
	v_and_b32_e32 v49, 0xffff0000, v115
	v_fma_f32 v22, v120, v22, v48
	v_fma_f32 v23, v120, v23, v49
	v_lshlrev_b32_e32 v48, 16, v116
	v_and_b32_e32 v49, 0xffff0000, v116
	v_fma_f32 v24, v120, v24, v48
	v_fma_f32 v25, v120, v25, v49
	v_lshlrev_b32_e32 v48, 16, v117
	v_and_b32_e32 v49, 0xffff0000, v117
	v_fma_f32 v26, v120, v26, v48
	v_fma_f32 v27, v120, v27, v49
	v_lshlrev_b32_e32 v48, 16, v118
	v_and_b32_e32 v49, 0xffff0000, v118
	v_fma_f32 v28, v120, v28, v48
	v_fma_f32 v29, v120, v29, v49
	v_lshlrev_b32_e32 v48, 16, v119
	v_and_b32_e32 v49, 0xffff0000, v119
	v_fma_f32 v30, v120, v30, v48
	v_fma_f32 v31, v120, v31, v49
	s_waitcnt vmcnt(23)
	v_cvt_pk_bf16_f32 v32, v16, v17
	v_cvt_pk_bf16_f32 v33, v18, v19
	v_cvt_pk_bf16_f32 v34, v20, v21
	v_cvt_pk_bf16_f32 v35, v22, v23
	global_store_dwordx4 v2, v[32:35], s[12:13] nt
	v_cvt_pk_bf16_f32 v36, v24, v25
	v_cvt_pk_bf16_f32 v37, v26, v27
	v_cvt_pk_bf16_f32 v38, v28, v29
	v_cvt_pk_bf16_f32 v39, v30, v31
	global_store_dwordx4 v3, v[36:39], s[12:13] nt
	s_add_u32 s12, s12, 0x40000
	s_addc_u32 s13, s13, 0
	v_lshlrev_b32_e32 v48, 16, v128
	v_and_b32_e32 v49, 0xffff0000, v128
	v_fma_f32 v16, v136, v16, v48
	v_fma_f32 v17, v136, v17, v49
	v_lshlrev_b32_e32 v48, 16, v129
	v_and_b32_e32 v49, 0xffff0000, v129
	v_fma_f32 v18, v136, v18, v48
	v_fma_f32 v19, v136, v19, v49
	v_lshlrev_b32_e32 v48, 16, v130
	v_and_b32_e32 v49, 0xffff0000, v130
	v_fma_f32 v20, v136, v20, v48
	v_fma_f32 v21, v136, v21, v49
	v_lshlrev_b32_e32 v48, 16, v131
	v_and_b32_e32 v49, 0xffff0000, v131
	v_fma_f32 v22, v136, v22, v48
	v_fma_f32 v23, v136, v23, v49
	v_lshlrev_b32_e32 v48, 16, v132
	v_and_b32_e32 v49, 0xffff0000, v132
	v_fma_f32 v24, v136, v24, v48
	v_fma_f32 v25, v136, v25, v49
	v_lshlrev_b32_e32 v48, 16, v133
	v_and_b32_e32 v49, 0xffff0000, v133
	v_fma_f32 v26, v136, v26, v48
	v_fma_f32 v27, v136, v27, v49
	v_lshlrev_b32_e32 v48, 16, v134
	v_and_b32_e32 v49, 0xffff0000, v134
	v_fma_f32 v28, v136, v28, v48
	v_fma_f32 v29, v136, v29, v49
	v_lshlrev_b32_e32 v48, 16, v135
	v_and_b32_e32 v49, 0xffff0000, v135
	v_fma_f32 v30, v136, v30, v48
	v_fma_f32 v31, v136, v31, v49
	s_waitcnt vmcnt(20)
	v_cvt_pk_bf16_f32 v40, v16, v17
	v_cvt_pk_bf16_f32 v41, v18, v19
	v_cvt_pk_bf16_f32 v42, v20, v21
	v_cvt_pk_bf16_f32 v43, v22, v23
	global_store_dwordx4 v2, v[40:43], s[12:13] nt
	v_cvt_pk_bf16_f32 v44, v24, v25
	v_cvt_pk_bf16_f32 v45, v26, v27
	v_cvt_pk_bf16_f32 v46, v28, v29
	v_cvt_pk_bf16_f32 v47, v30, v31
	global_store_dwordx4 v3, v[44:47], s[12:13] nt
	s_add_u32 s12, s12, 0x40000
	s_addc_u32 s13, s13, 0
	v_lshlrev_b32_e32 v48, 16, v144
	v_and_b32_e32 v49, 0xffff0000, v144
	v_fma_f32 v16, v152, v16, v48
	v_fma_f32 v17, v152, v17, v49
	v_lshlrev_b32_e32 v48, 16, v145
	v_and_b32_e32 v49, 0xffff0000, v145
	v_fma_f32 v18, v152, v18, v48
	v_fma_f32 v19, v152, v19, v49
	v_lshlrev_b32_e32 v48, 16, v146
	v_and_b32_e32 v49, 0xffff0000, v146
	v_fma_f32 v20, v152, v20, v48
	v_fma_f32 v21, v152, v21, v49
	v_lshlrev_b32_e32 v48, 16, v147
	v_and_b32_e32 v49, 0xffff0000, v147
	v_fma_f32 v22, v152, v22, v48
	v_fma_f32 v23, v152, v23, v49
	v_lshlrev_b32_e32 v48, 16, v148
	v_and_b32_e32 v49, 0xffff0000, v148
	v_fma_f32 v24, v152, v24, v48
	v_fma_f32 v25, v152, v25, v49
	v_lshlrev_b32_e32 v48, 16, v149
	v_and_b32_e32 v49, 0xffff0000, v149
	v_fma_f32 v26, v152, v26, v48
	v_fma_f32 v27, v152, v27, v49
	v_lshlrev_b32_e32 v48, 16, v150
	v_and_b32_e32 v49, 0xffff0000, v150
	v_fma_f32 v28, v152, v28, v48
	v_fma_f32 v29, v152, v29, v49
	v_lshlrev_b32_e32 v48, 16, v151
	v_and_b32_e32 v49, 0xffff0000, v151
	v_fma_f32 v30, v152, v30, v48
	v_fma_f32 v31, v152, v31, v49
	s_waitcnt vmcnt(17)
	v_cvt_pk_bf16_f32 v32, v16, v17
	v_cvt_pk_bf16_f32 v33, v18, v19
	v_cvt_pk_bf16_f32 v34, v20, v21
	v_cvt_pk_bf16_f32 v35, v22, v23
	global_store_dwordx4 v2, v[32:35], s[12:13] nt
	v_cvt_pk_bf16_f32 v36, v24, v25
	v_cvt_pk_bf16_f32 v37, v26, v27
	v_cvt_pk_bf16_f32 v38, v28, v29
	v_cvt_pk_bf16_f32 v39, v30, v31
	global_store_dwordx4 v3, v[36:39], s[12:13] nt
	s_add_u32 s12, s12, 0x40000
	s_addc_u32 s13, s13, 0
	v_lshlrev_b32_e32 v48, 16, v160
	v_and_b32_e32 v49, 0xffff0000, v160
	v_fma_f32 v16, v168, v16, v48
	v_fma_f32 v17, v168, v17, v49
	v_lshlrev_b32_e32 v48, 16, v161
	v_and_b32_e32 v49, 0xffff0000, v161
	v_fma_f32 v18, v168, v18, v48
	v_fma_f32 v19, v168, v19, v49
	v_lshlrev_b32_e32 v48, 16, v162
	v_and_b32_e32 v49, 0xffff0000, v162
	v_fma_f32 v20, v168, v20, v48
	v_fma_f32 v21, v168, v21, v49
	v_lshlrev_b32_e32 v48, 16, v163
	v_and_b32_e32 v49, 0xffff0000, v163
	v_fma_f32 v22, v168, v22, v48
	v_fma_f32 v23, v168, v23, v49
	v_lshlrev_b32_e32 v48, 16, v164
	v_and_b32_e32 v49, 0xffff0000, v164
	v_fma_f32 v24, v168, v24, v48
	v_fma_f32 v25, v168, v25, v49
	v_lshlrev_b32_e32 v48, 16, v165
	v_and_b32_e32 v49, 0xffff0000, v165
	v_fma_f32 v26, v168, v26, v48
	v_fma_f32 v27, v168, v27, v49
	v_lshlrev_b32_e32 v48, 16, v166
	v_and_b32_e32 v49, 0xffff0000, v166
	v_fma_f32 v28, v168, v28, v48
	v_fma_f32 v29, v168, v29, v49
	v_lshlrev_b32_e32 v48, 16, v167
	v_and_b32_e32 v49, 0xffff0000, v167
	v_fma_f32 v30, v168, v30, v48
	v_fma_f32 v31, v168, v31, v49
	s_waitcnt vmcnt(14)
; __device__ __forceinline__ float bf2f(unsigned h) { return __uint_as_float(h << 16); }
; __device__ __forceinline__ unsigned pk2(float lo, float hi) { return pg8::cvt_pk_bf16(lo, hi); }
; __device__ __forceinline__ void b2_scan(const Ctx& C) {
;     ...
;     if (!gla) { const int b = r >> 13, h = (r >> 9) & 15, e = r & 511;
;         base = (bf16*)(C.ws + WS_HS) + ((size_t)(b * NC) * 16 + h) * 8192 + (size_t)e * 8; vstride = 512 * 8; cstride = (size_t)16 * 8192; dec = SDEC + (b * NC) * 16 + h; dstride = 16; }
;     else { const int b = r >> 13, h = (r >> 11) & 3, q = r & 2047, doct = q & 15, vp = q >> 4;
;         base = (bf16*)(C.ws + WS_GS) + ((size_t)(b * NC) * 4 + h) * 32768 + (size_t)(2 * vp) * 128 + doct * 8; vstride = 128; cstride = (size_t)4 * 32768; dec = GDEC + ((b * NC) * 4 + h) * 128 + doct * 8; dstride = 512; }
;     float run[2][8];
; #pragma unroll
;     for (int j = 0; j < 2; ++j)
; #pragma unroll
;         for (int q = 0; q < 8; ++q) run[j][q] = 0.f;
;     v4u loc[2][4][2]; f32x4 d0[2][4], d1[2][4];
;     ...
;     B2_LOAD(0, 0);
; #pragma unroll
;     for (int g = 0; g < 8; ++g) {
;         const int cur = g & 1;
;         if (g + 1 < 8) B2_LOAD(g + 1, cur ^ 1);
; #pragma unroll
;         for (int k = 0; k < 4; ++k) {
;             const int c = 4 * g + k;
;             const float dd[8] = {d0[cur][k][0], d0[cur][k][1], d0[cur][k][2], d0[cur][k][3], d1[cur][k][0], d1[cur][k][1], d1[cur][k][2], d1[cur][k][3]};
; #pragma unroll
;             for (int j = 0; j < 2; ++j) {
;                 v4u o; o.x = pk2(run[j][0], run[j][1]); o.y = pk2(run[j][2], run[j][3]); o.z = pk2(run[j][4], run[j][5]); o.w = pk2(run[j][6], run[j][7]);
;                 __builtin_nontemporal_store(o, (v4u*)(base + (size_t)c * cstride + (size_t)j * vstride));
;                 const unsigned lw[4] = {loc[cur][k][j].x, loc[cur][k][j].y, loc[cur][k][j].z, loc[cur][k][j].w};
; #pragma unroll
;                 for (int q = 0; q < 4; ++q) {
;                     run[j][2 * q] = dd[2 * q] * run[j][2 * q] + bf2f(lw[q] & 0xffffu);
;                     run[j][2 * q + 1] = dd[2 * q + 1] * run[j][2 * q + 1] + __uint_as_float(lw[q] & 0xffff0000u);
;                 }
;             }
	v_cvt_pk_bf16_f32 v40, v16, v17
	v_cvt_pk_bf16_f32 v41, v18, v19
	v_cvt_pk_bf16_f32 v42, v20, v21
	v_cvt_pk_bf16_f32 v43, v22, v23
	global_store_dwordx4 v2, v[40:43], s[12:13] nt
	v_cvt_pk_bf16_f32 v44, v24, v25
	v_cvt_pk_bf16_f32 v45, v26, v27
	v_cvt_pk_bf16_f32 v46, v28, v29
	v_cvt_pk_bf16_f32 v47, v30, v31
	global_store_dwordx4 v3, v[44:47], s[12:13] nt
	s_add_u32 s12, s12, 0x40000
	s_addc_u32 s13, s13, 0
	v_lshlrev_b32_e32 v48, 16, v176
	v_and_b32_e32 v49, 0xffff0000, v176
	v_fma_f32 v16, v184, v16, v48
	v_fma_f32 v17, v184, v17, v49
	v_lshlrev_b32_e32 v48, 16, v177
	v_and_b32_e32 v49, 0xffff0000, v177
	v_fma_f32 v18, v184, v18, v48
	v_fma_f32 v19, v184, v19, v49
	v_lshlrev_b32_e32 v48, 16, v178
	v_and_b32_e32 v49, 0xffff0000, v178
	v_fma_f32 v20, v184, v20, v48
	v_fma_f32 v21, v184, v21, v49
	v_lshlrev_b32_e32 v48, 16, v179
	v_and_b32_e32 v49, 0xffff0000, v179
	v_fma_f32 v22, v184, v22, v48
	v_fma_f32 v23, v184, v23, v49
	v_lshlrev_b32_e32 v48, 16, v180
	v_and_b32_e32 v49, 0xffff0000, v180
	v_fma_f32 v24, v184, v24, v48
	v_fma_f32 v25, v184, v25, v49
	v_lshlrev_b32_e32 v48, 16, v181
	v_and_b32_e32 v49, 0xffff0000, v181
	v_fma_f32 v26, v184, v26, v48
	v_fma_f32 v27, v184, v27, v49
	v_lshlrev_b32_e32 v48, 16, v182
	v_and_b32_e32 v49, 0xffff0000, v182
	v_fma_f32 v28, v184, v28, v48
	v_fma_f32 v29, v184, v29, v49
	v_lshlrev_b32_e32 v48, 16, v183
	v_and_b32_e32 v49, 0xffff0000, v183
	v_fma_f32 v30, v184, v30, v48
	v_fma_f32 v31, v184, v31, v49
	s_branch .Lb2_end_l1
.Lb2_gla_l1:
	s_sub_u32 s10, s2, 128
	s_and_b32 s16, s10, 7
	s_lshl_b32 s16, s16, 7
	s_lshr_b32 s12, s10, 5
	s_add_u32 s16, s16, s12
	s_lshr_b32 s12, s10, 3
	s_and_b32 s12, s12, 3
	s_lshl_b32 s12, s12, 14
	s_lshl_b32 s10, s16, 16
	s_add_u32 s10, s10, s12
	s_lshl_b32 s16, s16, 9
	v_lshrrev_b32_e32 v2, 4, v234
	v_lshlrev_b32_e32 v2, 9, v2
	v_and_b32_e32 v5, 15, v234
	v_lshl_add_u32 v2, v5, 4, v2
	v_add_u32_e32 v3, 0x100, v2
	v_lshlrev_b32_e32 v5, 5, v5
	s_waitcnt lgkmcnt(0)
	s_add_u32 s10, s10, s18
	s_addc_u32 s11, s19, 0
	s_add_u32 s10, s10, 0x21c00000
	s_addc_u32 s11, s11, 0
	s_add_u32 s16, s16, s18
	s_addc_u32 s17, s19, 0
	s_add_u32 s16, s16, 0x25c10000
	s_addc_u32 s17, s17, 0
	s_mov_b32 s12, s10
	s_mov_b32 s13, s11
	global_load_dwordx4 v[64:67], v2, s[10:11] nt
	global_load_dwordx4 v[68:71], v3, s[10:11] nt
	global_load_dwordx4 v[72:75], v5, s[16:17]
	global_load_dwordx4 v[76:79], v5, s[16:17] offset:16
	s_add_u32 s10, s10, 0x40000
	s_addc_u32 s11, s11, 0
	s_add_u32 s16, s16, 2048
	s_addc_u32 s17, s17, 0
	global_load_dwordx4 v[80:83], v2, s[10:11] nt
	global_load_dwordx4 v[84:87], v3, s[10:11] nt
	global_load_dwordx4 v[88:91], v5, s[16:17]
	global_load_dwordx4 v[92:95], v5, s[16:17] offset:16
	s_add_u32 s10, s10, 0x40000
	s_addc_u32 s11, s11, 0
	s_add_u32 s16, s16, 2048
	s_addc_u32 s17, s17, 0
	global_load_dwordx4 v[96:99], v2, s[10:11] nt
	global_load_dwordx4 v[100:103], v3, s[10:11] nt
	global_load_dwordx4 v[104:107], v5, s[16:17]
	global_load_dwordx4 v[108:111], v5, s[16:17] offset:16
	s_add_u32 s10, s10, 0x40000
	s_addc_u32 s11, s11, 0
	s_add_u32 s16, s16, 2048
	s_addc_u32 s17, s17, 0
	global_load_dwordx4 v[112:115], v2, s[10:11] nt
	global_load_dwordx4 v[116:119], v3, s[10:11] nt
	global_load_dwordx4 v[120:123], v5, s[16:17]
	global_load_dwordx4 v[124:127], v5, s[16:17] offset:16
	s_add_u32 s10, s10, 0x40000
	s_addc_u32 s11, s11, 0
	s_add_u32 s16, s16, 2048
	s_addc_u32 s17, s17, 0
	global_load_dwordx4 v[128:131], v2, s[10:11] nt
	global_load_dwordx4 v[132:135], v3, s[10:11] nt
	global_load_dwordx4 v[136:139], v5, s[16:17]
	global_load_dwordx4 v[140:143], v5, s[16:17] offset:16
	s_add_u32 s10, s10, 0x40000
	s_addc_u32 s11, s11, 0
	s_add_u32 s16, s16, 2048
	s_addc_u32 s17, s17, 0
	global_load_dwordx4 v[144:147], v2, s[10:11] nt
	global_load_dwordx4 v[148:151], v3, s[10:11] nt
	global_load_dwordx4 v[152:155], v5, s[16:17]
	global_load_dwordx4 v[156:159], v5, s[16:17] offset:16
	s_add_u32 s10, s10, 0x40000
	s_addc_u32 s11, s11, 0
	s_add_u32 s16, s16, 2048
	s_addc_u32 s17, s17, 0
	global_load_dwordx4 v[160:163], v2, s[10:11] nt
	global_load_dwordx4 v[164:167], v3, s[10:11] nt
	global_load_dwordx4 v[168:171], v5, s[16:17]
	global_load_dwordx4 v[172:175], v5, s[16:17] offset:16
	s_add_u32 s10, s10, 0x40000
	s_addc_u32 s11, s11, 0
	s_add_u32 s16, s16, 2048
	s_addc_u32 s17, s17, 0
	global_load_dwordx4 v[176:179], v2, s[10:11] nt
	global_load_dwordx4 v[180:183], v3, s[10:11] nt
	global_load_dwordx4 v[184:187], v5, s[16:17]
	global_load_dwordx4 v[188:191], v5, s[16:17] offset:16
	s_add_u32 s10, s10, 0x40000
	s_addc_u32 s11, s11, 0
	s_add_u32 s16, s16, 2048
	s_addc_u32 s17, s17, 0
	s_waitcnt vmcnt(28)
	v_cvt_pk_bf16_f32 v32, v16, v17
	v_cvt_pk_bf16_f32 v33, v18, v19
	v_cvt_pk_bf16_f32 v34, v20, v21
	v_cvt_pk_bf16_f32 v35, v22, v23
	global_store_dwordx4 v2, v[32:35], s[12:13] nt
	v_cvt_pk_bf16_f32 v36, v24, v25
	v_cvt_pk_bf16_f32 v37, v26, v27
	v_cvt_pk_bf16_f32 v38, v28, v29
	v_cvt_pk_bf16_f32 v39, v30, v31
	global_store_dwordx4 v3, v[36:39], s[12:13] nt
	s_add_u32 s12, s12, 0x40000
	s_addc_u32 s13, s13, 0
	v_lshlrev_b32_e32 v48, 16, v64
	v_and_b32_e32 v49, 0xffff0000, v64
	v_fma_f32 v16, v72, v16, v48
	v_fma_f32 v17, v73, v17, v49
	v_lshlrev_b32_e32 v48, 16, v65
	v_and_b32_e32 v49, 0xffff0000, v65
	v_fma_f32 v18, v74, v18, v48
	v_fma_f32 v19, v75, v19, v49
	v_lshlrev_b32_e32 v48, 16, v66
	v_and_b32_e32 v49, 0xffff0000, v66
	v_fma_f32 v20, v76, v20, v48
	v_fma_f32 v21, v77, v21, v49
	v_lshlrev_b32_e32 v48, 16, v67
	v_and_b32_e32 v49, 0xffff0000, v67
	v_fma_f32 v22, v78, v22, v48
	v_fma_f32 v23, v79, v23, v49
	v_lshlrev_b32_e32 v48, 16, v68
	v_and_b32_e32 v49, 0xffff0000, v68
	v_fma_f32 v24, v72, v24, v48
	v_fma_f32 v25, v73, v25, v49
	v_lshlrev_b32_e32 v48, 16, v69
	v_and_b32_e32 v49, 0xffff0000, v69
	v_fma_f32 v26, v74, v26, v48
	v_fma_f32 v27, v75, v27, v49
	v_lshlrev_b32_e32 v48, 16, v70
	v_and_b32_e32 v49, 0xffff0000, v70
	v_fma_f32 v28, v76, v28, v48
	v_fma_f32 v29, v77, v29, v49
	v_lshlrev_b32_e32 v48, 16, v71
	v_and_b32_e32 v49, 0xffff0000, v71
	v_fma_f32 v30, v78, v30, v48
	v_fma_f32 v31, v79, v31, v49
	global_load_dwordx4 v[64:67], v2, s[10:11] nt
	global_load_dwordx4 v[68:71], v3, s[10:11] nt
	global_load_dwordx4 v[72:75], v5, s[16:17]
	global_load_dwordx4 v[76:79], v5, s[16:17] offset:16
	s_add_u32 s10, s10, 0x40000
	s_addc_u32 s11, s11, 0
	s_add_u32 s16, s16, 2048
	s_addc_u32 s17, s17, 0
	s_waitcnt vmcnt(30)
; __device__ __forceinline__ float bf2f(unsigned h) { return __uint_as_float(h << 16); }
; __device__ __forceinline__ unsigned pk2(float lo, float hi) { return pg8::cvt_pk_bf16(lo, hi); }
; __device__ __forceinline__ void b2_scan(const Ctx& C) {
;     ...
;     B2_LOAD(0, 0);
; #pragma unroll
;     for (int g = 0; g < 8; ++g) {
;         const int cur = g & 1;
;         if (g + 1 < 8) B2_LOAD(g + 1, cur ^ 1);
; #pragma unroll
;         for (int k = 0; k < 4; ++k) {
;             const int c = 4 * g + k;
;             const float dd[8] = {d0[cur][k][0], d0[cur][k][1], d0[cur][k][2], d0[cur][k][3], d1[cur][k][0], d1[cur][k][1], d1[cur][k][2], d1[cur][k][3]};
; #pragma unroll
;             for (int j = 0; j < 2; ++j) {
;                 v4u o; o.x = pk2(run[j][0], run[j][1]); o.y = pk2(run[j][2], run[j][3]); o.z = pk2(run[j][4], run[j][5]); o.w = pk2(run[j][6], run[j][7]);
;                 __builtin_nontemporal_store(o, (v4u*)(base + (size_t)c * cstride + (size_t)j * vstride));
;                 const unsigned lw[4] = {loc[cur][k][j].x, loc[cur][k][j].y, loc[cur][k][j].z, loc[cur][k][j].w};
; #pragma unroll
;                 for (int q = 0; q < 4; ++q) {
;                     run[j][2 * q] = dd[2 * q] * run[j][2 * q] + bf2f(lw[q] & 0xffffu);
;                     run[j][2 * q + 1] = dd[2 * q + 1] * run[j][2 * q + 1] + __uint_as_float(lw[q] & 0xffff0000u);
;                 }
;             }
	v_cvt_pk_bf16_f32 v40, v16, v17
	v_cvt_pk_bf16_f32 v41, v18, v19
	v_cvt_pk_bf16_f32 v42, v20, v21
	v_cvt_pk_bf16_f32 v43, v22, v23
	global_store_dwordx4 v2, v[40:43], s[12:13] nt
	v_cvt_pk_bf16_f32 v44, v24, v25
	v_cvt_pk_bf16_f32 v45, v26, v27
	v_cvt_pk_bf16_f32 v46, v28, v29
	v_cvt_pk_bf16_f32 v47, v30, v31
	global_store_dwordx4 v3, v[44:47], s[12:13] nt
	s_add_u32 s12, s12, 0x40000
	s_addc_u32 s13, s13, 0
	v_lshlrev_b32_e32 v48, 16, v80
	v_and_b32_e32 v49, 0xffff0000, v80
	v_fma_f32 v16, v88, v16, v48
	v_fma_f32 v17, v89, v17, v49
	v_lshlrev_b32_e32 v48, 16, v81
	v_and_b32_e32 v49, 0xffff0000, v81
	v_fma_f32 v18, v90, v18, v48
	v_fma_f32 v19, v91, v19, v49
	v_lshlrev_b32_e32 v48, 16, v82
	v_and_b32_e32 v49, 0xffff0000, v82
	v_fma_f32 v20, v92, v20, v48
	v_fma_f32 v21, v93, v21, v49
	v_lshlrev_b32_e32 v48, 16, v83
	v_and_b32_e32 v49, 0xffff0000, v83
	v_fma_f32 v22, v94, v22, v48
	v_fma_f32 v23, v95, v23, v49
	v_lshlrev_b32_e32 v48, 16, v84
	v_and_b32_e32 v49, 0xffff0000, v84
	v_fma_f32 v24, v88, v24, v48
	v_fma_f32 v25, v89, v25, v49
	v_lshlrev_b32_e32 v48, 16, v85
	v_and_b32_e32 v49, 0xffff0000, v85
	v_fma_f32 v26, v90, v26, v48
	v_fma_f32 v27, v91, v27, v49
	v_lshlrev_b32_e32 v48, 16, v86
	v_and_b32_e32 v49, 0xffff0000, v86
	v_fma_f32 v28, v92, v28, v48
	v_fma_f32 v29, v93, v29, v49
	v_lshlrev_b32_e32 v48, 16, v87
	v_and_b32_e32 v49, 0xffff0000, v87
	v_fma_f32 v30, v94, v30, v48
	v_fma_f32 v31, v95, v31, v49
	global_load_dwordx4 v[80:83], v2, s[10:11] nt
	global_load_dwordx4 v[84:87], v3, s[10:11] nt
	global_load_dwordx4 v[88:91], v5, s[16:17]
	global_load_dwordx4 v[92:95], v5, s[16:17] offset:16
	s_add_u32 s10, s10, 0x40000
	s_addc_u32 s11, s11, 0
	s_add_u32 s16, s16, 2048
	s_addc_u32 s17, s17, 0
	s_waitcnt vmcnt(32)
	v_cvt_pk_bf16_f32 v32, v16, v17
	v_cvt_pk_bf16_f32 v33, v18, v19
	v_cvt_pk_bf16_f32 v34, v20, v21
	v_cvt_pk_bf16_f32 v35, v22, v23
	global_store_dwordx4 v2, v[32:35], s[12:13] nt
	v_cvt_pk_bf16_f32 v36, v24, v25
	v_cvt_pk_bf16_f32 v37, v26, v27
	v_cvt_pk_bf16_f32 v38, v28, v29
	v_cvt_pk_bf16_f32 v39, v30, v31
	global_store_dwordx4 v3, v[36:39], s[12:13] nt
	s_add_u32 s12, s12, 0x40000
	s_addc_u32 s13, s13, 0
	v_lshlrev_b32_e32 v48, 16, v96
	v_and_b32_e32 v49, 0xffff0000, v96
	v_fma_f32 v16, v104, v16, v48
	v_fma_f32 v17, v105, v17, v49
	v_lshlrev_b32_e32 v48, 16, v97
	v_and_b32_e32 v49, 0xffff0000, v97
	v_fma_f32 v18, v106, v18, v48
	v_fma_f32 v19, v107, v19, v49
	v_lshlrev_b32_e32 v48, 16, v98
	v_and_b32_e32 v49, 0xffff0000, v98
	v_fma_f32 v20, v108, v20, v48
	v_fma_f32 v21, v109, v21, v49
	v_lshlrev_b32_e32 v48, 16, v99
	v_and_b32_e32 v49, 0xffff0000, v99
	v_fma_f32 v22, v110, v22, v48
	v_fma_f32 v23, v111, v23, v49
	v_lshlrev_b32_e32 v48, 16, v100
	v_and_b32_e32 v49, 0xffff0000, v100
	v_fma_f32 v24, v104, v24, v48
	v_fma_f32 v25, v105, v25, v49
	v_lshlrev_b32_e32 v48, 16, v101
	v_and_b32_e32 v49, 0xffff0000, v101
	v_fma_f32 v26, v106, v26, v48
	v_fma_f32 v27, v107, v27, v49
	v_lshlrev_b32_e32 v48, 16, v102
	v_and_b32_e32 v49, 0xffff0000, v102
	v_fma_f32 v28, v108, v28, v48
	v_fma_f32 v29, v109, v29, v49
	v_lshlrev_b32_e32 v48, 16, v103
	v_and_b32_e32 v49, 0xffff0000, v103
	v_fma_f32 v30, v110, v30, v48
	v_fma_f32 v31, v111, v31, v49
	global_load_dwordx4 v[96:99], v2, s[10:11] nt
	global_load_dwordx4 v[100:103], v3, s[10:11] nt
	global_load_dwordx4 v[104:107], v5, s[16:17]
	global_load_dwordx4 v[108:111], v5, s[16:17] offset:16
	s_add_u32 s10, s10, 0x40000
	s_addc_u32 s11, s11, 0
	s_add_u32 s16, s16, 2048
	s_addc_u32 s17, s17, 0
	s_waitcnt vmcnt(34)
	v_cvt_pk_bf16_f32 v40, v16, v17
	v_cvt_pk_bf16_f32 v41, v18, v19
	v_cvt_pk_bf16_f32 v42, v20, v21
	v_cvt_pk_bf16_f32 v43, v22, v23
	global_store_dwordx4 v2, v[40:43], s[12:13] nt
	v_cvt_pk_bf16_f32 v44, v24, v25
	v_cvt_pk_bf16_f32 v45, v26, v27
	v_cvt_pk_bf16_f32 v46, v28, v29
	v_cvt_pk_bf16_f32 v47, v30, v31
	global_store_dwordx4 v3, v[44:47], s[12:13] nt
	s_add_u32 s12, s12, 0x40000
	s_addc_u32 s13, s13, 0
	v_lshlrev_b32_e32 v48, 16, v112
	v_and_b32_e32 v49, 0xffff0000, v112
	v_fma_f32 v16, v120, v16, v48
	v_fma_f32 v17, v121, v17, v49
	v_lshlrev_b32_e32 v48, 16, v113
	v_and_b32_e32 v49, 0xffff0000, v113
	v_fma_f32 v18, v122, v18, v48
	v_fma_f32 v19, v123, v19, v49
	v_lshlrev_b32_e32 v48, 16, v114
	v_and_b32_e32 v49, 0xffff0000, v114
	v_fma_f32 v20, v124, v20, v48
	v_fma_f32 v21, v125, v21, v49
	v_lshlrev_b32_e32 v48, 16, v115
	v_and_b32_e32 v49, 0xffff0000, v115
	v_fma_f32 v22, v126, v22, v48
	v_fma_f32 v23, v127, v23, v49
	v_lshlrev_b32_e32 v48, 16, v116
	v_and_b32_e32 v49, 0xffff0000, v116
	v_fma_f32 v24, v120, v24, v48
	v_fma_f32 v25, v121, v25, v49
	v_lshlrev_b32_e32 v48, 16, v117
	v_and_b32_e32 v49, 0xffff0000, v117
	v_fma_f32 v26, v122, v26, v48
	v_fma_f32 v27, v123, v27, v49
	v_lshlrev_b32_e32 v48, 16, v118
	v_and_b32_e32 v49, 0xffff0000, v118
	v_fma_f32 v28, v124, v28, v48
	v_fma_f32 v29, v125, v29, v49
	v_lshlrev_b32_e32 v48, 16, v119
	v_and_b32_e32 v49, 0xffff0000, v119
	v_fma_f32 v30, v126, v30, v48
	v_fma_f32 v31, v127, v31, v49
	global_load_dwordx4 v[112:115], v2, s[10:11] nt
	global_load_dwordx4 v[116:119], v3, s[10:11] nt
	global_load_dwordx4 v[120:123], v5, s[16:17]
	global_load_dwordx4 v[124:127], v5, s[16:17] offset:16
	s_add_u32 s10, s10, 0x40000
	s_addc_u32 s11, s11, 0
	s_add_u32 s16, s16, 2048
	s_addc_u32 s17, s17, 0
	s_waitcnt vmcnt(36)
; __device__ __forceinline__ float bf2f(unsigned h) { return __uint_as_float(h << 16); }
; __device__ __forceinline__ unsigned pk2(float lo, float hi) { return pg8::cvt_pk_bf16(lo, hi); }
; __device__ __forceinline__ void b2_scan(const Ctx& C) {
;     ...
;     B2_LOAD(0, 0);
; #pragma unroll
;     for (int g = 0; g < 8; ++g) {
;         const int cur = g & 1;
;         if (g + 1 < 8) B2_LOAD(g + 1, cur ^ 1);
; #pragma unroll
;         for (int k = 0; k < 4; ++k) {
;             const int c = 4 * g + k;
;             const float dd[8] = {d0[cur][k][0], d0[cur][k][1], d0[cur][k][2], d0[cur][k][3], d1[cur][k][0], d1[cur][k][1], d1[cur][k][2], d1[cur][k][3]};
; #pragma unroll
;             for (int j = 0; j < 2; ++j) {
;                 v4u o; o.x = pk2(run[j][0], run[j][1]); o.y = pk2(run[j][2], run[j][3]); o.z = pk2(run[j][4], run[j][5]); o.w = pk2(run[j][6], run[j][7]);
;                 __builtin_nontemporal_store(o, (v4u*)(base + (size_t)c * cstride + (size_t)j * vstride));
;                 const unsigned lw[4] = {loc[cur][k][j].x, loc[cur][k][j].y, loc[cur][k][j].z, loc[cur][k][j].w};
; #pragma unroll
;                 for (int q = 0; q < 4; ++q) {
;                     run[j][2 * q] = dd[2 * q] * run[j][2 * q] + bf2f(lw[q] & 0xffffu);
;                     run[j][2 * q + 1] = dd[2 * q + 1] * run[j][2 * q + 1] + __uint_as_float(lw[q] & 0xffff0000u);
;                 }
;             }
	v_cvt_pk_bf16_f32 v32, v16, v17
	v_cvt_pk_bf16_f32 v33, v18, v19
	v_cvt_pk_bf16_f32 v34, v20, v21
	v_cvt_pk_bf16_f32 v35, v22, v23
	global_store_dwordx4 v2, v[32:35], s[12:13] nt
	v_cvt_pk_bf16_f32 v36, v24, v25
	v_cvt_pk_bf16_f32 v37, v26, v27
	v_cvt_pk_bf16_f32 v38, v28, v29
	v_cvt_pk_bf16_f32 v39, v30, v31
	global_store_dwordx4 v3, v[36:39], s[12:13] nt
	s_add_u32 s12, s12, 0x40000
	s_addc_u32 s13, s13, 0
	v_lshlrev_b32_e32 v48, 16, v128
	v_and_b32_e32 v49, 0xffff0000, v128
	v_fma_f32 v16, v136, v16, v48
	v_fma_f32 v17, v137, v17, v49
	v_lshlrev_b32_e32 v48, 16, v129
	v_and_b32_e32 v49, 0xffff0000, v129
	v_fma_f32 v18, v138, v18, v48
	v_fma_f32 v19, v139, v19, v49
	v_lshlrev_b32_e32 v48, 16, v130
	v_and_b32_e32 v49, 0xffff0000, v130
	v_fma_f32 v20, v140, v20, v48
	v_fma_f32 v21, v141, v21, v49
	v_lshlrev_b32_e32 v48, 16, v131
	v_and_b32_e32 v49, 0xffff0000, v131
	v_fma_f32 v22, v142, v22, v48
	v_fma_f32 v23, v143, v23, v49
	v_lshlrev_b32_e32 v48, 16, v132
	v_and_b32_e32 v49, 0xffff0000, v132
	v_fma_f32 v24, v136, v24, v48
	v_fma_f32 v25, v137, v25, v49
	v_lshlrev_b32_e32 v48, 16, v133
	v_and_b32_e32 v49, 0xffff0000, v133
	v_fma_f32 v26, v138, v26, v48
	v_fma_f32 v27, v139, v27, v49
	v_lshlrev_b32_e32 v48, 16, v134
	v_and_b32_e32 v49, 0xffff0000, v134
	v_fma_f32 v28, v140, v28, v48
	v_fma_f32 v29, v141, v29, v49
	v_lshlrev_b32_e32 v48, 16, v135
	v_and_b32_e32 v49, 0xffff0000, v135
	v_fma_f32 v30, v142, v30, v48
	v_fma_f32 v31, v143, v31, v49
	global_load_dwordx4 v[128:131], v2, s[10:11] nt
	global_load_dwordx4 v[132:135], v3, s[10:11] nt
	global_load_dwordx4 v[136:139], v5, s[16:17]
	global_load_dwordx4 v[140:143], v5, s[16:17] offset:16
	s_add_u32 s10, s10, 0x40000
	s_addc_u32 s11, s11, 0
	s_add_u32 s16, s16, 2048
	s_addc_u32 s17, s17, 0
	s_waitcnt vmcnt(38)
	v_cvt_pk_bf16_f32 v40, v16, v17
	v_cvt_pk_bf16_f32 v41, v18, v19
	v_cvt_pk_bf16_f32 v42, v20, v21
	v_cvt_pk_bf16_f32 v43, v22, v23
	global_store_dwordx4 v2, v[40:43], s[12:13] nt
	v_cvt_pk_bf16_f32 v44, v24, v25
	v_cvt_pk_bf16_f32 v45, v26, v27
	v_cvt_pk_bf16_f32 v46, v28, v29
	v_cvt_pk_bf16_f32 v47, v30, v31
	global_store_dwordx4 v3, v[44:47], s[12:13] nt
	s_add_u32 s12, s12, 0x40000
	s_addc_u32 s13, s13, 0
	v_lshlrev_b32_e32 v48, 16, v144
	v_and_b32_e32 v49, 0xffff0000, v144
	v_fma_f32 v16, v152, v16, v48
	v_fma_f32 v17, v153, v17, v49
	v_lshlrev_b32_e32 v48, 16, v145
	v_and_b32_e32 v49, 0xffff0000, v145
	v_fma_f32 v18, v154, v18, v48
	v_fma_f32 v19, v155, v19, v49
	v_lshlrev_b32_e32 v48, 16, v146
	v_and_b32_e32 v49, 0xffff0000, v146
	v_fma_f32 v20, v156, v20, v48
	v_fma_f32 v21, v157, v21, v49
	v_lshlrev_b32_e32 v48, 16, v147
	v_and_b32_e32 v49, 0xffff0000, v147
	v_fma_f32 v22, v158, v22, v48
	v_fma_f32 v23, v159, v23, v49
	v_lshlrev_b32_e32 v48, 16, v148
	v_and_b32_e32 v49, 0xffff0000, v148
	v_fma_f32 v24, v152, v24, v48
	v_fma_f32 v25, v153, v25, v49
	v_lshlrev_b32_e32 v48, 16, v149
	v_and_b32_e32 v49, 0xffff0000, v149
	v_fma_f32 v26, v154, v26, v48
	v_fma_f32 v27, v155, v27, v49
	v_lshlrev_b32_e32 v48, 16, v150
	v_and_b32_e32 v49, 0xffff0000, v150
	v_fma_f32 v28, v156, v28, v48
	v_fma_f32 v29, v157, v29, v49
	v_lshlrev_b32_e32 v48, 16, v151
	v_and_b32_e32 v49, 0xffff0000, v151
	v_fma_f32 v30, v158, v30, v48
	v_fma_f32 v31, v159, v31, v49
	global_load_dwordx4 v[144:147], v2, s[10:11] nt
	global_load_dwordx4 v[148:151], v3, s[10:11] nt
	global_load_dwordx4 v[152:155], v5, s[16:17]
	global_load_dwordx4 v[156:159], v5, s[16:17] offset:16
	s_add_u32 s10, s10, 0x40000
	s_addc_u32 s11, s11, 0
	s_add_u32 s16, s16, 2048
	s_addc_u32 s17, s17, 0
	s_waitcnt vmcnt(40)
	v_cvt_pk_bf16_f32 v32, v16, v17
	v_cvt_pk_bf16_f32 v33, v18, v19
	v_cvt_pk_bf16_f32 v34, v20, v21
	v_cvt_pk_bf16_f32 v35, v22, v23
	global_store_dwordx4 v2, v[32:35], s[12:13] nt
	v_cvt_pk_bf16_f32 v36, v24, v25
	v_cvt_pk_bf16_f32 v37, v26, v27
	v_cvt_pk_bf16_f32 v38, v28, v29
	v_cvt_pk_bf16_f32 v39, v30, v31
	global_store_dwordx4 v3, v[36:39], s[12:13] nt
	s_add_u32 s12, s12, 0x40000
	s_addc_u32 s13, s13, 0
	v_lshlrev_b32_e32 v48, 16, v160
	v_and_b32_e32 v49, 0xffff0000, v160
	v_fma_f32 v16, v168, v16, v48
	v_fma_f32 v17, v169, v17, v49
	v_lshlrev_b32_e32 v48, 16, v161
	v_and_b32_e32 v49, 0xffff0000, v161
	v_fma_f32 v18, v170, v18, v48
	v_fma_f32 v19, v171, v19, v49
	v_lshlrev_b32_e32 v48, 16, v162
	v_and_b32_e32 v49, 0xffff0000, v162
	v_fma_f32 v20, v172, v20, v48
	v_fma_f32 v21, v173, v21, v49
	v_lshlrev_b32_e32 v48, 16, v163
	v_and_b32_e32 v49, 0xffff0000, v163
	v_fma_f32 v22, v174, v22, v48
	v_fma_f32 v23, v175, v23, v49
	v_lshlrev_b32_e32 v48, 16, v164
	v_and_b32_e32 v49, 0xffff0000, v164
	v_fma_f32 v24, v168, v24, v48
	v_fma_f32 v25, v169, v25, v49
	v_lshlrev_b32_e32 v48, 16, v165
	v_and_b32_e32 v49, 0xffff0000, v165
	v_fma_f32 v26, v170, v26, v48
	v_fma_f32 v27, v171, v27, v49
	v_lshlrev_b32_e32 v48, 16, v166
	v_and_b32_e32 v49, 0xffff0000, v166
	v_fma_f32 v28, v172, v28, v48
	v_fma_f32 v29, v173, v29, v49
	v_lshlrev_b32_e32 v48, 16, v167
	v_and_b32_e32 v49, 0xffff0000, v167
	v_fma_f32 v30, v174, v30, v48
	v_fma_f32 v31, v175, v31, v49
	global_load_dwordx4 v[160:163], v2, s[10:11] nt
	global_load_dwordx4 v[164:167], v3, s[10:11] nt
	global_load_dwordx4 v[168:171], v5, s[16:17]
	global_load_dwordx4 v[172:175], v5, s[16:17] offset:16
	s_add_u32 s10, s10, 0x40000
	s_addc_u32 s11, s11, 0
	s_add_u32 s16, s16, 2048
	s_addc_u32 s17, s17, 0
	s_waitcnt vmcnt(42)
; __device__ __forceinline__ float bf2f(unsigned h) { return __uint_as_float(h << 16); }
; __device__ __forceinline__ unsigned pk2(float lo, float hi) { return pg8::cvt_pk_bf16(lo, hi); }
; __device__ __forceinline__ void b2_scan(const Ctx& C) {
;     ...
;     B2_LOAD(0, 0);
; #pragma unroll
;     for (int g = 0; g < 8; ++g) {
;         const int cur = g & 1;
;         if (g + 1 < 8) B2_LOAD(g + 1, cur ^ 1);
; #pragma unroll
;         for (int k = 0; k < 4; ++k) {
;             const int c = 4 * g + k;
;             const float dd[8] = {d0[cur][k][0], d0[cur][k][1], d0[cur][k][2], d0[cur][k][3], d1[cur][k][0], d1[cur][k][1], d1[cur][k][2], d1[cur][k][3]};
; #pragma unroll
;             for (int j = 0; j < 2; ++j) {
;                 v4u o; o.x = pk2(run[j][0], run[j][1]); o.y = pk2(run[j][2], run[j][3]); o.z = pk2(run[j][4], run[j][5]); o.w = pk2(run[j][6], run[j][7]);
;                 __builtin_nontemporal_store(o, (v4u*)(base + (size_t)c * cstride + (size_t)j * vstride));
;                 const unsigned lw[4] = {loc[cur][k][j].x, loc[cur][k][j].y, loc[cur][k][j].z, loc[cur][k][j].w};
; #pragma unroll
;                 for (int q = 0; q < 4; ++q) {
;                     run[j][2 * q] = dd[2 * q] * run[j][2 * q] + bf2f(lw[q] & 0xffffu);
;                     run[j][2 * q + 1] = dd[2 * q + 1] * run[j][2 * q + 1] + __uint_as_float(lw[q] & 0xffff0000u);
;                 }
;             }
	v_cvt_pk_bf16_f32 v40, v16, v17
	v_cvt_pk_bf16_f32 v41, v18, v19
	v_cvt_pk_bf16_f32 v42, v20, v21
	v_cvt_pk_bf16_f32 v43, v22, v23
	global_store_dwordx4 v2, v[40:43], s[12:13] nt
	v_cvt_pk_bf16_f32 v44, v24, v25
	v_cvt_pk_bf16_f32 v45, v26, v27
	v_cvt_pk_bf16_f32 v46, v28, v29
	v_cvt_pk_bf16_f32 v47, v30, v31
	global_store_dwordx4 v3, v[44:47], s[12:13] nt
	s_add_u32 s12, s12, 0x40000
	s_addc_u32 s13, s13, 0
	v_lshlrev_b32_e32 v48, 16, v176
	v_and_b32_e32 v49, 0xffff0000, v176
	v_fma_f32 v16, v184, v16, v48
	v_fma_f32 v17, v185, v17, v49
	v_lshlrev_b32_e32 v48, 16, v177
	v_and_b32_e32 v49, 0xffff0000, v177
	v_fma_f32 v18, v186, v18, v48
	v_fma_f32 v19, v187, v19, v49
	v_lshlrev_b32_e32 v48, 16, v178
	v_and_b32_e32 v49, 0xffff0000, v178
	v_fma_f32 v20, v188, v20, v48
	v_fma_f32 v21, v189, v21, v49
	v_lshlrev_b32_e32 v48, 16, v179
	v_and_b32_e32 v49, 0xffff0000, v179
	v_fma_f32 v22, v190, v22, v48
	v_fma_f32 v23, v191, v23, v49
	v_lshlrev_b32_e32 v48, 16, v180
	v_and_b32_e32 v49, 0xffff0000, v180
	v_fma_f32 v24, v184, v24, v48
	v_fma_f32 v25, v185, v25, v49
	v_lshlrev_b32_e32 v48, 16, v181
	v_and_b32_e32 v49, 0xffff0000, v181
	v_fma_f32 v26, v186, v26, v48
	v_fma_f32 v27, v187, v27, v49
	v_lshlrev_b32_e32 v48, 16, v182
	v_and_b32_e32 v49, 0xffff0000, v182
	v_fma_f32 v28, v188, v28, v48
	v_fma_f32 v29, v189, v29, v49
	v_lshlrev_b32_e32 v48, 16, v183
	v_and_b32_e32 v49, 0xffff0000, v183
	v_fma_f32 v30, v190, v30, v48
	v_fma_f32 v31, v191, v31, v49
	global_load_dwordx4 v[176:179], v2, s[10:11] nt
	global_load_dwordx4 v[180:183], v3, s[10:11] nt
	global_load_dwordx4 v[184:187], v5, s[16:17]
	global_load_dwordx4 v[188:191], v5, s[16:17] offset:16
	s_add_u32 s10, s10, 0x40000
	s_addc_u32 s11, s11, 0
	s_add_u32 s16, s16, 2048
	s_addc_u32 s17, s17, 0
	s_waitcnt vmcnt(42)
	v_cvt_pk_bf16_f32 v32, v16, v17
	v_cvt_pk_bf16_f32 v33, v18, v19
	v_cvt_pk_bf16_f32 v34, v20, v21
	v_cvt_pk_bf16_f32 v35, v22, v23
	global_store_dwordx4 v2, v[32:35], s[12:13] nt
	v_cvt_pk_bf16_f32 v36, v24, v25
	v_cvt_pk_bf16_f32 v37, v26, v27
	v_cvt_pk_bf16_f32 v38, v28, v29
	v_cvt_pk_bf16_f32 v39, v30, v31
	global_store_dwordx4 v3, v[36:39], s[12:13] nt
	s_add_u32 s12, s12, 0x40000
	s_addc_u32 s13, s13, 0
	v_lshlrev_b32_e32 v48, 16, v64
	v_and_b32_e32 v49, 0xffff0000, v64
	v_fma_f32 v16, v72, v16, v48
	v_fma_f32 v17, v73, v17, v49
	v_lshlrev_b32_e32 v48, 16, v65
	v_and_b32_e32 v49, 0xffff0000, v65
	v_fma_f32 v18, v74, v18, v48
	v_fma_f32 v19, v75, v19, v49
	v_lshlrev_b32_e32 v48, 16, v66
	v_and_b32_e32 v49, 0xffff0000, v66
	v_fma_f32 v20, v76, v20, v48
	v_fma_f32 v21, v77, v21, v49
	v_lshlrev_b32_e32 v48, 16, v67
	v_and_b32_e32 v49, 0xffff0000, v67
	v_fma_f32 v22, v78, v22, v48
	v_fma_f32 v23, v79, v23, v49
	v_lshlrev_b32_e32 v48, 16, v68
	v_and_b32_e32 v49, 0xffff0000, v68
	v_fma_f32 v24, v72, v24, v48
	v_fma_f32 v25, v73, v25, v49
	v_lshlrev_b32_e32 v48, 16, v69
	v_and_b32_e32 v49, 0xffff0000, v69
	v_fma_f32 v26, v74, v26, v48
	v_fma_f32 v27, v75, v27, v49
	v_lshlrev_b32_e32 v48, 16, v70
	v_and_b32_e32 v49, 0xffff0000, v70
	v_fma_f32 v28, v76, v28, v48
	v_fma_f32 v29, v77, v29, v49
	v_lshlrev_b32_e32 v48, 16, v71
	v_and_b32_e32 v49, 0xffff0000, v71
	v_fma_f32 v30, v78, v30, v48
	v_fma_f32 v31, v79, v31, v49
	global_load_dwordx4 v[64:67], v2, s[10:11] nt
	global_load_dwordx4 v[68:71], v3, s[10:11] nt
	global_load_dwordx4 v[72:75], v5, s[16:17]
	global_load_dwordx4 v[76:79], v5, s[16:17] offset:16
	s_add_u32 s10, s10, 0x40000
	s_addc_u32 s11, s11, 0
	s_add_u32 s16, s16, 2048
	s_addc_u32 s17, s17, 0
	s_waitcnt vmcnt(42)
	v_cvt_pk_bf16_f32 v40, v16, v17
	v_cvt_pk_bf16_f32 v41, v18, v19
	v_cvt_pk_bf16_f32 v42, v20, v21
	v_cvt_pk_bf16_f32 v43, v22, v23
	global_store_dwordx4 v2, v[40:43], s[12:13] nt
	v_cvt_pk_bf16_f32 v44, v24, v25
	v_cvt_pk_bf16_f32 v45, v26, v27
	v_cvt_pk_bf16_f32 v46, v28, v29
	v_cvt_pk_bf16_f32 v47, v30, v31
	global_store_dwordx4 v3, v[44:47], s[12:13] nt
	s_add_u32 s12, s12, 0x40000
	s_addc_u32 s13, s13, 0
	v_lshlrev_b32_e32 v48, 16, v80
	v_and_b32_e32 v49, 0xffff0000, v80
	v_fma_f32 v16, v88, v16, v48
	v_fma_f32 v17, v89, v17, v49
	v_lshlrev_b32_e32 v48, 16, v81
	v_and_b32_e32 v49, 0xffff0000, v81
	v_fma_f32 v18, v90, v18, v48
	v_fma_f32 v19, v91, v19, v49
	v_lshlrev_b32_e32 v48, 16, v82
	v_and_b32_e32 v49, 0xffff0000, v82
	v_fma_f32 v20, v92, v20, v48
	v_fma_f32 v21, v93, v21, v49
	v_lshlrev_b32_e32 v48, 16, v83
	v_and_b32_e32 v49, 0xffff0000, v83
	v_fma_f32 v22, v94, v22, v48
	v_fma_f32 v23, v95, v23, v49
	v_lshlrev_b32_e32 v48, 16, v84
	v_and_b32_e32 v49, 0xffff0000, v84
	v_fma_f32 v24, v88, v24, v48
	v_fma_f32 v25, v89, v25, v49
	v_lshlrev_b32_e32 v48, 16, v85
	v_and_b32_e32 v49, 0xffff0000, v85
	v_fma_f32 v26, v90, v26, v48
	v_fma_f32 v27, v91, v27, v49
	v_lshlrev_b32_e32 v48, 16, v86
	v_and_b32_e32 v49, 0xffff0000, v86
	v_fma_f32 v28, v92, v28, v48
	v_fma_f32 v29, v93, v29, v49
	v_lshlrev_b32_e32 v48, 16, v87
	v_and_b32_e32 v49, 0xffff0000, v87
	v_fma_f32 v30, v94, v30, v48
	v_fma_f32 v31, v95, v31, v49
	global_load_dwordx4 v[80:83], v2, s[10:11] nt
	global_load_dwordx4 v[84:87], v3, s[10:11] nt
	global_load_dwordx4 v[88:91], v5, s[16:17]
	global_load_dwordx4 v[92:95], v5, s[16:17] offset:16
	s_add_u32 s10, s10, 0x40000
	s_addc_u32 s11, s11, 0
	s_add_u32 s16, s16, 2048
	s_addc_u32 s17, s17, 0
	s_waitcnt vmcnt(42)
; __device__ __forceinline__ float bf2f(unsigned h) { return __uint_as_float(h << 16); }
; __device__ __forceinline__ unsigned pk2(float lo, float hi) { return pg8::cvt_pk_bf16(lo, hi); }
; __device__ __forceinline__ void b2_scan(const Ctx& C) {
;     ...
;     B2_LOAD(0, 0);
; #pragma unroll
;     for (int g = 0; g < 8; ++g) {
;         const int cur = g & 1;
;         if (g + 1 < 8) B2_LOAD(g + 1, cur ^ 1);
; #pragma unroll
;         for (int k = 0; k < 4; ++k) {
;             const int c = 4 * g + k;
;             const float dd[8] = {d0[cur][k][0], d0[cur][k][1], d0[cur][k][2], d0[cur][k][3], d1[cur][k][0], d1[cur][k][1], d1[cur][k][2], d1[cur][k][3]};
; #pragma unroll
;             for (int j = 0; j < 2; ++j) {
;                 v4u o; o.x = pk2(run[j][0], run[j][1]); o.y = pk2(run[j][2], run[j][3]); o.z = pk2(run[j][4], run[j][5]); o.w = pk2(run[j][6], run[j][7]);
;                 __builtin_nontemporal_store(o, (v4u*)(base + (size_t)c * cstride + (size_t)j * vstride));
;                 const unsigned lw[4] = {loc[cur][k][j].x, loc[cur][k][j].y, loc[cur][k][j].z, loc[cur][k][j].w};
; #pragma unroll
;                 for (int q = 0; q < 4; ++q) {
;                     run[j][2 * q] = dd[2 * q] * run[j][2 * q] + bf2f(lw[q] & 0xffffu);
;                     run[j][2 * q + 1] = dd[2 * q + 1] * run[j][2 * q + 1] + __uint_as_float(lw[q] & 0xffff0000u);
;                 }
;             }
	v_cvt_pk_bf16_f32 v32, v16, v17
	v_cvt_pk_bf16_f32 v33, v18, v19
	v_cvt_pk_bf16_f32 v34, v20, v21
	v_cvt_pk_bf16_f32 v35, v22, v23
	global_store_dwordx4 v2, v[32:35], s[12:13] nt
	v_cvt_pk_bf16_f32 v36, v24, v25
	v_cvt_pk_bf16_f32 v37, v26, v27
	v_cvt_pk_bf16_f32 v38, v28, v29
	v_cvt_pk_bf16_f32 v39, v30, v31
	global_store_dwordx4 v3, v[36:39], s[12:13] nt
	s_add_u32 s12, s12, 0x40000
	s_addc_u32 s13, s13, 0
	v_lshlrev_b32_e32 v48, 16, v96
	v_and_b32_e32 v49, 0xffff0000, v96
	v_fma_f32 v16, v104, v16, v48
	v_fma_f32 v17, v105, v17, v49
	v_lshlrev_b32_e32 v48, 16, v97
	v_and_b32_e32 v49, 0xffff0000, v97
	v_fma_f32 v18, v106, v18, v48
	v_fma_f32 v19, v107, v19, v49
	v_lshlrev_b32_e32 v48, 16, v98
	v_and_b32_e32 v49, 0xffff0000, v98
	v_fma_f32 v20, v108, v20, v48
	v_fma_f32 v21, v109, v21, v49
	v_lshlrev_b32_e32 v48, 16, v99
	v_and_b32_e32 v49, 0xffff0000, v99
	v_fma_f32 v22, v110, v22, v48
	v_fma_f32 v23, v111, v23, v49
	v_lshlrev_b32_e32 v48, 16, v100
	v_and_b32_e32 v49, 0xffff0000, v100
	v_fma_f32 v24, v104, v24, v48
	v_fma_f32 v25, v105, v25, v49
	v_lshlrev_b32_e32 v48, 16, v101
	v_and_b32_e32 v49, 0xffff0000, v101
	v_fma_f32 v26, v106, v26, v48
	v_fma_f32 v27, v107, v27, v49
	v_lshlrev_b32_e32 v48, 16, v102
	v_and_b32_e32 v49, 0xffff0000, v102
	v_fma_f32 v28, v108, v28, v48
	v_fma_f32 v29, v109, v29, v49
	v_lshlrev_b32_e32 v48, 16, v103
	v_and_b32_e32 v49, 0xffff0000, v103
	v_fma_f32 v30, v110, v30, v48
	v_fma_f32 v31, v111, v31, v49
	global_load_dwordx4 v[96:99], v2, s[10:11] nt
	global_load_dwordx4 v[100:103], v3, s[10:11] nt
	global_load_dwordx4 v[104:107], v5, s[16:17]
	global_load_dwordx4 v[108:111], v5, s[16:17] offset:16
	s_add_u32 s10, s10, 0x40000
	s_addc_u32 s11, s11, 0
	s_add_u32 s16, s16, 2048
	s_addc_u32 s17, s17, 0
	s_waitcnt vmcnt(42)
	v_cvt_pk_bf16_f32 v40, v16, v17
	v_cvt_pk_bf16_f32 v41, v18, v19
	v_cvt_pk_bf16_f32 v42, v20, v21
	v_cvt_pk_bf16_f32 v43, v22, v23
	global_store_dwordx4 v2, v[40:43], s[12:13] nt
	v_cvt_pk_bf16_f32 v44, v24, v25
	v_cvt_pk_bf16_f32 v45, v26, v27
	v_cvt_pk_bf16_f32 v46, v28, v29
	v_cvt_pk_bf16_f32 v47, v30, v31
	global_store_dwordx4 v3, v[44:47], s[12:13] nt
	s_add_u32 s12, s12, 0x40000
	s_addc_u32 s13, s13, 0
	v_lshlrev_b32_e32 v48, 16, v112
	v_and_b32_e32 v49, 0xffff0000, v112
	v_fma_f32 v16, v120, v16, v48
	v_fma_f32 v17, v121, v17, v49
	v_lshlrev_b32_e32 v48, 16, v113
	v_and_b32_e32 v49, 0xffff0000, v113
	v_fma_f32 v18, v122, v18, v48
	v_fma_f32 v19, v123, v19, v49
	v_lshlrev_b32_e32 v48, 16, v114
	v_and_b32_e32 v49, 0xffff0000, v114
	v_fma_f32 v20, v124, v20, v48
	v_fma_f32 v21, v125, v21, v49
	v_lshlrev_b32_e32 v48, 16, v115
	v_and_b32_e32 v49, 0xffff0000, v115
	v_fma_f32 v22, v126, v22, v48
	v_fma_f32 v23, v127, v23, v49
	v_lshlrev_b32_e32 v48, 16, v116
	v_and_b32_e32 v49, 0xffff0000, v116
	v_fma_f32 v24, v120, v24, v48
	v_fma_f32 v25, v121, v25, v49
	v_lshlrev_b32_e32 v48, 16, v117
	v_and_b32_e32 v49, 0xffff0000, v117
	v_fma_f32 v26, v122, v26, v48
	v_fma_f32 v27, v123, v27, v49
	v_lshlrev_b32_e32 v48, 16, v118
	v_and_b32_e32 v49, 0xffff0000, v118
	v_fma_f32 v28, v124, v28, v48
	v_fma_f32 v29, v125, v29, v49
	v_lshlrev_b32_e32 v48, 16, v119
	v_and_b32_e32 v49, 0xffff0000, v119
	v_fma_f32 v30, v126, v30, v48
	v_fma_f32 v31, v127, v31, v49
	global_load_dwordx4 v[112:115], v2, s[10:11] nt
	global_load_dwordx4 v[116:119], v3, s[10:11] nt
	global_load_dwordx4 v[120:123], v5, s[16:17]
	global_load_dwordx4 v[124:127], v5, s[16:17] offset:16
	s_add_u32 s10, s10, 0x40000
	s_addc_u32 s11, s11, 0
	s_add_u32 s16, s16, 2048
	s_addc_u32 s17, s17, 0
	s_waitcnt vmcnt(42)
	v_cvt_pk_bf16_f32 v32, v16, v17
	v_cvt_pk_bf16_f32 v33, v18, v19
	v_cvt_pk_bf16_f32 v34, v20, v21
	v_cvt_pk_bf16_f32 v35, v22, v23
	global_store_dwordx4 v2, v[32:35], s[12:13] nt
	v_cvt_pk_bf16_f32 v36, v24, v25
	v_cvt_pk_bf16_f32 v37, v26, v27
	v_cvt_pk_bf16_f32 v38, v28, v29
	v_cvt_pk_bf16_f32 v39, v30, v31
	global_store_dwordx4 v3, v[36:39], s[12:13] nt
	s_add_u32 s12, s12, 0x40000
	s_addc_u32 s13, s13, 0
	v_lshlrev_b32_e32 v48, 16, v128
	v_and_b32_e32 v49, 0xffff0000, v128
	v_fma_f32 v16, v136, v16, v48
	v_fma_f32 v17, v137, v17, v49
	v_lshlrev_b32_e32 v48, 16, v129
	v_and_b32_e32 v49, 0xffff0000, v129
	v_fma_f32 v18, v138, v18, v48
	v_fma_f32 v19, v139, v19, v49
	v_lshlrev_b32_e32 v48, 16, v130
	v_and_b32_e32 v49, 0xffff0000, v130
	v_fma_f32 v20, v140, v20, v48
	v_fma_f32 v21, v141, v21, v49
	v_lshlrev_b32_e32 v48, 16, v131
	v_and_b32_e32 v49, 0xffff0000, v131
	v_fma_f32 v22, v142, v22, v48
	v_fma_f32 v23, v143, v23, v49
	v_lshlrev_b32_e32 v48, 16, v132
	v_and_b32_e32 v49, 0xffff0000, v132
	v_fma_f32 v24, v136, v24, v48
	v_fma_f32 v25, v137, v25, v49
	v_lshlrev_b32_e32 v48, 16, v133
	v_and_b32_e32 v49, 0xffff0000, v133
	v_fma_f32 v26, v138, v26, v48
	v_fma_f32 v27, v139, v27, v49
	v_lshlrev_b32_e32 v48, 16, v134
	v_and_b32_e32 v49, 0xffff0000, v134
	v_fma_f32 v28, v140, v28, v48
	v_fma_f32 v29, v141, v29, v49
	v_lshlrev_b32_e32 v48, 16, v135
	v_and_b32_e32 v49, 0xffff0000, v135
	v_fma_f32 v30, v142, v30, v48
	v_fma_f32 v31, v143, v31, v49
	global_load_dwordx4 v[128:131], v2, s[10:11] nt
	global_load_dwordx4 v[132:135], v3, s[10:11] nt
	global_load_dwordx4 v[136:139], v5, s[16:17]
	global_load_dwordx4 v[140:143], v5, s[16:17] offset:16
	s_add_u32 s10, s10, 0x40000
	s_addc_u32 s11, s11, 0
	s_add_u32 s16, s16, 2048
	s_addc_u32 s17, s17, 0
	s_waitcnt vmcnt(42)
; __device__ __forceinline__ float bf2f(unsigned h) { return __uint_as_float(h << 16); }
; __device__ __forceinline__ unsigned pk2(float lo, float hi) { return pg8::cvt_pk_bf16(lo, hi); }
; __device__ __forceinline__ void b2_scan(const Ctx& C) {
;     ...
;     B2_LOAD(0, 0);
; #pragma unroll
;     for (int g = 0; g < 8; ++g) {
;         const int cur = g & 1;
;         if (g + 1 < 8) B2_LOAD(g + 1, cur ^ 1);
; #pragma unroll
;         for (int k = 0; k < 4; ++k) {
;             const int c = 4 * g + k;
;             const float dd[8] = {d0[cur][k][0], d0[cur][k][1], d0[cur][k][2], d0[cur][k][3], d1[cur][k][0], d1[cur][k][1], d1[cur][k][2], d1[cur][k][3]};
; #pragma unroll
;             for (int j = 0; j < 2; ++j) {
;                 v4u o; o.x = pk2(run[j][0], run[j][1]); o.y = pk2(run[j][2], run[j][3]); o.z = pk2(run[j][4], run[j][5]); o.w = pk2(run[j][6], run[j][7]);
;                 __builtin_nontemporal_store(o, (v4u*)(base + (size_t)c * cstride + (size_t)j * vstride));
;                 const unsigned lw[4] = {loc[cur][k][j].x, loc[cur][k][j].y, loc[cur][k][j].z, loc[cur][k][j].w};
; #pragma unroll
;                 for (int q = 0; q < 4; ++q) {
;                     run[j][2 * q] = dd[2 * q] * run[j][2 * q] + bf2f(lw[q] & 0xffffu);
;                     run[j][2 * q + 1] = dd[2 * q + 1] * run[j][2 * q + 1] + __uint_as_float(lw[q] & 0xffff0000u);
;                 }
;             }
	v_cvt_pk_bf16_f32 v40, v16, v17
	v_cvt_pk_bf16_f32 v41, v18, v19
	v_cvt_pk_bf16_f32 v42, v20, v21
	v_cvt_pk_bf16_f32 v43, v22, v23
	global_store_dwordx4 v2, v[40:43], s[12:13] nt
	v_cvt_pk_bf16_f32 v44, v24, v25
	v_cvt_pk_bf16_f32 v45, v26, v27
	v_cvt_pk_bf16_f32 v46, v28, v29
	v_cvt_pk_bf16_f32 v47, v30, v31
	global_store_dwordx4 v3, v[44:47], s[12:13] nt
	s_add_u32 s12, s12, 0x40000
	s_addc_u32 s13, s13, 0
	v_lshlrev_b32_e32 v48, 16, v144
	v_and_b32_e32 v49, 0xffff0000, v144
	v_fma_f32 v16, v152, v16, v48
	v_fma_f32 v17, v153, v17, v49
	v_lshlrev_b32_e32 v48, 16, v145
	v_and_b32_e32 v49, 0xffff0000, v145
	v_fma_f32 v18, v154, v18, v48
	v_fma_f32 v19, v155, v19, v49
	v_lshlrev_b32_e32 v48, 16, v146
	v_and_b32_e32 v49, 0xffff0000, v146
	v_fma_f32 v20, v156, v20, v48
	v_fma_f32 v21, v157, v21, v49
	v_lshlrev_b32_e32 v48, 16, v147
	v_and_b32_e32 v49, 0xffff0000, v147
	v_fma_f32 v22, v158, v22, v48
	v_fma_f32 v23, v159, v23, v49
	v_lshlrev_b32_e32 v48, 16, v148
	v_and_b32_e32 v49, 0xffff0000, v148
	v_fma_f32 v24, v152, v24, v48
	v_fma_f32 v25, v153, v25, v49
	v_lshlrev_b32_e32 v48, 16, v149
	v_and_b32_e32 v49, 0xffff0000, v149
	v_fma_f32 v26, v154, v26, v48
	v_fma_f32 v27, v155, v27, v49
	v_lshlrev_b32_e32 v48, 16, v150
	v_and_b32_e32 v49, 0xffff0000, v150
	v_fma_f32 v28, v156, v28, v48
	v_fma_f32 v29, v157, v29, v49
	v_lshlrev_b32_e32 v48, 16, v151
	v_and_b32_e32 v49, 0xffff0000, v151
	v_fma_f32 v30, v158, v30, v48
	v_fma_f32 v31, v159, v31, v49
	global_load_dwordx4 v[144:147], v2, s[10:11] nt
	global_load_dwordx4 v[148:151], v3, s[10:11] nt
	global_load_dwordx4 v[152:155], v5, s[16:17]
	global_load_dwordx4 v[156:159], v5, s[16:17] offset:16
	s_add_u32 s10, s10, 0x40000
	s_addc_u32 s11, s11, 0
	s_add_u32 s16, s16, 2048
	s_addc_u32 s17, s17, 0
	s_waitcnt vmcnt(42)
	v_cvt_pk_bf16_f32 v32, v16, v17
	v_cvt_pk_bf16_f32 v33, v18, v19
	v_cvt_pk_bf16_f32 v34, v20, v21
	v_cvt_pk_bf16_f32 v35, v22, v23
	global_store_dwordx4 v2, v[32:35], s[12:13] nt
	v_cvt_pk_bf16_f32 v36, v24, v25
	v_cvt_pk_bf16_f32 v37, v26, v27
	v_cvt_pk_bf16_f32 v38, v28, v29
	v_cvt_pk_bf16_f32 v39, v30, v31
	global_store_dwordx4 v3, v[36:39], s[12:13] nt
	s_add_u32 s12, s12, 0x40000
	s_addc_u32 s13, s13, 0
	v_lshlrev_b32_e32 v48, 16, v160
	v_and_b32_e32 v49, 0xffff0000, v160
	v_fma_f32 v16, v168, v16, v48
	v_fma_f32 v17, v169, v17, v49
	v_lshlrev_b32_e32 v48, 16, v161
	v_and_b32_e32 v49, 0xffff0000, v161
	v_fma_f32 v18, v170, v18, v48
	v_fma_f32 v19, v171, v19, v49
	v_lshlrev_b32_e32 v48, 16, v162
	v_and_b32_e32 v49, 0xffff0000, v162
	v_fma_f32 v20, v172, v20, v48
	v_fma_f32 v21, v173, v21, v49
	v_lshlrev_b32_e32 v48, 16, v163
	v_and_b32_e32 v49, 0xffff0000, v163
	v_fma_f32 v22, v174, v22, v48
	v_fma_f32 v23, v175, v23, v49
	v_lshlrev_b32_e32 v48, 16, v164
	v_and_b32_e32 v49, 0xffff0000, v164
	v_fma_f32 v24, v168, v24, v48
	v_fma_f32 v25, v169, v25, v49
	v_lshlrev_b32_e32 v48, 16, v165
	v_and_b32_e32 v49, 0xffff0000, v165
	v_fma_f32 v26, v170, v26, v48
	v_fma_f32 v27, v171, v27, v49
	v_lshlrev_b32_e32 v48, 16, v166
	v_and_b32_e32 v49, 0xffff0000, v166
	v_fma_f32 v28, v172, v28, v48
	v_fma_f32 v29, v173, v29, v49
	v_lshlrev_b32_e32 v48, 16, v167
	v_and_b32_e32 v49, 0xffff0000, v167
	v_fma_f32 v30, v174, v30, v48
	v_fma_f32 v31, v175, v31, v49
	global_load_dwordx4 v[160:163], v2, s[10:11] nt
	global_load_dwordx4 v[164:167], v3, s[10:11] nt
	global_load_dwordx4 v[168:171], v5, s[16:17]
	global_load_dwordx4 v[172:175], v5, s[16:17] offset:16
	s_add_u32 s10, s10, 0x40000
	s_addc_u32 s11, s11, 0
	s_add_u32 s16, s16, 2048
	s_addc_u32 s17, s17, 0
	s_waitcnt vmcnt(42)
	v_cvt_pk_bf16_f32 v40, v16, v17
	v_cvt_pk_bf16_f32 v41, v18, v19
	v_cvt_pk_bf16_f32 v42, v20, v21
	v_cvt_pk_bf16_f32 v43, v22, v23
	global_store_dwordx4 v2, v[40:43], s[12:13] nt
	v_cvt_pk_bf16_f32 v44, v24, v25
	v_cvt_pk_bf16_f32 v45, v26, v27
	v_cvt_pk_bf16_f32 v46, v28, v29
	v_cvt_pk_bf16_f32 v47, v30, v31
	global_store_dwordx4 v3, v[44:47], s[12:13] nt
	s_add_u32 s12, s12, 0x40000
	s_addc_u32 s13, s13, 0
	v_lshlrev_b32_e32 v48, 16, v176
	v_and_b32_e32 v49, 0xffff0000, v176
	v_fma_f32 v16, v184, v16, v48
	v_fma_f32 v17, v185, v17, v49
	v_lshlrev_b32_e32 v48, 16, v177
	v_and_b32_e32 v49, 0xffff0000, v177
	v_fma_f32 v18, v186, v18, v48
	v_fma_f32 v19, v187, v19, v49
	v_lshlrev_b32_e32 v48, 16, v178
	v_and_b32_e32 v49, 0xffff0000, v178
	v_fma_f32 v20, v188, v20, v48
	v_fma_f32 v21, v189, v21, v49
	v_lshlrev_b32_e32 v48, 16, v179
	v_and_b32_e32 v49, 0xffff0000, v179
	v_fma_f32 v22, v190, v22, v48
	v_fma_f32 v23, v191, v23, v49
	v_lshlrev_b32_e32 v48, 16, v180
	v_and_b32_e32 v49, 0xffff0000, v180
	v_fma_f32 v24, v184, v24, v48
	v_fma_f32 v25, v185, v25, v49
	v_lshlrev_b32_e32 v48, 16, v181
	v_and_b32_e32 v49, 0xffff0000, v181
	v_fma_f32 v26, v186, v26, v48
	v_fma_f32 v27, v187, v27, v49
	v_lshlrev_b32_e32 v48, 16, v182
	v_and_b32_e32 v49, 0xffff0000, v182
	v_fma_f32 v28, v188, v28, v48
	v_fma_f32 v29, v189, v29, v49
	v_lshlrev_b32_e32 v48, 16, v183
	v_and_b32_e32 v49, 0xffff0000, v183
	v_fma_f32 v30, v190, v30, v48
	v_fma_f32 v31, v191, v31, v49
	global_load_dwordx4 v[176:179], v2, s[10:11] nt
	global_load_dwordx4 v[180:183], v3, s[10:11] nt
	global_load_dwordx4 v[184:187], v5, s[16:17]
	global_load_dwordx4 v[188:191], v5, s[16:17] offset:16
	s_add_u32 s10, s10, 0x40000
	s_addc_u32 s11, s11, 0
	s_add_u32 s16, s16, 2048
	s_addc_u32 s17, s17, 0
	s_waitcnt vmcnt(42)
; __device__ __forceinline__ float bf2f(unsigned h) { return __uint_as_float(h << 16); }
; __device__ __forceinline__ unsigned pk2(float lo, float hi) { return pg8::cvt_pk_bf16(lo, hi); }
; __device__ __forceinline__ void b2_scan(const Ctx& C) {
;     ...
;     B2_LOAD(0, 0);
; #pragma unroll
;     for (int g = 0; g < 8; ++g) {
;         const int cur = g & 1;
;         if (g + 1 < 8) B2_LOAD(g + 1, cur ^ 1);
; #pragma unroll
;         for (int k = 0; k < 4; ++k) {
;             const int c = 4 * g + k;
;             const float dd[8] = {d0[cur][k][0], d0[cur][k][1], d0[cur][k][2], d0[cur][k][3], d1[cur][k][0], d1[cur][k][1], d1[cur][k][2], d1[cur][k][3]};
; #pragma unroll
;             for (int j = 0; j < 2; ++j) {
;                 v4u o; o.x = pk2(run[j][0], run[j][1]); o.y = pk2(run[j][2], run[j][3]); o.z = pk2(run[j][4], run[j][5]); o.w = pk2(run[j][6], run[j][7]);
;                 __builtin_nontemporal_store(o, (v4u*)(base + (size_t)c * cstride + (size_t)j * vstride));
;                 const unsigned lw[4] = {loc[cur][k][j].x, loc[cur][k][j].y, loc[cur][k][j].z, loc[cur][k][j].w};
; #pragma unroll
;                 for (int q = 0; q < 4; ++q) {
;                     run[j][2 * q] = dd[2 * q] * run[j][2 * q] + bf2f(lw[q] & 0xffffu);
;                     run[j][2 * q + 1] = dd[2 * q + 1] * run[j][2 * q + 1] + __uint_as_float(lw[q] & 0xffff0000u);
;                 }
;             }
	v_cvt_pk_bf16_f32 v32, v16, v17
	v_cvt_pk_bf16_f32 v33, v18, v19
	v_cvt_pk_bf16_f32 v34, v20, v21
	v_cvt_pk_bf16_f32 v35, v22, v23
	global_store_dwordx4 v2, v[32:35], s[12:13] nt
	v_cvt_pk_bf16_f32 v36, v24, v25
	v_cvt_pk_bf16_f32 v37, v26, v27
	v_cvt_pk_bf16_f32 v38, v28, v29
	v_cvt_pk_bf16_f32 v39, v30, v31
	global_store_dwordx4 v3, v[36:39], s[12:13] nt
	s_add_u32 s12, s12, 0x40000
	s_addc_u32 s13, s13, 0
	v_lshlrev_b32_e32 v48, 16, v64
	v_and_b32_e32 v49, 0xffff0000, v64
	v_fma_f32 v16, v72, v16, v48
	v_fma_f32 v17, v73, v17, v49
	v_lshlrev_b32_e32 v48, 16, v65
	v_and_b32_e32 v49, 0xffff0000, v65
	v_fma_f32 v18, v74, v18, v48
	v_fma_f32 v19, v75, v19, v49
	v_lshlrev_b32_e32 v48, 16, v66
	v_and_b32_e32 v49, 0xffff0000, v66
	v_fma_f32 v20, v76, v20, v48
	v_fma_f32 v21, v77, v21, v49
	v_lshlrev_b32_e32 v48, 16, v67
	v_and_b32_e32 v49, 0xffff0000, v67
	v_fma_f32 v22, v78, v22, v48
	v_fma_f32 v23, v79, v23, v49
	v_lshlrev_b32_e32 v48, 16, v68
	v_and_b32_e32 v49, 0xffff0000, v68
	v_fma_f32 v24, v72, v24, v48
	v_fma_f32 v25, v73, v25, v49
	v_lshlrev_b32_e32 v48, 16, v69
	v_and_b32_e32 v49, 0xffff0000, v69
	v_fma_f32 v26, v74, v26, v48
	v_fma_f32 v27, v75, v27, v49
	v_lshlrev_b32_e32 v48, 16, v70
	v_and_b32_e32 v49, 0xffff0000, v70
	v_fma_f32 v28, v76, v28, v48
	v_fma_f32 v29, v77, v29, v49
	v_lshlrev_b32_e32 v48, 16, v71
	v_and_b32_e32 v49, 0xffff0000, v71
	v_fma_f32 v30, v78, v30, v48
	v_fma_f32 v31, v79, v31, v49
	global_load_dwordx4 v[64:67], v2, s[10:11] nt
	global_load_dwordx4 v[68:71], v3, s[10:11] nt
	global_load_dwordx4 v[72:75], v5, s[16:17]
	global_load_dwordx4 v[76:79], v5, s[16:17] offset:16
	s_add_u32 s10, s10, 0x40000
	s_addc_u32 s11, s11, 0
	s_add_u32 s16, s16, 2048
	s_addc_u32 s17, s17, 0
	s_waitcnt vmcnt(42)
	v_cvt_pk_bf16_f32 v40, v16, v17
	v_cvt_pk_bf16_f32 v41, v18, v19
	v_cvt_pk_bf16_f32 v42, v20, v21
	v_cvt_pk_bf16_f32 v43, v22, v23
	global_store_dwordx4 v2, v[40:43], s[12:13] nt
	v_cvt_pk_bf16_f32 v44, v24, v25
	v_cvt_pk_bf16_f32 v45, v26, v27
	v_cvt_pk_bf16_f32 v46, v28, v29
	v_cvt_pk_bf16_f32 v47, v30, v31
	global_store_dwordx4 v3, v[44:47], s[12:13] nt
	s_add_u32 s12, s12, 0x40000
	s_addc_u32 s13, s13, 0
	v_lshlrev_b32_e32 v48, 16, v80
	v_and_b32_e32 v49, 0xffff0000, v80
	v_fma_f32 v16, v88, v16, v48
	v_fma_f32 v17, v89, v17, v49
	v_lshlrev_b32_e32 v48, 16, v81
	v_and_b32_e32 v49, 0xffff0000, v81
	v_fma_f32 v18, v90, v18, v48
	v_fma_f32 v19, v91, v19, v49
	v_lshlrev_b32_e32 v48, 16, v82
	v_and_b32_e32 v49, 0xffff0000, v82
	v_fma_f32 v20, v92, v20, v48
	v_fma_f32 v21, v93, v21, v49
	v_lshlrev_b32_e32 v48, 16, v83
	v_and_b32_e32 v49, 0xffff0000, v83
	v_fma_f32 v22, v94, v22, v48
	v_fma_f32 v23, v95, v23, v49
	v_lshlrev_b32_e32 v48, 16, v84
	v_and_b32_e32 v49, 0xffff0000, v84
	v_fma_f32 v24, v88, v24, v48
	v_fma_f32 v25, v89, v25, v49
	v_lshlrev_b32_e32 v48, 16, v85
	v_and_b32_e32 v49, 0xffff0000, v85
	v_fma_f32 v26, v90, v26, v48
	v_fma_f32 v27, v91, v27, v49
	v_lshlrev_b32_e32 v48, 16, v86
	v_and_b32_e32 v49, 0xffff0000, v86
	v_fma_f32 v28, v92, v28, v48
	v_fma_f32 v29, v93, v29, v49
	v_lshlrev_b32_e32 v48, 16, v87
	v_and_b32_e32 v49, 0xffff0000, v87
	v_fma_f32 v30, v94, v30, v48
	v_fma_f32 v31, v95, v31, v49
	global_load_dwordx4 v[80:83], v2, s[10:11] nt
	global_load_dwordx4 v[84:87], v3, s[10:11] nt
	global_load_dwordx4 v[88:91], v5, s[16:17]
	global_load_dwordx4 v[92:95], v5, s[16:17] offset:16
	s_add_u32 s10, s10, 0x40000
	s_addc_u32 s11, s11, 0
	s_add_u32 s16, s16, 2048
	s_addc_u32 s17, s17, 0
	s_waitcnt vmcnt(42)
	v_cvt_pk_bf16_f32 v32, v16, v17
	v_cvt_pk_bf16_f32 v33, v18, v19
	v_cvt_pk_bf16_f32 v34, v20, v21
	v_cvt_pk_bf16_f32 v35, v22, v23
	global_store_dwordx4 v2, v[32:35], s[12:13] nt
	v_cvt_pk_bf16_f32 v36, v24, v25
	v_cvt_pk_bf16_f32 v37, v26, v27
	v_cvt_pk_bf16_f32 v38, v28, v29
	v_cvt_pk_bf16_f32 v39, v30, v31
	global_store_dwordx4 v3, v[36:39], s[12:13] nt
	s_add_u32 s12, s12, 0x40000
	s_addc_u32 s13, s13, 0
	v_lshlrev_b32_e32 v48, 16, v96
	v_and_b32_e32 v49, 0xffff0000, v96
	v_fma_f32 v16, v104, v16, v48
	v_fma_f32 v17, v105, v17, v49
	v_lshlrev_b32_e32 v48, 16, v97
	v_and_b32_e32 v49, 0xffff0000, v97
	v_fma_f32 v18, v106, v18, v48
	v_fma_f32 v19, v107, v19, v49
	v_lshlrev_b32_e32 v48, 16, v98
	v_and_b32_e32 v49, 0xffff0000, v98
	v_fma_f32 v20, v108, v20, v48
	v_fma_f32 v21, v109, v21, v49
	v_lshlrev_b32_e32 v48, 16, v99
	v_and_b32_e32 v49, 0xffff0000, v99
	v_fma_f32 v22, v110, v22, v48
	v_fma_f32 v23, v111, v23, v49
	v_lshlrev_b32_e32 v48, 16, v100
	v_and_b32_e32 v49, 0xffff0000, v100
	v_fma_f32 v24, v104, v24, v48
	v_fma_f32 v25, v105, v25, v49
	v_lshlrev_b32_e32 v48, 16, v101
	v_and_b32_e32 v49, 0xffff0000, v101
	v_fma_f32 v26, v106, v26, v48
	v_fma_f32 v27, v107, v27, v49
	v_lshlrev_b32_e32 v48, 16, v102
	v_and_b32_e32 v49, 0xffff0000, v102
	v_fma_f32 v28, v108, v28, v48
	v_fma_f32 v29, v109, v29, v49
	v_lshlrev_b32_e32 v48, 16, v103
	v_and_b32_e32 v49, 0xffff0000, v103
	v_fma_f32 v30, v110, v30, v48
	v_fma_f32 v31, v111, v31, v49
	global_load_dwordx4 v[96:99], v2, s[10:11] nt
	global_load_dwordx4 v[100:103], v3, s[10:11] nt
	global_load_dwordx4 v[104:107], v5, s[16:17]
	global_load_dwordx4 v[108:111], v5, s[16:17] offset:16
	s_add_u32 s10, s10, 0x40000
	s_addc_u32 s11, s11, 0
	s_add_u32 s16, s16, 2048
	s_addc_u32 s17, s17, 0
	s_waitcnt vmcnt(42)
; __device__ __forceinline__ float bf2f(unsigned h) { return __uint_as_float(h << 16); }
; __device__ __forceinline__ unsigned pk2(float lo, float hi) { return pg8::cvt_pk_bf16(lo, hi); }
; __device__ __forceinline__ void b2_scan(const Ctx& C) {
;     ...
;     B2_LOAD(0, 0);
; #pragma unroll
;     for (int g = 0; g < 8; ++g) {
;         const int cur = g & 1;
;         if (g + 1 < 8) B2_LOAD(g + 1, cur ^ 1);
; #pragma unroll
;         for (int k = 0; k < 4; ++k) {
;             const int c = 4 * g + k;
;             const float dd[8] = {d0[cur][k][0], d0[cur][k][1], d0[cur][k][2], d0[cur][k][3], d1[cur][k][0], d1[cur][k][1], d1[cur][k][2], d1[cur][k][3]};
; #pragma unroll
;             for (int j = 0; j < 2; ++j) {
;                 v4u o; o.x = pk2(run[j][0], run[j][1]); o.y = pk2(run[j][2], run[j][3]); o.z = pk2(run[j][4], run[j][5]); o.w = pk2(run[j][6], run[j][7]);
;                 __builtin_nontemporal_store(o, (v4u*)(base + (size_t)c * cstride + (size_t)j * vstride));
;                 const unsigned lw[4] = {loc[cur][k][j].x, loc[cur][k][j].y, loc[cur][k][j].z, loc[cur][k][j].w};
; #pragma unroll
;                 for (int q = 0; q < 4; ++q) {
;                     run[j][2 * q] = dd[2 * q] * run[j][2 * q] + bf2f(lw[q] & 0xffffu);
;                     run[j][2 * q + 1] = dd[2 * q + 1] * run[j][2 * q + 1] + __uint_as_float(lw[q] & 0xffff0000u);
;                 }
;             }
	v_cvt_pk_bf16_f32 v40, v16, v17
	v_cvt_pk_bf16_f32 v41, v18, v19
	v_cvt_pk_bf16_f32 v42, v20, v21
	v_cvt_pk_bf16_f32 v43, v22, v23
	global_store_dwordx4 v2, v[40:43], s[12:13] nt
	v_cvt_pk_bf16_f32 v44, v24, v25
	v_cvt_pk_bf16_f32 v45, v26, v27
	v_cvt_pk_bf16_f32 v46, v28, v29
	v_cvt_pk_bf16_f32 v47, v30, v31
	global_store_dwordx4 v3, v[44:47], s[12:13] nt
	s_add_u32 s12, s12, 0x40000
	s_addc_u32 s13, s13, 0
	v_lshlrev_b32_e32 v48, 16, v112
	v_and_b32_e32 v49, 0xffff0000, v112
	v_fma_f32 v16, v120, v16, v48
	v_fma_f32 v17, v121, v17, v49
	v_lshlrev_b32_e32 v48, 16, v113
	v_and_b32_e32 v49, 0xffff0000, v113
	v_fma_f32 v18, v122, v18, v48
	v_fma_f32 v19, v123, v19, v49
	v_lshlrev_b32_e32 v48, 16, v114
	v_and_b32_e32 v49, 0xffff0000, v114
	v_fma_f32 v20, v124, v20, v48
	v_fma_f32 v21, v125, v21, v49
	v_lshlrev_b32_e32 v48, 16, v115
	v_and_b32_e32 v49, 0xffff0000, v115
	v_fma_f32 v22, v126, v22, v48
	v_fma_f32 v23, v127, v23, v49
	v_lshlrev_b32_e32 v48, 16, v116
	v_and_b32_e32 v49, 0xffff0000, v116
	v_fma_f32 v24, v120, v24, v48
	v_fma_f32 v25, v121, v25, v49
	v_lshlrev_b32_e32 v48, 16, v117
	v_and_b32_e32 v49, 0xffff0000, v117
	v_fma_f32 v26, v122, v26, v48
	v_fma_f32 v27, v123, v27, v49
	v_lshlrev_b32_e32 v48, 16, v118
	v_and_b32_e32 v49, 0xffff0000, v118
	v_fma_f32 v28, v124, v28, v48
	v_fma_f32 v29, v125, v29, v49
	v_lshlrev_b32_e32 v48, 16, v119
	v_and_b32_e32 v49, 0xffff0000, v119
	v_fma_f32 v30, v126, v30, v48
	v_fma_f32 v31, v127, v31, v49
	global_load_dwordx4 v[112:115], v2, s[10:11] nt
	global_load_dwordx4 v[116:119], v3, s[10:11] nt
	global_load_dwordx4 v[120:123], v5, s[16:17]
	global_load_dwordx4 v[124:127], v5, s[16:17] offset:16
	s_add_u32 s10, s10, 0x40000
	s_addc_u32 s11, s11, 0
	s_add_u32 s16, s16, 2048
	s_addc_u32 s17, s17, 0
	s_waitcnt vmcnt(42)
	v_cvt_pk_bf16_f32 v32, v16, v17
	v_cvt_pk_bf16_f32 v33, v18, v19
	v_cvt_pk_bf16_f32 v34, v20, v21
	v_cvt_pk_bf16_f32 v35, v22, v23
	global_store_dwordx4 v2, v[32:35], s[12:13] nt
	v_cvt_pk_bf16_f32 v36, v24, v25
	v_cvt_pk_bf16_f32 v37, v26, v27
	v_cvt_pk_bf16_f32 v38, v28, v29
	v_cvt_pk_bf16_f32 v39, v30, v31
	global_store_dwordx4 v3, v[36:39], s[12:13] nt
	s_add_u32 s12, s12, 0x40000
	s_addc_u32 s13, s13, 0
	v_lshlrev_b32_e32 v48, 16, v128
	v_and_b32_e32 v49, 0xffff0000, v128
	v_fma_f32 v16, v136, v16, v48
	v_fma_f32 v17, v137, v17, v49
	v_lshlrev_b32_e32 v48, 16, v129
	v_and_b32_e32 v49, 0xffff0000, v129
	v_fma_f32 v18, v138, v18, v48
	v_fma_f32 v19, v139, v19, v49
	v_lshlrev_b32_e32 v48, 16, v130
	v_and_b32_e32 v49, 0xffff0000, v130
	v_fma_f32 v20, v140, v20, v48
	v_fma_f32 v21, v141, v21, v49
	v_lshlrev_b32_e32 v48, 16, v131
	v_and_b32_e32 v49, 0xffff0000, v131
	v_fma_f32 v22, v142, v22, v48
	v_fma_f32 v23, v143, v23, v49
	v_lshlrev_b32_e32 v48, 16, v132
	v_and_b32_e32 v49, 0xffff0000, v132
	v_fma_f32 v24, v136, v24, v48
	v_fma_f32 v25, v137, v25, v49
	v_lshlrev_b32_e32 v48, 16, v133
	v_and_b32_e32 v49, 0xffff0000, v133
	v_fma_f32 v26, v138, v26, v48
	v_fma_f32 v27, v139, v27, v49
	v_lshlrev_b32_e32 v48, 16, v134
	v_and_b32_e32 v49, 0xffff0000, v134
	v_fma_f32 v28, v140, v28, v48
	v_fma_f32 v29, v141, v29, v49
	v_lshlrev_b32_e32 v48, 16, v135
	v_and_b32_e32 v49, 0xffff0000, v135
	v_fma_f32 v30, v142, v30, v48
	v_fma_f32 v31, v143, v31, v49
	global_load_dwordx4 v[128:131], v2, s[10:11] nt
	global_load_dwordx4 v[132:135], v3, s[10:11] nt
	global_load_dwordx4 v[136:139], v5, s[16:17]
	global_load_dwordx4 v[140:143], v5, s[16:17] offset:16
	s_add_u32 s10, s10, 0x40000
	s_addc_u32 s11, s11, 0
	s_add_u32 s16, s16, 2048
	s_addc_u32 s17, s17, 0
	s_waitcnt vmcnt(42)
	v_cvt_pk_bf16_f32 v40, v16, v17
	v_cvt_pk_bf16_f32 v41, v18, v19
	v_cvt_pk_bf16_f32 v42, v20, v21
	v_cvt_pk_bf16_f32 v43, v22, v23
	global_store_dwordx4 v2, v[40:43], s[12:13] nt
	v_cvt_pk_bf16_f32 v44, v24, v25
	v_cvt_pk_bf16_f32 v45, v26, v27
	v_cvt_pk_bf16_f32 v46, v28, v29
	v_cvt_pk_bf16_f32 v47, v30, v31
	global_store_dwordx4 v3, v[44:47], s[12:13] nt
	s_add_u32 s12, s12, 0x40000
	s_addc_u32 s13, s13, 0
	v_lshlrev_b32_e32 v48, 16, v144
	v_and_b32_e32 v49, 0xffff0000, v144
	v_fma_f32 v16, v152, v16, v48
	v_fma_f32 v17, v153, v17, v49
	v_lshlrev_b32_e32 v48, 16, v145
	v_and_b32_e32 v49, 0xffff0000, v145
	v_fma_f32 v18, v154, v18, v48
	v_fma_f32 v19, v155, v19, v49
	v_lshlrev_b32_e32 v48, 16, v146
	v_and_b32_e32 v49, 0xffff0000, v146
	v_fma_f32 v20, v156, v20, v48
	v_fma_f32 v21, v157, v21, v49
	v_lshlrev_b32_e32 v48, 16, v147
	v_and_b32_e32 v49, 0xffff0000, v147
	v_fma_f32 v22, v158, v22, v48
	v_fma_f32 v23, v159, v23, v49
	v_lshlrev_b32_e32 v48, 16, v148
	v_and_b32_e32 v49, 0xffff0000, v148
	v_fma_f32 v24, v152, v24, v48
	v_fma_f32 v25, v153, v25, v49
	v_lshlrev_b32_e32 v48, 16, v149
	v_and_b32_e32 v49, 0xffff0000, v149
	v_fma_f32 v26, v154, v26, v48
	v_fma_f32 v27, v155, v27, v49
	v_lshlrev_b32_e32 v48, 16, v150
	v_and_b32_e32 v49, 0xffff0000, v150
	v_fma_f32 v28, v156, v28, v48
	v_fma_f32 v29, v157, v29, v49
	v_lshlrev_b32_e32 v48, 16, v151
	v_and_b32_e32 v49, 0xffff0000, v151
	v_fma_f32 v30, v158, v30, v48
	v_fma_f32 v31, v159, v31, v49
	global_load_dwordx4 v[144:147], v2, s[10:11] nt
	global_load_dwordx4 v[148:151], v3, s[10:11] nt
	global_load_dwordx4 v[152:155], v5, s[16:17]
	global_load_dwordx4 v[156:159], v5, s[16:17] offset:16
	s_add_u32 s10, s10, 0x40000
	s_addc_u32 s11, s11, 0
	s_add_u32 s16, s16, 2048
	s_addc_u32 s17, s17, 0
	s_waitcnt vmcnt(42)
; __device__ __forceinline__ float bf2f(unsigned h) { return __uint_as_float(h << 16); }
; __device__ __forceinline__ unsigned pk2(float lo, float hi) { return pg8::cvt_pk_bf16(lo, hi); }
; __device__ __forceinline__ void b2_scan(const Ctx& C) {
;     ...
;     B2_LOAD(0, 0);
; #pragma unroll
;     for (int g = 0; g < 8; ++g) {
;         const int cur = g & 1;
;         if (g + 1 < 8) B2_LOAD(g + 1, cur ^ 1);
; #pragma unroll
;         for (int k = 0; k < 4; ++k) {
;             const int c = 4 * g + k;
;             const float dd[8] = {d0[cur][k][0], d0[cur][k][1], d0[cur][k][2], d0[cur][k][3], d1[cur][k][0], d1[cur][k][1], d1[cur][k][2], d1[cur][k][3]};
; #pragma unroll
;             for (int j = 0; j < 2; ++j) {
;                 v4u o; o.x = pk2(run[j][0], run[j][1]); o.y = pk2(run[j][2], run[j][3]); o.z = pk2(run[j][4], run[j][5]); o.w = pk2(run[j][6], run[j][7]);
;                 __builtin_nontemporal_store(o, (v4u*)(base + (size_t)c * cstride + (size_t)j * vstride));
;                 const unsigned lw[4] = {loc[cur][k][j].x, loc[cur][k][j].y, loc[cur][k][j].z, loc[cur][k][j].w};
; #pragma unroll
;                 for (int q = 0; q < 4; ++q) {
;                     run[j][2 * q] = dd[2 * q] * run[j][2 * q] + bf2f(lw[q] & 0xffffu);
;                     run[j][2 * q + 1] = dd[2 * q + 1] * run[j][2 * q + 1] + __uint_as_float(lw[q] & 0xffff0000u);
;                 }
;             }
	v_cvt_pk_bf16_f32 v32, v16, v17
	v_cvt_pk_bf16_f32 v33, v18, v19
	v_cvt_pk_bf16_f32 v34, v20, v21
	v_cvt_pk_bf16_f32 v35, v22, v23
	global_store_dwordx4 v2, v[32:35], s[12:13] nt
	v_cvt_pk_bf16_f32 v36, v24, v25
	v_cvt_pk_bf16_f32 v37, v26, v27
	v_cvt_pk_bf16_f32 v38, v28, v29
	v_cvt_pk_bf16_f32 v39, v30, v31
	global_store_dwordx4 v3, v[36:39], s[12:13] nt
	s_add_u32 s12, s12, 0x40000
	s_addc_u32 s13, s13, 0
	v_lshlrev_b32_e32 v48, 16, v160
	v_and_b32_e32 v49, 0xffff0000, v160
	v_fma_f32 v16, v168, v16, v48
	v_fma_f32 v17, v169, v17, v49
	v_lshlrev_b32_e32 v48, 16, v161
	v_and_b32_e32 v49, 0xffff0000, v161
	v_fma_f32 v18, v170, v18, v48
	v_fma_f32 v19, v171, v19, v49
	v_lshlrev_b32_e32 v48, 16, v162
	v_and_b32_e32 v49, 0xffff0000, v162
	v_fma_f32 v20, v172, v20, v48
	v_fma_f32 v21, v173, v21, v49
	v_lshlrev_b32_e32 v48, 16, v163
	v_and_b32_e32 v49, 0xffff0000, v163
	v_fma_f32 v22, v174, v22, v48
	v_fma_f32 v23, v175, v23, v49
	v_lshlrev_b32_e32 v48, 16, v164
	v_and_b32_e32 v49, 0xffff0000, v164
	v_fma_f32 v24, v168, v24, v48
	v_fma_f32 v25, v169, v25, v49
	v_lshlrev_b32_e32 v48, 16, v165
	v_and_b32_e32 v49, 0xffff0000, v165
	v_fma_f32 v26, v170, v26, v48
	v_fma_f32 v27, v171, v27, v49
	v_lshlrev_b32_e32 v48, 16, v166
	v_and_b32_e32 v49, 0xffff0000, v166
	v_fma_f32 v28, v172, v28, v48
	v_fma_f32 v29, v173, v29, v49
	v_lshlrev_b32_e32 v48, 16, v167
	v_and_b32_e32 v49, 0xffff0000, v167
	v_fma_f32 v30, v174, v30, v48
	v_fma_f32 v31, v175, v31, v49
	global_load_dwordx4 v[160:163], v2, s[10:11] nt
	global_load_dwordx4 v[164:167], v3, s[10:11] nt
	global_load_dwordx4 v[168:171], v5, s[16:17]
	global_load_dwordx4 v[172:175], v5, s[16:17] offset:16
	s_add_u32 s10, s10, 0x40000
	s_addc_u32 s11, s11, 0
	s_add_u32 s16, s16, 2048
	s_addc_u32 s17, s17, 0
	s_waitcnt vmcnt(42)
	v_cvt_pk_bf16_f32 v40, v16, v17
	v_cvt_pk_bf16_f32 v41, v18, v19
	v_cvt_pk_bf16_f32 v42, v20, v21
	v_cvt_pk_bf16_f32 v43, v22, v23
	global_store_dwordx4 v2, v[40:43], s[12:13] nt
	v_cvt_pk_bf16_f32 v44, v24, v25
	v_cvt_pk_bf16_f32 v45, v26, v27
	v_cvt_pk_bf16_f32 v46, v28, v29
	v_cvt_pk_bf16_f32 v47, v30, v31
	global_store_dwordx4 v3, v[44:47], s[12:13] nt
	s_add_u32 s12, s12, 0x40000
	s_addc_u32 s13, s13, 0
	v_lshlrev_b32_e32 v48, 16, v176
	v_and_b32_e32 v49, 0xffff0000, v176
	v_fma_f32 v16, v184, v16, v48
	v_fma_f32 v17, v185, v17, v49
	v_lshlrev_b32_e32 v48, 16, v177
	v_and_b32_e32 v49, 0xffff0000, v177
	v_fma_f32 v18, v186, v18, v48
	v_fma_f32 v19, v187, v19, v49
	v_lshlrev_b32_e32 v48, 16, v178
	v_and_b32_e32 v49, 0xffff0000, v178
	v_fma_f32 v20, v188, v20, v48
	v_fma_f32 v21, v189, v21, v49
	v_lshlrev_b32_e32 v48, 16, v179
	v_and_b32_e32 v49, 0xffff0000, v179
	v_fma_f32 v22, v190, v22, v48
	v_fma_f32 v23, v191, v23, v49
	v_lshlrev_b32_e32 v48, 16, v180
	v_and_b32_e32 v49, 0xffff0000, v180
	v_fma_f32 v24, v184, v24, v48
	v_fma_f32 v25, v185, v25, v49
	v_lshlrev_b32_e32 v48, 16, v181
	v_and_b32_e32 v49, 0xffff0000, v181
	v_fma_f32 v26, v186, v26, v48
	v_fma_f32 v27, v187, v27, v49
	v_lshlrev_b32_e32 v48, 16, v182
	v_and_b32_e32 v49, 0xffff0000, v182
	v_fma_f32 v28, v188, v28, v48
	v_fma_f32 v29, v189, v29, v49
	v_lshlrev_b32_e32 v48, 16, v183
	v_and_b32_e32 v49, 0xffff0000, v183
	v_fma_f32 v30, v190, v30, v48
	v_fma_f32 v31, v191, v31, v49
	global_load_dwordx4 v[176:179], v2, s[10:11] nt
	global_load_dwordx4 v[180:183], v3, s[10:11] nt
	global_load_dwordx4 v[184:187], v5, s[16:17]
	global_load_dwordx4 v[188:191], v5, s[16:17] offset:16
	s_add_u32 s10, s10, 0x40000
	s_addc_u32 s11, s11, 0
	s_add_u32 s16, s16, 2048
	s_addc_u32 s17, s17, 0
	s_waitcnt vmcnt(42)
	v_cvt_pk_bf16_f32 v32, v16, v17
	v_cvt_pk_bf16_f32 v33, v18, v19
	v_cvt_pk_bf16_f32 v34, v20, v21
	v_cvt_pk_bf16_f32 v35, v22, v23
	global_store_dwordx4 v2, v[32:35], s[12:13] nt
	v_cvt_pk_bf16_f32 v36, v24, v25
	v_cvt_pk_bf16_f32 v37, v26, v27
	v_cvt_pk_bf16_f32 v38, v28, v29
	v_cvt_pk_bf16_f32 v39, v30, v31
	global_store_dwordx4 v3, v[36:39], s[12:13] nt
	s_add_u32 s12, s12, 0x40000
	s_addc_u32 s13, s13, 0
	v_lshlrev_b32_e32 v48, 16, v64
	v_and_b32_e32 v49, 0xffff0000, v64
	v_fma_f32 v16, v72, v16, v48
	v_fma_f32 v17, v73, v17, v49
	v_lshlrev_b32_e32 v48, 16, v65
	v_and_b32_e32 v49, 0xffff0000, v65
	v_fma_f32 v18, v74, v18, v48
	v_fma_f32 v19, v75, v19, v49
	v_lshlrev_b32_e32 v48, 16, v66
	v_and_b32_e32 v49, 0xffff0000, v66
	v_fma_f32 v20, v76, v20, v48
	v_fma_f32 v21, v77, v21, v49
	v_lshlrev_b32_e32 v48, 16, v67
	v_and_b32_e32 v49, 0xffff0000, v67
	v_fma_f32 v22, v78, v22, v48
	v_fma_f32 v23, v79, v23, v49
	v_lshlrev_b32_e32 v48, 16, v68
	v_and_b32_e32 v49, 0xffff0000, v68
	v_fma_f32 v24, v72, v24, v48
	v_fma_f32 v25, v73, v25, v49
	v_lshlrev_b32_e32 v48, 16, v69
	v_and_b32_e32 v49, 0xffff0000, v69
	v_fma_f32 v26, v74, v26, v48
	v_fma_f32 v27, v75, v27, v49
	v_lshlrev_b32_e32 v48, 16, v70
	v_and_b32_e32 v49, 0xffff0000, v70
	v_fma_f32 v28, v76, v28, v48
	v_fma_f32 v29, v77, v29, v49
	v_lshlrev_b32_e32 v48, 16, v71
	v_and_b32_e32 v49, 0xffff0000, v71
	v_fma_f32 v30, v78, v30, v48
	v_fma_f32 v31, v79, v31, v49
	s_waitcnt vmcnt(38)
; __device__ __forceinline__ float bf2f(unsigned h) { return __uint_as_float(h << 16); }
; __device__ __forceinline__ unsigned pk2(float lo, float hi) { return pg8::cvt_pk_bf16(lo, hi); }
; __device__ __forceinline__ void b2_scan(const Ctx& C) {
;     ...
;     B2_LOAD(0, 0);
; #pragma unroll
;     for (int g = 0; g < 8; ++g) {
;         const int cur = g & 1;
;         if (g + 1 < 8) B2_LOAD(g + 1, cur ^ 1);
; #pragma unroll
;         for (int k = 0; k < 4; ++k) {
;             const int c = 4 * g + k;
;             const float dd[8] = {d0[cur][k][0], d0[cur][k][1], d0[cur][k][2], d0[cur][k][3], d1[cur][k][0], d1[cur][k][1], d1[cur][k][2], d1[cur][k][3]};
; #pragma unroll
;             for (int j = 0; j < 2; ++j) {
;                 v4u o; o.x = pk2(run[j][0], run[j][1]); o.y = pk2(run[j][2], run[j][3]); o.z = pk2(run[j][4], run[j][5]); o.w = pk2(run[j][6], run[j][7]);
;                 __builtin_nontemporal_store(o, (v4u*)(base + (size_t)c * cstride + (size_t)j * vstride));
;                 const unsigned lw[4] = {loc[cur][k][j].x, loc[cur][k][j].y, loc[cur][k][j].z, loc[cur][k][j].w};
; #pragma unroll
;                 for (int q = 0; q < 4; ++q) {
;                     run[j][2 * q] = dd[2 * q] * run[j][2 * q] + bf2f(lw[q] & 0xffffu);
;                     run[j][2 * q + 1] = dd[2 * q + 1] * run[j][2 * q + 1] + __uint_as_float(lw[q] & 0xffff0000u);
;                 }
;             }
	v_cvt_pk_bf16_f32 v40, v16, v17
	v_cvt_pk_bf16_f32 v41, v18, v19
	v_cvt_pk_bf16_f32 v42, v20, v21
	v_cvt_pk_bf16_f32 v43, v22, v23
	global_store_dwordx4 v2, v[40:43], s[12:13] nt
	v_cvt_pk_bf16_f32 v44, v24, v25
	v_cvt_pk_bf16_f32 v45, v26, v27
	v_cvt_pk_bf16_f32 v46, v28, v29
	v_cvt_pk_bf16_f32 v47, v30, v31
	global_store_dwordx4 v3, v[44:47], s[12:13] nt
	s_add_u32 s12, s12, 0x40000
	s_addc_u32 s13, s13, 0
	v_lshlrev_b32_e32 v48, 16, v80
	v_and_b32_e32 v49, 0xffff0000, v80
	v_fma_f32 v16, v88, v16, v48
	v_fma_f32 v17, v89, v17, v49
	v_lshlrev_b32_e32 v48, 16, v81
	v_and_b32_e32 v49, 0xffff0000, v81
	v_fma_f32 v18, v90, v18, v48
	v_fma_f32 v19, v91, v19, v49
	v_lshlrev_b32_e32 v48, 16, v82
	v_and_b32_e32 v49, 0xffff0000, v82
	v_fma_f32 v20, v92, v20, v48
	v_fma_f32 v21, v93, v21, v49
	v_lshlrev_b32_e32 v48, 16, v83
	v_and_b32_e32 v49, 0xffff0000, v83
	v_fma_f32 v22, v94, v22, v48
	v_fma_f32 v23, v95, v23, v49
	v_lshlrev_b32_e32 v48, 16, v84
	v_and_b32_e32 v49, 0xffff0000, v84
	v_fma_f32 v24, v88, v24, v48
	v_fma_f32 v25, v89, v25, v49
	v_lshlrev_b32_e32 v48, 16, v85
	v_and_b32_e32 v49, 0xffff0000, v85
	v_fma_f32 v26, v90, v26, v48
	v_fma_f32 v27, v91, v27, v49
	v_lshlrev_b32_e32 v48, 16, v86
	v_and_b32_e32 v49, 0xffff0000, v86
	v_fma_f32 v28, v92, v28, v48
	v_fma_f32 v29, v93, v29, v49
	v_lshlrev_b32_e32 v48, 16, v87
	v_and_b32_e32 v49, 0xffff0000, v87
	v_fma_f32 v30, v94, v30, v48
	v_fma_f32 v31, v95, v31, v49
	s_waitcnt vmcnt(34)
	v_cvt_pk_bf16_f32 v32, v16, v17
	v_cvt_pk_bf16_f32 v33, v18, v19
	v_cvt_pk_bf16_f32 v34, v20, v21
	v_cvt_pk_bf16_f32 v35, v22, v23
	global_store_dwordx4 v2, v[32:35], s[12:13] nt
	v_cvt_pk_bf16_f32 v36, v24, v25
	v_cvt_pk_bf16_f32 v37, v26, v27
	v_cvt_pk_bf16_f32 v38, v28, v29
	v_cvt_pk_bf16_f32 v39, v30, v31
	global_store_dwordx4 v3, v[36:39], s[12:13] nt
	s_add_u32 s12, s12, 0x40000
	s_addc_u32 s13, s13, 0
	v_lshlrev_b32_e32 v48, 16, v96
	v_and_b32_e32 v49, 0xffff0000, v96
	v_fma_f32 v16, v104, v16, v48
	v_fma_f32 v17, v105, v17, v49
	v_lshlrev_b32_e32 v48, 16, v97
	v_and_b32_e32 v49, 0xffff0000, v97
	v_fma_f32 v18, v106, v18, v48
	v_fma_f32 v19, v107, v19, v49
	v_lshlrev_b32_e32 v48, 16, v98
	v_and_b32_e32 v49, 0xffff0000, v98
	v_fma_f32 v20, v108, v20, v48
	v_fma_f32 v21, v109, v21, v49
	v_lshlrev_b32_e32 v48, 16, v99
	v_and_b32_e32 v49, 0xffff0000, v99
	v_fma_f32 v22, v110, v22, v48
	v_fma_f32 v23, v111, v23, v49
	v_lshlrev_b32_e32 v48, 16, v100
	v_and_b32_e32 v49, 0xffff0000, v100
	v_fma_f32 v24, v104, v24, v48
	v_fma_f32 v25, v105, v25, v49
	v_lshlrev_b32_e32 v48, 16, v101
	v_and_b32_e32 v49, 0xffff0000, v101
	v_fma_f32 v26, v106, v26, v48
	v_fma_f32 v27, v107, v27, v49
	v_lshlrev_b32_e32 v48, 16, v102
	v_and_b32_e32 v49, 0xffff0000, v102
	v_fma_f32 v28, v108, v28, v48
	v_fma_f32 v29, v109, v29, v49
	v_lshlrev_b32_e32 v48, 16, v103
	v_and_b32_e32 v49, 0xffff0000, v103
	v_fma_f32 v30, v110, v30, v48
	v_fma_f32 v31, v111, v31, v49
	s_waitcnt vmcnt(30)
	v_cvt_pk_bf16_f32 v40, v16, v17
	v_cvt_pk_bf16_f32 v41, v18, v19
	v_cvt_pk_bf16_f32 v42, v20, v21
	v_cvt_pk_bf16_f32 v43, v22, v23
	global_store_dwordx4 v2, v[40:43], s[12:13] nt
	v_cvt_pk_bf16_f32 v44, v24, v25
	v_cvt_pk_bf16_f32 v45, v26, v27
	v_cvt_pk_bf16_f32 v46, v28, v29
	v_cvt_pk_bf16_f32 v47, v30, v31
	global_store_dwordx4 v3, v[44:47], s[12:13] nt
	s_add_u32 s12, s12, 0x40000
	s_addc_u32 s13, s13, 0
	v_lshlrev_b32_e32 v48, 16, v112
	v_and_b32_e32 v49, 0xffff0000, v112
	v_fma_f32 v16, v120, v16, v48
	v_fma_f32 v17, v121, v17, v49
	v_lshlrev_b32_e32 v48, 16, v113
	v_and_b32_e32 v49, 0xffff0000, v113
	v_fma_f32 v18, v122, v18, v48
	v_fma_f32 v19, v123, v19, v49
	v_lshlrev_b32_e32 v48, 16, v114
	v_and_b32_e32 v49, 0xffff0000, v114
	v_fma_f32 v20, v124, v20, v48
	v_fma_f32 v21, v125, v21, v49
	v_lshlrev_b32_e32 v48, 16, v115
	v_and_b32_e32 v49, 0xffff0000, v115
	v_fma_f32 v22, v126, v22, v48
	v_fma_f32 v23, v127, v23, v49
	v_lshlrev_b32_e32 v48, 16, v116
	v_and_b32_e32 v49, 0xffff0000, v116
	v_fma_f32 v24, v120, v24, v48
	v_fma_f32 v25, v121, v25, v49
	v_lshlrev_b32_e32 v48, 16, v117
	v_and_b32_e32 v49, 0xffff0000, v117
	v_fma_f32 v26, v122, v26, v48
	v_fma_f32 v27, v123, v27, v49
	v_lshlrev_b32_e32 v48, 16, v118
	v_and_b32_e32 v49, 0xffff0000, v118
	v_fma_f32 v28, v124, v28, v48
	v_fma_f32 v29, v125, v29, v49
	v_lshlrev_b32_e32 v48, 16, v119
	v_and_b32_e32 v49, 0xffff0000, v119
	v_fma_f32 v30, v126, v30, v48
	v_fma_f32 v31, v127, v31, v49
	s_waitcnt vmcnt(26)
	v_cvt_pk_bf16_f32 v32, v16, v17
	v_cvt_pk_bf16_f32 v33, v18, v19
	v_cvt_pk_bf16_f32 v34, v20, v21
	v_cvt_pk_bf16_f32 v35, v22, v23
	global_store_dwordx4 v2, v[32:35], s[12:13] nt
	v_cvt_pk_bf16_f32 v36, v24, v25
	v_cvt_pk_bf16_f32 v37, v26, v27
	v_cvt_pk_bf16_f32 v38, v28, v29
	v_cvt_pk_bf16_f32 v39, v30, v31
	global_store_dwordx4 v3, v[36:39], s[12:13] nt
	s_add_u32 s12, s12, 0x40000
	s_addc_u32 s13, s13, 0
	v_lshlrev_b32_e32 v48, 16, v128
	v_and_b32_e32 v49, 0xffff0000, v128
	v_fma_f32 v16, v136, v16, v48
	v_fma_f32 v17, v137, v17, v49
	v_lshlrev_b32_e32 v48, 16, v129
	v_and_b32_e32 v49, 0xffff0000, v129
	v_fma_f32 v18, v138, v18, v48
	v_fma_f32 v19, v139, v19, v49
	v_lshlrev_b32_e32 v48, 16, v130
	v_and_b32_e32 v49, 0xffff0000, v130
	v_fma_f32 v20, v140, v20, v48
	v_fma_f32 v21, v141, v21, v49
	v_lshlrev_b32_e32 v48, 16, v131
	v_and_b32_e32 v49, 0xffff0000, v131
	v_fma_f32 v22, v142, v22, v48
	v_fma_f32 v23, v143, v23, v49
	v_lshlrev_b32_e32 v48, 16, v132
	v_and_b32_e32 v49, 0xffff0000, v132
	v_fma_f32 v24, v136, v24, v48
	v_fma_f32 v25, v137, v25, v49
	v_lshlrev_b32_e32 v48, 16, v133
	v_and_b32_e32 v49, 0xffff0000, v133
	v_fma_f32 v26, v138, v26, v48
	v_fma_f32 v27, v139, v27, v49
	v_lshlrev_b32_e32 v48, 16, v134
	v_and_b32_e32 v49, 0xffff0000, v134
	v_fma_f32 v28, v140, v28, v48
	v_fma_f32 v29, v141, v29, v49
	v_lshlrev_b32_e32 v48, 16, v135
	v_and_b32_e32 v49, 0xffff0000, v135
	v_fma_f32 v30, v142, v30, v48
	v_fma_f32 v31, v143, v31, v49
	s_waitcnt vmcnt(22)
; __device__ __forceinline__ float bf2f(unsigned h) { return __uint_as_float(h << 16); }
; __device__ __forceinline__ unsigned pk2(float lo, float hi) { return pg8::cvt_pk_bf16(lo, hi); }
; __device__ __forceinline__ void b2_scan(const Ctx& C) {
;     ...
;     B2_LOAD(0, 0);
; #pragma unroll
;     for (int g = 0; g < 8; ++g) {
;         const int cur = g & 1;
;         if (g + 1 < 8) B2_LOAD(g + 1, cur ^ 1);
; #pragma unroll
;         for (int k = 0; k < 4; ++k) {
;             const int c = 4 * g + k;
;             const float dd[8] = {d0[cur][k][0], d0[cur][k][1], d0[cur][k][2], d0[cur][k][3], d1[cur][k][0], d1[cur][k][1], d1[cur][k][2], d1[cur][k][3]};
; #pragma unroll
;             for (int j = 0; j < 2; ++j) {
;                 v4u o; o.x = pk2(run[j][0], run[j][1]); o.y = pk2(run[j][2], run[j][3]); o.z = pk2(run[j][4], run[j][5]); o.w = pk2(run[j][6], run[j][7]);
;                 __builtin_nontemporal_store(o, (v4u*)(base + (size_t)c * cstride + (size_t)j * vstride));
;                 const unsigned lw[4] = {loc[cur][k][j].x, loc[cur][k][j].y, loc[cur][k][j].z, loc[cur][k][j].w};
; #pragma unroll
;                 for (int q = 0; q < 4; ++q) {
;                     run[j][2 * q] = dd[2 * q] * run[j][2 * q] + bf2f(lw[q] & 0xffffu);
;                     run[j][2 * q + 1] = dd[2 * q + 1] * run[j][2 * q + 1] + __uint_as_float(lw[q] & 0xffff0000u);
;                 }
;             }
	v_cvt_pk_bf16_f32 v40, v16, v17
	v_cvt_pk_bf16_f32 v41, v18, v19
	v_cvt_pk_bf16_f32 v42, v20, v21
	v_cvt_pk_bf16_f32 v43, v22, v23
	global_store_dwordx4 v2, v[40:43], s[12:13] nt
	v_cvt_pk_bf16_f32 v44, v24, v25
	v_cvt_pk_bf16_f32 v45, v26, v27
	v_cvt_pk_bf16_f32 v46, v28, v29
	v_cvt_pk_bf16_f32 v47, v30, v31
	global_store_dwordx4 v3, v[44:47], s[12:13] nt
	s_add_u32 s12, s12, 0x40000
	s_addc_u32 s13, s13, 0
	v_lshlrev_b32_e32 v48, 16, v144
	v_and_b32_e32 v49, 0xffff0000, v144
	v_fma_f32 v16, v152, v16, v48
	v_fma_f32 v17, v153, v17, v49
	v_lshlrev_b32_e32 v48, 16, v145
	v_and_b32_e32 v49, 0xffff0000, v145
	v_fma_f32 v18, v154, v18, v48
	v_fma_f32 v19, v155, v19, v49
	v_lshlrev_b32_e32 v48, 16, v146
	v_and_b32_e32 v49, 0xffff0000, v146
	v_fma_f32 v20, v156, v20, v48
	v_fma_f32 v21, v157, v21, v49
	v_lshlrev_b32_e32 v48, 16, v147
	v_and_b32_e32 v49, 0xffff0000, v147
	v_fma_f32 v22, v158, v22, v48
	v_fma_f32 v23, v159, v23, v49
	v_lshlrev_b32_e32 v48, 16, v148
	v_and_b32_e32 v49, 0xffff0000, v148
	v_fma_f32 v24, v152, v24, v48
	v_fma_f32 v25, v153, v25, v49
	v_lshlrev_b32_e32 v48, 16, v149
	v_and_b32_e32 v49, 0xffff0000, v149
	v_fma_f32 v26, v154, v26, v48
	v_fma_f32 v27, v155, v27, v49
	v_lshlrev_b32_e32 v48, 16, v150
	v_and_b32_e32 v49, 0xffff0000, v150
	v_fma_f32 v28, v156, v28, v48
	v_fma_f32 v29, v157, v29, v49
	v_lshlrev_b32_e32 v48, 16, v151
	v_and_b32_e32 v49, 0xffff0000, v151
	v_fma_f32 v30, v158, v30, v48
	v_fma_f32 v31, v159, v31, v49
	s_waitcnt vmcnt(18)
	v_cvt_pk_bf16_f32 v32, v16, v17
	v_cvt_pk_bf16_f32 v33, v18, v19
	v_cvt_pk_bf16_f32 v34, v20, v21
	v_cvt_pk_bf16_f32 v35, v22, v23
	global_store_dwordx4 v2, v[32:35], s[12:13] nt
	v_cvt_pk_bf16_f32 v36, v24, v25
	v_cvt_pk_bf16_f32 v37, v26, v27
	v_cvt_pk_bf16_f32 v38, v28, v29
	v_cvt_pk_bf16_f32 v39, v30, v31
	global_store_dwordx4 v3, v[36:39], s[12:13] nt
	s_add_u32 s12, s12, 0x40000
	s_addc_u32 s13, s13, 0
	v_lshlrev_b32_e32 v48, 16, v160
	v_and_b32_e32 v49, 0xffff0000, v160
	v_fma_f32 v16, v168, v16, v48
	v_fma_f32 v17, v169, v17, v49
	v_lshlrev_b32_e32 v48, 16, v161
	v_and_b32_e32 v49, 0xffff0000, v161
	v_fma_f32 v18, v170, v18, v48
	v_fma_f32 v19, v171, v19, v49
	v_lshlrev_b32_e32 v48, 16, v162
	v_and_b32_e32 v49, 0xffff0000, v162
	v_fma_f32 v20, v172, v20, v48
	v_fma_f32 v21, v173, v21, v49
	v_lshlrev_b32_e32 v48, 16, v163
	v_and_b32_e32 v49, 0xffff0000, v163
	v_fma_f32 v22, v174, v22, v48
	v_fma_f32 v23, v175, v23, v49
	v_lshlrev_b32_e32 v48, 16, v164
	v_and_b32_e32 v49, 0xffff0000, v164
	v_fma_f32 v24, v168, v24, v48
	v_fma_f32 v25, v169, v25, v49
	v_lshlrev_b32_e32 v48, 16, v165
	v_and_b32_e32 v49, 0xffff0000, v165
	v_fma_f32 v26, v170, v26, v48
	v_fma_f32 v27, v171, v27, v49
	v_lshlrev_b32_e32 v48, 16, v166
	v_and_b32_e32 v49, 0xffff0000, v166
	v_fma_f32 v28, v172, v28, v48
	v_fma_f32 v29, v173, v29, v49
	v_lshlrev_b32_e32 v48, 16, v167
	v_and_b32_e32 v49, 0xffff0000, v167
	v_fma_f32 v30, v174, v30, v48
	v_fma_f32 v31, v175, v31, v49
	s_waitcnt vmcnt(14)
	v_cvt_pk_bf16_f32 v40, v16, v17
	v_cvt_pk_bf16_f32 v41, v18, v19
	v_cvt_pk_bf16_f32 v42, v20, v21
	v_cvt_pk_bf16_f32 v43, v22, v23
	global_store_dwordx4 v2, v[40:43], s[12:13] nt
	v_cvt_pk_bf16_f32 v44, v24, v25
	v_cvt_pk_bf16_f32 v45, v26, v27
	v_cvt_pk_bf16_f32 v46, v28, v29
	v_cvt_pk_bf16_f32 v47, v30, v31
	global_store_dwordx4 v3, v[44:47], s[12:13] nt
	s_add_u32 s12, s12, 0x40000
	s_addc_u32 s13, s13, 0
	v_lshlrev_b32_e32 v48, 16, v176
	v_and_b32_e32 v49, 0xffff0000, v176
	v_fma_f32 v16, v184, v16, v48
	v_fma_f32 v17, v185, v17, v49
	v_lshlrev_b32_e32 v48, 16, v177
	v_and_b32_e32 v49, 0xffff0000, v177
	v_fma_f32 v18, v186, v18, v48
	v_fma_f32 v19, v187, v19, v49
	v_lshlrev_b32_e32 v48, 16, v178
	v_and_b32_e32 v49, 0xffff0000, v178
	v_fma_f32 v20, v188, v20, v48
	v_fma_f32 v21, v189, v21, v49
	v_lshlrev_b32_e32 v48, 16, v179
	v_and_b32_e32 v49, 0xffff0000, v179
	v_fma_f32 v22, v190, v22, v48
	v_fma_f32 v23, v191, v23, v49
	v_lshlrev_b32_e32 v48, 16, v180
	v_and_b32_e32 v49, 0xffff0000, v180
	v_fma_f32 v24, v184, v24, v48
	v_fma_f32 v25, v185, v25, v49
	v_lshlrev_b32_e32 v48, 16, v181
	v_and_b32_e32 v49, 0xffff0000, v181
	v_fma_f32 v26, v186, v26, v48
	v_fma_f32 v27, v187, v27, v49
	v_lshlrev_b32_e32 v48, 16, v182
	v_and_b32_e32 v49, 0xffff0000, v182
	v_fma_f32 v28, v188, v28, v48
	v_fma_f32 v29, v189, v29, v49
	v_lshlrev_b32_e32 v48, 16, v183
	v_and_b32_e32 v49, 0xffff0000, v183
	v_fma_f32 v30, v190, v30, v48
	v_fma_f32 v31, v191, v31, v49

; #define LAS __attribute__((address_space(3)))
; __device__ __forceinline__ void b3_gla_item(const Ctx& C, int li, int b, int c, int h) {
;     const bf16* PROJ = (const bf16*)(C.ws + WS_PROJ);
;     LAS float* GKL = (LAS float*)(C.lds); LAS float* TOT = (LAS float*)(C.lds + 4096);
;     LAS bf16* QE = (LAS bf16*)(C.lds + 6144);
;     LAS bf16* KE = (LAS bf16*)(C.lds + 23552);
;     LAS bf16* VT = (LAS bf16*)(C.lds + 40960);
;     LAS bf16* PP = (LAS bf16*)(C.lds + 77824);
;     LAS float* SSQ = (LAS float*)(C.lds + 87040);
;     const int row0 = b * SEQ + c * CL, tid = C.tid, lane = C.lane, w = C.wave, fr = lane & 15, fq = lane >> 4;
;     gla_stage_gkl(C, PROJ, row0, GKL);
; __global__ void __launch_bounds__(NTHR, 2) fwd_megakernel(Args args) {
;     ...
; #pragma unroll 1
;         for (int it = blockIdx.x; it < 1536; it += gridDim.x) { MKCTX();
;             if (it < 1024) b3_gla_item(C, li, it >> 7, (it >> 2) & 31, it & 3);
;             else { const int r = it - 1024; b3_ssd_item(C, li, r >> 6, (r >> 1) & 31, r & 1); }
;         }
.LBB0_1737:
	s_or_b64 exec, exec, s[48:49]
	s_waitcnt lgkmcnt(0)
	s_barrier
	s_load_dwordx2 s[24:25], s[0:1], 0xc0
	s_and_b64 vcc, exec, s[8:9]
	s_cbranch_vccnz .LBB0_1901
	v_mbcnt_hi_u32_b32 v113, -1, v235
	s_lshl_b32 s37, s2, 4
	s_lshl_b32 s39, s46, 4
	s_mov_b32 s27, 0
	s_movk_i32 s49, 0x2e00
	s_movk_i32 s62, 0x2000
	s_mov_b32 s63, 0x800000
	s_mov_b32 s64, 0x3f317217
	s_mov_b32 s65, 0x7f800000
	s_movk_i32 s66, 0x1700
	v_mov_b32_e32 v105, 0
	s_mov_b64 s[28:29], 0x1800
	s_movk_i32 s67, 0x90
	s_movk_i32 s72, 0x5000
	s_mov_b32 s73, 0x8000
	s_mov_b32 s74, 0xb000
	s_mov_b32 s75, 0xe000
	s_mov_b32 s76, 0x11000
	s_mov_b32 s77, 0x14000
	s_movk_i32 s78, 0x1000
	s_mov_b64 s[30:31], 0x3000
	s_movk_i32 s79, 0x3000
	s_mov_b64 s[34:35], 0x4800
	s_movk_i32 s80, 0x4000
	s_mov_b32 s81, 0xffff0000
	s_mov_b32 s82, 0xbfb8aa3b
	s_movk_i32 s83, 0x7fff
	s_add_i32 s84, 0, 0x12000
	s_add_i32 s85, 0, 0x16400
	s_movk_i32 s86, 0x110
	s_add_i32 s87, 0, 0x1a800
	s_mov_b32 s36, 0x3b000000
	s_mov_b32 s38, 0x358637bd
	s_mov_b32 s88, 0xe400000
	s_mov_b32 s89, 0x9000
	s_mov_b32 s90, 0xa000
	s_mov_b32 s91, 0xc000
	s_mov_b32 s92, 0xd000
	s_mov_b32 s93, 0xf000
	s_movk_i32 s94, 0x88
	s_movk_i32 s95, 0x7000
	s_add_i32 s96, 0, 0x13000
	s_mov_b64 s[40:41], 0x2400
	s_mov_b64 s[42:43], 0xe400800
	s_mov_b32 s48, 0x3b800000
	v_mov_b32_e32 v112, 0x41b17218
	v_and_b32_e32 v114, 64, v113
	v_add_u32_e32 v115, -1, v113
	v_add_u32_e32 v116, -2, v113
	v_add_u32_e32 v117, -4, v113
	v_add_u32_e32 v118, -8, v113
	v_add_u32_e32 v119, -16, v113
	v_subrev_u32_e32 v120, 32, v113
	v_mov_b32_e32 v121, 0x1200
	v_mov_b32_e32 v122, 0x1000
	v_mov_b32_e32 v123, 0x500
	v_mov_b32_e32 v124, 0x400
	s_and_b32 s97, s2, 7
	s_lshl_b32 s97, s97, 7
	s_lshr_b32 s8, s2, 3
	s_add_u32 s97, s97, s8
	s_lshl_b32 s37, s97, 4
	s_mov_b32 m0, 0
	s_branch .LBB0_1741

; __global__ void __launch_bounds__(NTHR, 2) fwd_megakernel(Args args) {
;     ...
; #pragma unroll 1
;         for (int it = blockIdx.x; it < 1536; it += gridDim.x) { MKCTX();
.LBB0_1740:
	s_add_u32 s8, m0, 1
	s_mov_b32 m0, s8
	s_add_i32 s97, s97, 32
	s_cmp_eq_u32 s8, 4
	s_cbranch_scc0 .Lrg_skip_b3l1
	s_and_b32 s8, s2, 7
	s_lshl_b32 s8, s8, 6
	s_sub_i32 s97, s97, s8
	s_addk_i32 s97, 0x380
.Lrg_skip_b3l1:
	s_lshl_b32 s37, s97, 4
	s_cmp_gt_u32 m0, 5
	s_cbranch_scc1 .LBB0_1900
